# all neutral trims stacked on v61: rotate folded into select, rare-path select chain, nt final-LN stores, prologue DMA batch hoist, align barrier at first store
# baseline (speedup 1.0000x reference)
; #define PG8_STAGE(bufoff, gbase, voff) do { _Pragma("unroll") for (int _i = 0; _i < 2; ++_i) \
;         __builtin_amdgcn_global_load_lds((const unsigned*)((const char*)(gbase) + (voff)[_i]), (LAS unsigned*)(lds + (bufoff) + ldsw + _i * 8192), 16, 0, 0); } while (0)
; #define PG8_LDA(dst, b, h) do { _Pragma("unroll") for (int m = 0; m < 4; ++m) _Pragma("unroll") for (int k = 0; k < 2; ++k) dst[m][k] = *(const LAS bf16x8*)(lds + PG8_SA(b, h) + aoff + m * 2048 + k * 1024); } while (0)
; #define PG8_LDB(dst, b, h) do { _Pragma("unroll") for (int n = 0; n < 2; ++n) _Pragma("unroll") for (int k = 0; k < 2; ++k) dst[n][k] = *(const LAS bf16x8*)(lds + PG8_SB(b, h) + boff + n * 2048 + k * 1024); } while (0)
; #define PG8_MMA(ai, bj, At, Bt) do { __builtin_amdgcn_s_setprio(1); _Pragma("unroll") for (int m = 0; m < 4; ++m) _Pragma("unroll") for (int n = 0; n < 2; ++n) _Pragma("unroll") for (int k = 0; k < 2; ++k) \
;         acc[ai][bj][m][n] = __builtin_amdgcn_mfma_f32_16x16x32_bf16(Bt[n][k], At[m][k], acc[ai][bj][m][n], 0, 0, 0); __builtin_amdgcn_s_setprio(0); } while (0)
; #define PG8_WAIT_V(n) asm volatile("s_waitcnt vmcnt(" #n ")" ::: "memory")
; #define PG8_WAIT_L(n) asm volatile("s_waitcnt lgkmcnt(" #n ")" ::: "memory")
; #define PG8_BAR __builtin_amdgcn_s_barrier()
; #define PG8_SCHED __builtin_amdgcn_sched_barrier(0)
; template <class Epi, class Sched, bool ABLK = false, bool ALIGN_EPI = true, bool SP2 = true, bool BBLK = true>
; __device__ __forceinline__ void gemm_phase(LAS unsigned char* lds, const Gemm g, const Sched& S, const Epi& E) {
;     ...
;             PG8_LDB(B0, 0, 0); PG8_LDB(B1, 0, 1); PG8_SCHED; PG8_LDA(At, 0, 0); PG8_STAGE(PG8_SA(1, 1), a1 + hstepA, voffA);
;             PG8_WAIT_V(8); PG8_WAIT_L(0); PG8_BAR; PG8_MMA(0, 0, At, B0); PG8_MMA(0, 1, At, B1); PG8_BAR; PG8_SCHED;
;             PG8_LDA(At, 0, 1); PG8_STAGE(PG8_SB(0, 0), b2, voffB); PG8_STAGE(PG8_SB(0, 1), b2 + hstepB, voffB); PG8_STAGE(PG8_SA(0, 0), a2, voffA);
;             PG8_WAIT_V(8); PG8_WAIT_L(0); PG8_BAR; PG8_MMA(1, 0, At, B0); PG8_MMA(1, 1, At, B1); PG8_BAR; PG8_SCHED;
.Lksel_3_back:
	s_mov_b32 m0, s53
	v_lshl_add_u64 v[236:237], v[164:165], 0, s[28:29]
	ds_read_b128 v[204:207], v170
	ds_read_b128 v[208:211], v170 offset:1024
	ds_read_b128 v[212:215], v170 offset:2048
	ds_read_b128 v[216:219], v170 offset:3072
	ds_read_b128 v[220:223], v170 offset:4096
	ds_read_b128 v[224:227], v170 offset:5120
	ds_read_b128 v[228:231], v170 offset:6144
	ds_read_b128 v[232:235], v170 offset:7168
	global_load_lds_dwordx4 v[236:237], off
	v_lshl_add_u64 v[236:237], v[166:167], 0, s[28:29]
	s_mov_b32 m0, s54
	s_nop 0
	global_load_lds_dwordx4 v[236:237], off
	s_waitcnt vmcnt(8) lgkmcnt(0)
	s_barrier
	v_mfma_f32_16x16x32_bf16 v[126:129], v[172:175], v[204:207], v[126:129]
	v_mfma_f32_16x16x32_bf16 v[122:125], v[180:183], v[204:207], v[122:125]
	v_mfma_f32_16x16x32_bf16 v[110:113], v[172:175], v[212:215], v[110:113]
	v_mfma_f32_16x16x32_bf16 v[106:109], v[180:183], v[212:215], v[106:109]
	v_mfma_f32_16x16x32_bf16 v[94:97], v[172:175], v[220:223], v[94:97]
	v_mfma_f32_16x16x32_bf16 v[90:93], v[180:183], v[220:223], v[90:93]
	v_mfma_f32_16x16x32_bf16 v[78:81], v[172:175], v[228:231], v[78:81]
	v_mfma_f32_16x16x32_bf16 v[74:77], v[180:183], v[228:231], v[74:77]
	v_mfma_f32_16x16x32_bf16 v[126:129], v[176:179], v[208:211], v[126:129]
	v_mfma_f32_16x16x32_bf16 v[122:125], v[184:187], v[208:211], v[122:125]
	v_mfma_f32_16x16x32_bf16 v[110:113], v[176:179], v[216:219], v[110:113]
	v_mfma_f32_16x16x32_bf16 v[106:109], v[184:187], v[216:219], v[106:109]
	v_mfma_f32_16x16x32_bf16 v[94:97], v[176:179], v[224:227], v[94:97]
	v_mfma_f32_16x16x32_bf16 v[90:93], v[184:187], v[224:227], v[90:93]
	v_mfma_f32_16x16x32_bf16 v[78:81], v[176:179], v[232:235], v[78:81]
	v_mfma_f32_16x16x32_bf16 v[74:77], v[184:187], v[232:235], v[74:77]
	v_mfma_f32_16x16x32_bf16 v[118:121], v[188:191], v[204:207], v[118:121]
	v_mfma_f32_16x16x32_bf16 v[114:117], v[196:199], v[204:207], v[114:117]
	v_mfma_f32_16x16x32_bf16 v[102:105], v[188:191], v[212:215], v[102:105]
	v_mfma_f32_16x16x32_bf16 v[98:101], v[196:199], v[212:215], v[98:101]
	v_mfma_f32_16x16x32_bf16 v[86:89], v[188:191], v[220:223], v[86:89]
	v_mfma_f32_16x16x32_bf16 v[82:85], v[196:199], v[220:223], v[82:85]
	v_mfma_f32_16x16x32_bf16 v[70:73], v[188:191], v[228:231], v[70:73]
	v_mfma_f32_16x16x32_bf16 v[66:69], v[196:199], v[228:231], v[66:69]
	v_mfma_f32_16x16x32_bf16 v[118:121], v[192:195], v[208:211], v[118:121]
	v_mfma_f32_16x16x32_bf16 v[114:117], v[200:203], v[208:211], v[114:117]
	v_mfma_f32_16x16x32_bf16 v[102:105], v[192:195], v[216:219], v[102:105]
	v_mfma_f32_16x16x32_bf16 v[98:101], v[200:203], v[216:219], v[98:101]
	v_mfma_f32_16x16x32_bf16 v[86:89], v[192:195], v[224:227], v[86:89]
	v_mfma_f32_16x16x32_bf16 v[82:85], v[200:203], v[224:227], v[82:85]
	v_mfma_f32_16x16x32_bf16 v[70:73], v[192:195], v[232:235], v[70:73]
	v_mfma_f32_16x16x32_bf16 v[66:69], v[200:203], v[232:235], v[66:69]
	s_barrier
	s_mov_b32 m0, s55
	s_add_u32 s62, s34, 0x4000
	ds_read_b128 v[204:207], v170 offset:16384
	ds_read_b128 v[208:211], v170 offset:17408
	ds_read_b128 v[212:215], v170 offset:18432
	ds_read_b128 v[216:219], v170 offset:19456
	ds_read_b128 v[220:223], v170 offset:20480
	ds_read_b128 v[224:227], v170 offset:21504
	ds_read_b128 v[228:231], v170 offset:22528
	ds_read_b128 v[232:235], v170 offset:23552
	global_load_lds_dwordx4 v134, s[34:35]
	s_mov_b32 m0, s56
	s_addc_u32 s63, s35, 0
	s_add_i32 s61, s52, s40
	global_load_lds_dwordx4 v130, s[34:35]
	s_mov_b32 m0, s61
	s_nop 0
	global_load_lds_dwordx4 v134, s[62:63]
	s_add_i32 m0, s61, 0x2000
	s_nop 0
	global_load_lds_dwordx4 v130, s[62:63]
	s_mov_b32 m0, s25
	s_nop 0
	global_load_lds_dwordx4 v136, s[36:37]
	s_mov_b32 m0, s43
	s_nop 0
	global_load_lds_dwordx4 v132, s[36:37]
	s_waitcnt vmcnt(8) lgkmcnt(0)
	s_barrier
	v_mfma_f32_16x16x32_bf16 v[62:65], v[172:175], v[204:207], v[62:65]
	v_mfma_f32_16x16x32_bf16 v[58:61], v[180:183], v[204:207], v[58:61]
	v_mfma_f32_16x16x32_bf16 v[46:49], v[172:175], v[212:215], v[46:49]
	v_mfma_f32_16x16x32_bf16 v[42:45], v[180:183], v[212:215], v[42:45]
	v_mfma_f32_16x16x32_bf16 v[30:33], v[172:175], v[220:223], v[30:33]
	v_mfma_f32_16x16x32_bf16 v[26:29], v[180:183], v[220:223], v[26:29]
	v_mfma_f32_16x16x32_bf16 v[14:17], v[172:175], v[228:231], v[14:17]
	v_mfma_f32_16x16x32_bf16 v[10:13], v[180:183], v[228:231], v[10:13]
	v_mfma_f32_16x16x32_bf16 v[62:65], v[176:179], v[208:211], v[62:65]
	v_mfma_f32_16x16x32_bf16 v[58:61], v[184:187], v[208:211], v[58:61]
	v_mfma_f32_16x16x32_bf16 v[46:49], v[176:179], v[216:219], v[46:49]
	v_mfma_f32_16x16x32_bf16 v[42:45], v[184:187], v[216:219], v[42:45]
	v_mfma_f32_16x16x32_bf16 v[30:33], v[176:179], v[224:227], v[30:33]
	v_mfma_f32_16x16x32_bf16 v[26:29], v[184:187], v[224:227], v[26:29]
	v_mfma_f32_16x16x32_bf16 v[14:17], v[176:179], v[232:235], v[14:17]
	v_mfma_f32_16x16x32_bf16 v[10:13], v[184:187], v[232:235], v[10:13]
	v_mfma_f32_16x16x32_bf16 v[54:57], v[188:191], v[204:207], v[54:57]
	v_mfma_f32_16x16x32_bf16 v[50:53], v[196:199], v[204:207], v[50:53]
	v_mfma_f32_16x16x32_bf16 v[38:41], v[188:191], v[212:215], v[38:41]
	v_mfma_f32_16x16x32_bf16 v[34:37], v[196:199], v[212:215], v[34:37]
	v_mfma_f32_16x16x32_bf16 v[22:25], v[188:191], v[220:223], v[22:25]
	v_mfma_f32_16x16x32_bf16 v[18:21], v[196:199], v[220:223], v[18:21]
	v_mfma_f32_16x16x32_bf16 v[6:9], v[188:191], v[228:231], v[6:9]
	v_mfma_f32_16x16x32_bf16 v[2:5], v[196:199], v[228:231], v[2:5]
	v_mfma_f32_16x16x32_bf16 v[54:57], v[192:195], v[208:211], v[54:57]
	v_mfma_f32_16x16x32_bf16 v[50:53], v[200:203], v[208:211], v[50:53]
	v_mfma_f32_16x16x32_bf16 v[38:41], v[192:195], v[216:219], v[38:41]
	v_mfma_f32_16x16x32_bf16 v[34:37], v[200:203], v[216:219], v[34:37]
	v_mfma_f32_16x16x32_bf16 v[22:25], v[192:195], v[224:227], v[22:25]
	v_mfma_f32_16x16x32_bf16 v[18:21], v[200:203], v[224:227], v[18:21]
	v_mfma_f32_16x16x32_bf16 v[6:9], v[192:195], v[232:235], v[6:9]
	v_mfma_f32_16x16x32_bf16 v[2:5], v[200:203], v[232:235], v[2:5]
	s_barrier
; #define PG8_STAGE(bufoff, gbase, voff) do { _Pragma("unroll") for (int _i = 0; _i < 2; ++_i) \
;         __builtin_amdgcn_global_load_lds((const unsigned*)((const char*)(gbase) + (voff)[_i]), (LAS unsigned*)(lds + (bufoff) + ldsw + _i * 8192), 16, 0, 0); } while (0)
; #define PG8_LDA(dst, b, h) do { _Pragma("unroll") for (int m = 0; m < 4; ++m) _Pragma("unroll") for (int k = 0; k < 2; ++k) dst[m][k] = *(const LAS bf16x8*)(lds + PG8_SA(b, h) + aoff + m * 2048 + k * 1024); } while (0)
; #define PG8_LDB(dst, b, h) do { _Pragma("unroll") for (int n = 0; n < 2; ++n) _Pragma("unroll") for (int k = 0; k < 2; ++k) dst[n][k] = *(const LAS bf16x8*)(lds + PG8_SB(b, h) + boff + n * 2048 + k * 1024); } while (0)
; #define PG8_MMA(ai, bj, At, Bt) do { __builtin_amdgcn_s_setprio(1); _Pragma("unroll") for (int m = 0; m < 4; ++m) _Pragma("unroll") for (int n = 0; n < 2; ++n) _Pragma("unroll") for (int k = 0; k < 2; ++k) \
;         acc[ai][bj][m][n] = __builtin_amdgcn_mfma_f32_16x16x32_bf16(Bt[n][k], At[m][k], acc[ai][bj][m][n], 0, 0, 0); __builtin_amdgcn_s_setprio(0); } while (0)
; #define PG8_WAIT_V(n) asm volatile("s_waitcnt vmcnt(" #n ")" ::: "memory")
; #define PG8_WAIT_L(n) asm volatile("s_waitcnt lgkmcnt(" #n ")" ::: "memory")
; #define PG8_BAR __builtin_amdgcn_s_barrier()
; #define PG8_SCHED __builtin_amdgcn_sched_barrier(0)
; template <class Epi, class Sched, bool ABLK = false, bool ALIGN_EPI = true, bool SP2 = true, bool BBLK = true>
; __device__ __forceinline__ void gemm_phase(LAS unsigned char* lds, const Gemm g, const Sched& S, const Epi& E) {
;     ...
;             PG8_LDB(B0, 1, 0); PG8_LDB(B1, 1, 1); PG8_SCHED; PG8_LDA(At, 1, 0); PG8_STAGE(PG8_SA(0, 1), a2 + hstepA, voffA);
;             PG8_WAIT_V(8); PG8_WAIT_L(0); PG8_BAR; PG8_MMA(0, 0, At, B0); PG8_MMA(0, 1, At, B1); PG8_BAR; PG8_SCHED;
;             PG8_LDA(At, 1, 1); PG8_STAGE(PG8_SB(1, 0), b3, voffB); PG8_STAGE(PG8_SB(1, 1), b3 + hstepB, voffB); PG8_STAGE(PG8_SA(1, 0), a3, voffA);
;             PG8_WAIT_V(8); PG8_WAIT_L(0); PG8_BAR; PG8_MMA(1, 0, At, B0); PG8_MMA(1, 1, At, B1); PG8_BAR; PG8_SCHED;
	s_add_i32 s61, 0, 0x18000
	v_add_u32_e32 v171, s61, v1
	s_add_i32 s62, 0, 0x1c000
	ds_read_b128 v[172:175], v171
	ds_read_b128 v[176:179], v171 offset:1024
	ds_read_b128 v[180:183], v171 offset:2048
	ds_read_b128 v[184:187], v171 offset:3072
	v_add_u32_e32 v171, s62, v1
	ds_read_b128 v[188:191], v171
	ds_read_b128 v[192:195], v171 offset:1024
	ds_read_b128 v[196:199], v171 offset:2048
	ds_read_b128 v[200:203], v171 offset:3072
	s_add_u32 s36, s36, 0x80000
	s_addc_u32 s37, s37, 0
	s_mov_b32 m0, s46
	ds_read_b128 v[204:207], v170 offset:32768
	ds_read_b128 v[208:211], v170 offset:33792
	ds_read_b128 v[212:215], v170 offset:34816
	ds_read_b128 v[216:219], v170 offset:35840
	ds_read_b128 v[220:223], v170 offset:36864
	ds_read_b128 v[224:227], v170 offset:37888
	ds_read_b128 v[228:231], v170 offset:38912
	ds_read_b128 v[232:235], v170 offset:39936
	global_load_lds_dwordx4 v136, s[36:37]
	s_mov_b32 m0, s47
	s_nop 0
	global_load_lds_dwordx4 v132, s[36:37]
	s_waitcnt vmcnt(8) lgkmcnt(0)
	s_barrier
	v_mfma_f32_16x16x32_bf16 v[126:129], v[172:175], v[204:207], v[126:129]
	v_mfma_f32_16x16x32_bf16 v[122:125], v[180:183], v[204:207], v[122:125]
	v_mfma_f32_16x16x32_bf16 v[110:113], v[172:175], v[212:215], v[110:113]
	v_mfma_f32_16x16x32_bf16 v[106:109], v[180:183], v[212:215], v[106:109]
	v_mfma_f32_16x16x32_bf16 v[94:97], v[172:175], v[220:223], v[94:97]
	v_mfma_f32_16x16x32_bf16 v[90:93], v[180:183], v[220:223], v[90:93]
	v_mfma_f32_16x16x32_bf16 v[78:81], v[172:175], v[228:231], v[78:81]
	v_mfma_f32_16x16x32_bf16 v[74:77], v[180:183], v[228:231], v[74:77]
	v_mfma_f32_16x16x32_bf16 v[126:129], v[176:179], v[208:211], v[126:129]
	v_mfma_f32_16x16x32_bf16 v[122:125], v[184:187], v[208:211], v[122:125]
	v_mfma_f32_16x16x32_bf16 v[110:113], v[176:179], v[216:219], v[110:113]
	v_mfma_f32_16x16x32_bf16 v[106:109], v[184:187], v[216:219], v[106:109]
	v_mfma_f32_16x16x32_bf16 v[94:97], v[176:179], v[224:227], v[94:97]
	v_mfma_f32_16x16x32_bf16 v[90:93], v[184:187], v[224:227], v[90:93]
	v_mfma_f32_16x16x32_bf16 v[78:81], v[176:179], v[232:235], v[78:81]
	v_mfma_f32_16x16x32_bf16 v[74:77], v[184:187], v[232:235], v[74:77]
	v_mfma_f32_16x16x32_bf16 v[118:121], v[188:191], v[204:207], v[118:121]
	v_mfma_f32_16x16x32_bf16 v[114:117], v[196:199], v[204:207], v[114:117]
	v_mfma_f32_16x16x32_bf16 v[102:105], v[188:191], v[212:215], v[102:105]
	v_mfma_f32_16x16x32_bf16 v[98:101], v[196:199], v[212:215], v[98:101]
	v_mfma_f32_16x16x32_bf16 v[86:89], v[188:191], v[220:223], v[86:89]
	v_mfma_f32_16x16x32_bf16 v[82:85], v[196:199], v[220:223], v[82:85]
	v_mfma_f32_16x16x32_bf16 v[70:73], v[188:191], v[228:231], v[70:73]
	v_mfma_f32_16x16x32_bf16 v[66:69], v[196:199], v[228:231], v[66:69]
	v_mfma_f32_16x16x32_bf16 v[118:121], v[192:195], v[208:211], v[118:121]
	v_mfma_f32_16x16x32_bf16 v[114:117], v[200:203], v[208:211], v[114:117]
	v_mfma_f32_16x16x32_bf16 v[102:105], v[192:195], v[216:219], v[102:105]
	v_mfma_f32_16x16x32_bf16 v[98:101], v[200:203], v[216:219], v[98:101]
	v_mfma_f32_16x16x32_bf16 v[86:89], v[192:195], v[224:227], v[86:89]
	v_mfma_f32_16x16x32_bf16 v[82:85], v[200:203], v[224:227], v[82:85]
	v_mfma_f32_16x16x32_bf16 v[70:73], v[192:195], v[232:235], v[70:73]
	v_mfma_f32_16x16x32_bf16 v[66:69], v[200:203], v[232:235], v[66:69]
	s_barrier
	s_add_u32 s36, s34, 0x8000
	s_addc_u32 s37, s35, 0
	s_add_i32 s61, s61, s40
	s_mov_b32 m0, s61
	ds_read_b128 v[204:207], v170 offset:49152
	ds_read_b128 v[208:211], v170 offset:50176
	ds_read_b128 v[212:215], v170 offset:51200
	ds_read_b128 v[216:219], v170 offset:52224
	ds_read_b128 v[220:223], v170 offset:53248
	ds_read_b128 v[224:227], v170 offset:54272
	ds_read_b128 v[228:231], v170 offset:55296
	ds_read_b128 v[232:235], v170 offset:56320
	global_load_lds_dwordx4 v134, s[36:37]
	s_add_i32 m0, s61, 0x2000
	s_add_u32 s34, s34, 0xc000
	v_lshl_add_u64 v[236:237], s[36:37], 0, v[130:131]
	s_addc_u32 s35, s35, 0
	s_add_i32 s36, s62, s40
	global_load_lds_dwordx4 v[236:237], off
	s_mov_b32 m0, s36
	s_nop 0
	global_load_lds_dwordx4 v134, s[34:35]
	s_add_i32 m0, s36, 0x2000
	s_nop 0
	global_load_lds_dwordx4 v130, s[34:35]
	s_mov_b32 m0, s50
	s_nop 0
	global_load_lds_dwordx4 v136, s[30:31]
	s_mov_b32 m0, s51
	s_nop 0
	global_load_lds_dwordx4 v132, s[30:31]
	s_waitcnt vmcnt(8) lgkmcnt(0)
	s_barrier
	v_mfma_f32_16x16x32_bf16 v[62:65], v[172:175], v[204:207], v[62:65]
	v_mfma_f32_16x16x32_bf16 v[58:61], v[180:183], v[204:207], v[58:61]
	v_mfma_f32_16x16x32_bf16 v[46:49], v[172:175], v[212:215], v[46:49]
	v_mfma_f32_16x16x32_bf16 v[42:45], v[180:183], v[212:215], v[42:45]
	v_mfma_f32_16x16x32_bf16 v[30:33], v[172:175], v[220:223], v[30:33]
	v_mfma_f32_16x16x32_bf16 v[26:29], v[180:183], v[220:223], v[26:29]
	v_mfma_f32_16x16x32_bf16 v[14:17], v[172:175], v[228:231], v[14:17]
	v_mfma_f32_16x16x32_bf16 v[10:13], v[180:183], v[228:231], v[10:13]
	v_mfma_f32_16x16x32_bf16 v[62:65], v[176:179], v[208:211], v[62:65]
	v_mfma_f32_16x16x32_bf16 v[58:61], v[184:187], v[208:211], v[58:61]
	v_mfma_f32_16x16x32_bf16 v[46:49], v[176:179], v[216:219], v[46:49]
	v_mfma_f32_16x16x32_bf16 v[42:45], v[184:187], v[216:219], v[42:45]
	v_mfma_f32_16x16x32_bf16 v[30:33], v[176:179], v[224:227], v[30:33]
	v_mfma_f32_16x16x32_bf16 v[26:29], v[184:187], v[224:227], v[26:29]
	v_mfma_f32_16x16x32_bf16 v[14:17], v[176:179], v[232:235], v[14:17]
	v_mfma_f32_16x16x32_bf16 v[10:13], v[184:187], v[232:235], v[10:13]
	v_mfma_f32_16x16x32_bf16 v[54:57], v[188:191], v[204:207], v[54:57]
	v_mfma_f32_16x16x32_bf16 v[50:53], v[196:199], v[204:207], v[50:53]
	v_mfma_f32_16x16x32_bf16 v[38:41], v[188:191], v[212:215], v[38:41]
	v_mfma_f32_16x16x32_bf16 v[34:37], v[196:199], v[212:215], v[34:37]
	v_mfma_f32_16x16x32_bf16 v[22:25], v[188:191], v[220:223], v[22:25]
	v_mfma_f32_16x16x32_bf16 v[18:21], v[196:199], v[220:223], v[18:21]
	v_mfma_f32_16x16x32_bf16 v[6:9], v[188:191], v[228:231], v[6:9]
	v_mfma_f32_16x16x32_bf16 v[2:5], v[196:199], v[228:231], v[2:5]
	v_mfma_f32_16x16x32_bf16 v[54:57], v[192:195], v[208:211], v[54:57]
	v_mfma_f32_16x16x32_bf16 v[50:53], v[200:203], v[208:211], v[50:53]
	v_mfma_f32_16x16x32_bf16 v[38:41], v[192:195], v[216:219], v[38:41]
	v_mfma_f32_16x16x32_bf16 v[34:37], v[200:203], v[216:219], v[34:37]
	v_mfma_f32_16x16x32_bf16 v[22:25], v[192:195], v[224:227], v[22:25]
	v_mfma_f32_16x16x32_bf16 v[18:21], v[200:203], v[224:227], v[18:21]
	v_mfma_f32_16x16x32_bf16 v[6:9], v[192:195], v[232:235], v[6:9]
	v_mfma_f32_16x16x32_bf16 v[2:5], v[200:203], v[232:235], v[2:5]
	s_barrier
; __device__ __forceinline__ unsigned pk2(float lo, float hi) { const f32x2 v = {lo, hi}; return __builtin_bit_cast(unsigned, __builtin_convertvector(v, bf16x2_t)); }
; #define PG8_BAR __builtin_amdgcn_s_barrier()
; template <class Epi, class Sched, bool ABLK = false, bool ALIGN_EPI = true, bool SP2 = true, bool BBLK = true>
; __device__ __forceinline__ void gemm_phase(LAS unsigned char* lds, const Gemm g, const Sched& S, const Epi& E) {
;     ...
;         if constexpr (ALIGN_EPI) { if (wr == 0) PG8_BAR; }
;         E(acc, cur, wr, wc, fr, fq); S.done(cur);
;     __device__ __forceinline__ void operator()(const f32x4 (&acc)[2][2][4][2], const Unit& u, int wr, int wc, int fr, int fq) const {
; #pragma unroll
;         for (int ai = 0; ai < 2; ++ai)
; #pragma unroll
;             for (int m = 0; m < 4; ++m) { unsigned char* rowp = (unsigned char*)(H + ((size_t)(u.pm * (FF / 64) + u.pn * 4 + wc) * 256 + (wr * 64 + fr + ai * 128 + m * 16)) * 64 + 8 * fq); u32x4 w[2];
; #pragma unroll
;                 for (int bj = 0; bj < 2; ++bj) { f32x4 v0 = acc[ai][bj][m][0], v1 = acc[ai][bj][m][1];
; #pragma unroll
;                     for (int j = 0; j < 4; ++j) { const float a = fmaxf(v0[j], 0.f), b = fmaxf(v1[j], 0.f); v0[j] = a * a; v1[j] = b * b; }
;                     w[bj].x = pk2(v0[0], v0[1]); w[bj].y = pk2(v0[2], v0[3]); w[bj].z = pk2(v1[0], v1[1]); w[bj].w = pk2(v1[2], v1[3]); }
;                 store_pair(rowp, (size_t)8 * 64 * 2, 64, w[0], w[1], fr >= 8); }
	s_add_i32 s60, s60, 2
	s_add_u32 s28, s28, 0x100
	s_addc_u32 s29, s29, 0
	s_add_u32 s58, s58, 0x10000
	s_addc_u32 s59, s59, 0
	s_cmp_gt_u32 s60, 29
	s_cbranch_scc0 .LBB0_475
	s_lshl_b32 s4, s22, 7
	s_lshl_b32 s5, s24, 2
	s_add_i32 s5, s5, s4
	s_or_b32 s4, s5, s49
	s_ashr_i32 s5, s4, 31
	s_lshl_b64 s[4:5], s[4:5], 15
	s_add_u32 s22, s1, s4
	v_max_f32_e32 v126, 0, v126
	v_max_f32_e32 v122, 0, v122
	v_max_f32_e32 v127, 0, v127
	v_max_f32_e32 v123, 0, v123
	v_max_f32_e32 v128, 0, v128
	v_max_f32_e32 v124, 0, v124
	v_max_f32_e32 v129, 0, v129
	v_max_f32_e32 v125, 0, v125
	v_max_f32_e32 v118, 0, v118
	v_max_f32_e32 v114, 0, v114
	v_max_f32_e32 v119, 0, v119
	v_max_f32_e32 v115, 0, v115
	v_max_f32_e32 v120, 0, v120
	v_max_f32_e32 v116, 0, v116
	v_max_f32_e32 v121, 0, v121
	v_max_f32_e32 v117, 0, v117
	s_addc_u32 s23, s33, s5
	v_pk_mul_f32 v[126:127], v[126:127], v[126:127]
	v_pk_mul_f32 v[122:123], v[122:123], v[122:123]
	v_pk_mul_f32 v[128:129], v[128:129], v[128:129]
	v_pk_mul_f32 v[124:125], v[124:125], v[124:125]
	v_pk_mul_f32 v[118:119], v[118:119], v[118:119]
	v_pk_mul_f32 v[114:115], v[114:115], v[114:115]
	v_pk_mul_f32 v[120:121], v[120:121], v[120:121]
	v_pk_mul_f32 v[116:117], v[116:117], v[116:117]
	v_lshl_add_u64 v[164:165], s[22:23], 0, v[144:145]
	v_cvt_pk_bf16_f32 v126, v126, v127
	v_cvt_pk_bf16_f32 v127, v128, v129
	v_cvt_pk_bf16_f32 v128, v122, v123
	v_cvt_pk_bf16_f32 v129, v124, v125
	v_cvt_pk_bf16_f32 v118, v118, v119
	v_cvt_pk_bf16_f32 v119, v120, v121
	v_cvt_pk_bf16_f32 v114, v114, v115
	v_cvt_pk_bf16_f32 v115, v116, v117
	v_lshl_add_u64 v[122:123], v[164:165], 0, v[138:139]
	s_mov_b64 vcc, s[6:7]
	v_mov_b32_dpp v164, v118 row_ror:8 row_mask:0xf bank_mask:0xf bound_ctrl:1
	v_mov_b32_dpp v165, v119 row_ror:8 row_mask:0xf bank_mask:0xf bound_ctrl:1
	v_mov_b32_dpp v166, v114 row_ror:8 row_mask:0xf bank_mask:0xf bound_ctrl:1
	v_mov_b32_dpp v167, v115 row_ror:8 row_mask:0xf bank_mask:0xf bound_ctrl:1
	v_max_f32_e32 v110, 0, v110
	v_max_f32_e32 v106, 0, v106
	v_max_f32_e32 v111, 0, v111
	v_max_f32_e32 v107, 0, v107
	v_max_f32_e32 v112, 0, v112
	v_max_f32_e32 v108, 0, v108
	v_max_f32_e32 v113, 0, v113
	v_max_f32_e32 v109, 0, v109
	v_max_f32_e32 v102, 0, v102
	v_max_f32_e32 v98, 0, v98
	v_max_f32_e32 v103, 0, v103
	v_max_f32_e32 v99, 0, v99
	v_max_f32_e32 v104, 0, v104
	v_max_f32_e32 v100, 0, v100
	v_max_f32_e32 v105, 0, v105
	v_max_f32_e32 v101, 0, v101
	v_lshl_add_u64 v[124:125], v[122:123], 0, v[140:141]
	v_cndmask_b32_dpp v117, v129, v115, vcc row_ror:8 row_mask:0xf bank_mask:0xf bound_ctrl:1
	v_cndmask_b32_dpp v116, v128, v114, vcc row_ror:8 row_mask:0xf bank_mask:0xf bound_ctrl:1
	v_cndmask_b32_dpp v115, v127, v119, vcc row_ror:8 row_mask:0xf bank_mask:0xf bound_ctrl:1
	v_cndmask_b32_dpp v114, v126, v118, vcc row_ror:8 row_mask:0xf bank_mask:0xf bound_ctrl:1
	v_cndmask_b32_e64 v121, v129, v167, s[6:7]
	v_cndmask_b32_e64 v120, v128, v166, s[6:7]
	v_cndmask_b32_e64 v119, v127, v165, s[6:7]
	v_cndmask_b32_e64 v118, v126, v164, s[6:7]
	v_pk_mul_f32 v[110:111], v[110:111], v[110:111]
	v_pk_mul_f32 v[106:107], v[106:107], v[106:107]
	v_pk_mul_f32 v[112:113], v[112:113], v[112:113]
	v_pk_mul_f32 v[108:109], v[108:109], v[108:109]
	v_pk_mul_f32 v[102:103], v[102:103], v[102:103]
	v_pk_mul_f32 v[98:99], v[98:99], v[98:99]
	v_pk_mul_f32 v[104:105], v[104:105], v[104:105]
	v_pk_mul_f32 v[100:101], v[100:101], v[100:101]
	v_lshl_add_u64 v[122:123], v[122:123], 0, v[142:143]
	s_and_b64 vcc, exec, s[8:9]
	s_cbranch_vccz .LBB0_478
	s_barrier
.LBB0_478:
	global_store_dwordx4 v[124:125], v[118:121], off
	global_store_dwordx4 v[122:123], v[114:117], off
	v_cvt_pk_bf16_f32 v110, v110, v111
	v_cvt_pk_bf16_f32 v111, v112, v113
	v_lshl_add_u64 v[114:115], s[22:23], 0, v[146:147]
	v_cvt_pk_bf16_f32 v112, v106, v107
	v_cvt_pk_bf16_f32 v113, v108, v109
	v_cvt_pk_bf16_f32 v102, v102, v103
	v_cvt_pk_bf16_f32 v103, v104, v105
	v_cvt_pk_bf16_f32 v98, v98, v99
	v_cvt_pk_bf16_f32 v99, v100, v101
	v_lshl_add_u64 v[106:107], v[114:115], 0, v[138:139]
	s_mov_b64 vcc, s[6:7]
	v_mov_b32_dpp v114, v102 row_ror:8 row_mask:0xf bank_mask:0xf bound_ctrl:1
	v_mov_b32_dpp v115, v103 row_ror:8 row_mask:0xf bank_mask:0xf bound_ctrl:1
	v_mov_b32_dpp v116, v98 row_ror:8 row_mask:0xf bank_mask:0xf bound_ctrl:1
	v_mov_b32_dpp v117, v99 row_ror:8 row_mask:0xf bank_mask:0xf bound_ctrl:1
	v_max_f32_e32 v94, 0, v94
	v_max_f32_e32 v90, 0, v90
	v_max_f32_e32 v95, 0, v95
	v_max_f32_e32 v91, 0, v91
	v_max_f32_e32 v96, 0, v96
	v_max_f32_e32 v92, 0, v92
	v_max_f32_e32 v97, 0, v97
	v_max_f32_e32 v93, 0, v93
	v_max_f32_e32 v86, 0, v86
	v_max_f32_e32 v82, 0, v82
	v_max_f32_e32 v87, 0, v87
	v_max_f32_e32 v83, 0, v83
	v_max_f32_e32 v88, 0, v88
	v_max_f32_e32 v84, 0, v84
	v_max_f32_e32 v89, 0, v89
	v_max_f32_e32 v85, 0, v85
	v_lshl_add_u64 v[108:109], v[106:107], 0, v[140:141]
	v_cndmask_b32_dpp v101, v113, v99, vcc row_ror:8 row_mask:0xf bank_mask:0xf bound_ctrl:1
	v_cndmask_b32_dpp v100, v112, v98, vcc row_ror:8 row_mask:0xf bank_mask:0xf bound_ctrl:1
	v_cndmask_b32_dpp v99, v111, v103, vcc row_ror:8 row_mask:0xf bank_mask:0xf bound_ctrl:1
	v_cndmask_b32_dpp v98, v110, v102, vcc row_ror:8 row_mask:0xf bank_mask:0xf bound_ctrl:1
	v_cndmask_b32_e64 v105, v113, v117, s[6:7]
	v_cndmask_b32_e64 v104, v112, v116, s[6:7]
	v_cndmask_b32_e64 v103, v111, v115, s[6:7]
	v_cndmask_b32_e64 v102, v110, v114, s[6:7]
	v_pk_mul_f32 v[94:95], v[94:95], v[94:95]
	v_pk_mul_f32 v[90:91], v[90:91], v[90:91]
	v_pk_mul_f32 v[96:97], v[96:97], v[96:97]
	v_pk_mul_f32 v[92:93], v[92:93], v[92:93]
	v_pk_mul_f32 v[86:87], v[86:87], v[86:87]
	v_pk_mul_f32 v[82:83], v[82:83], v[82:83]
	v_pk_mul_f32 v[88:89], v[88:89], v[88:89]
; __device__ __forceinline__ unsigned pk2(float lo, float hi) { const f32x2 v = {lo, hi}; return __builtin_bit_cast(unsigned, __builtin_convertvector(v, bf16x2_t)); }
; __device__ __forceinline__ void store_pair(unsigned char* own, size_t stride8, int hi_off, u32x4 lo, u32x4 hi, bool upper) {
;     const u32x4 tlo = ror8(lo), thi = ror8(hi);
;     const u32x4 A = upper ? thi : lo, B = upper ? hi : tlo;
;     unsigned char* pa = upper ? own - stride8 + hi_off : own;
;     unsigned char* pb = upper ? own + hi_off : own + stride8;
;     *(u32x4*)pa = A; *(u32x4*)pb = B;
; }
;     __device__ __forceinline__ void operator()(const f32x4 (&acc)[2][2][4][2], const Unit& u, int wr, int wc, int fr, int fq) const {
;     ...
;             for (int m = 0; m < 4; ++m) { unsigned char* rowp = (unsigned char*)(H + ((size_t)(u.pm * (FF / 64) + u.pn * 4 + wc) * 256 + (wr * 64 + fr + ai * 128 + m * 16)) * 64 + 8 * fq); u32x4 w[2];
; #pragma unroll
;                 for (int bj = 0; bj < 2; ++bj) { f32x4 v0 = acc[ai][bj][m][0], v1 = acc[ai][bj][m][1];
; #pragma unroll
;                     for (int j = 0; j < 4; ++j) { const float a = fmaxf(v0[j], 0.f), b = fmaxf(v1[j], 0.f); v0[j] = a * a; v1[j] = b * b; }
;                     w[bj].x = pk2(v0[0], v0[1]); w[bj].y = pk2(v0[2], v0[3]); w[bj].z = pk2(v1[0], v1[1]); w[bj].w = pk2(v1[2], v1[3]); }
;                 store_pair(rowp, (size_t)8 * 64 * 2, 64, w[0], w[1], fr >= 8); }
	v_pk_mul_f32 v[84:85], v[84:85], v[84:85]
	v_lshl_add_u64 v[106:107], v[106:107], 0, v[142:143]
	global_store_dwordx4 v[108:109], v[102:105], off
	global_store_dwordx4 v[106:107], v[98:101], off
	v_cvt_pk_bf16_f32 v94, v94, v95
	v_cvt_pk_bf16_f32 v95, v96, v97
	v_lshl_add_u64 v[98:99], s[22:23], 0, v[148:149]
	v_cvt_pk_bf16_f32 v96, v90, v91
	v_cvt_pk_bf16_f32 v97, v92, v93
	v_cvt_pk_bf16_f32 v86, v86, v87
	v_cvt_pk_bf16_f32 v87, v88, v89
	v_cvt_pk_bf16_f32 v82, v82, v83
	v_cvt_pk_bf16_f32 v83, v84, v85
	v_lshl_add_u64 v[90:91], v[98:99], 0, v[138:139]
	s_mov_b64 vcc, s[6:7]
	v_mov_b32_dpp v98, v86 row_ror:8 row_mask:0xf bank_mask:0xf bound_ctrl:1
	v_mov_b32_dpp v99, v87 row_ror:8 row_mask:0xf bank_mask:0xf bound_ctrl:1
	v_mov_b32_dpp v100, v82 row_ror:8 row_mask:0xf bank_mask:0xf bound_ctrl:1
	v_mov_b32_dpp v101, v83 row_ror:8 row_mask:0xf bank_mask:0xf bound_ctrl:1
	v_max_f32_e32 v78, 0, v78
	v_max_f32_e32 v74, 0, v74
	v_max_f32_e32 v79, 0, v79
	v_max_f32_e32 v75, 0, v75
	v_max_f32_e32 v80, 0, v80
	v_max_f32_e32 v76, 0, v76
	v_max_f32_e32 v81, 0, v81
	v_max_f32_e32 v77, 0, v77
	v_max_f32_e32 v70, 0, v70
	v_max_f32_e32 v66, 0, v66
	v_max_f32_e32 v71, 0, v71
	v_max_f32_e32 v67, 0, v67
	v_max_f32_e32 v72, 0, v72
	v_max_f32_e32 v68, 0, v68
	v_max_f32_e32 v73, 0, v73
	v_max_f32_e32 v69, 0, v69
	v_lshl_add_u64 v[92:93], v[90:91], 0, v[140:141]
	v_cndmask_b32_dpp v85, v97, v83, vcc row_ror:8 row_mask:0xf bank_mask:0xf bound_ctrl:1
	v_cndmask_b32_dpp v84, v96, v82, vcc row_ror:8 row_mask:0xf bank_mask:0xf bound_ctrl:1
	v_cndmask_b32_dpp v83, v95, v87, vcc row_ror:8 row_mask:0xf bank_mask:0xf bound_ctrl:1
	v_cndmask_b32_dpp v82, v94, v86, vcc row_ror:8 row_mask:0xf bank_mask:0xf bound_ctrl:1
	v_cndmask_b32_e64 v89, v97, v101, s[6:7]
	v_cndmask_b32_e64 v88, v96, v100, s[6:7]
	v_cndmask_b32_e64 v87, v95, v99, s[6:7]
	v_cndmask_b32_e64 v86, v94, v98, s[6:7]
	v_pk_mul_f32 v[78:79], v[78:79], v[78:79]
	v_pk_mul_f32 v[74:75], v[74:75], v[74:75]
	v_pk_mul_f32 v[80:81], v[80:81], v[80:81]
	v_pk_mul_f32 v[76:77], v[76:77], v[76:77]
	v_pk_mul_f32 v[70:71], v[70:71], v[70:71]
	v_pk_mul_f32 v[66:67], v[66:67], v[66:67]
	v_pk_mul_f32 v[72:73], v[72:73], v[72:73]
	v_pk_mul_f32 v[68:69], v[68:69], v[68:69]
	v_lshl_add_u64 v[90:91], v[90:91], 0, v[142:143]
	global_store_dwordx4 v[92:93], v[86:89], off
	global_store_dwordx4 v[90:91], v[82:85], off
	v_cvt_pk_bf16_f32 v78, v78, v79
	v_cvt_pk_bf16_f32 v79, v80, v81
	v_lshl_add_u64 v[82:83], s[22:23], 0, v[150:151]
	v_cvt_pk_bf16_f32 v80, v74, v75
	v_cvt_pk_bf16_f32 v81, v76, v77
	v_cvt_pk_bf16_f32 v70, v70, v71
	v_cvt_pk_bf16_f32 v71, v72, v73
	v_cvt_pk_bf16_f32 v66, v66, v67
	v_cvt_pk_bf16_f32 v67, v68, v69
	v_lshl_add_u64 v[74:75], v[82:83], 0, v[138:139]
	s_mov_b64 vcc, s[6:7]
	v_mov_b32_dpp v82, v70 row_ror:8 row_mask:0xf bank_mask:0xf bound_ctrl:1
	v_mov_b32_dpp v83, v71 row_ror:8 row_mask:0xf bank_mask:0xf bound_ctrl:1
	v_mov_b32_dpp v84, v66 row_ror:8 row_mask:0xf bank_mask:0xf bound_ctrl:1
	v_mov_b32_dpp v85, v67 row_ror:8 row_mask:0xf bank_mask:0xf bound_ctrl:1
	v_max_f32_e32 v62, 0, v62
	v_max_f32_e32 v58, 0, v58
	v_max_f32_e32 v63, 0, v63
	v_max_f32_e32 v59, 0, v59
	v_max_f32_e32 v64, 0, v64
	v_max_f32_e32 v60, 0, v60
	v_max_f32_e32 v65, 0, v65
	v_max_f32_e32 v61, 0, v61
	v_max_f32_e32 v54, 0, v54
	v_max_f32_e32 v50, 0, v50
	v_max_f32_e32 v55, 0, v55
	v_max_f32_e32 v51, 0, v51
	v_max_f32_e32 v56, 0, v56
	v_max_f32_e32 v52, 0, v52
	v_max_f32_e32 v57, 0, v57
	v_max_f32_e32 v53, 0, v53
	v_lshl_add_u64 v[76:77], v[74:75], 0, v[140:141]
	v_cndmask_b32_dpp v69, v81, v67, vcc row_ror:8 row_mask:0xf bank_mask:0xf bound_ctrl:1
	v_cndmask_b32_dpp v68, v80, v66, vcc row_ror:8 row_mask:0xf bank_mask:0xf bound_ctrl:1
	v_cndmask_b32_dpp v67, v79, v71, vcc row_ror:8 row_mask:0xf bank_mask:0xf bound_ctrl:1
	v_cndmask_b32_dpp v66, v78, v70, vcc row_ror:8 row_mask:0xf bank_mask:0xf bound_ctrl:1
	v_cndmask_b32_e64 v73, v81, v85, s[6:7]
	v_cndmask_b32_e64 v72, v80, v84, s[6:7]
	v_cndmask_b32_e64 v71, v79, v83, s[6:7]
	v_cndmask_b32_e64 v70, v78, v82, s[6:7]
	v_pk_mul_f32 v[62:63], v[62:63], v[62:63]
	v_pk_mul_f32 v[58:59], v[58:59], v[58:59]
	v_pk_mul_f32 v[64:65], v[64:65], v[64:65]
	v_pk_mul_f32 v[60:61], v[60:61], v[60:61]
	v_pk_mul_f32 v[54:55], v[54:55], v[54:55]
	v_pk_mul_f32 v[50:51], v[50:51], v[50:51]
	v_pk_mul_f32 v[56:57], v[56:57], v[56:57]
	v_pk_mul_f32 v[52:53], v[52:53], v[52:53]
	v_lshl_add_u64 v[74:75], v[74:75], 0, v[142:143]
	global_store_dwordx4 v[76:77], v[70:73], off
	global_store_dwordx4 v[74:75], v[66:69], off
	v_cvt_pk_bf16_f32 v62, v62, v63
	v_cvt_pk_bf16_f32 v63, v64, v65
	v_lshl_add_u64 v[66:67], s[22:23], 0, v[152:153]
	v_cvt_pk_bf16_f32 v64, v58, v59
	v_cvt_pk_bf16_f32 v65, v60, v61
	v_cvt_pk_bf16_f32 v54, v54, v55
	v_cvt_pk_bf16_f32 v55, v56, v57
	v_cvt_pk_bf16_f32 v50, v50, v51
	v_cvt_pk_bf16_f32 v51, v52, v53
	v_lshl_add_u64 v[58:59], v[66:67], 0, v[138:139]
	s_mov_b64 vcc, s[6:7]
	v_mov_b32_dpp v66, v54 row_ror:8 row_mask:0xf bank_mask:0xf bound_ctrl:1
	v_mov_b32_dpp v67, v55 row_ror:8 row_mask:0xf bank_mask:0xf bound_ctrl:1
	v_mov_b32_dpp v68, v50 row_ror:8 row_mask:0xf bank_mask:0xf bound_ctrl:1
	v_mov_b32_dpp v69, v51 row_ror:8 row_mask:0xf bank_mask:0xf bound_ctrl:1
	v_max_f32_e32 v46, 0, v46
	v_max_f32_e32 v42, 0, v42
	v_max_f32_e32 v47, 0, v47
	v_max_f32_e32 v43, 0, v43
	v_max_f32_e32 v48, 0, v48
	v_max_f32_e32 v44, 0, v44
	v_max_f32_e32 v49, 0, v49
	v_max_f32_e32 v45, 0, v45
	v_max_f32_e32 v38, 0, v38
	v_max_f32_e32 v34, 0, v34
	v_max_f32_e32 v39, 0, v39
	v_max_f32_e32 v35, 0, v35
	v_max_f32_e32 v40, 0, v40
	v_max_f32_e32 v36, 0, v36
	v_max_f32_e32 v41, 0, v41
	v_max_f32_e32 v37, 0, v37
; __device__ __forceinline__ unsigned pk2(float lo, float hi) { const f32x2 v = {lo, hi}; return __builtin_bit_cast(unsigned, __builtin_convertvector(v, bf16x2_t)); }
; #define PG8_BAR __builtin_amdgcn_s_barrier()
; template <class Epi, class Sched, bool ABLK = false, bool ALIGN_EPI = true, bool SP2 = true, bool BBLK = true>
; __device__ __forceinline__ void gemm_phase(LAS unsigned char* lds, const Gemm g, const Sched& S, const Epi& E) {
;     ...
;         if (!has_next) break;
; #pragma unroll
;         for (int a = 0; a < 2; ++a)
; #pragma unroll
;             for (int b = 0; b < 2; ++b)
; #pragma unroll
;                 for (int m = 0; m < 4; ++m)
; #pragma unroll
;                     for (int n = 0; n < 2; ++n) acc[a][b][m][n] = (f32x4){0.f, 0.f, 0.f, 0.f};
;         cur = nxt; uA = nuA; tbA = ntbA; cB = nB; ++ui;
;         if constexpr (ALIGN_EPI) { if (wr == 1) PG8_BAR; }
;     __device__ __forceinline__ void operator()(const f32x4 (&acc)[2][2][4][2], const Unit& u, int wr, int wc, int fr, int fq) const {
;     ...
;             for (int m = 0; m < 4; ++m) { unsigned char* rowp = (unsigned char*)(H + ((size_t)(u.pm * (FF / 64) + u.pn * 4 + wc) * 256 + (wr * 64 + fr + ai * 128 + m * 16)) * 64 + 8 * fq); u32x4 w[2];
; #pragma unroll
;                 for (int bj = 0; bj < 2; ++bj) { f32x4 v0 = acc[ai][bj][m][0], v1 = acc[ai][bj][m][1];
; #pragma unroll
;                     for (int j = 0; j < 4; ++j) { const float a = fmaxf(v0[j], 0.f), b = fmaxf(v1[j], 0.f); v0[j] = a * a; v1[j] = b * b; }
;                     w[bj].x = pk2(v0[0], v0[1]); w[bj].y = pk2(v0[2], v0[3]); w[bj].z = pk2(v1[0], v1[1]); w[bj].w = pk2(v1[2], v1[3]); }
;                 store_pair(rowp, (size_t)8 * 64 * 2, 64, w[0], w[1], fr >= 8); }
	v_lshl_add_u64 v[60:61], v[58:59], 0, v[140:141]
	v_cndmask_b32_dpp v53, v65, v51, vcc row_ror:8 row_mask:0xf bank_mask:0xf bound_ctrl:1
	v_cndmask_b32_dpp v52, v64, v50, vcc row_ror:8 row_mask:0xf bank_mask:0xf bound_ctrl:1
	v_cndmask_b32_dpp v51, v63, v55, vcc row_ror:8 row_mask:0xf bank_mask:0xf bound_ctrl:1
	v_cndmask_b32_dpp v50, v62, v54, vcc row_ror:8 row_mask:0xf bank_mask:0xf bound_ctrl:1
	v_cndmask_b32_e64 v57, v65, v69, s[6:7]
	v_cndmask_b32_e64 v56, v64, v68, s[6:7]
	v_cndmask_b32_e64 v55, v63, v67, s[6:7]
	v_cndmask_b32_e64 v54, v62, v66, s[6:7]
	v_pk_mul_f32 v[46:47], v[46:47], v[46:47]
	v_pk_mul_f32 v[42:43], v[42:43], v[42:43]
	v_pk_mul_f32 v[48:49], v[48:49], v[48:49]
	v_pk_mul_f32 v[44:45], v[44:45], v[44:45]
	v_pk_mul_f32 v[38:39], v[38:39], v[38:39]
	v_pk_mul_f32 v[34:35], v[34:35], v[34:35]
	v_pk_mul_f32 v[40:41], v[40:41], v[40:41]
	v_pk_mul_f32 v[36:37], v[36:37], v[36:37]
	v_lshl_add_u64 v[58:59], v[58:59], 0, v[142:143]
	global_store_dwordx4 v[60:61], v[54:57], off
	global_store_dwordx4 v[58:59], v[50:53], off
	v_cvt_pk_bf16_f32 v46, v46, v47
	v_cvt_pk_bf16_f32 v47, v48, v49
	v_lshl_add_u64 v[50:51], s[22:23], 0, v[154:155]
	v_cvt_pk_bf16_f32 v48, v42, v43
	v_cvt_pk_bf16_f32 v49, v44, v45
	v_cvt_pk_bf16_f32 v38, v38, v39
	v_cvt_pk_bf16_f32 v39, v40, v41
	v_cvt_pk_bf16_f32 v34, v34, v35
	v_cvt_pk_bf16_f32 v35, v36, v37
	v_lshl_add_u64 v[42:43], v[50:51], 0, v[138:139]
	s_mov_b64 vcc, s[6:7]
	v_mov_b32_dpp v50, v38 row_ror:8 row_mask:0xf bank_mask:0xf bound_ctrl:1
	v_mov_b32_dpp v51, v39 row_ror:8 row_mask:0xf bank_mask:0xf bound_ctrl:1
	v_mov_b32_dpp v52, v34 row_ror:8 row_mask:0xf bank_mask:0xf bound_ctrl:1
	v_mov_b32_dpp v53, v35 row_ror:8 row_mask:0xf bank_mask:0xf bound_ctrl:1
	v_max_f32_e32 v30, 0, v30
	v_max_f32_e32 v26, 0, v26
	v_max_f32_e32 v31, 0, v31
	v_max_f32_e32 v27, 0, v27
	v_max_f32_e32 v32, 0, v32
	v_max_f32_e32 v28, 0, v28
	v_max_f32_e32 v33, 0, v33
	v_max_f32_e32 v29, 0, v29
	v_max_f32_e32 v22, 0, v22
	v_max_f32_e32 v18, 0, v18
	v_max_f32_e32 v23, 0, v23
	v_max_f32_e32 v19, 0, v19
	v_max_f32_e32 v24, 0, v24
	v_max_f32_e32 v20, 0, v20
	v_max_f32_e32 v25, 0, v25
	v_max_f32_e32 v21, 0, v21
	v_lshl_add_u64 v[44:45], v[42:43], 0, v[140:141]
	v_cndmask_b32_dpp v37, v49, v35, vcc row_ror:8 row_mask:0xf bank_mask:0xf bound_ctrl:1
	v_cndmask_b32_dpp v36, v48, v34, vcc row_ror:8 row_mask:0xf bank_mask:0xf bound_ctrl:1
	v_cndmask_b32_dpp v35, v47, v39, vcc row_ror:8 row_mask:0xf bank_mask:0xf bound_ctrl:1
	v_cndmask_b32_dpp v34, v46, v38, vcc row_ror:8 row_mask:0xf bank_mask:0xf bound_ctrl:1
	v_cndmask_b32_e64 v41, v49, v53, s[6:7]
	v_cndmask_b32_e64 v40, v48, v52, s[6:7]
	v_cndmask_b32_e64 v39, v47, v51, s[6:7]
	v_cndmask_b32_e64 v38, v46, v50, s[6:7]
	v_pk_mul_f32 v[30:31], v[30:31], v[30:31]
	v_pk_mul_f32 v[26:27], v[26:27], v[26:27]
	v_pk_mul_f32 v[32:33], v[32:33], v[32:33]
	v_pk_mul_f32 v[28:29], v[28:29], v[28:29]
	v_pk_mul_f32 v[22:23], v[22:23], v[22:23]
	v_pk_mul_f32 v[18:19], v[18:19], v[18:19]
	v_pk_mul_f32 v[24:25], v[24:25], v[24:25]
	v_pk_mul_f32 v[20:21], v[20:21], v[20:21]
	v_lshl_add_u64 v[42:43], v[42:43], 0, v[142:143]
	global_store_dwordx4 v[44:45], v[38:41], off
	global_store_dwordx4 v[42:43], v[34:37], off
	v_cvt_pk_bf16_f32 v30, v30, v31
	v_cvt_pk_bf16_f32 v31, v32, v33
	v_lshl_add_u64 v[34:35], s[22:23], 0, v[156:157]
	v_cvt_pk_bf16_f32 v32, v26, v27
	v_cvt_pk_bf16_f32 v33, v28, v29
	v_cvt_pk_bf16_f32 v22, v22, v23
	v_cvt_pk_bf16_f32 v23, v24, v25
	v_cvt_pk_bf16_f32 v18, v18, v19
	v_cvt_pk_bf16_f32 v19, v20, v21
	v_lshl_add_u64 v[26:27], v[34:35], 0, v[138:139]
	s_mov_b64 vcc, s[6:7]
	v_mov_b32_dpp v34, v22 row_ror:8 row_mask:0xf bank_mask:0xf bound_ctrl:1
	v_mov_b32_dpp v35, v23 row_ror:8 row_mask:0xf bank_mask:0xf bound_ctrl:1
	v_mov_b32_dpp v36, v18 row_ror:8 row_mask:0xf bank_mask:0xf bound_ctrl:1
	v_mov_b32_dpp v37, v19 row_ror:8 row_mask:0xf bank_mask:0xf bound_ctrl:1
	v_max_f32_e32 v14, 0, v14
	v_max_f32_e32 v10, 0, v10
	v_max_f32_e32 v15, 0, v15
	v_max_f32_e32 v11, 0, v11
	v_max_f32_e32 v16, 0, v16
	v_max_f32_e32 v12, 0, v12
	v_max_f32_e32 v17, 0, v17
	v_max_f32_e32 v13, 0, v13
	v_max_f32_e32 v6, 0, v6
	v_max_f32_e32 v2, 0, v2
	v_max_f32_e32 v7, 0, v7
	v_max_f32_e32 v3, 0, v3
	v_max_f32_e32 v8, 0, v8
	v_max_f32_e32 v4, 0, v4
	v_max_f32_e32 v9, 0, v9
	v_max_f32_e32 v5, 0, v5
	v_lshl_add_u64 v[28:29], v[26:27], 0, v[140:141]
	v_cndmask_b32_dpp v21, v33, v19, vcc row_ror:8 row_mask:0xf bank_mask:0xf bound_ctrl:1
	v_cndmask_b32_dpp v20, v32, v18, vcc row_ror:8 row_mask:0xf bank_mask:0xf bound_ctrl:1
	v_cndmask_b32_dpp v19, v31, v23, vcc row_ror:8 row_mask:0xf bank_mask:0xf bound_ctrl:1
	v_cndmask_b32_dpp v18, v30, v22, vcc row_ror:8 row_mask:0xf bank_mask:0xf bound_ctrl:1
	v_cndmask_b32_e64 v25, v33, v37, s[6:7]
	v_cndmask_b32_e64 v24, v32, v36, s[6:7]
	v_cndmask_b32_e64 v23, v31, v35, s[6:7]
	v_cndmask_b32_e64 v22, v30, v34, s[6:7]
	v_pk_mul_f32 v[14:15], v[14:15], v[14:15]
	v_pk_mul_f32 v[10:11], v[10:11], v[10:11]
	v_pk_mul_f32 v[16:17], v[16:17], v[16:17]
	v_pk_mul_f32 v[12:13], v[12:13], v[12:13]
	v_pk_mul_f32 v[6:7], v[6:7], v[6:7]
	v_pk_mul_f32 v[2:3], v[2:3], v[2:3]
	v_pk_mul_f32 v[8:9], v[8:9], v[8:9]
	v_pk_mul_f32 v[4:5], v[4:5], v[4:5]
	v_lshl_add_u64 v[26:27], v[26:27], 0, v[142:143]
	global_store_dwordx4 v[28:29], v[22:25], off
	global_store_dwordx4 v[26:27], v[18:21], off
	v_cvt_pk_bf16_f32 v14, v14, v15
	v_cvt_pk_bf16_f32 v15, v16, v17
	v_lshl_add_u64 v[18:19], s[22:23], 0, v[158:159]
	v_cvt_pk_bf16_f32 v16, v10, v11
	v_cvt_pk_bf16_f32 v17, v12, v13
	v_cvt_pk_bf16_f32 v6, v6, v7
	v_cvt_pk_bf16_f32 v7, v8, v9
	v_cvt_pk_bf16_f32 v2, v2, v3
	v_cvt_pk_bf16_f32 v3, v4, v5
	v_lshl_add_u64 v[10:11], v[18:19], 0, v[138:139]
	s_mov_b64 vcc, s[6:7]
	v_mov_b32_dpp v18, v6 row_ror:8 row_mask:0xf bank_mask:0xf bound_ctrl:1
	v_mov_b32_dpp v19, v7 row_ror:8 row_mask:0xf bank_mask:0xf bound_ctrl:1
	v_mov_b32_dpp v20, v2 row_ror:8 row_mask:0xf bank_mask:0xf bound_ctrl:1
	v_mov_b32_dpp v21, v3 row_ror:8 row_mask:0xf bank_mask:0xf bound_ctrl:1
	v_lshl_add_u64 v[12:13], v[10:11], 0, v[140:141]
	v_cndmask_b32_dpp v5, v17, v3, vcc row_ror:8 row_mask:0xf bank_mask:0xf bound_ctrl:1
	v_cndmask_b32_dpp v4, v16, v2, vcc row_ror:8 row_mask:0xf bank_mask:0xf bound_ctrl:1
	v_cndmask_b32_dpp v3, v15, v7, vcc row_ror:8 row_mask:0xf bank_mask:0xf bound_ctrl:1
	v_cndmask_b32_dpp v2, v14, v6, vcc row_ror:8 row_mask:0xf bank_mask:0xf bound_ctrl:1
	v_cndmask_b32_e64 v9, v17, v21, s[6:7]
	v_cndmask_b32_e64 v8, v16, v20, s[6:7]
	v_cndmask_b32_e64 v7, v15, v19, s[6:7]
	v_cndmask_b32_e64 v6, v14, v18, s[6:7]
	s_andn2_b64 vcc, exec, s[18:19]
	s_mov_b64 s[4:5], -1
	v_lshl_add_u64 v[10:11], v[10:11], 0, v[142:143]
	global_store_dwordx4 v[12:13], v[6:9], off
	global_store_dwordx4 v[10:11], v[2:5], off
	s_cbranch_vccnz .LBB0_471
	s_andn2_b64 vcc, exec, s[2:3]
	s_cbranch_vccnz .LBB0_470
	s_barrier
	s_branch .LBB0_470

; #define PG8_STAGE(bufoff, gbase, voff) do { _Pragma("unroll") for (int _i = 0; _i < 2; ++_i) \
;         __builtin_amdgcn_global_load_lds((const unsigned*)((const char*)(gbase) + (voff)[_i]), (LAS unsigned*)(lds + (bufoff) + ldsw + _i * 8192), 16, 0, 0); } while (0)
; #define PG8_LDA(dst, b, h) do { _Pragma("unroll") for (int m = 0; m < 4; ++m) _Pragma("unroll") for (int k = 0; k < 2; ++k) dst[m][k] = *(const LAS bf16x8*)(lds + PG8_SA(b, h) + aoff + m * 2048 + k * 1024); } while (0)
; #define PG8_LDB(dst, b, h) do { _Pragma("unroll") for (int n = 0; n < 2; ++n) _Pragma("unroll") for (int k = 0; k < 2; ++k) dst[n][k] = *(const LAS bf16x8*)(lds + PG8_SB(b, h) + boff + n * 2048 + k * 1024); } while (0)
; #define PG8_MMA(ai, bj, At, Bt) do { __builtin_amdgcn_s_setprio(1); _Pragma("unroll") for (int m = 0; m < 4; ++m) _Pragma("unroll") for (int n = 0; n < 2; ++n) _Pragma("unroll") for (int k = 0; k < 2; ++k) \
;         acc[ai][bj][m][n] = __builtin_amdgcn_mfma_f32_16x16x32_bf16(Bt[n][k], At[m][k], acc[ai][bj][m][n], 0, 0, 0); __builtin_amdgcn_s_setprio(0); } while (0)
; #define PG8_WAIT_V(n) asm volatile("s_waitcnt vmcnt(" #n ")" ::: "memory")
; #define PG8_WAIT_L(n) asm volatile("s_waitcnt lgkmcnt(" #n ")" ::: "memory")
; #define PG8_BAR __builtin_amdgcn_s_barrier()
; #define PG8_SCHED __builtin_amdgcn_sched_barrier(0)
; template <class Epi, class Sched, bool ABLK = false, bool ALIGN_EPI = true, bool SP2 = true, bool BBLK = true>
; __device__ __forceinline__ void gemm_phase(LAS unsigned char* lds, const Gemm g, const Sched& S, const Epi& E) {
;     ...
;             PG8_LDB(B0, 0, 0); PG8_LDB(B1, 0, 1); PG8_SCHED; PG8_LDA(At, 0, 0); PG8_STAGE(PG8_SA(1, 1), a1 + hstepA, voffA);
;             PG8_WAIT_V(8); PG8_WAIT_L(0); PG8_BAR; PG8_MMA(0, 0, At, B0); PG8_MMA(0, 1, At, B1); PG8_BAR; PG8_SCHED;
;             PG8_LDA(At, 0, 1); PG8_STAGE(PG8_SB(0, 0), b2, voffB); PG8_STAGE(PG8_SB(0, 1), b2 + hstepB, voffB); PG8_STAGE(PG8_SA(0, 0), a2, voffA);
;             PG8_WAIT_V(8); PG8_WAIT_L(0); PG8_BAR; PG8_MMA(1, 0, At, B0); PG8_MMA(1, 1, At, B1); PG8_BAR; PG8_SCHED;
.Lksel_5_back:
	v_lshl_add_u64 v[216:217], v[142:143], 0, s[40:41]
	s_add_i32 m0, s52, 0xc000
	ds_read_b128 v[184:187], v150
	ds_read_b128 v[188:191], v150 offset:1024
	ds_read_b128 v[192:195], v150 offset:2048
	ds_read_b128 v[196:199], v150 offset:3072
	ds_read_b128 v[200:203], v150 offset:4096
	ds_read_b128 v[204:207], v150 offset:5120
	ds_read_b128 v[208:211], v150 offset:6144
	ds_read_b128 v[212:215], v150 offset:7168
	global_load_lds_dwordx4 v[216:217], off
	v_lshl_add_u64 v[216:217], v[144:145], 0, s[40:41]
	s_add_i32 m0, s52, 0xe000
	s_nop 0
	global_load_lds_dwordx4 v[216:217], off
	s_waitcnt vmcnt(8) lgkmcnt(0)
	s_barrier
	v_mfma_f32_16x16x32_bf16 v[126:129], v[152:155], v[184:187], v[126:129]
	v_mfma_f32_16x16x32_bf16 v[122:125], v[160:163], v[184:187], v[122:125]
	v_mfma_f32_16x16x32_bf16 v[110:113], v[152:155], v[192:195], v[110:113]
	v_mfma_f32_16x16x32_bf16 v[106:109], v[160:163], v[192:195], v[106:109]
	v_mfma_f32_16x16x32_bf16 v[94:97], v[152:155], v[200:203], v[94:97]
	v_mfma_f32_16x16x32_bf16 v[90:93], v[160:163], v[200:203], v[90:93]
	v_mfma_f32_16x16x32_bf16 v[78:81], v[152:155], v[208:211], v[78:81]
	v_mfma_f32_16x16x32_bf16 v[74:77], v[160:163], v[208:211], v[74:77]
	v_mfma_f32_16x16x32_bf16 v[126:129], v[156:159], v[188:191], v[126:129]
	v_mfma_f32_16x16x32_bf16 v[122:125], v[164:167], v[188:191], v[122:125]
	v_mfma_f32_16x16x32_bf16 v[110:113], v[156:159], v[196:199], v[110:113]
	v_mfma_f32_16x16x32_bf16 v[106:109], v[164:167], v[196:199], v[106:109]
	v_mfma_f32_16x16x32_bf16 v[94:97], v[156:159], v[204:207], v[94:97]
	v_mfma_f32_16x16x32_bf16 v[90:93], v[164:167], v[204:207], v[90:93]
	v_mfma_f32_16x16x32_bf16 v[78:81], v[156:159], v[212:215], v[78:81]
	v_mfma_f32_16x16x32_bf16 v[74:77], v[164:167], v[212:215], v[74:77]
	v_mfma_f32_16x16x32_bf16 v[118:121], v[168:171], v[184:187], v[118:121]
	v_mfma_f32_16x16x32_bf16 v[114:117], v[176:179], v[184:187], v[114:117]
	v_mfma_f32_16x16x32_bf16 v[102:105], v[168:171], v[192:195], v[102:105]
	v_mfma_f32_16x16x32_bf16 v[98:101], v[176:179], v[192:195], v[98:101]
	v_mfma_f32_16x16x32_bf16 v[86:89], v[168:171], v[200:203], v[86:89]
	v_mfma_f32_16x16x32_bf16 v[82:85], v[176:179], v[200:203], v[82:85]
	v_mfma_f32_16x16x32_bf16 v[70:73], v[168:171], v[208:211], v[70:73]
	v_mfma_f32_16x16x32_bf16 v[66:69], v[176:179], v[208:211], v[66:69]
	v_mfma_f32_16x16x32_bf16 v[118:121], v[172:175], v[188:191], v[118:121]
	v_mfma_f32_16x16x32_bf16 v[114:117], v[180:183], v[188:191], v[114:117]
	v_mfma_f32_16x16x32_bf16 v[102:105], v[172:175], v[196:199], v[102:105]
	v_mfma_f32_16x16x32_bf16 v[98:101], v[180:183], v[196:199], v[98:101]
	v_mfma_f32_16x16x32_bf16 v[86:89], v[172:175], v[204:207], v[86:89]
	v_mfma_f32_16x16x32_bf16 v[82:85], v[180:183], v[204:207], v[82:85]
	v_mfma_f32_16x16x32_bf16 v[70:73], v[172:175], v[212:215], v[70:73]
	v_mfma_f32_16x16x32_bf16 v[66:69], v[180:183], v[212:215], v[66:69]
	s_barrier
	s_add_i32 s60, s72, s51
	s_mov_b32 m0, s60
	ds_read_b128 v[184:187], v150 offset:16384
	ds_read_b128 v[188:191], v150 offset:17408
	ds_read_b128 v[192:195], v150 offset:18432
	ds_read_b128 v[196:199], v150 offset:19456
	ds_read_b128 v[200:203], v150 offset:20480
	ds_read_b128 v[204:207], v150 offset:21504
	ds_read_b128 v[208:211], v150 offset:22528
	ds_read_b128 v[212:215], v150 offset:23552
	global_load_lds_dwordx4 v130, s[46:47]
	s_add_i32 m0, s60, 0x2000
	s_add_u32 s60, s46, 0x4000
	s_addc_u32 s61, s47, 0
	s_add_i32 s81, s73, s51
	global_load_lds_dwordx4 v132, s[46:47]
	s_mov_b32 m0, s81
	s_nop 0
	global_load_lds_dwordx4 v130, s[60:61]
	s_add_i32 m0, s81, 0x2000
	s_nop 0
	global_load_lds_dwordx4 v132, s[60:61]
	s_mov_b32 m0, s52
	s_nop 0
	global_load_lds_dwordx4 v130, s[48:49]
	s_mov_b32 m0, s53
	s_nop 0
	global_load_lds_dwordx4 v132, s[48:49]
	s_waitcnt vmcnt(8) lgkmcnt(0)
	s_barrier
	v_mfma_f32_16x16x32_bf16 v[62:65], v[152:155], v[184:187], v[62:65]
	v_mfma_f32_16x16x32_bf16 v[58:61], v[160:163], v[184:187], v[58:61]
	v_mfma_f32_16x16x32_bf16 v[46:49], v[152:155], v[192:195], v[46:49]
	v_mfma_f32_16x16x32_bf16 v[42:45], v[160:163], v[192:195], v[42:45]
	v_mfma_f32_16x16x32_bf16 v[30:33], v[152:155], v[200:203], v[30:33]
	v_mfma_f32_16x16x32_bf16 v[26:29], v[160:163], v[200:203], v[26:29]
	v_mfma_f32_16x16x32_bf16 v[14:17], v[152:155], v[208:211], v[14:17]
	v_mfma_f32_16x16x32_bf16 v[10:13], v[160:163], v[208:211], v[10:13]
	v_mfma_f32_16x16x32_bf16 v[62:65], v[156:159], v[188:191], v[62:65]
	v_mfma_f32_16x16x32_bf16 v[58:61], v[164:167], v[188:191], v[58:61]
	v_mfma_f32_16x16x32_bf16 v[46:49], v[156:159], v[196:199], v[46:49]
	v_mfma_f32_16x16x32_bf16 v[42:45], v[164:167], v[196:199], v[42:45]
	v_mfma_f32_16x16x32_bf16 v[30:33], v[156:159], v[204:207], v[30:33]
	v_mfma_f32_16x16x32_bf16 v[26:29], v[164:167], v[204:207], v[26:29]
	v_mfma_f32_16x16x32_bf16 v[14:17], v[156:159], v[212:215], v[14:17]
	v_mfma_f32_16x16x32_bf16 v[10:13], v[164:167], v[212:215], v[10:13]
	v_mfma_f32_16x16x32_bf16 v[54:57], v[168:171], v[184:187], v[54:57]
	v_mfma_f32_16x16x32_bf16 v[50:53], v[176:179], v[184:187], v[50:53]
	v_mfma_f32_16x16x32_bf16 v[38:41], v[168:171], v[192:195], v[38:41]
	v_mfma_f32_16x16x32_bf16 v[34:37], v[176:179], v[192:195], v[34:37]
	v_mfma_f32_16x16x32_bf16 v[22:25], v[168:171], v[200:203], v[22:25]
	v_mfma_f32_16x16x32_bf16 v[18:21], v[176:179], v[200:203], v[18:21]
	v_mfma_f32_16x16x32_bf16 v[6:9], v[168:171], v[208:211], v[6:9]
	v_mfma_f32_16x16x32_bf16 v[2:5], v[176:179], v[208:211], v[2:5]
	v_mfma_f32_16x16x32_bf16 v[54:57], v[172:175], v[188:191], v[54:57]
	v_mfma_f32_16x16x32_bf16 v[50:53], v[180:183], v[188:191], v[50:53]
	v_mfma_f32_16x16x32_bf16 v[38:41], v[172:175], v[196:199], v[38:41]
	v_mfma_f32_16x16x32_bf16 v[34:37], v[180:183], v[196:199], v[34:37]
	v_mfma_f32_16x16x32_bf16 v[22:25], v[172:175], v[204:207], v[22:25]
	v_mfma_f32_16x16x32_bf16 v[18:21], v[180:183], v[204:207], v[18:21]
	v_mfma_f32_16x16x32_bf16 v[6:9], v[172:175], v[212:215], v[6:9]
	v_mfma_f32_16x16x32_bf16 v[2:5], v[180:183], v[212:215], v[2:5]
	s_barrier
; #define PG8_STAGE(bufoff, gbase, voff) do { _Pragma("unroll") for (int _i = 0; _i < 2; ++_i) \
;         __builtin_amdgcn_global_load_lds((const unsigned*)((const char*)(gbase) + (voff)[_i]), (LAS unsigned*)(lds + (bufoff) + ldsw + _i * 8192), 16, 0, 0); } while (0)
; #define PG8_LDA(dst, b, h) do { _Pragma("unroll") for (int m = 0; m < 4; ++m) _Pragma("unroll") for (int k = 0; k < 2; ++k) dst[m][k] = *(const LAS bf16x8*)(lds + PG8_SA(b, h) + aoff + m * 2048 + k * 1024); } while (0)
; #define PG8_LDB(dst, b, h) do { _Pragma("unroll") for (int n = 0; n < 2; ++n) _Pragma("unroll") for (int k = 0; k < 2; ++k) dst[n][k] = *(const LAS bf16x8*)(lds + PG8_SB(b, h) + boff + n * 2048 + k * 1024); } while (0)
; #define PG8_MMA(ai, bj, At, Bt) do { __builtin_amdgcn_s_setprio(1); _Pragma("unroll") for (int m = 0; m < 4; ++m) _Pragma("unroll") for (int n = 0; n < 2; ++n) _Pragma("unroll") for (int k = 0; k < 2; ++k) \
;         acc[ai][bj][m][n] = __builtin_amdgcn_mfma_f32_16x16x32_bf16(Bt[n][k], At[m][k], acc[ai][bj][m][n], 0, 0, 0); __builtin_amdgcn_s_setprio(0); } while (0)
; #define PG8_WAIT_V(n) asm volatile("s_waitcnt vmcnt(" #n ")" ::: "memory")
; #define PG8_WAIT_L(n) asm volatile("s_waitcnt lgkmcnt(" #n ")" ::: "memory")
; #define PG8_BAR __builtin_amdgcn_s_barrier()
; #define PG8_SCHED __builtin_amdgcn_sched_barrier(0)
; template <class Epi, class Sched, bool ABLK = false, bool ALIGN_EPI = true, bool SP2 = true, bool BBLK = true>
; __device__ __forceinline__ void gemm_phase(LAS unsigned char* lds, const Gemm g, const Sched& S, const Epi& E) {
;     ...
;             PG8_LDB(B0, 1, 0); PG8_LDB(B1, 1, 1); PG8_SCHED; PG8_LDA(At, 1, 0); PG8_STAGE(PG8_SA(0, 1), a2 + hstepA, voffA);
;             PG8_WAIT_V(8); PG8_WAIT_L(0); PG8_BAR; PG8_MMA(0, 0, At, B0); PG8_MMA(0, 1, At, B1); PG8_BAR; PG8_SCHED;
;             PG8_LDA(At, 1, 1); PG8_STAGE(PG8_SB(1, 0), b3, voffB); PG8_STAGE(PG8_SB(1, 1), b3 + hstepB, voffB); PG8_STAGE(PG8_SA(1, 0), a3, voffA);
;             PG8_WAIT_V(8); PG8_WAIT_L(0); PG8_BAR; PG8_MMA(1, 0, At, B0); PG8_MMA(1, 1, At, B1); PG8_BAR; PG8_SCHED;
	s_add_i32 s60, 0, 0x18000
	v_add_u32_e32 v151, s60, v146
	s_add_i32 s61, 0, 0x1c000
	ds_read_b128 v[152:155], v151
	ds_read_b128 v[156:159], v151 offset:1024
	ds_read_b128 v[160:163], v151 offset:2048
	ds_read_b128 v[164:167], v151 offset:3072
	v_add_u32_e32 v151, s61, v146
	ds_read_b128 v[168:171], v151
	ds_read_b128 v[172:175], v151 offset:1024
	ds_read_b128 v[176:179], v151 offset:2048
	ds_read_b128 v[180:183], v151 offset:3072
	s_add_u32 s48, s48, 0x4000
	s_addc_u32 s49, s49, 0
	s_mov_b32 m0, s54
	ds_read_b128 v[184:187], v150 offset:32768
	ds_read_b128 v[188:191], v150 offset:33792
	ds_read_b128 v[192:195], v150 offset:34816
	ds_read_b128 v[196:199], v150 offset:35840
	ds_read_b128 v[200:203], v150 offset:36864
	ds_read_b128 v[204:207], v150 offset:37888
	ds_read_b128 v[208:211], v150 offset:38912
	ds_read_b128 v[212:215], v150 offset:39936
	global_load_lds_dwordx4 v130, s[48:49]
	s_mov_b32 m0, s55
	s_nop 0
	global_load_lds_dwordx4 v132, s[48:49]
	s_waitcnt vmcnt(8) lgkmcnt(0)
	s_barrier
	v_mfma_f32_16x16x32_bf16 v[126:129], v[152:155], v[184:187], v[126:129]
	v_mfma_f32_16x16x32_bf16 v[122:125], v[160:163], v[184:187], v[122:125]
	v_mfma_f32_16x16x32_bf16 v[110:113], v[152:155], v[192:195], v[110:113]
	v_mfma_f32_16x16x32_bf16 v[106:109], v[160:163], v[192:195], v[106:109]
	v_mfma_f32_16x16x32_bf16 v[94:97], v[152:155], v[200:203], v[94:97]
	v_mfma_f32_16x16x32_bf16 v[90:93], v[160:163], v[200:203], v[90:93]
	v_mfma_f32_16x16x32_bf16 v[78:81], v[152:155], v[208:211], v[78:81]
	v_mfma_f32_16x16x32_bf16 v[74:77], v[160:163], v[208:211], v[74:77]
	v_mfma_f32_16x16x32_bf16 v[126:129], v[156:159], v[188:191], v[126:129]
	v_mfma_f32_16x16x32_bf16 v[122:125], v[164:167], v[188:191], v[122:125]
	v_mfma_f32_16x16x32_bf16 v[110:113], v[156:159], v[196:199], v[110:113]
	v_mfma_f32_16x16x32_bf16 v[106:109], v[164:167], v[196:199], v[106:109]
	v_mfma_f32_16x16x32_bf16 v[94:97], v[156:159], v[204:207], v[94:97]
	v_mfma_f32_16x16x32_bf16 v[90:93], v[164:167], v[204:207], v[90:93]
	v_mfma_f32_16x16x32_bf16 v[78:81], v[156:159], v[212:215], v[78:81]
	v_mfma_f32_16x16x32_bf16 v[74:77], v[164:167], v[212:215], v[74:77]
	v_mfma_f32_16x16x32_bf16 v[118:121], v[168:171], v[184:187], v[118:121]
	v_mfma_f32_16x16x32_bf16 v[114:117], v[176:179], v[184:187], v[114:117]
	v_mfma_f32_16x16x32_bf16 v[102:105], v[168:171], v[192:195], v[102:105]
	v_mfma_f32_16x16x32_bf16 v[98:101], v[176:179], v[192:195], v[98:101]
	v_mfma_f32_16x16x32_bf16 v[86:89], v[168:171], v[200:203], v[86:89]
	v_mfma_f32_16x16x32_bf16 v[82:85], v[176:179], v[200:203], v[82:85]
	v_mfma_f32_16x16x32_bf16 v[70:73], v[168:171], v[208:211], v[70:73]
	v_mfma_f32_16x16x32_bf16 v[66:69], v[176:179], v[208:211], v[66:69]
	v_mfma_f32_16x16x32_bf16 v[118:121], v[172:175], v[188:191], v[118:121]
	v_mfma_f32_16x16x32_bf16 v[114:117], v[180:183], v[188:191], v[114:117]
	v_mfma_f32_16x16x32_bf16 v[102:105], v[172:175], v[196:199], v[102:105]
	v_mfma_f32_16x16x32_bf16 v[98:101], v[180:183], v[196:199], v[98:101]
	v_mfma_f32_16x16x32_bf16 v[86:89], v[172:175], v[204:207], v[86:89]
	v_mfma_f32_16x16x32_bf16 v[82:85], v[180:183], v[204:207], v[82:85]
	v_mfma_f32_16x16x32_bf16 v[70:73], v[172:175], v[212:215], v[70:73]
	v_mfma_f32_16x16x32_bf16 v[66:69], v[180:183], v[212:215], v[66:69]
	s_barrier
	s_add_u32 s48, s46, 0x8000
	s_addc_u32 s49, s47, 0
	s_add_i32 s81, s60, s51
	s_mov_b32 m0, s81
	ds_read_b128 v[184:187], v150 offset:49152
	ds_read_b128 v[188:191], v150 offset:50176
	ds_read_b128 v[192:195], v150 offset:51200
	ds_read_b128 v[196:199], v150 offset:52224
	ds_read_b128 v[200:203], v150 offset:53248
	ds_read_b128 v[204:207], v150 offset:54272
	ds_read_b128 v[208:211], v150 offset:55296
	ds_read_b128 v[212:215], v150 offset:56320
	global_load_lds_dwordx4 v130, s[48:49]
	s_add_i32 m0, s81, 0x2000
	s_add_u32 s46, s46, 0xc000
	v_lshl_add_u64 v[216:217], s[48:49], 0, v[132:133]
	s_addc_u32 s47, s47, 0
	s_add_i32 s48, s61, s51
	global_load_lds_dwordx4 v[216:217], off
	s_mov_b32 m0, s48
	s_nop 0
	global_load_lds_dwordx4 v130, s[46:47]
	s_add_i32 m0, s48, 0x2000
	s_nop 0
	global_load_lds_dwordx4 v132, s[46:47]
	s_mov_b32 m0, s56
	s_nop 0
	global_load_lds_dwordx4 v130, s[42:43]
	s_mov_b32 m0, s57
	s_nop 0
	global_load_lds_dwordx4 v132, s[42:43]
	s_waitcnt vmcnt(8) lgkmcnt(0)
	s_barrier
	v_mfma_f32_16x16x32_bf16 v[62:65], v[152:155], v[184:187], v[62:65]
	v_mfma_f32_16x16x32_bf16 v[58:61], v[160:163], v[184:187], v[58:61]
	v_mfma_f32_16x16x32_bf16 v[46:49], v[152:155], v[192:195], v[46:49]
	v_mfma_f32_16x16x32_bf16 v[42:45], v[160:163], v[192:195], v[42:45]
	v_mfma_f32_16x16x32_bf16 v[30:33], v[152:155], v[200:203], v[30:33]
	v_mfma_f32_16x16x32_bf16 v[26:29], v[160:163], v[200:203], v[26:29]
	v_mfma_f32_16x16x32_bf16 v[14:17], v[152:155], v[208:211], v[14:17]
	v_mfma_f32_16x16x32_bf16 v[10:13], v[160:163], v[208:211], v[10:13]
	v_mfma_f32_16x16x32_bf16 v[62:65], v[156:159], v[188:191], v[62:65]
	v_mfma_f32_16x16x32_bf16 v[58:61], v[164:167], v[188:191], v[58:61]
	v_mfma_f32_16x16x32_bf16 v[46:49], v[156:159], v[196:199], v[46:49]
	v_mfma_f32_16x16x32_bf16 v[42:45], v[164:167], v[196:199], v[42:45]
	v_mfma_f32_16x16x32_bf16 v[30:33], v[156:159], v[204:207], v[30:33]
	v_mfma_f32_16x16x32_bf16 v[26:29], v[164:167], v[204:207], v[26:29]
	v_mfma_f32_16x16x32_bf16 v[14:17], v[156:159], v[212:215], v[14:17]
	v_mfma_f32_16x16x32_bf16 v[10:13], v[164:167], v[212:215], v[10:13]
	v_mfma_f32_16x16x32_bf16 v[54:57], v[168:171], v[184:187], v[54:57]
	v_mfma_f32_16x16x32_bf16 v[50:53], v[176:179], v[184:187], v[50:53]
	v_mfma_f32_16x16x32_bf16 v[38:41], v[168:171], v[192:195], v[38:41]
	v_mfma_f32_16x16x32_bf16 v[34:37], v[176:179], v[192:195], v[34:37]
	v_mfma_f32_16x16x32_bf16 v[22:25], v[168:171], v[200:203], v[22:25]
	v_mfma_f32_16x16x32_bf16 v[18:21], v[176:179], v[200:203], v[18:21]
	v_mfma_f32_16x16x32_bf16 v[6:9], v[168:171], v[208:211], v[6:9]
	v_mfma_f32_16x16x32_bf16 v[2:5], v[176:179], v[208:211], v[2:5]
	v_mfma_f32_16x16x32_bf16 v[54:57], v[172:175], v[188:191], v[54:57]
	v_mfma_f32_16x16x32_bf16 v[50:53], v[180:183], v[188:191], v[50:53]
	v_mfma_f32_16x16x32_bf16 v[38:41], v[172:175], v[196:199], v[38:41]
	v_mfma_f32_16x16x32_bf16 v[34:37], v[180:183], v[196:199], v[34:37]
	v_mfma_f32_16x16x32_bf16 v[22:25], v[172:175], v[204:207], v[22:25]
	v_mfma_f32_16x16x32_bf16 v[18:21], v[180:183], v[204:207], v[18:21]
	v_mfma_f32_16x16x32_bf16 v[6:9], v[172:175], v[212:215], v[6:9]
	v_mfma_f32_16x16x32_bf16 v[2:5], v[180:183], v[212:215], v[2:5]
	s_barrier
; __device__ __forceinline__ unsigned pk2(float lo, float hi) { const f32x2 v = {lo, hi}; return __builtin_bit_cast(unsigned, __builtin_convertvector(v, bf16x2_t)); }
; __device__ __forceinline__ void store_pair(unsigned char* own, size_t stride8, int hi_off, u32x4 lo, u32x4 hi, bool upper) {
;     const u32x4 tlo = ror8(lo), thi = ror8(hi);
;     const u32x4 A = upper ? thi : lo, B = upper ? hi : tlo;
;     unsigned char* pa = upper ? own - stride8 + hi_off : own;
;     unsigned char* pb = upper ? own + hi_off : own + stride8;
;     *(u32x4*)pa = A; *(u32x4*)pb = B;
; }
;     __device__ __forceinline__ void operator()(const f32x4 (&acc)[2][2][4][2], const Unit& u, int wr, int wc, int fr, int fq) const {
;         const int row0 = u.pm * 256 + wr * 64 + fr, col0 = u.pn * 256 + wc * 64 + 8 * fq;
;         bf16_t* base = u.part == 0 ? Z + (size_t)row0 * D + col0 : P + ((size_t)(u.part - 1) * MS + (row0 - MP)) * D + col0;
; #pragma unroll
;         for (int ai = 0; ai < 2; ++ai)
; #pragma unroll
;             for (int m = 0; m < 4; ++m) { u32x4 w[2];
; #pragma unroll
;                 for (int bj = 0; bj < 2; ++bj) { const f32x4 v0 = acc[ai][bj][m][0], v1 = acc[ai][bj][m][1]; w[bj].x = pk2(v0[0], v0[1]); w[bj].y = pk2(v0[2], v0[3]); w[bj].z = pk2(v1[0], v1[1]); w[bj].w = pk2(v1[2], v1[3]); }
;                 store_pair((unsigned char*)(base + (size_t)(ai * 128 + m * 16) * D), (size_t)8 * D * 2, 64, w[0], w[1], fr >= 8); }
	s_add_u32 s40, s40, 0x10000
	s_addc_u32 s41, s41, 0
	s_cmp_ge_u32 s79, s59
	s_cbranch_scc0 .LBB0_540
	v_lshl_add_u32 v143, s62, 8, v1
	v_add_u32_e32 v144, 0xffffe000, v143
	v_sub_co_u32_e64 v142, vcc, s58, 1
	v_mov_b32_e32 v145, s17
	s_nop 0
	v_cndmask_b32_e32 v144, v144, v143, vcc
	v_ashrrev_i32_e32 v143, 31, v142
	v_lshlrev_b64 v[142:143], 23, v[142:143]
	v_lshl_add_u64 v[142:143], s[10:11], 0, v[142:143]
	v_cndmask_b32_e32 v143, v143, v145, vcc
	v_mov_b32_e32 v145, s16
	v_cndmask_b32_e32 v142, v142, v145, vcc
	v_ashrrev_i32_e32 v145, 31, v144
	v_lshl_or_b32 v152, s78, 8, v147
	v_lshlrev_b64 v[144:145], 12, v[144:145]
	v_lshl_add_u64 v[142:143], v[142:143], 0, v[144:145]
	v_ashrrev_i32_e32 v153, 31, v152
	v_cvt_pk_bf16_f32 v126, v126, v127
	v_cvt_pk_bf16_f32 v127, v128, v129
	v_cvt_pk_bf16_f32 v128, v122, v123
	v_cvt_pk_bf16_f32 v124, v124, v125
	v_cvt_pk_bf16_f32 v118, v118, v119
	v_cvt_pk_bf16_f32 v119, v120, v121
	v_cvt_pk_bf16_f32 v114, v114, v115
	v_cvt_pk_bf16_f32 v115, v116, v117
	v_lshl_add_u64 v[142:143], v[152:153], 1, v[142:143]
	s_mov_b64 vcc, s[6:7]
	v_mov_b32_dpp v125, v118 row_ror:8 row_mask:0xf bank_mask:0xf bound_ctrl:1
	v_mov_b32_dpp v129, v119 row_ror:8 row_mask:0xf bank_mask:0xf bound_ctrl:1
	v_mov_b32_dpp v144, v114 row_ror:8 row_mask:0xf bank_mask:0xf bound_ctrl:1
	v_mov_b32_dpp v145, v115 row_ror:8 row_mask:0xf bank_mask:0xf bound_ctrl:1
	v_lshl_add_u64 v[122:123], v[142:143], 0, v[134:135]
	v_cndmask_b32_dpp v117, v124, v115, vcc row_ror:8 row_mask:0xf bank_mask:0xf bound_ctrl:1
	v_cndmask_b32_dpp v116, v128, v114, vcc row_ror:8 row_mask:0xf bank_mask:0xf bound_ctrl:1
	v_cndmask_b32_dpp v115, v127, v119, vcc row_ror:8 row_mask:0xf bank_mask:0xf bound_ctrl:1
	v_cndmask_b32_dpp v114, v126, v118, vcc row_ror:8 row_mask:0xf bank_mask:0xf bound_ctrl:1
	v_cndmask_b32_e64 v121, v124, v145, s[6:7]
	v_cndmask_b32_e64 v120, v128, v144, s[6:7]
	v_cndmask_b32_e64 v119, v127, v129, s[6:7]
	v_cndmask_b32_e64 v118, v126, v125, s[6:7]
	v_cvt_pk_bf16_f32 v110, v110, v111
	v_cvt_pk_bf16_f32 v111, v112, v113
	v_cvt_pk_bf16_f32 v112, v106, v107
	v_cvt_pk_bf16_f32 v113, v108, v109
	v_cvt_pk_bf16_f32 v102, v102, v103
	v_cvt_pk_bf16_f32 v103, v104, v105
	v_cvt_pk_bf16_f32 v98, v98, v99
	v_cvt_pk_bf16_f32 v99, v100, v101
	v_lshl_add_u64 v[124:125], v[142:143], 0, v[136:137]
	s_and_b64 vcc, exec, s[12:13]
	s_cbranch_vccz .LBB0_543
	s_barrier
.LBB0_543:
	global_store_dwordx4 v[122:123], v[118:121], off
	global_store_dwordx4 v[124:125], v[114:117], off
	v_lshl_add_u64 v[106:107], v[142:143], 0, s[14:15]
	s_mov_b64 vcc, s[6:7]
	v_mov_b32_dpp v114, v102 row_ror:8 row_mask:0xf bank_mask:0xf bound_ctrl:1
	v_mov_b32_dpp v115, v103 row_ror:8 row_mask:0xf bank_mask:0xf bound_ctrl:1
	v_mov_b32_dpp v116, v98 row_ror:8 row_mask:0xf bank_mask:0xf bound_ctrl:1
	v_mov_b32_dpp v117, v99 row_ror:8 row_mask:0xf bank_mask:0xf bound_ctrl:1
	v_lshl_add_u64 v[108:109], v[106:107], 0, v[134:135]
	v_cndmask_b32_dpp v101, v113, v99, vcc row_ror:8 row_mask:0xf bank_mask:0xf bound_ctrl:1
	v_cndmask_b32_dpp v100, v112, v98, vcc row_ror:8 row_mask:0xf bank_mask:0xf bound_ctrl:1
	v_cndmask_b32_dpp v99, v111, v103, vcc row_ror:8 row_mask:0xf bank_mask:0xf bound_ctrl:1
	v_cndmask_b32_dpp v98, v110, v102, vcc row_ror:8 row_mask:0xf bank_mask:0xf bound_ctrl:1
	v_cndmask_b32_e64 v105, v113, v117, s[6:7]
	v_cndmask_b32_e64 v104, v112, v116, s[6:7]
	v_cndmask_b32_e64 v103, v111, v115, s[6:7]
	v_cndmask_b32_e64 v102, v110, v114, s[6:7]
	v_cvt_pk_bf16_f32 v94, v94, v95
	v_cvt_pk_bf16_f32 v95, v96, v97
	v_cvt_pk_bf16_f32 v96, v90, v91
	v_cvt_pk_bf16_f32 v97, v92, v93
	v_cvt_pk_bf16_f32 v86, v86, v87
	v_cvt_pk_bf16_f32 v87, v88, v89
	v_cvt_pk_bf16_f32 v82, v82, v83
	v_cvt_pk_bf16_f32 v83, v84, v85
	v_lshl_add_u64 v[106:107], v[106:107], 0, v[136:137]
	global_store_dwordx4 v[108:109], v[102:105], off
	global_store_dwordx4 v[106:107], v[98:101], off
	v_lshl_add_u64 v[90:91], v[142:143], 0, s[18:19]
	s_mov_b64 vcc, s[6:7]
	v_mov_b32_dpp v98, v86 row_ror:8 row_mask:0xf bank_mask:0xf bound_ctrl:1
	v_mov_b32_dpp v99, v87 row_ror:8 row_mask:0xf bank_mask:0xf bound_ctrl:1
	v_mov_b32_dpp v100, v82 row_ror:8 row_mask:0xf bank_mask:0xf bound_ctrl:1
	v_mov_b32_dpp v101, v83 row_ror:8 row_mask:0xf bank_mask:0xf bound_ctrl:1
	v_lshl_add_u64 v[92:93], v[90:91], 0, v[134:135]
	v_cndmask_b32_dpp v85, v97, v83, vcc row_ror:8 row_mask:0xf bank_mask:0xf bound_ctrl:1
	v_cndmask_b32_dpp v84, v96, v82, vcc row_ror:8 row_mask:0xf bank_mask:0xf bound_ctrl:1
	v_cndmask_b32_dpp v83, v95, v87, vcc row_ror:8 row_mask:0xf bank_mask:0xf bound_ctrl:1
	v_cndmask_b32_dpp v82, v94, v86, vcc row_ror:8 row_mask:0xf bank_mask:0xf bound_ctrl:1
	v_cndmask_b32_e64 v89, v97, v101, s[6:7]
	v_cndmask_b32_e64 v88, v96, v100, s[6:7]
	v_cndmask_b32_e64 v87, v95, v99, s[6:7]
	v_cndmask_b32_e64 v86, v94, v98, s[6:7]
	v_cvt_pk_bf16_f32 v78, v78, v79
	v_cvt_pk_bf16_f32 v79, v80, v81
	v_cvt_pk_bf16_f32 v80, v74, v75
	v_cvt_pk_bf16_f32 v81, v76, v77
	v_cvt_pk_bf16_f32 v70, v70, v71
	v_cvt_pk_bf16_f32 v71, v72, v73
	v_cvt_pk_bf16_f32 v66, v66, v67
	v_cvt_pk_bf16_f32 v67, v68, v69
	v_lshl_add_u64 v[90:91], v[90:91], 0, v[136:137]
	global_store_dwordx4 v[92:93], v[86:89], off
	global_store_dwordx4 v[90:91], v[82:85], off
	v_lshl_add_u64 v[74:75], v[142:143], 0, s[20:21]
	s_mov_b64 vcc, s[6:7]
	v_mov_b32_dpp v82, v70 row_ror:8 row_mask:0xf bank_mask:0xf bound_ctrl:1
	v_mov_b32_dpp v83, v71 row_ror:8 row_mask:0xf bank_mask:0xf bound_ctrl:1
	v_mov_b32_dpp v84, v66 row_ror:8 row_mask:0xf bank_mask:0xf bound_ctrl:1
	v_mov_b32_dpp v85, v67 row_ror:8 row_mask:0xf bank_mask:0xf bound_ctrl:1
	v_lshl_add_u64 v[76:77], v[74:75], 0, v[134:135]
; __device__ __forceinline__ unsigned pk2(float lo, float hi) { const f32x2 v = {lo, hi}; return __builtin_bit_cast(unsigned, __builtin_convertvector(v, bf16x2_t)); }
; #define PG8_BAR __builtin_amdgcn_s_barrier()
; template <class Epi, class Sched, bool ABLK = false, bool ALIGN_EPI = true, bool SP2 = true, bool BBLK = true>
; __device__ __forceinline__ void gemm_phase(LAS unsigned char* lds, const Gemm g, const Sched& S, const Epi& E) {
;     ...
;         if (!has_next) break;
; #pragma unroll
;         for (int a = 0; a < 2; ++a)
; #pragma unroll
;             for (int b = 0; b < 2; ++b)
; #pragma unroll
;                 for (int m = 0; m < 4; ++m)
; #pragma unroll
;                     for (int n = 0; n < 2; ++n) acc[a][b][m][n] = (f32x4){0.f, 0.f, 0.f, 0.f};
;         cur = nxt; uA = nuA; tbA = ntbA; cB = nB; ++ui;
;         if constexpr (ALIGN_EPI) { if (wr == 1) PG8_BAR; }
;     __device__ __forceinline__ void operator()(const f32x4 (&acc)[2][2][4][2], const Unit& u, int wr, int wc, int fr, int fq) const {
;     ...
;             for (int m = 0; m < 4; ++m) { u32x4 w[2];
; #pragma unroll
;                 for (int bj = 0; bj < 2; ++bj) { const f32x4 v0 = acc[ai][bj][m][0], v1 = acc[ai][bj][m][1]; w[bj].x = pk2(v0[0], v0[1]); w[bj].y = pk2(v0[2], v0[3]); w[bj].z = pk2(v1[0], v1[1]); w[bj].w = pk2(v1[2], v1[3]); }
;                 store_pair((unsigned char*)(base + (size_t)(ai * 128 + m * 16) * D), (size_t)8 * D * 2, 64, w[0], w[1], fr >= 8); }
	v_cndmask_b32_dpp v69, v81, v67, vcc row_ror:8 row_mask:0xf bank_mask:0xf bound_ctrl:1
	v_cndmask_b32_dpp v68, v80, v66, vcc row_ror:8 row_mask:0xf bank_mask:0xf bound_ctrl:1
	v_cndmask_b32_dpp v67, v79, v71, vcc row_ror:8 row_mask:0xf bank_mask:0xf bound_ctrl:1
	v_cndmask_b32_dpp v66, v78, v70, vcc row_ror:8 row_mask:0xf bank_mask:0xf bound_ctrl:1
	v_cndmask_b32_e64 v73, v81, v85, s[6:7]
	v_cndmask_b32_e64 v72, v80, v84, s[6:7]
	v_cndmask_b32_e64 v71, v79, v83, s[6:7]
	v_cndmask_b32_e64 v70, v78, v82, s[6:7]
	v_cvt_pk_bf16_f32 v62, v62, v63
	v_cvt_pk_bf16_f32 v63, v64, v65
	v_cvt_pk_bf16_f32 v64, v58, v59
	v_cvt_pk_bf16_f32 v65, v60, v61
	v_cvt_pk_bf16_f32 v54, v54, v55
	v_cvt_pk_bf16_f32 v55, v56, v57
	v_cvt_pk_bf16_f32 v50, v50, v51
	v_cvt_pk_bf16_f32 v51, v52, v53
	v_lshl_add_u64 v[74:75], v[74:75], 0, v[136:137]
	global_store_dwordx4 v[76:77], v[70:73], off
	global_store_dwordx4 v[74:75], v[66:69], off
	v_lshl_add_u64 v[58:59], v[142:143], 0, s[22:23]
	s_mov_b64 vcc, s[6:7]
	v_mov_b32_dpp v66, v54 row_ror:8 row_mask:0xf bank_mask:0xf bound_ctrl:1
	v_mov_b32_dpp v67, v55 row_ror:8 row_mask:0xf bank_mask:0xf bound_ctrl:1
	v_mov_b32_dpp v68, v50 row_ror:8 row_mask:0xf bank_mask:0xf bound_ctrl:1
	v_mov_b32_dpp v69, v51 row_ror:8 row_mask:0xf bank_mask:0xf bound_ctrl:1
	v_lshl_add_u64 v[60:61], v[58:59], 0, v[134:135]
	v_cndmask_b32_dpp v53, v65, v51, vcc row_ror:8 row_mask:0xf bank_mask:0xf bound_ctrl:1
	v_cndmask_b32_dpp v52, v64, v50, vcc row_ror:8 row_mask:0xf bank_mask:0xf bound_ctrl:1
	v_cndmask_b32_dpp v51, v63, v55, vcc row_ror:8 row_mask:0xf bank_mask:0xf bound_ctrl:1
	v_cndmask_b32_dpp v50, v62, v54, vcc row_ror:8 row_mask:0xf bank_mask:0xf bound_ctrl:1
	v_cndmask_b32_e64 v57, v65, v69, s[6:7]
	v_cndmask_b32_e64 v56, v64, v68, s[6:7]
	v_cndmask_b32_e64 v55, v63, v67, s[6:7]
	v_cndmask_b32_e64 v54, v62, v66, s[6:7]
	v_cvt_pk_bf16_f32 v46, v46, v47
	v_cvt_pk_bf16_f32 v47, v48, v49
	v_cvt_pk_bf16_f32 v48, v42, v43
	v_cvt_pk_bf16_f32 v49, v44, v45
	v_cvt_pk_bf16_f32 v38, v38, v39
	v_cvt_pk_bf16_f32 v39, v40, v41
	v_cvt_pk_bf16_f32 v34, v34, v35
	v_cvt_pk_bf16_f32 v35, v36, v37
	v_lshl_add_u64 v[58:59], v[58:59], 0, v[136:137]
	global_store_dwordx4 v[60:61], v[54:57], off
	global_store_dwordx4 v[58:59], v[50:53], off
	v_lshl_add_u64 v[42:43], v[142:143], 0, s[24:25]
	s_mov_b64 vcc, s[6:7]
	v_mov_b32_dpp v50, v38 row_ror:8 row_mask:0xf bank_mask:0xf bound_ctrl:1
	v_mov_b32_dpp v51, v39 row_ror:8 row_mask:0xf bank_mask:0xf bound_ctrl:1
	v_mov_b32_dpp v52, v34 row_ror:8 row_mask:0xf bank_mask:0xf bound_ctrl:1
	v_mov_b32_dpp v53, v35 row_ror:8 row_mask:0xf bank_mask:0xf bound_ctrl:1
	v_lshl_add_u64 v[44:45], v[42:43], 0, v[134:135]
	v_cndmask_b32_dpp v37, v49, v35, vcc row_ror:8 row_mask:0xf bank_mask:0xf bound_ctrl:1
	v_cndmask_b32_dpp v36, v48, v34, vcc row_ror:8 row_mask:0xf bank_mask:0xf bound_ctrl:1
	v_cndmask_b32_dpp v35, v47, v39, vcc row_ror:8 row_mask:0xf bank_mask:0xf bound_ctrl:1
	v_cndmask_b32_dpp v34, v46, v38, vcc row_ror:8 row_mask:0xf bank_mask:0xf bound_ctrl:1
	v_cndmask_b32_e64 v41, v49, v53, s[6:7]
	v_cndmask_b32_e64 v40, v48, v52, s[6:7]
	v_cndmask_b32_e64 v39, v47, v51, s[6:7]
	v_cndmask_b32_e64 v38, v46, v50, s[6:7]
	v_cvt_pk_bf16_f32 v30, v30, v31
	v_cvt_pk_bf16_f32 v31, v32, v33
	v_cvt_pk_bf16_f32 v32, v26, v27
	v_cvt_pk_bf16_f32 v33, v28, v29
	v_cvt_pk_bf16_f32 v22, v22, v23
	v_cvt_pk_bf16_f32 v23, v24, v25
	v_cvt_pk_bf16_f32 v18, v18, v19
	v_cvt_pk_bf16_f32 v19, v20, v21
	v_lshl_add_u64 v[42:43], v[42:43], 0, v[136:137]
	global_store_dwordx4 v[44:45], v[38:41], off
	global_store_dwordx4 v[42:43], v[34:37], off
	v_lshl_add_u64 v[26:27], v[142:143], 0, s[26:27]
	s_mov_b64 vcc, s[6:7]
	v_mov_b32_dpp v34, v22 row_ror:8 row_mask:0xf bank_mask:0xf bound_ctrl:1
	v_mov_b32_dpp v35, v23 row_ror:8 row_mask:0xf bank_mask:0xf bound_ctrl:1
	v_mov_b32_dpp v36, v18 row_ror:8 row_mask:0xf bank_mask:0xf bound_ctrl:1
	v_mov_b32_dpp v37, v19 row_ror:8 row_mask:0xf bank_mask:0xf bound_ctrl:1
	v_lshl_add_u64 v[28:29], v[26:27], 0, v[134:135]
	v_cndmask_b32_dpp v21, v33, v19, vcc row_ror:8 row_mask:0xf bank_mask:0xf bound_ctrl:1
	v_cndmask_b32_dpp v20, v32, v18, vcc row_ror:8 row_mask:0xf bank_mask:0xf bound_ctrl:1
	v_cndmask_b32_dpp v19, v31, v23, vcc row_ror:8 row_mask:0xf bank_mask:0xf bound_ctrl:1
	v_cndmask_b32_dpp v18, v30, v22, vcc row_ror:8 row_mask:0xf bank_mask:0xf bound_ctrl:1
	v_cndmask_b32_e64 v25, v33, v37, s[6:7]
	v_cndmask_b32_e64 v24, v32, v36, s[6:7]
	v_cndmask_b32_e64 v23, v31, v35, s[6:7]
	v_cndmask_b32_e64 v22, v30, v34, s[6:7]
	v_cvt_pk_bf16_f32 v14, v14, v15
	v_cvt_pk_bf16_f32 v15, v16, v17
	v_cvt_pk_bf16_f32 v16, v10, v11
	v_cvt_pk_bf16_f32 v17, v12, v13
	v_cvt_pk_bf16_f32 v6, v6, v7
	v_cvt_pk_bf16_f32 v7, v8, v9
	v_cvt_pk_bf16_f32 v2, v2, v3
	v_cvt_pk_bf16_f32 v3, v4, v5
	v_lshl_add_u64 v[26:27], v[26:27], 0, v[136:137]
	global_store_dwordx4 v[28:29], v[22:25], off
	global_store_dwordx4 v[26:27], v[18:21], off
	v_lshl_add_u64 v[10:11], v[142:143], 0, s[28:29]
	s_mov_b64 vcc, s[6:7]
	v_mov_b32_dpp v18, v6 row_ror:8 row_mask:0xf bank_mask:0xf bound_ctrl:1
	v_mov_b32_dpp v19, v7 row_ror:8 row_mask:0xf bank_mask:0xf bound_ctrl:1
	v_mov_b32_dpp v20, v2 row_ror:8 row_mask:0xf bank_mask:0xf bound_ctrl:1
	v_mov_b32_dpp v21, v3 row_ror:8 row_mask:0xf bank_mask:0xf bound_ctrl:1
	v_lshl_add_u64 v[12:13], v[10:11], 0, v[134:135]
	v_cndmask_b32_dpp v5, v17, v3, vcc row_ror:8 row_mask:0xf bank_mask:0xf bound_ctrl:1
	v_cndmask_b32_dpp v4, v16, v2, vcc row_ror:8 row_mask:0xf bank_mask:0xf bound_ctrl:1
	v_cndmask_b32_dpp v3, v15, v7, vcc row_ror:8 row_mask:0xf bank_mask:0xf bound_ctrl:1
	v_cndmask_b32_dpp v2, v14, v6, vcc row_ror:8 row_mask:0xf bank_mask:0xf bound_ctrl:1
	v_cndmask_b32_e64 v9, v17, v21, s[6:7]
	v_cndmask_b32_e64 v8, v16, v20, s[6:7]
	v_cndmask_b32_e64 v7, v15, v19, s[6:7]
	v_cndmask_b32_e64 v6, v14, v18, s[6:7]
	s_and_b64 vcc, exec, s[8:9]
	s_mov_b64 s[8:9], -1
	v_lshl_add_u64 v[10:11], v[10:11], 0, v[136:137]
	global_store_dwordx4 v[12:13], v[6:9], off
	global_store_dwordx4 v[10:11], v[2:5], off
	s_cbranch_vccnz .LBB0_538
	s_andn2_b64 vcc, exec, s[2:3]
	s_cbranch_vccnz .LBB0_537
	s_barrier
	s_branch .LBB0_537

; #define PG8_STAGE(bufoff, gbase, voff) do { _Pragma("unroll") for (int _i = 0; _i < 2; ++_i) \
;         __builtin_amdgcn_global_load_lds((const unsigned*)((const char*)(gbase) + (voff)[_i]), (LAS unsigned*)(lds + (bufoff) + ldsw + _i * 8192), 16, 0, 0); } while (0)
; #define PG8_LDA(dst, b, h) do { _Pragma("unroll") for (int m = 0; m < 4; ++m) _Pragma("unroll") for (int k = 0; k < 2; ++k) dst[m][k] = *(const LAS bf16x8*)(lds + PG8_SA(b, h) + aoff + m * 2048 + k * 1024); } while (0)
; #define PG8_LDB(dst, b, h) do { _Pragma("unroll") for (int n = 0; n < 2; ++n) _Pragma("unroll") for (int k = 0; k < 2; ++k) dst[n][k] = *(const LAS bf16x8*)(lds + PG8_SB(b, h) + boff + n * 2048 + k * 1024); } while (0)
; #define PG8_MMA(ai, bj, At, Bt) do { __builtin_amdgcn_s_setprio(1); _Pragma("unroll") for (int m = 0; m < 4; ++m) _Pragma("unroll") for (int n = 0; n < 2; ++n) _Pragma("unroll") for (int k = 0; k < 2; ++k) \
;         acc[ai][bj][m][n] = __builtin_amdgcn_mfma_f32_16x16x32_bf16(Bt[n][k], At[m][k], acc[ai][bj][m][n], 0, 0, 0); __builtin_amdgcn_s_setprio(0); } while (0)
; #define PG8_WAIT_V(n) asm volatile("s_waitcnt vmcnt(" #n ")" ::: "memory")
; #define PG8_WAIT_L(n) asm volatile("s_waitcnt lgkmcnt(" #n ")" ::: "memory")
; #define PG8_BAR __builtin_amdgcn_s_barrier()
; #define PG8_SCHED __builtin_amdgcn_sched_barrier(0)
; template <class Epi, class Sched, bool ABLK = false, bool ALIGN_EPI = true, bool SP2 = true, bool BBLK = true>
; __device__ __forceinline__ void gemm_phase(LAS unsigned char* lds, const Gemm g, const Sched& S, const Epi& E) {
;     ...
;             PG8_LDB(B0, 0, 0); PG8_LDB(B1, 0, 1); PG8_SCHED; PG8_LDA(At, 0, 0); PG8_STAGE(PG8_SA(1, 1), a1 + hstepA, voffA);
;             PG8_WAIT_V(8); PG8_WAIT_L(0); PG8_BAR; PG8_MMA(0, 0, At, B0); PG8_MMA(0, 1, At, B1); PG8_BAR; PG8_SCHED;
;             PG8_LDA(At, 0, 1); PG8_STAGE(PG8_SB(0, 0), b2, voffB); PG8_STAGE(PG8_SB(0, 1), b2 + hstepB, voffB); PG8_STAGE(PG8_SA(0, 0), a2, voffA);
;             PG8_WAIT_V(8); PG8_WAIT_L(0); PG8_BAR; PG8_MMA(1, 0, At, B0); PG8_MMA(1, 1, At, B1); PG8_BAR; PG8_SCHED;
.Lksel_9_back:
	v_lshl_add_u64 v[220:221], v[146:147], 0, s[20:21]
	s_add_i32 m0, s35, 0xc000
	ds_read_b128 v[188:191], v155
	ds_read_b128 v[192:195], v155 offset:1024
	ds_read_b128 v[196:199], v155 offset:2048
	ds_read_b128 v[200:203], v155 offset:3072
	ds_read_b128 v[204:207], v155 offset:4096
	ds_read_b128 v[208:211], v155 offset:5120
	ds_read_b128 v[212:215], v155 offset:6144
	ds_read_b128 v[216:219], v155 offset:7168
	global_load_lds_dwordx4 v[220:221], off
	v_lshl_add_u64 v[220:221], v[148:149], 0, s[20:21]
	s_add_i32 m0, s35, 0xe000
	s_nop 0
	global_load_lds_dwordx4 v[220:221], off
	s_waitcnt vmcnt(8) lgkmcnt(0)
	s_barrier
	v_mfma_f32_16x16x32_bf16 v[126:129], v[156:159], v[188:191], v[126:129]
	v_mfma_f32_16x16x32_bf16 v[122:125], v[164:167], v[188:191], v[122:125]
	v_mfma_f32_16x16x32_bf16 v[110:113], v[156:159], v[196:199], v[110:113]
	v_mfma_f32_16x16x32_bf16 v[106:109], v[164:167], v[196:199], v[106:109]
	v_mfma_f32_16x16x32_bf16 v[94:97], v[156:159], v[204:207], v[94:97]
	v_mfma_f32_16x16x32_bf16 v[90:93], v[164:167], v[204:207], v[90:93]
	v_mfma_f32_16x16x32_bf16 v[78:81], v[156:159], v[212:215], v[78:81]
	v_mfma_f32_16x16x32_bf16 v[74:77], v[164:167], v[212:215], v[74:77]
	v_mfma_f32_16x16x32_bf16 v[126:129], v[160:163], v[192:195], v[126:129]
	v_mfma_f32_16x16x32_bf16 v[122:125], v[168:171], v[192:195], v[122:125]
	v_mfma_f32_16x16x32_bf16 v[110:113], v[160:163], v[200:203], v[110:113]
	v_mfma_f32_16x16x32_bf16 v[106:109], v[168:171], v[200:203], v[106:109]
	v_mfma_f32_16x16x32_bf16 v[94:97], v[160:163], v[208:211], v[94:97]
	v_mfma_f32_16x16x32_bf16 v[90:93], v[168:171], v[208:211], v[90:93]
	v_mfma_f32_16x16x32_bf16 v[78:81], v[160:163], v[216:219], v[78:81]
	v_mfma_f32_16x16x32_bf16 v[74:77], v[168:171], v[216:219], v[74:77]
	v_mfma_f32_16x16x32_bf16 v[118:121], v[172:175], v[188:191], v[118:121]
	v_mfma_f32_16x16x32_bf16 v[114:117], v[180:183], v[188:191], v[114:117]
	v_mfma_f32_16x16x32_bf16 v[102:105], v[172:175], v[196:199], v[102:105]
	v_mfma_f32_16x16x32_bf16 v[98:101], v[180:183], v[196:199], v[98:101]
	v_mfma_f32_16x16x32_bf16 v[86:89], v[172:175], v[204:207], v[86:89]
	v_mfma_f32_16x16x32_bf16 v[82:85], v[180:183], v[204:207], v[82:85]
	v_mfma_f32_16x16x32_bf16 v[70:73], v[172:175], v[212:215], v[70:73]
	v_mfma_f32_16x16x32_bf16 v[66:69], v[180:183], v[212:215], v[66:69]
	v_mfma_f32_16x16x32_bf16 v[118:121], v[176:179], v[192:195], v[118:121]
	v_mfma_f32_16x16x32_bf16 v[114:117], v[184:187], v[192:195], v[114:117]
	v_mfma_f32_16x16x32_bf16 v[102:105], v[176:179], v[200:203], v[102:105]
	v_mfma_f32_16x16x32_bf16 v[98:101], v[184:187], v[200:203], v[98:101]
	v_mfma_f32_16x16x32_bf16 v[86:89], v[176:179], v[208:211], v[86:89]
	v_mfma_f32_16x16x32_bf16 v[82:85], v[184:187], v[208:211], v[82:85]
	v_mfma_f32_16x16x32_bf16 v[70:73], v[176:179], v[216:219], v[70:73]
	v_mfma_f32_16x16x32_bf16 v[66:69], v[184:187], v[216:219], v[66:69]
	s_barrier
	s_add_i32 s66, s72, s34
	s_mov_b32 m0, s66
	ds_read_b128 v[188:191], v155 offset:16384
	ds_read_b128 v[192:195], v155 offset:17408
	ds_read_b128 v[196:199], v155 offset:18432
	ds_read_b128 v[200:203], v155 offset:19456
	ds_read_b128 v[204:207], v155 offset:20480
	ds_read_b128 v[208:211], v155 offset:21504
	ds_read_b128 v[212:215], v155 offset:22528
	ds_read_b128 v[216:219], v155 offset:23552
	global_load_lds_dwordx4 v132, s[24:25]
	s_add_i32 m0, s66, 0x2000
	s_add_u32 s66, s24, 0x4000
	s_addc_u32 s67, s25, 0
	s_add_i32 s75, s73, s34
	global_load_lds_dwordx4 v136, s[24:25]
	s_mov_b32 m0, s75
	s_nop 0
	global_load_lds_dwordx4 v132, s[66:67]
	s_add_i32 m0, s75, 0x2000
	s_nop 0
	global_load_lds_dwordx4 v136, s[66:67]
	s_mov_b32 m0, s35
	s_nop 0
	global_load_lds_dwordx4 v130, s[26:27]
	s_mov_b32 m0, s36
	s_nop 0
	global_load_lds_dwordx4 v134, s[26:27]
	s_waitcnt vmcnt(8) lgkmcnt(0)
	s_barrier
	v_mfma_f32_16x16x32_bf16 v[62:65], v[156:159], v[188:191], v[62:65]
	v_mfma_f32_16x16x32_bf16 v[58:61], v[164:167], v[188:191], v[58:61]
	v_mfma_f32_16x16x32_bf16 v[46:49], v[156:159], v[196:199], v[46:49]
	v_mfma_f32_16x16x32_bf16 v[42:45], v[164:167], v[196:199], v[42:45]
	v_mfma_f32_16x16x32_bf16 v[30:33], v[156:159], v[204:207], v[30:33]
	v_mfma_f32_16x16x32_bf16 v[26:29], v[164:167], v[204:207], v[26:29]
	v_mfma_f32_16x16x32_bf16 v[14:17], v[156:159], v[212:215], v[14:17]
	v_mfma_f32_16x16x32_bf16 v[10:13], v[164:167], v[212:215], v[10:13]
	v_mfma_f32_16x16x32_bf16 v[62:65], v[160:163], v[192:195], v[62:65]
	v_mfma_f32_16x16x32_bf16 v[58:61], v[168:171], v[192:195], v[58:61]
	v_mfma_f32_16x16x32_bf16 v[46:49], v[160:163], v[200:203], v[46:49]
	v_mfma_f32_16x16x32_bf16 v[42:45], v[168:171], v[200:203], v[42:45]
	v_mfma_f32_16x16x32_bf16 v[30:33], v[160:163], v[208:211], v[30:33]
	v_mfma_f32_16x16x32_bf16 v[26:29], v[168:171], v[208:211], v[26:29]
	v_mfma_f32_16x16x32_bf16 v[14:17], v[160:163], v[216:219], v[14:17]
	v_mfma_f32_16x16x32_bf16 v[10:13], v[168:171], v[216:219], v[10:13]
	v_mfma_f32_16x16x32_bf16 v[54:57], v[172:175], v[188:191], v[54:57]
	v_mfma_f32_16x16x32_bf16 v[50:53], v[180:183], v[188:191], v[50:53]
	v_mfma_f32_16x16x32_bf16 v[38:41], v[172:175], v[196:199], v[38:41]
	v_mfma_f32_16x16x32_bf16 v[34:37], v[180:183], v[196:199], v[34:37]
	v_mfma_f32_16x16x32_bf16 v[22:25], v[172:175], v[204:207], v[22:25]
	v_mfma_f32_16x16x32_bf16 v[18:21], v[180:183], v[204:207], v[18:21]
	v_mfma_f32_16x16x32_bf16 v[6:9], v[172:175], v[212:215], v[6:9]
	v_mfma_f32_16x16x32_bf16 v[2:5], v[180:183], v[212:215], v[2:5]
	v_mfma_f32_16x16x32_bf16 v[54:57], v[176:179], v[192:195], v[54:57]
	v_mfma_f32_16x16x32_bf16 v[50:53], v[184:187], v[192:195], v[50:53]
	v_mfma_f32_16x16x32_bf16 v[38:41], v[176:179], v[200:203], v[38:41]
	v_mfma_f32_16x16x32_bf16 v[34:37], v[184:187], v[200:203], v[34:37]
	v_mfma_f32_16x16x32_bf16 v[22:25], v[176:179], v[208:211], v[22:25]
	v_mfma_f32_16x16x32_bf16 v[18:21], v[184:187], v[208:211], v[18:21]
	v_mfma_f32_16x16x32_bf16 v[6:9], v[176:179], v[216:219], v[6:9]
	v_mfma_f32_16x16x32_bf16 v[2:5], v[184:187], v[216:219], v[2:5]
	s_barrier
; #define PG8_STAGE(bufoff, gbase, voff) do { _Pragma("unroll") for (int _i = 0; _i < 2; ++_i) \
;         __builtin_amdgcn_global_load_lds((const unsigned*)((const char*)(gbase) + (voff)[_i]), (LAS unsigned*)(lds + (bufoff) + ldsw + _i * 8192), 16, 0, 0); } while (0)
; #define PG8_LDA(dst, b, h) do { _Pragma("unroll") for (int m = 0; m < 4; ++m) _Pragma("unroll") for (int k = 0; k < 2; ++k) dst[m][k] = *(const LAS bf16x8*)(lds + PG8_SA(b, h) + aoff + m * 2048 + k * 1024); } while (0)
; #define PG8_LDB(dst, b, h) do { _Pragma("unroll") for (int n = 0; n < 2; ++n) _Pragma("unroll") for (int k = 0; k < 2; ++k) dst[n][k] = *(const LAS bf16x8*)(lds + PG8_SB(b, h) + boff + n * 2048 + k * 1024); } while (0)
; #define PG8_MMA(ai, bj, At, Bt) do { __builtin_amdgcn_s_setprio(1); _Pragma("unroll") for (int m = 0; m < 4; ++m) _Pragma("unroll") for (int n = 0; n < 2; ++n) _Pragma("unroll") for (int k = 0; k < 2; ++k) \
;         acc[ai][bj][m][n] = __builtin_amdgcn_mfma_f32_16x16x32_bf16(Bt[n][k], At[m][k], acc[ai][bj][m][n], 0, 0, 0); __builtin_amdgcn_s_setprio(0); } while (0)
; #define PG8_WAIT_V(n) asm volatile("s_waitcnt vmcnt(" #n ")" ::: "memory")
; #define PG8_WAIT_L(n) asm volatile("s_waitcnt lgkmcnt(" #n ")" ::: "memory")
; #define PG8_BAR __builtin_amdgcn_s_barrier()
; #define PG8_SCHED __builtin_amdgcn_sched_barrier(0)
; template <class Epi, class Sched, bool ABLK = false, bool ALIGN_EPI = true, bool SP2 = true, bool BBLK = true>
; __device__ __forceinline__ void gemm_phase(LAS unsigned char* lds, const Gemm g, const Sched& S, const Epi& E) {
;     ...
;             PG8_LDB(B0, 1, 0); PG8_LDB(B1, 1, 1); PG8_SCHED; PG8_LDA(At, 1, 0); PG8_STAGE(PG8_SA(0, 1), a2 + hstepA, voffA);
;             PG8_WAIT_V(8); PG8_WAIT_L(0); PG8_BAR; PG8_MMA(0, 0, At, B0); PG8_MMA(0, 1, At, B1); PG8_BAR; PG8_SCHED;
;             PG8_LDA(At, 1, 1); PG8_STAGE(PG8_SB(1, 0), b3, voffB); PG8_STAGE(PG8_SB(1, 1), b3 + hstepB, voffB); PG8_STAGE(PG8_SA(1, 0), a3, voffA);
;             PG8_WAIT_V(8); PG8_WAIT_L(0); PG8_BAR; PG8_MMA(1, 0, At, B0); PG8_MMA(1, 1, At, B1); PG8_BAR; PG8_SCHED;
	v_add_u32_e32 v168, s60, v151
	v_add_u32_e32 v184, s61, v151
	ds_read_b128 v[156:159], v168
	ds_read_b128 v[160:163], v168 offset:1024
	ds_read_b128 v[164:167], v168 offset:2048
	ds_read_b128 v[168:171], v168 offset:3072
	ds_read_b128 v[172:175], v184
	ds_read_b128 v[176:179], v184 offset:1024
	ds_read_b128 v[180:183], v184 offset:2048
	ds_read_b128 v[184:187], v184 offset:3072
	s_add_u32 s26, s26, 0x80000
	s_addc_u32 s27, s27, 0
	s_mov_b32 m0, s37
	ds_read_b128 v[188:191], v155 offset:32768
	ds_read_b128 v[192:195], v155 offset:33792
	ds_read_b128 v[196:199], v155 offset:34816
	ds_read_b128 v[200:203], v155 offset:35840
	ds_read_b128 v[204:207], v155 offset:36864
	ds_read_b128 v[208:211], v155 offset:37888
	ds_read_b128 v[212:215], v155 offset:38912
	ds_read_b128 v[216:219], v155 offset:39936
	global_load_lds_dwordx4 v130, s[26:27]
	s_mov_b32 m0, s40
	s_nop 0
	global_load_lds_dwordx4 v134, s[26:27]
	s_waitcnt vmcnt(8) lgkmcnt(0)
	s_barrier
	v_mfma_f32_16x16x32_bf16 v[126:129], v[156:159], v[188:191], v[126:129]
	v_mfma_f32_16x16x32_bf16 v[122:125], v[164:167], v[188:191], v[122:125]
	v_mfma_f32_16x16x32_bf16 v[110:113], v[156:159], v[196:199], v[110:113]
	v_mfma_f32_16x16x32_bf16 v[106:109], v[164:167], v[196:199], v[106:109]
	v_mfma_f32_16x16x32_bf16 v[94:97], v[156:159], v[204:207], v[94:97]
	v_mfma_f32_16x16x32_bf16 v[90:93], v[164:167], v[204:207], v[90:93]
	v_mfma_f32_16x16x32_bf16 v[78:81], v[156:159], v[212:215], v[78:81]
	v_mfma_f32_16x16x32_bf16 v[74:77], v[164:167], v[212:215], v[74:77]
	v_mfma_f32_16x16x32_bf16 v[126:129], v[160:163], v[192:195], v[126:129]
	v_mfma_f32_16x16x32_bf16 v[122:125], v[168:171], v[192:195], v[122:125]
	v_mfma_f32_16x16x32_bf16 v[110:113], v[160:163], v[200:203], v[110:113]
	v_mfma_f32_16x16x32_bf16 v[106:109], v[168:171], v[200:203], v[106:109]
	v_mfma_f32_16x16x32_bf16 v[94:97], v[160:163], v[208:211], v[94:97]
	v_mfma_f32_16x16x32_bf16 v[90:93], v[168:171], v[208:211], v[90:93]
	v_mfma_f32_16x16x32_bf16 v[78:81], v[160:163], v[216:219], v[78:81]
	v_mfma_f32_16x16x32_bf16 v[74:77], v[168:171], v[216:219], v[74:77]
	v_mfma_f32_16x16x32_bf16 v[118:121], v[172:175], v[188:191], v[118:121]
	v_mfma_f32_16x16x32_bf16 v[114:117], v[180:183], v[188:191], v[114:117]
	v_mfma_f32_16x16x32_bf16 v[102:105], v[172:175], v[196:199], v[102:105]
	v_mfma_f32_16x16x32_bf16 v[98:101], v[180:183], v[196:199], v[98:101]
	v_mfma_f32_16x16x32_bf16 v[86:89], v[172:175], v[204:207], v[86:89]
	v_mfma_f32_16x16x32_bf16 v[82:85], v[180:183], v[204:207], v[82:85]
	v_mfma_f32_16x16x32_bf16 v[70:73], v[172:175], v[212:215], v[70:73]
	v_mfma_f32_16x16x32_bf16 v[66:69], v[180:183], v[212:215], v[66:69]
	v_mfma_f32_16x16x32_bf16 v[118:121], v[176:179], v[192:195], v[118:121]
	v_mfma_f32_16x16x32_bf16 v[114:117], v[184:187], v[192:195], v[114:117]
	v_mfma_f32_16x16x32_bf16 v[102:105], v[176:179], v[200:203], v[102:105]
	v_mfma_f32_16x16x32_bf16 v[98:101], v[184:187], v[200:203], v[98:101]
	v_mfma_f32_16x16x32_bf16 v[86:89], v[176:179], v[208:211], v[86:89]
	v_mfma_f32_16x16x32_bf16 v[82:85], v[184:187], v[208:211], v[82:85]
	v_mfma_f32_16x16x32_bf16 v[70:73], v[176:179], v[216:219], v[70:73]
	v_mfma_f32_16x16x32_bf16 v[66:69], v[184:187], v[216:219], v[66:69]
	s_barrier
	s_add_u32 s26, s24, 0x8000
	s_addc_u32 s27, s25, 0
	s_add_i32 s66, s60, s34
	s_mov_b32 m0, s66
	ds_read_b128 v[188:191], v155 offset:49152
	ds_read_b128 v[192:195], v155 offset:50176
	ds_read_b128 v[196:199], v155 offset:51200
	ds_read_b128 v[200:203], v155 offset:52224
	ds_read_b128 v[204:207], v155 offset:53248
	ds_read_b128 v[208:211], v155 offset:54272
	ds_read_b128 v[212:215], v155 offset:55296
	ds_read_b128 v[216:219], v155 offset:56320
	global_load_lds_dwordx4 v132, s[26:27]
	s_add_i32 m0, s66, 0x2000
	s_add_u32 s24, s24, 0xc000
	v_lshl_add_u64 v[220:221], s[26:27], 0, v[136:137]
	s_addc_u32 s25, s25, 0
	s_add_i32 s26, s61, s34
	global_load_lds_dwordx4 v[220:221], off
	s_mov_b32 m0, s26
	s_nop 0
	global_load_lds_dwordx4 v132, s[24:25]
	s_add_i32 m0, s26, 0x2000
	s_nop 0
	global_load_lds_dwordx4 v136, s[24:25]
	s_mov_b32 m0, s41
	s_nop 0
	global_load_lds_dwordx4 v130, s[22:23]
	s_mov_b32 m0, s42
	s_nop 0
	global_load_lds_dwordx4 v134, s[22:23]
	s_waitcnt vmcnt(8) lgkmcnt(0)
	s_barrier
	v_mfma_f32_16x16x32_bf16 v[62:65], v[156:159], v[188:191], v[62:65]
	v_mfma_f32_16x16x32_bf16 v[58:61], v[164:167], v[188:191], v[58:61]
	v_mfma_f32_16x16x32_bf16 v[46:49], v[156:159], v[196:199], v[46:49]
	v_mfma_f32_16x16x32_bf16 v[42:45], v[164:167], v[196:199], v[42:45]
	v_mfma_f32_16x16x32_bf16 v[30:33], v[156:159], v[204:207], v[30:33]
	v_mfma_f32_16x16x32_bf16 v[26:29], v[164:167], v[204:207], v[26:29]
	v_mfma_f32_16x16x32_bf16 v[14:17], v[156:159], v[212:215], v[14:17]
	v_mfma_f32_16x16x32_bf16 v[10:13], v[164:167], v[212:215], v[10:13]
	v_mfma_f32_16x16x32_bf16 v[62:65], v[160:163], v[192:195], v[62:65]
	v_mfma_f32_16x16x32_bf16 v[58:61], v[168:171], v[192:195], v[58:61]
	v_mfma_f32_16x16x32_bf16 v[46:49], v[160:163], v[200:203], v[46:49]
	v_mfma_f32_16x16x32_bf16 v[42:45], v[168:171], v[200:203], v[42:45]
	v_mfma_f32_16x16x32_bf16 v[30:33], v[160:163], v[208:211], v[30:33]
	v_mfma_f32_16x16x32_bf16 v[26:29], v[168:171], v[208:211], v[26:29]
	v_mfma_f32_16x16x32_bf16 v[14:17], v[160:163], v[216:219], v[14:17]
	v_mfma_f32_16x16x32_bf16 v[10:13], v[168:171], v[216:219], v[10:13]
	v_mfma_f32_16x16x32_bf16 v[54:57], v[172:175], v[188:191], v[54:57]
	v_mfma_f32_16x16x32_bf16 v[50:53], v[180:183], v[188:191], v[50:53]
	v_mfma_f32_16x16x32_bf16 v[38:41], v[172:175], v[196:199], v[38:41]
	v_mfma_f32_16x16x32_bf16 v[34:37], v[180:183], v[196:199], v[34:37]
	v_mfma_f32_16x16x32_bf16 v[22:25], v[172:175], v[204:207], v[22:25]
	v_mfma_f32_16x16x32_bf16 v[18:21], v[180:183], v[204:207], v[18:21]
	v_mfma_f32_16x16x32_bf16 v[6:9], v[172:175], v[212:215], v[6:9]
	v_mfma_f32_16x16x32_bf16 v[2:5], v[180:183], v[212:215], v[2:5]
	v_mfma_f32_16x16x32_bf16 v[54:57], v[176:179], v[192:195], v[54:57]
	v_mfma_f32_16x16x32_bf16 v[50:53], v[184:187], v[192:195], v[50:53]
	v_mfma_f32_16x16x32_bf16 v[38:41], v[176:179], v[200:203], v[38:41]
	v_mfma_f32_16x16x32_bf16 v[34:37], v[184:187], v[200:203], v[34:37]
	v_mfma_f32_16x16x32_bf16 v[22:25], v[176:179], v[208:211], v[22:25]
	v_mfma_f32_16x16x32_bf16 v[18:21], v[184:187], v[208:211], v[18:21]
	v_mfma_f32_16x16x32_bf16 v[6:9], v[176:179], v[216:219], v[6:9]
	v_mfma_f32_16x16x32_bf16 v[2:5], v[184:187], v[216:219], v[2:5]
	s_barrier
; __device__ __forceinline__ unsigned pk2(float lo, float hi) { const f32x2 v = {lo, hi}; return __builtin_bit_cast(unsigned, __builtin_convertvector(v, bf16x2_t)); }
; __device__ __forceinline__ void store_pair(unsigned char* own, size_t stride8, int hi_off, u32x4 lo, u32x4 hi, bool upper) {
;     const u32x4 tlo = ror8(lo), thi = ror8(hi);
;     const u32x4 A = upper ? thi : lo, B = upper ? hi : tlo;
;     unsigned char* pa = upper ? own - stride8 + hi_off : own;
;     unsigned char* pb = upper ? own + hi_off : own + stride8;
;     *(u32x4*)pa = A; *(u32x4*)pb = B;
; }
;     __device__ __forceinline__ void operator()(const f32x4 (&acc)[2][2][4][2], const Unit& u, int wr, int wc, int fr, int fq) const {
;         const int row0 = u.pm * 256 + wr * 64 + fr, col0 = u.pn * 256 + wc * 64 + 8 * fq;
;         bf16_t* base = u.part == 0 ? Z + (size_t)row0 * D + col0 : P + ((size_t)(u.part - 1) * MS + (row0 - MP)) * D + col0;
; #pragma unroll
;         for (int ai = 0; ai < 2; ++ai)
; #pragma unroll
;             for (int m = 0; m < 4; ++m) { u32x4 w[2];
; #pragma unroll
;                 for (int bj = 0; bj < 2; ++bj) { const f32x4 v0 = acc[ai][bj][m][0], v1 = acc[ai][bj][m][1]; w[bj].x = pk2(v0[0], v0[1]); w[bj].y = pk2(v0[2], v0[3]); w[bj].z = pk2(v1[0], v1[1]); w[bj].w = pk2(v1[2], v1[3]); }
;                 store_pair((unsigned char*)(base + (size_t)(ai * 128 + m * 16) * D), (size_t)8 * D * 2, 64, w[0], w[1], fr >= 8); }
	s_add_u32 s51, s51, 0x10000
	s_addc_u32 s55, s55, 0
	s_add_u32 s20, s20, 0x100
	s_addc_u32 s21, s21, 0
	s_cmp_ge_u32 s65, s46
	s_cbranch_scc0 .LBB0_1038
	v_lshl_add_u32 v147, s47, 8, v150
	v_add_u32_e32 v148, 0xffffe000, v147
	v_sub_co_u32_e64 v146, vcc, s43, 1
	v_mov_b32_e32 v149, s54
	s_nop 0
	v_cndmask_b32_e32 v148, v148, v147, vcc
	v_ashrrev_i32_e32 v147, 31, v146
	v_lshlrev_b64 v[146:147], 23, v[146:147]
	v_lshl_add_u64 v[146:147], s[12:13], 0, v[146:147]
	v_cndmask_b32_e32 v147, v147, v149, vcc
	v_mov_b32_e32 v149, s52
	v_cndmask_b32_e32 v146, v146, v149, vcc
	v_ashrrev_i32_e32 v149, 31, v148
	v_lshl_or_b32 v156, s78, 8, v152
	v_lshlrev_b64 v[148:149], 12, v[148:149]
	v_lshl_add_u64 v[146:147], v[146:147], 0, v[148:149]
	v_ashrrev_i32_e32 v157, 31, v156
	v_cvt_pk_bf16_f32 v126, v126, v127
	v_cvt_pk_bf16_f32 v127, v128, v129
	v_cvt_pk_bf16_f32 v128, v122, v123
	v_cvt_pk_bf16_f32 v124, v124, v125
	v_cvt_pk_bf16_f32 v118, v118, v119
	v_cvt_pk_bf16_f32 v119, v120, v121
	v_cvt_pk_bf16_f32 v114, v114, v115
	v_cvt_pk_bf16_f32 v115, v116, v117
	v_lshl_add_u64 v[146:147], v[156:157], 1, v[146:147]
	s_mov_b64 vcc, s[6:7]
	v_mov_b32_dpp v125, v118 row_ror:8 row_mask:0xf bank_mask:0xf bound_ctrl:1
	v_mov_b32_dpp v129, v119 row_ror:8 row_mask:0xf bank_mask:0xf bound_ctrl:1
	v_mov_b32_dpp v148, v114 row_ror:8 row_mask:0xf bank_mask:0xf bound_ctrl:1
	v_mov_b32_dpp v149, v115 row_ror:8 row_mask:0xf bank_mask:0xf bound_ctrl:1
	v_lshl_add_u64 v[122:123], v[146:147], 0, v[138:139]
	v_cndmask_b32_dpp v117, v124, v115, vcc row_ror:8 row_mask:0xf bank_mask:0xf bound_ctrl:1
	v_cndmask_b32_dpp v116, v128, v114, vcc row_ror:8 row_mask:0xf bank_mask:0xf bound_ctrl:1
	v_cndmask_b32_dpp v115, v127, v119, vcc row_ror:8 row_mask:0xf bank_mask:0xf bound_ctrl:1
	v_cndmask_b32_dpp v114, v126, v118, vcc row_ror:8 row_mask:0xf bank_mask:0xf bound_ctrl:1
	v_cndmask_b32_e64 v121, v124, v149, s[6:7]
	v_cndmask_b32_e64 v120, v128, v148, s[6:7]
	v_cndmask_b32_e64 v119, v127, v129, s[6:7]
	v_cndmask_b32_e64 v118, v126, v125, s[6:7]
	v_cvt_pk_bf16_f32 v110, v110, v111
	v_cvt_pk_bf16_f32 v111, v112, v113
	v_cvt_pk_bf16_f32 v112, v106, v107
	v_cvt_pk_bf16_f32 v113, v108, v109
	v_cvt_pk_bf16_f32 v102, v102, v103
	v_cvt_pk_bf16_f32 v103, v104, v105
	v_cvt_pk_bf16_f32 v98, v98, v99
	v_cvt_pk_bf16_f32 v99, v100, v101
	s_mov_b64 s[4:5], 0x10000
	v_lshl_add_u64 v[124:125], v[146:147], 0, v[140:141]
	s_and_b64 vcc, exec, s[10:11]
	s_cbranch_vccz .LBB0_1041
	s_barrier
.LBB0_1041:
	global_store_dwordx4 v[122:123], v[118:121], off
	global_store_dwordx4 v[124:125], v[114:117], off
	v_lshl_add_u64 v[106:107], v[146:147], 0, s[4:5]
	s_mov_b64 vcc, s[6:7]
	v_mov_b32_dpp v114, v102 row_ror:8 row_mask:0xf bank_mask:0xf bound_ctrl:1
	v_mov_b32_dpp v115, v103 row_ror:8 row_mask:0xf bank_mask:0xf bound_ctrl:1
	v_mov_b32_dpp v116, v98 row_ror:8 row_mask:0xf bank_mask:0xf bound_ctrl:1
	v_mov_b32_dpp v117, v99 row_ror:8 row_mask:0xf bank_mask:0xf bound_ctrl:1
	v_lshl_add_u64 v[108:109], v[106:107], 0, v[138:139]
	v_cndmask_b32_dpp v101, v113, v99, vcc row_ror:8 row_mask:0xf bank_mask:0xf bound_ctrl:1
	v_cndmask_b32_dpp v100, v112, v98, vcc row_ror:8 row_mask:0xf bank_mask:0xf bound_ctrl:1
	v_cndmask_b32_dpp v99, v111, v103, vcc row_ror:8 row_mask:0xf bank_mask:0xf bound_ctrl:1
	v_cndmask_b32_dpp v98, v110, v102, vcc row_ror:8 row_mask:0xf bank_mask:0xf bound_ctrl:1
	v_cndmask_b32_e64 v105, v113, v117, s[6:7]
	v_cndmask_b32_e64 v104, v112, v116, s[6:7]
	v_cndmask_b32_e64 v103, v111, v115, s[6:7]
	v_cndmask_b32_e64 v102, v110, v114, s[6:7]
	v_cvt_pk_bf16_f32 v94, v94, v95
	v_cvt_pk_bf16_f32 v95, v96, v97
	v_cvt_pk_bf16_f32 v96, v90, v91
	v_cvt_pk_bf16_f32 v97, v92, v93
	v_cvt_pk_bf16_f32 v86, v86, v87
	v_cvt_pk_bf16_f32 v87, v88, v89
	v_cvt_pk_bf16_f32 v82, v82, v83
	v_cvt_pk_bf16_f32 v83, v84, v85
	s_mov_b64 s[4:5], 0x20000
	v_lshl_add_u64 v[106:107], v[106:107], 0, v[140:141]
	global_store_dwordx4 v[108:109], v[102:105], off
	global_store_dwordx4 v[106:107], v[98:101], off
	v_lshl_add_u64 v[90:91], v[146:147], 0, s[4:5]
	s_mov_b64 vcc, s[6:7]
	v_mov_b32_dpp v98, v86 row_ror:8 row_mask:0xf bank_mask:0xf bound_ctrl:1
	v_mov_b32_dpp v99, v87 row_ror:8 row_mask:0xf bank_mask:0xf bound_ctrl:1
	v_mov_b32_dpp v100, v82 row_ror:8 row_mask:0xf bank_mask:0xf bound_ctrl:1
	v_mov_b32_dpp v101, v83 row_ror:8 row_mask:0xf bank_mask:0xf bound_ctrl:1
	v_lshl_add_u64 v[92:93], v[90:91], 0, v[138:139]
	v_cndmask_b32_dpp v85, v97, v83, vcc row_ror:8 row_mask:0xf bank_mask:0xf bound_ctrl:1
	v_cndmask_b32_dpp v84, v96, v82, vcc row_ror:8 row_mask:0xf bank_mask:0xf bound_ctrl:1
	v_cndmask_b32_dpp v83, v95, v87, vcc row_ror:8 row_mask:0xf bank_mask:0xf bound_ctrl:1
	v_cndmask_b32_dpp v82, v94, v86, vcc row_ror:8 row_mask:0xf bank_mask:0xf bound_ctrl:1
	v_cndmask_b32_e64 v89, v97, v101, s[6:7]
	v_cndmask_b32_e64 v88, v96, v100, s[6:7]
	v_cndmask_b32_e64 v87, v95, v99, s[6:7]
	v_cndmask_b32_e64 v86, v94, v98, s[6:7]
	v_cvt_pk_bf16_f32 v78, v78, v79
	v_cvt_pk_bf16_f32 v79, v80, v81
	v_cvt_pk_bf16_f32 v80, v74, v75
	v_cvt_pk_bf16_f32 v81, v76, v77
	v_cvt_pk_bf16_f32 v70, v70, v71
	v_cvt_pk_bf16_f32 v71, v72, v73
	v_cvt_pk_bf16_f32 v66, v66, v67
	v_cvt_pk_bf16_f32 v67, v68, v69
	s_mov_b64 s[4:5], 0x30000
	v_lshl_add_u64 v[90:91], v[90:91], 0, v[140:141]
	global_store_dwordx4 v[92:93], v[86:89], off
	global_store_dwordx4 v[90:91], v[82:85], off
	v_lshl_add_u64 v[74:75], v[146:147], 0, s[4:5]
	s_mov_b64 vcc, s[6:7]
	v_mov_b32_dpp v82, v70 row_ror:8 row_mask:0xf bank_mask:0xf bound_ctrl:1
	v_mov_b32_dpp v83, v71 row_ror:8 row_mask:0xf bank_mask:0xf bound_ctrl:1
	v_mov_b32_dpp v84, v66 row_ror:8 row_mask:0xf bank_mask:0xf bound_ctrl:1
; __device__ __forceinline__ unsigned pk2(float lo, float hi) { const f32x2 v = {lo, hi}; return __builtin_bit_cast(unsigned, __builtin_convertvector(v, bf16x2_t)); }
; #define PG8_BAR __builtin_amdgcn_s_barrier()
; template <class Epi, class Sched, bool ABLK = false, bool ALIGN_EPI = true, bool SP2 = true, bool BBLK = true>
; __device__ __forceinline__ void gemm_phase(LAS unsigned char* lds, const Gemm g, const Sched& S, const Epi& E) {
;     ...
;         if (!has_next) break;
; #pragma unroll
;         for (int a = 0; a < 2; ++a)
; #pragma unroll
;             for (int b = 0; b < 2; ++b)
; #pragma unroll
;                 for (int m = 0; m < 4; ++m)
; #pragma unroll
;                     for (int n = 0; n < 2; ++n) acc[a][b][m][n] = (f32x4){0.f, 0.f, 0.f, 0.f};
;         cur = nxt; uA = nuA; tbA = ntbA; cB = nB; ++ui;
;         if constexpr (ALIGN_EPI) { if (wr == 1) PG8_BAR; }
;     __device__ __forceinline__ void operator()(const f32x4 (&acc)[2][2][4][2], const Unit& u, int wr, int wc, int fr, int fq) const {
;     ...
;             for (int m = 0; m < 4; ++m) { u32x4 w[2];
; #pragma unroll
;                 for (int bj = 0; bj < 2; ++bj) { const f32x4 v0 = acc[ai][bj][m][0], v1 = acc[ai][bj][m][1]; w[bj].x = pk2(v0[0], v0[1]); w[bj].y = pk2(v0[2], v0[3]); w[bj].z = pk2(v1[0], v1[1]); w[bj].w = pk2(v1[2], v1[3]); }
;                 store_pair((unsigned char*)(base + (size_t)(ai * 128 + m * 16) * D), (size_t)8 * D * 2, 64, w[0], w[1], fr >= 8); }
	v_mov_b32_dpp v85, v67 row_ror:8 row_mask:0xf bank_mask:0xf bound_ctrl:1
	v_lshl_add_u64 v[76:77], v[74:75], 0, v[138:139]
	v_cndmask_b32_dpp v69, v81, v67, vcc row_ror:8 row_mask:0xf bank_mask:0xf bound_ctrl:1
	v_cndmask_b32_dpp v68, v80, v66, vcc row_ror:8 row_mask:0xf bank_mask:0xf bound_ctrl:1
	v_cndmask_b32_dpp v67, v79, v71, vcc row_ror:8 row_mask:0xf bank_mask:0xf bound_ctrl:1
	v_cndmask_b32_dpp v66, v78, v70, vcc row_ror:8 row_mask:0xf bank_mask:0xf bound_ctrl:1
	v_cndmask_b32_e64 v73, v81, v85, s[6:7]
	v_cndmask_b32_e64 v72, v80, v84, s[6:7]
	v_cndmask_b32_e64 v71, v79, v83, s[6:7]
	v_cndmask_b32_e64 v70, v78, v82, s[6:7]
	v_cvt_pk_bf16_f32 v62, v62, v63
	v_cvt_pk_bf16_f32 v63, v64, v65
	v_cvt_pk_bf16_f32 v64, v58, v59
	v_cvt_pk_bf16_f32 v65, v60, v61
	v_cvt_pk_bf16_f32 v54, v54, v55
	v_cvt_pk_bf16_f32 v55, v56, v57
	v_cvt_pk_bf16_f32 v50, v50, v51
	v_cvt_pk_bf16_f32 v51, v52, v53
	s_mov_b64 s[4:5], 0x80000
	v_lshl_add_u64 v[74:75], v[74:75], 0, v[140:141]
	global_store_dwordx4 v[76:77], v[70:73], off
	global_store_dwordx4 v[74:75], v[66:69], off
	v_lshl_add_u64 v[58:59], v[146:147], 0, s[4:5]
	s_mov_b64 vcc, s[6:7]
	v_mov_b32_dpp v66, v54 row_ror:8 row_mask:0xf bank_mask:0xf bound_ctrl:1
	v_mov_b32_dpp v67, v55 row_ror:8 row_mask:0xf bank_mask:0xf bound_ctrl:1
	v_mov_b32_dpp v68, v50 row_ror:8 row_mask:0xf bank_mask:0xf bound_ctrl:1
	v_mov_b32_dpp v69, v51 row_ror:8 row_mask:0xf bank_mask:0xf bound_ctrl:1
	v_lshl_add_u64 v[60:61], v[58:59], 0, v[138:139]
	v_cndmask_b32_dpp v53, v65, v51, vcc row_ror:8 row_mask:0xf bank_mask:0xf bound_ctrl:1
	v_cndmask_b32_dpp v52, v64, v50, vcc row_ror:8 row_mask:0xf bank_mask:0xf bound_ctrl:1
	v_cndmask_b32_dpp v51, v63, v55, vcc row_ror:8 row_mask:0xf bank_mask:0xf bound_ctrl:1
	v_cndmask_b32_dpp v50, v62, v54, vcc row_ror:8 row_mask:0xf bank_mask:0xf bound_ctrl:1
	v_cndmask_b32_e64 v57, v65, v69, s[6:7]
	v_cndmask_b32_e64 v56, v64, v68, s[6:7]
	v_cndmask_b32_e64 v55, v63, v67, s[6:7]
	v_cndmask_b32_e64 v54, v62, v66, s[6:7]
	v_cvt_pk_bf16_f32 v46, v46, v47
	v_cvt_pk_bf16_f32 v47, v48, v49
	v_cvt_pk_bf16_f32 v48, v42, v43
	v_cvt_pk_bf16_f32 v49, v44, v45
	v_cvt_pk_bf16_f32 v38, v38, v39
	v_cvt_pk_bf16_f32 v39, v40, v41
	v_cvt_pk_bf16_f32 v34, v34, v35
	v_cvt_pk_bf16_f32 v35, v36, v37
	s_mov_b64 s[4:5], 0x90000
	v_lshl_add_u64 v[58:59], v[58:59], 0, v[140:141]
	global_store_dwordx4 v[60:61], v[54:57], off
	global_store_dwordx4 v[58:59], v[50:53], off
	v_lshl_add_u64 v[42:43], v[146:147], 0, s[4:5]
	s_mov_b64 vcc, s[6:7]
	v_mov_b32_dpp v50, v38 row_ror:8 row_mask:0xf bank_mask:0xf bound_ctrl:1
	v_mov_b32_dpp v51, v39 row_ror:8 row_mask:0xf bank_mask:0xf bound_ctrl:1
	v_mov_b32_dpp v52, v34 row_ror:8 row_mask:0xf bank_mask:0xf bound_ctrl:1
	v_mov_b32_dpp v53, v35 row_ror:8 row_mask:0xf bank_mask:0xf bound_ctrl:1
	v_lshl_add_u64 v[44:45], v[42:43], 0, v[138:139]
	v_cndmask_b32_dpp v37, v49, v35, vcc row_ror:8 row_mask:0xf bank_mask:0xf bound_ctrl:1
	v_cndmask_b32_dpp v36, v48, v34, vcc row_ror:8 row_mask:0xf bank_mask:0xf bound_ctrl:1
	v_cndmask_b32_dpp v35, v47, v39, vcc row_ror:8 row_mask:0xf bank_mask:0xf bound_ctrl:1
	v_cndmask_b32_dpp v34, v46, v38, vcc row_ror:8 row_mask:0xf bank_mask:0xf bound_ctrl:1
	v_cndmask_b32_e64 v41, v49, v53, s[6:7]
	v_cndmask_b32_e64 v40, v48, v52, s[6:7]
	v_cndmask_b32_e64 v39, v47, v51, s[6:7]
	v_cndmask_b32_e64 v38, v46, v50, s[6:7]
	v_cvt_pk_bf16_f32 v30, v30, v31
	v_cvt_pk_bf16_f32 v31, v32, v33
	v_cvt_pk_bf16_f32 v32, v26, v27
	v_cvt_pk_bf16_f32 v33, v28, v29
	v_cvt_pk_bf16_f32 v22, v22, v23
	v_cvt_pk_bf16_f32 v23, v24, v25
	v_cvt_pk_bf16_f32 v18, v18, v19
	v_cvt_pk_bf16_f32 v19, v20, v21
	s_mov_b64 s[4:5], 0xa0000
	v_lshl_add_u64 v[42:43], v[42:43], 0, v[140:141]
	global_store_dwordx4 v[44:45], v[38:41], off
	global_store_dwordx4 v[42:43], v[34:37], off
	v_lshl_add_u64 v[26:27], v[146:147], 0, s[4:5]
	s_mov_b64 vcc, s[6:7]
	v_mov_b32_dpp v34, v22 row_ror:8 row_mask:0xf bank_mask:0xf bound_ctrl:1
	v_mov_b32_dpp v35, v23 row_ror:8 row_mask:0xf bank_mask:0xf bound_ctrl:1
	v_mov_b32_dpp v36, v18 row_ror:8 row_mask:0xf bank_mask:0xf bound_ctrl:1
	v_mov_b32_dpp v37, v19 row_ror:8 row_mask:0xf bank_mask:0xf bound_ctrl:1
	v_lshl_add_u64 v[28:29], v[26:27], 0, v[138:139]
	v_cndmask_b32_dpp v21, v33, v19, vcc row_ror:8 row_mask:0xf bank_mask:0xf bound_ctrl:1
	v_cndmask_b32_dpp v20, v32, v18, vcc row_ror:8 row_mask:0xf bank_mask:0xf bound_ctrl:1
	v_cndmask_b32_dpp v19, v31, v23, vcc row_ror:8 row_mask:0xf bank_mask:0xf bound_ctrl:1
	v_cndmask_b32_dpp v18, v30, v22, vcc row_ror:8 row_mask:0xf bank_mask:0xf bound_ctrl:1
	v_cndmask_b32_e64 v25, v33, v37, s[6:7]
	v_cndmask_b32_e64 v24, v32, v36, s[6:7]
	v_cndmask_b32_e64 v23, v31, v35, s[6:7]
	v_cndmask_b32_e64 v22, v30, v34, s[6:7]
	v_cvt_pk_bf16_f32 v14, v14, v15
	v_cvt_pk_bf16_f32 v15, v16, v17
	v_cvt_pk_bf16_f32 v16, v10, v11
	v_cvt_pk_bf16_f32 v17, v12, v13
	v_cvt_pk_bf16_f32 v6, v6, v7
	v_cvt_pk_bf16_f32 v7, v8, v9
	v_cvt_pk_bf16_f32 v2, v2, v3
	v_cvt_pk_bf16_f32 v3, v4, v5
	s_mov_b64 s[4:5], 0xb0000
	v_lshl_add_u64 v[26:27], v[26:27], 0, v[140:141]
	global_store_dwordx4 v[28:29], v[22:25], off
	global_store_dwordx4 v[26:27], v[18:21], off
	v_lshl_add_u64 v[10:11], v[146:147], 0, s[4:5]
	s_mov_b64 vcc, s[6:7]
	v_mov_b32_dpp v18, v6 row_ror:8 row_mask:0xf bank_mask:0xf bound_ctrl:1
	v_mov_b32_dpp v19, v7 row_ror:8 row_mask:0xf bank_mask:0xf bound_ctrl:1
	v_mov_b32_dpp v20, v2 row_ror:8 row_mask:0xf bank_mask:0xf bound_ctrl:1
	v_mov_b32_dpp v21, v3 row_ror:8 row_mask:0xf bank_mask:0xf bound_ctrl:1
	v_lshl_add_u64 v[12:13], v[10:11], 0, v[138:139]
	v_cndmask_b32_dpp v5, v17, v3, vcc row_ror:8 row_mask:0xf bank_mask:0xf bound_ctrl:1
	v_cndmask_b32_dpp v4, v16, v2, vcc row_ror:8 row_mask:0xf bank_mask:0xf bound_ctrl:1
	v_cndmask_b32_dpp v3, v15, v7, vcc row_ror:8 row_mask:0xf bank_mask:0xf bound_ctrl:1
	v_cndmask_b32_dpp v2, v14, v6, vcc row_ror:8 row_mask:0xf bank_mask:0xf bound_ctrl:1
	v_cndmask_b32_e64 v9, v17, v21, s[6:7]
	v_cndmask_b32_e64 v8, v16, v20, s[6:7]
	v_cndmask_b32_e64 v7, v15, v19, s[6:7]
	v_cndmask_b32_e64 v6, v14, v18, s[6:7]
	s_and_b64 vcc, exec, s[8:9]
	s_mov_b64 s[8:9], -1
	v_lshl_add_u64 v[10:11], v[10:11], 0, v[140:141]
	global_store_dwordx4 v[12:13], v[6:9], off
	global_store_dwordx4 v[10:11], v[2:5], off
	s_cbranch_vccnz .LBB0_1036
	s_andn2_b64 vcc, exec, s[2:3]
	s_cbranch_vccnz .LBB0_1035
	s_barrier
	s_branch .LBB0_1035

; #define PG8_STAGE(bufoff, gbase, voff) do { _Pragma("unroll") for (int _i = 0; _i < 2; ++_i) \
;         __builtin_amdgcn_global_load_lds((const unsigned*)((const char*)(gbase) + (voff)[_i]), (LAS unsigned*)(lds + (bufoff) + ldsw + _i * 8192), 16, 0, 0); } while (0)
; #define PG8_LDA(dst, b, h) do { _Pragma("unroll") for (int m = 0; m < 4; ++m) _Pragma("unroll") for (int k = 0; k < 2; ++k) dst[m][k] = *(const LAS bf16x8*)(lds + PG8_SA(b, h) + aoff + m * 2048 + k * 1024); } while (0)
; #define PG8_LDB(dst, b, h) do { _Pragma("unroll") for (int n = 0; n < 2; ++n) _Pragma("unroll") for (int k = 0; k < 2; ++k) dst[n][k] = *(const LAS bf16x8*)(lds + PG8_SB(b, h) + boff + n * 2048 + k * 1024); } while (0)
; #define PG8_MMA(ai, bj, At, Bt) do { __builtin_amdgcn_s_setprio(1); _Pragma("unroll") for (int m = 0; m < 4; ++m) _Pragma("unroll") for (int n = 0; n < 2; ++n) _Pragma("unroll") for (int k = 0; k < 2; ++k) \
;         acc[ai][bj][m][n] = __builtin_amdgcn_mfma_f32_16x16x32_bf16(Bt[n][k], At[m][k], acc[ai][bj][m][n], 0, 0, 0); __builtin_amdgcn_s_setprio(0); } while (0)
; #define PG8_WAIT_V(n) asm volatile("s_waitcnt vmcnt(" #n ")" ::: "memory")
; #define PG8_WAIT_L(n) asm volatile("s_waitcnt lgkmcnt(" #n ")" ::: "memory")
; #define PG8_BAR __builtin_amdgcn_s_barrier()
; #define PG8_SCHED __builtin_amdgcn_sched_barrier(0)
; template <class Epi, class Sched, bool ABLK = false, bool ALIGN_EPI = true, bool SP2 = true, bool BBLK = true>
; __device__ __forceinline__ void gemm_phase(LAS unsigned char* lds, const Gemm g, const Sched& S, const Epi& E) {
;     ...
;             PG8_LDB(B0, 0, 0); PG8_LDB(B1, 0, 1); PG8_SCHED; PG8_LDA(At, 0, 0); PG8_STAGE(PG8_SA(1, 1), a1 + hstepA, voffA);
;             PG8_WAIT_V(8); PG8_WAIT_L(0); PG8_BAR; PG8_MMA(0, 0, At, B0); PG8_MMA(0, 1, At, B1); PG8_BAR; PG8_SCHED;
;             PG8_LDA(At, 0, 1); PG8_STAGE(PG8_SB(0, 0), b2, voffB); PG8_STAGE(PG8_SB(0, 1), b2 + hstepB, voffB); PG8_STAGE(PG8_SA(0, 0), a2, voffA);
;             PG8_WAIT_V(8); PG8_WAIT_L(0); PG8_BAR; PG8_MMA(1, 0, At, B0); PG8_MMA(1, 1, At, B1); PG8_BAR; PG8_SCHED;
.Lksel_11_back:
	s_mov_b32 m0, s50
	v_lshl_add_u64 v[236:237], v[164:165], 0, s[28:29]
	ds_read_b128 v[204:207], v171
	ds_read_b128 v[208:211], v171 offset:1024
	ds_read_b128 v[212:215], v171 offset:2048
	ds_read_b128 v[216:219], v171 offset:3072
	ds_read_b128 v[220:223], v171 offset:4096
	ds_read_b128 v[224:227], v171 offset:5120
	ds_read_b128 v[228:231], v171 offset:6144
	ds_read_b128 v[232:235], v171 offset:7168
	global_load_lds_dwordx4 v[236:237], off
	v_lshl_add_u64 v[236:237], v[166:167], 0, s[28:29]
	s_mov_b32 m0, s51
	s_nop 0
	global_load_lds_dwordx4 v[236:237], off
	s_waitcnt vmcnt(8) lgkmcnt(0)
	s_barrier
	v_mfma_f32_16x16x32_bf16 v[126:129], v[172:175], v[204:207], v[126:129]
	v_mfma_f32_16x16x32_bf16 v[122:125], v[180:183], v[204:207], v[122:125]
	v_mfma_f32_16x16x32_bf16 v[110:113], v[172:175], v[212:215], v[110:113]
	v_mfma_f32_16x16x32_bf16 v[106:109], v[180:183], v[212:215], v[106:109]
	v_mfma_f32_16x16x32_bf16 v[94:97], v[172:175], v[220:223], v[94:97]
	v_mfma_f32_16x16x32_bf16 v[90:93], v[180:183], v[220:223], v[90:93]
	v_mfma_f32_16x16x32_bf16 v[78:81], v[172:175], v[228:231], v[78:81]
	v_mfma_f32_16x16x32_bf16 v[74:77], v[180:183], v[228:231], v[74:77]
	v_mfma_f32_16x16x32_bf16 v[126:129], v[176:179], v[208:211], v[126:129]
	v_mfma_f32_16x16x32_bf16 v[122:125], v[184:187], v[208:211], v[122:125]
	v_mfma_f32_16x16x32_bf16 v[110:113], v[176:179], v[216:219], v[110:113]
	v_mfma_f32_16x16x32_bf16 v[106:109], v[184:187], v[216:219], v[106:109]
	v_mfma_f32_16x16x32_bf16 v[94:97], v[176:179], v[224:227], v[94:97]
	v_mfma_f32_16x16x32_bf16 v[90:93], v[184:187], v[224:227], v[90:93]
	v_mfma_f32_16x16x32_bf16 v[78:81], v[176:179], v[232:235], v[78:81]
	v_mfma_f32_16x16x32_bf16 v[74:77], v[184:187], v[232:235], v[74:77]
	v_mfma_f32_16x16x32_bf16 v[118:121], v[188:191], v[204:207], v[118:121]
	v_mfma_f32_16x16x32_bf16 v[114:117], v[196:199], v[204:207], v[114:117]
	v_mfma_f32_16x16x32_bf16 v[102:105], v[188:191], v[212:215], v[102:105]
	v_mfma_f32_16x16x32_bf16 v[98:101], v[196:199], v[212:215], v[98:101]
	v_mfma_f32_16x16x32_bf16 v[86:89], v[188:191], v[220:223], v[86:89]
	v_mfma_f32_16x16x32_bf16 v[82:85], v[196:199], v[220:223], v[82:85]
	v_mfma_f32_16x16x32_bf16 v[70:73], v[188:191], v[228:231], v[70:73]
	v_mfma_f32_16x16x32_bf16 v[66:69], v[196:199], v[228:231], v[66:69]
	v_mfma_f32_16x16x32_bf16 v[118:121], v[192:195], v[208:211], v[118:121]
	v_mfma_f32_16x16x32_bf16 v[114:117], v[200:203], v[208:211], v[114:117]
	v_mfma_f32_16x16x32_bf16 v[102:105], v[192:195], v[216:219], v[102:105]
	v_mfma_f32_16x16x32_bf16 v[98:101], v[200:203], v[216:219], v[98:101]
	v_mfma_f32_16x16x32_bf16 v[86:89], v[192:195], v[224:227], v[86:89]
	v_mfma_f32_16x16x32_bf16 v[82:85], v[200:203], v[224:227], v[82:85]
	v_mfma_f32_16x16x32_bf16 v[70:73], v[192:195], v[232:235], v[70:73]
	v_mfma_f32_16x16x32_bf16 v[66:69], v[200:203], v[232:235], v[66:69]
	s_barrier
	s_mov_b32 m0, s55
	s_add_u32 s76, s34, 0x4000
	ds_read_b128 v[204:207], v171 offset:16384
	ds_read_b128 v[208:211], v171 offset:17408
	ds_read_b128 v[212:215], v171 offset:18432
	ds_read_b128 v[216:219], v171 offset:19456
	ds_read_b128 v[220:223], v171 offset:20480
	ds_read_b128 v[224:227], v171 offset:21504
	ds_read_b128 v[228:231], v171 offset:22528
	ds_read_b128 v[232:235], v171 offset:23552
	global_load_lds_dwordx4 v134, s[34:35]
	s_mov_b32 m0, s56
	s_addc_u32 s77, s35, 0
	s_add_i32 s67, s73, s42
	global_load_lds_dwordx4 v130, s[34:35]
	s_mov_b32 m0, s67
	s_nop 0
	global_load_lds_dwordx4 v134, s[76:77]
	s_add_i32 m0, s67, 0x2000
	s_nop 0
	global_load_lds_dwordx4 v130, s[76:77]
	s_mov_b32 m0, s25
	s_nop 0
	global_load_lds_dwordx4 v136, s[36:37]
	s_mov_b32 m0, s43
	s_nop 0
	global_load_lds_dwordx4 v132, s[36:37]
	s_waitcnt vmcnt(8) lgkmcnt(0)
	s_barrier
	v_mfma_f32_16x16x32_bf16 v[62:65], v[172:175], v[204:207], v[62:65]
	v_mfma_f32_16x16x32_bf16 v[58:61], v[180:183], v[204:207], v[58:61]
	v_mfma_f32_16x16x32_bf16 v[46:49], v[172:175], v[212:215], v[46:49]
	v_mfma_f32_16x16x32_bf16 v[42:45], v[180:183], v[212:215], v[42:45]
	v_mfma_f32_16x16x32_bf16 v[30:33], v[172:175], v[220:223], v[30:33]
	v_mfma_f32_16x16x32_bf16 v[26:29], v[180:183], v[220:223], v[26:29]
	v_mfma_f32_16x16x32_bf16 v[14:17], v[172:175], v[228:231], v[14:17]
	v_mfma_f32_16x16x32_bf16 v[10:13], v[180:183], v[228:231], v[10:13]
	v_mfma_f32_16x16x32_bf16 v[62:65], v[176:179], v[208:211], v[62:65]
	v_mfma_f32_16x16x32_bf16 v[58:61], v[184:187], v[208:211], v[58:61]
	v_mfma_f32_16x16x32_bf16 v[46:49], v[176:179], v[216:219], v[46:49]
	v_mfma_f32_16x16x32_bf16 v[42:45], v[184:187], v[216:219], v[42:45]
	v_mfma_f32_16x16x32_bf16 v[30:33], v[176:179], v[224:227], v[30:33]
	v_mfma_f32_16x16x32_bf16 v[26:29], v[184:187], v[224:227], v[26:29]
	v_mfma_f32_16x16x32_bf16 v[14:17], v[176:179], v[232:235], v[14:17]
	v_mfma_f32_16x16x32_bf16 v[10:13], v[184:187], v[232:235], v[10:13]
	v_mfma_f32_16x16x32_bf16 v[54:57], v[188:191], v[204:207], v[54:57]
	v_mfma_f32_16x16x32_bf16 v[50:53], v[196:199], v[204:207], v[50:53]
	v_mfma_f32_16x16x32_bf16 v[38:41], v[188:191], v[212:215], v[38:41]
	v_mfma_f32_16x16x32_bf16 v[34:37], v[196:199], v[212:215], v[34:37]
	v_mfma_f32_16x16x32_bf16 v[22:25], v[188:191], v[220:223], v[22:25]
	v_mfma_f32_16x16x32_bf16 v[18:21], v[196:199], v[220:223], v[18:21]
	v_mfma_f32_16x16x32_bf16 v[6:9], v[188:191], v[228:231], v[6:9]
	v_mfma_f32_16x16x32_bf16 v[2:5], v[196:199], v[228:231], v[2:5]
	v_mfma_f32_16x16x32_bf16 v[54:57], v[192:195], v[208:211], v[54:57]
	v_mfma_f32_16x16x32_bf16 v[50:53], v[200:203], v[208:211], v[50:53]
	v_mfma_f32_16x16x32_bf16 v[38:41], v[192:195], v[216:219], v[38:41]
	v_mfma_f32_16x16x32_bf16 v[34:37], v[200:203], v[216:219], v[34:37]
	v_mfma_f32_16x16x32_bf16 v[22:25], v[192:195], v[224:227], v[22:25]
	v_mfma_f32_16x16x32_bf16 v[18:21], v[200:203], v[224:227], v[18:21]
	v_mfma_f32_16x16x32_bf16 v[6:9], v[192:195], v[232:235], v[6:9]
	v_mfma_f32_16x16x32_bf16 v[2:5], v[200:203], v[232:235], v[2:5]
	s_barrier
; #define PG8_STAGE(bufoff, gbase, voff) do { _Pragma("unroll") for (int _i = 0; _i < 2; ++_i) \
;         __builtin_amdgcn_global_load_lds((const unsigned*)((const char*)(gbase) + (voff)[_i]), (LAS unsigned*)(lds + (bufoff) + ldsw + _i * 8192), 16, 0, 0); } while (0)
; #define PG8_LDA(dst, b, h) do { _Pragma("unroll") for (int m = 0; m < 4; ++m) _Pragma("unroll") for (int k = 0; k < 2; ++k) dst[m][k] = *(const LAS bf16x8*)(lds + PG8_SA(b, h) + aoff + m * 2048 + k * 1024); } while (0)
; #define PG8_LDB(dst, b, h) do { _Pragma("unroll") for (int n = 0; n < 2; ++n) _Pragma("unroll") for (int k = 0; k < 2; ++k) dst[n][k] = *(const LAS bf16x8*)(lds + PG8_SB(b, h) + boff + n * 2048 + k * 1024); } while (0)
; #define PG8_MMA(ai, bj, At, Bt) do { __builtin_amdgcn_s_setprio(1); _Pragma("unroll") for (int m = 0; m < 4; ++m) _Pragma("unroll") for (int n = 0; n < 2; ++n) _Pragma("unroll") for (int k = 0; k < 2; ++k) \
;         acc[ai][bj][m][n] = __builtin_amdgcn_mfma_f32_16x16x32_bf16(Bt[n][k], At[m][k], acc[ai][bj][m][n], 0, 0, 0); __builtin_amdgcn_s_setprio(0); } while (0)
; #define PG8_WAIT_V(n) asm volatile("s_waitcnt vmcnt(" #n ")" ::: "memory")
; #define PG8_WAIT_L(n) asm volatile("s_waitcnt lgkmcnt(" #n ")" ::: "memory")
; #define PG8_BAR __builtin_amdgcn_s_barrier()
; #define PG8_SCHED __builtin_amdgcn_sched_barrier(0)
; template <class Epi, class Sched, bool ABLK = false, bool ALIGN_EPI = true, bool SP2 = true, bool BBLK = true>
; __device__ __forceinline__ void gemm_phase(LAS unsigned char* lds, const Gemm g, const Sched& S, const Epi& E) {
;     ...
;             PG8_LDB(B0, 1, 0); PG8_LDB(B1, 1, 1); PG8_SCHED; PG8_LDA(At, 1, 0); PG8_STAGE(PG8_SA(0, 1), a2 + hstepA, voffA);
;             PG8_WAIT_V(8); PG8_WAIT_L(0); PG8_BAR; PG8_MMA(0, 0, At, B0); PG8_MMA(0, 1, At, B1); PG8_BAR; PG8_SCHED;
;             PG8_LDA(At, 1, 1); PG8_STAGE(PG8_SB(1, 0), b3, voffB); PG8_STAGE(PG8_SB(1, 1), b3 + hstepB, voffB); PG8_STAGE(PG8_SA(1, 0), a3, voffA);
;             PG8_WAIT_V(8); PG8_WAIT_L(0); PG8_BAR; PG8_MMA(1, 0, At, B0); PG8_MMA(1, 1, At, B1); PG8_BAR; PG8_SCHED;
	v_add_u32_e32 v184, s60, v168
	v_add_u32_e32 v200, s61, v168
	ds_read_b128 v[172:175], v184
	ds_read_b128 v[176:179], v184 offset:1024
	ds_read_b128 v[180:183], v184 offset:2048
	ds_read_b128 v[184:187], v184 offset:3072
	ds_read_b128 v[188:191], v200
	ds_read_b128 v[192:195], v200 offset:1024
	ds_read_b128 v[196:199], v200 offset:2048
	ds_read_b128 v[200:203], v200 offset:3072
	s_add_u32 s36, s36, 0x80000
	s_addc_u32 s37, s37, 0
	s_mov_b32 m0, s44
	ds_read_b128 v[204:207], v171 offset:32768
	ds_read_b128 v[208:211], v171 offset:33792
	ds_read_b128 v[212:215], v171 offset:34816
	ds_read_b128 v[216:219], v171 offset:35840
	ds_read_b128 v[220:223], v171 offset:36864
	ds_read_b128 v[224:227], v171 offset:37888
	ds_read_b128 v[228:231], v171 offset:38912
	ds_read_b128 v[232:235], v171 offset:39936
	global_load_lds_dwordx4 v136, s[36:37]
	s_mov_b32 m0, s45
	s_nop 0
	global_load_lds_dwordx4 v132, s[36:37]
	s_waitcnt vmcnt(8) lgkmcnt(0)
	s_barrier
	v_mfma_f32_16x16x32_bf16 v[126:129], v[172:175], v[204:207], v[126:129]
	v_mfma_f32_16x16x32_bf16 v[122:125], v[180:183], v[204:207], v[122:125]
	v_mfma_f32_16x16x32_bf16 v[110:113], v[172:175], v[212:215], v[110:113]
	v_mfma_f32_16x16x32_bf16 v[106:109], v[180:183], v[212:215], v[106:109]
	v_mfma_f32_16x16x32_bf16 v[94:97], v[172:175], v[220:223], v[94:97]
	v_mfma_f32_16x16x32_bf16 v[90:93], v[180:183], v[220:223], v[90:93]
	v_mfma_f32_16x16x32_bf16 v[78:81], v[172:175], v[228:231], v[78:81]
	v_mfma_f32_16x16x32_bf16 v[74:77], v[180:183], v[228:231], v[74:77]
	v_mfma_f32_16x16x32_bf16 v[126:129], v[176:179], v[208:211], v[126:129]
	v_mfma_f32_16x16x32_bf16 v[122:125], v[184:187], v[208:211], v[122:125]
	v_mfma_f32_16x16x32_bf16 v[110:113], v[176:179], v[216:219], v[110:113]
	v_mfma_f32_16x16x32_bf16 v[106:109], v[184:187], v[216:219], v[106:109]
	v_mfma_f32_16x16x32_bf16 v[94:97], v[176:179], v[224:227], v[94:97]
	v_mfma_f32_16x16x32_bf16 v[90:93], v[184:187], v[224:227], v[90:93]
	v_mfma_f32_16x16x32_bf16 v[78:81], v[176:179], v[232:235], v[78:81]
	v_mfma_f32_16x16x32_bf16 v[74:77], v[184:187], v[232:235], v[74:77]
	v_mfma_f32_16x16x32_bf16 v[118:121], v[188:191], v[204:207], v[118:121]
	v_mfma_f32_16x16x32_bf16 v[114:117], v[196:199], v[204:207], v[114:117]
	v_mfma_f32_16x16x32_bf16 v[102:105], v[188:191], v[212:215], v[102:105]
	v_mfma_f32_16x16x32_bf16 v[98:101], v[196:199], v[212:215], v[98:101]
	v_mfma_f32_16x16x32_bf16 v[86:89], v[188:191], v[220:223], v[86:89]
	v_mfma_f32_16x16x32_bf16 v[82:85], v[196:199], v[220:223], v[82:85]
	v_mfma_f32_16x16x32_bf16 v[70:73], v[188:191], v[228:231], v[70:73]
	v_mfma_f32_16x16x32_bf16 v[66:69], v[196:199], v[228:231], v[66:69]
	v_mfma_f32_16x16x32_bf16 v[118:121], v[192:195], v[208:211], v[118:121]
	v_mfma_f32_16x16x32_bf16 v[114:117], v[200:203], v[208:211], v[114:117]
	v_mfma_f32_16x16x32_bf16 v[102:105], v[192:195], v[216:219], v[102:105]
	v_mfma_f32_16x16x32_bf16 v[98:101], v[200:203], v[216:219], v[98:101]
	v_mfma_f32_16x16x32_bf16 v[86:89], v[192:195], v[224:227], v[86:89]
	v_mfma_f32_16x16x32_bf16 v[82:85], v[200:203], v[224:227], v[82:85]
	v_mfma_f32_16x16x32_bf16 v[70:73], v[192:195], v[232:235], v[70:73]
	v_mfma_f32_16x16x32_bf16 v[66:69], v[200:203], v[232:235], v[66:69]
	s_barrier
	s_add_u32 s36, s34, 0x8000
	s_addc_u32 s37, s35, 0
	s_add_i32 s67, s60, s42
	s_mov_b32 m0, s67
	ds_read_b128 v[204:207], v171 offset:49152
	ds_read_b128 v[208:211], v171 offset:50176
	ds_read_b128 v[212:215], v171 offset:51200
	ds_read_b128 v[216:219], v171 offset:52224
	ds_read_b128 v[220:223], v171 offset:53248
	ds_read_b128 v[224:227], v171 offset:54272
	ds_read_b128 v[228:231], v171 offset:55296
	ds_read_b128 v[232:235], v171 offset:56320
	global_load_lds_dwordx4 v134, s[36:37]
	s_add_i32 m0, s67, 0x2000
	s_add_u32 s34, s34, 0xc000
	v_lshl_add_u64 v[236:237], s[36:37], 0, v[130:131]
	s_addc_u32 s35, s35, 0
	s_add_i32 s36, s61, s42
	global_load_lds_dwordx4 v[236:237], off
	s_mov_b32 m0, s36
	s_nop 0
	global_load_lds_dwordx4 v134, s[34:35]
	s_add_i32 m0, s36, 0x2000
	s_nop 0
	global_load_lds_dwordx4 v130, s[34:35]
	s_mov_b32 m0, s48
	s_nop 0
	global_load_lds_dwordx4 v136, s[30:31]
	s_mov_b32 m0, s49
	s_nop 0
	global_load_lds_dwordx4 v132, s[30:31]
	s_waitcnt vmcnt(8) lgkmcnt(0)
	s_barrier
	v_mfma_f32_16x16x32_bf16 v[62:65], v[172:175], v[204:207], v[62:65]
	v_mfma_f32_16x16x32_bf16 v[58:61], v[180:183], v[204:207], v[58:61]
	v_mfma_f32_16x16x32_bf16 v[46:49], v[172:175], v[212:215], v[46:49]
	v_mfma_f32_16x16x32_bf16 v[42:45], v[180:183], v[212:215], v[42:45]
	v_mfma_f32_16x16x32_bf16 v[30:33], v[172:175], v[220:223], v[30:33]
	v_mfma_f32_16x16x32_bf16 v[26:29], v[180:183], v[220:223], v[26:29]
	v_mfma_f32_16x16x32_bf16 v[14:17], v[172:175], v[228:231], v[14:17]
	v_mfma_f32_16x16x32_bf16 v[10:13], v[180:183], v[228:231], v[10:13]
	v_mfma_f32_16x16x32_bf16 v[62:65], v[176:179], v[208:211], v[62:65]
	v_mfma_f32_16x16x32_bf16 v[58:61], v[184:187], v[208:211], v[58:61]
	v_mfma_f32_16x16x32_bf16 v[46:49], v[176:179], v[216:219], v[46:49]
	v_mfma_f32_16x16x32_bf16 v[42:45], v[184:187], v[216:219], v[42:45]
	v_mfma_f32_16x16x32_bf16 v[30:33], v[176:179], v[224:227], v[30:33]
	v_mfma_f32_16x16x32_bf16 v[26:29], v[184:187], v[224:227], v[26:29]
	v_mfma_f32_16x16x32_bf16 v[14:17], v[176:179], v[232:235], v[14:17]
	v_mfma_f32_16x16x32_bf16 v[10:13], v[184:187], v[232:235], v[10:13]
	v_mfma_f32_16x16x32_bf16 v[54:57], v[188:191], v[204:207], v[54:57]
	v_mfma_f32_16x16x32_bf16 v[50:53], v[196:199], v[204:207], v[50:53]
	v_mfma_f32_16x16x32_bf16 v[38:41], v[188:191], v[212:215], v[38:41]
	v_mfma_f32_16x16x32_bf16 v[34:37], v[196:199], v[212:215], v[34:37]
	v_mfma_f32_16x16x32_bf16 v[22:25], v[188:191], v[220:223], v[22:25]
	v_mfma_f32_16x16x32_bf16 v[18:21], v[196:199], v[220:223], v[18:21]
	v_mfma_f32_16x16x32_bf16 v[6:9], v[188:191], v[228:231], v[6:9]
	v_mfma_f32_16x16x32_bf16 v[2:5], v[196:199], v[228:231], v[2:5]
	v_mfma_f32_16x16x32_bf16 v[54:57], v[192:195], v[208:211], v[54:57]
	v_mfma_f32_16x16x32_bf16 v[50:53], v[200:203], v[208:211], v[50:53]
	v_mfma_f32_16x16x32_bf16 v[38:41], v[192:195], v[216:219], v[38:41]
	v_mfma_f32_16x16x32_bf16 v[34:37], v[200:203], v[216:219], v[34:37]
	v_mfma_f32_16x16x32_bf16 v[22:25], v[192:195], v[224:227], v[22:25]
	v_mfma_f32_16x16x32_bf16 v[18:21], v[200:203], v[224:227], v[18:21]
	v_mfma_f32_16x16x32_bf16 v[6:9], v[192:195], v[232:235], v[6:9]
	v_mfma_f32_16x16x32_bf16 v[2:5], v[200:203], v[232:235], v[2:5]
	s_barrier
; __device__ __forceinline__ unsigned pk2(float lo, float hi) { const f32x2 v = {lo, hi}; return __builtin_bit_cast(unsigned, __builtin_convertvector(v, bf16x2_t)); }
; __device__ __forceinline__ u32x4 ror8(u32x4 v) { u32x4 r;
; #pragma unroll
;     for (int i = 0; i < 4; ++i) r[i] = (unsigned)__builtin_amdgcn_mov_dpp((int)v[i], 0x128, 0xf, 0xf, true);
;     return r; }
; __device__ __forceinline__ void store_pair(unsigned char* own, size_t stride8, int hi_off, u32x4 lo, u32x4 hi, bool upper) {
;     const u32x4 tlo = ror8(lo), thi = ror8(hi);
;     const u32x4 A = upper ? thi : lo, B = upper ? hi : tlo;
;     unsigned char* pa = upper ? own - stride8 + hi_off : own;
;     unsigned char* pb = upper ? own + hi_off : own + stride8;
;     *(u32x4*)pa = A; *(u32x4*)pb = B;
;     __device__ __forceinline__ void operator()(const f32x4 (&acc)[2][2][4][2], const Unit& u, int wr, int wc, int fr, int fq) const {
; #pragma unroll
;         for (int ai = 0; ai < 2; ++ai)
; #pragma unroll
;             for (int m = 0; m < 4; ++m) { unsigned char* rowp = (unsigned char*)(H + ((size_t)(u.pm * (FF / 64) + u.pn * 4 + wc) * 256 + (wr * 64 + fr + ai * 128 + m * 16)) * 64 + 8 * fq); u32x4 w[2];
; #pragma unroll
;                 for (int bj = 0; bj < 2; ++bj) { f32x4 v0 = acc[ai][bj][m][0], v1 = acc[ai][bj][m][1];
; #pragma unroll
;                     for (int j = 0; j < 4; ++j) { const float a = fmaxf(v0[j], 0.f), b = fmaxf(v1[j], 0.f); v0[j] = a * a; v1[j] = b * b; }
;                     w[bj].x = pk2(v0[0], v0[1]); w[bj].y = pk2(v0[2], v0[3]); w[bj].z = pk2(v1[0], v1[1]); w[bj].w = pk2(v1[2], v1[3]); }
;                 store_pair(rowp, (size_t)8 * 64 * 2, 64, w[0], w[1], fr >= 8); }
;     }
	s_add_i32 s66, s66, 2
	s_add_u32 s28, s28, 0x100
	s_addc_u32 s29, s29, 0
	s_add_u32 s64, s64, 0x10000
	s_addc_u32 s65, s65, 0
	s_cmp_gt_u32 s66, 29
	s_cbranch_scc0 .LBB0_1164
	s_lshl_b32 s4, s22, 7
	s_lshl_b32 s5, s24, 2
	s_add_i32 s5, s5, s4
	s_or_b32 s4, s5, s47
	s_ashr_i32 s5, s4, 31
	s_lshl_b64 s[4:5], s[4:5], 15
	s_add_u32 s22, s1, s4
	v_max_f32_e32 v126, 0, v126
	v_max_f32_e32 v122, 0, v122
	v_max_f32_e32 v127, 0, v127
	v_max_f32_e32 v123, 0, v123
	v_max_f32_e32 v128, 0, v128
	v_max_f32_e32 v124, 0, v124
	v_max_f32_e32 v129, 0, v129
	v_max_f32_e32 v125, 0, v125
	v_max_f32_e32 v118, 0, v118
	v_max_f32_e32 v114, 0, v114
	v_max_f32_e32 v119, 0, v119
	v_max_f32_e32 v115, 0, v115
	v_max_f32_e32 v120, 0, v120
	v_max_f32_e32 v116, 0, v116
	v_max_f32_e32 v121, 0, v121
	v_max_f32_e32 v117, 0, v117
	s_addc_u32 s23, s33, s5
	v_pk_mul_f32 v[126:127], v[126:127], v[126:127]
	v_pk_mul_f32 v[122:123], v[122:123], v[122:123]
	v_pk_mul_f32 v[128:129], v[128:129], v[128:129]
	v_pk_mul_f32 v[124:125], v[124:125], v[124:125]
	v_pk_mul_f32 v[118:119], v[118:119], v[118:119]
	v_pk_mul_f32 v[114:115], v[114:115], v[114:115]
	v_pk_mul_f32 v[120:121], v[120:121], v[120:121]
	v_pk_mul_f32 v[116:117], v[116:117], v[116:117]
	v_lshl_add_u64 v[164:165], s[22:23], 0, v[144:145]
	v_cvt_pk_bf16_f32 v126, v126, v127
	v_cvt_pk_bf16_f32 v127, v128, v129
	v_cvt_pk_bf16_f32 v128, v122, v123
	v_cvt_pk_bf16_f32 v129, v124, v125
	v_cvt_pk_bf16_f32 v118, v118, v119
	v_cvt_pk_bf16_f32 v119, v120, v121
	v_cvt_pk_bf16_f32 v114, v114, v115
	v_cvt_pk_bf16_f32 v115, v116, v117
	v_lshl_add_u64 v[122:123], v[164:165], 0, v[138:139]
	s_mov_b64 vcc, s[8:9]
	v_mov_b32_dpp v164, v118 row_ror:8 row_mask:0xf bank_mask:0xf bound_ctrl:1
	v_mov_b32_dpp v165, v119 row_ror:8 row_mask:0xf bank_mask:0xf bound_ctrl:1
	v_mov_b32_dpp v166, v114 row_ror:8 row_mask:0xf bank_mask:0xf bound_ctrl:1
	v_mov_b32_dpp v167, v115 row_ror:8 row_mask:0xf bank_mask:0xf bound_ctrl:1
	v_max_f32_e32 v110, 0, v110
	v_max_f32_e32 v106, 0, v106
	v_max_f32_e32 v111, 0, v111
	v_max_f32_e32 v107, 0, v107
	v_max_f32_e32 v112, 0, v112
	v_max_f32_e32 v108, 0, v108
	v_max_f32_e32 v113, 0, v113
	v_max_f32_e32 v109, 0, v109
	v_max_f32_e32 v102, 0, v102
	v_max_f32_e32 v98, 0, v98
	v_max_f32_e32 v103, 0, v103
	v_max_f32_e32 v99, 0, v99
	v_max_f32_e32 v104, 0, v104
	v_max_f32_e32 v100, 0, v100
	v_max_f32_e32 v105, 0, v105
	v_max_f32_e32 v101, 0, v101
	v_lshl_add_u64 v[124:125], v[122:123], 0, v[140:141]
	v_cndmask_b32_dpp v117, v129, v115, vcc row_ror:8 row_mask:0xf bank_mask:0xf bound_ctrl:1
	v_cndmask_b32_dpp v116, v128, v114, vcc row_ror:8 row_mask:0xf bank_mask:0xf bound_ctrl:1
	v_cndmask_b32_dpp v115, v127, v119, vcc row_ror:8 row_mask:0xf bank_mask:0xf bound_ctrl:1
	v_cndmask_b32_dpp v114, v126, v118, vcc row_ror:8 row_mask:0xf bank_mask:0xf bound_ctrl:1
	v_cndmask_b32_e64 v121, v129, v167, s[8:9]
	v_cndmask_b32_e64 v120, v128, v166, s[8:9]
	v_cndmask_b32_e64 v119, v127, v165, s[8:9]
	v_cndmask_b32_e64 v118, v126, v164, s[8:9]
	v_pk_mul_f32 v[110:111], v[110:111], v[110:111]
	v_pk_mul_f32 v[106:107], v[106:107], v[106:107]
	v_pk_mul_f32 v[112:113], v[112:113], v[112:113]
	v_pk_mul_f32 v[108:109], v[108:109], v[108:109]
	v_pk_mul_f32 v[102:103], v[102:103], v[102:103]
	v_pk_mul_f32 v[98:99], v[98:99], v[98:99]
	v_pk_mul_f32 v[104:105], v[104:105], v[104:105]
	v_pk_mul_f32 v[100:101], v[100:101], v[100:101]
	v_lshl_add_u64 v[122:123], v[122:123], 0, v[142:143]
	s_and_b64 vcc, exec, s[6:7]
	s_cbranch_vccz .LBB0_1167
	s_barrier
.LBB0_1167:
	global_store_dwordx4 v[124:125], v[118:121], off
	global_store_dwordx4 v[122:123], v[114:117], off
	v_cvt_pk_bf16_f32 v110, v110, v111
	v_cvt_pk_bf16_f32 v111, v112, v113
	v_lshl_add_u64 v[114:115], s[22:23], 0, v[146:147]
	v_cvt_pk_bf16_f32 v112, v106, v107
	v_cvt_pk_bf16_f32 v113, v108, v109
	v_cvt_pk_bf16_f32 v102, v102, v103
	v_cvt_pk_bf16_f32 v103, v104, v105
	v_cvt_pk_bf16_f32 v98, v98, v99
	v_cvt_pk_bf16_f32 v99, v100, v101
	v_lshl_add_u64 v[106:107], v[114:115], 0, v[138:139]
	s_mov_b64 vcc, s[8:9]
	v_mov_b32_dpp v114, v102 row_ror:8 row_mask:0xf bank_mask:0xf bound_ctrl:1
	v_mov_b32_dpp v115, v103 row_ror:8 row_mask:0xf bank_mask:0xf bound_ctrl:1
	v_mov_b32_dpp v116, v98 row_ror:8 row_mask:0xf bank_mask:0xf bound_ctrl:1
	v_mov_b32_dpp v117, v99 row_ror:8 row_mask:0xf bank_mask:0xf bound_ctrl:1
	v_max_f32_e32 v94, 0, v94
	v_max_f32_e32 v90, 0, v90
	v_max_f32_e32 v95, 0, v95
	v_max_f32_e32 v91, 0, v91
	v_max_f32_e32 v96, 0, v96
	v_max_f32_e32 v92, 0, v92
	v_max_f32_e32 v97, 0, v97
	v_max_f32_e32 v93, 0, v93
	v_max_f32_e32 v86, 0, v86
	v_max_f32_e32 v82, 0, v82
	v_max_f32_e32 v87, 0, v87
	v_max_f32_e32 v83, 0, v83
	v_max_f32_e32 v88, 0, v88
	v_max_f32_e32 v84, 0, v84
	v_max_f32_e32 v89, 0, v89
	v_max_f32_e32 v85, 0, v85
	v_lshl_add_u64 v[108:109], v[106:107], 0, v[140:141]
	v_cndmask_b32_dpp v101, v113, v99, vcc row_ror:8 row_mask:0xf bank_mask:0xf bound_ctrl:1
	v_cndmask_b32_dpp v100, v112, v98, vcc row_ror:8 row_mask:0xf bank_mask:0xf bound_ctrl:1
	v_cndmask_b32_dpp v99, v111, v103, vcc row_ror:8 row_mask:0xf bank_mask:0xf bound_ctrl:1
	v_cndmask_b32_dpp v98, v110, v102, vcc row_ror:8 row_mask:0xf bank_mask:0xf bound_ctrl:1
	v_cndmask_b32_e64 v105, v113, v117, s[8:9]
	v_cndmask_b32_e64 v104, v112, v116, s[8:9]
	v_cndmask_b32_e64 v103, v111, v115, s[8:9]
	v_cndmask_b32_e64 v102, v110, v114, s[8:9]
	v_pk_mul_f32 v[94:95], v[94:95], v[94:95]
	v_pk_mul_f32 v[90:91], v[90:91], v[90:91]
	v_pk_mul_f32 v[96:97], v[96:97], v[96:97]
	v_pk_mul_f32 v[92:93], v[92:93], v[92:93]
	v_pk_mul_f32 v[86:87], v[86:87], v[86:87]
	v_pk_mul_f32 v[82:83], v[82:83], v[82:83]
	v_pk_mul_f32 v[88:89], v[88:89], v[88:89]
; __device__ __forceinline__ unsigned pk2(float lo, float hi) { const f32x2 v = {lo, hi}; return __builtin_bit_cast(unsigned, __builtin_convertvector(v, bf16x2_t)); }
; __device__ __forceinline__ u32x4 ror8(u32x4 v) { u32x4 r;
; #pragma unroll
;     for (int i = 0; i < 4; ++i) r[i] = (unsigned)__builtin_amdgcn_mov_dpp((int)v[i], 0x128, 0xf, 0xf, true);
;     return r; }
; __device__ __forceinline__ void store_pair(unsigned char* own, size_t stride8, int hi_off, u32x4 lo, u32x4 hi, bool upper) {
;     const u32x4 tlo = ror8(lo), thi = ror8(hi);
;     const u32x4 A = upper ? thi : lo, B = upper ? hi : tlo;
;     unsigned char* pa = upper ? own - stride8 + hi_off : own;
;     unsigned char* pb = upper ? own + hi_off : own + stride8;
;     *(u32x4*)pa = A; *(u32x4*)pb = B;
;     __device__ __forceinline__ void operator()(const f32x4 (&acc)[2][2][4][2], const Unit& u, int wr, int wc, int fr, int fq) const {
; #pragma unroll
;         for (int ai = 0; ai < 2; ++ai)
; #pragma unroll
;             for (int m = 0; m < 4; ++m) { unsigned char* rowp = (unsigned char*)(H + ((size_t)(u.pm * (FF / 64) + u.pn * 4 + wc) * 256 + (wr * 64 + fr + ai * 128 + m * 16)) * 64 + 8 * fq); u32x4 w[2];
; #pragma unroll
;                 for (int bj = 0; bj < 2; ++bj) { f32x4 v0 = acc[ai][bj][m][0], v1 = acc[ai][bj][m][1];
; #pragma unroll
;                     for (int j = 0; j < 4; ++j) { const float a = fmaxf(v0[j], 0.f), b = fmaxf(v1[j], 0.f); v0[j] = a * a; v1[j] = b * b; }
;                     w[bj].x = pk2(v0[0], v0[1]); w[bj].y = pk2(v0[2], v0[3]); w[bj].z = pk2(v1[0], v1[1]); w[bj].w = pk2(v1[2], v1[3]); }
;                 store_pair(rowp, (size_t)8 * 64 * 2, 64, w[0], w[1], fr >= 8); }
;     }
	v_pk_mul_f32 v[84:85], v[84:85], v[84:85]
	v_lshl_add_u64 v[106:107], v[106:107], 0, v[142:143]
	global_store_dwordx4 v[108:109], v[102:105], off
	global_store_dwordx4 v[106:107], v[98:101], off
	v_cvt_pk_bf16_f32 v94, v94, v95
	v_cvt_pk_bf16_f32 v95, v96, v97
	v_lshl_add_u64 v[98:99], s[22:23], 0, v[148:149]
	v_cvt_pk_bf16_f32 v96, v90, v91
	v_cvt_pk_bf16_f32 v97, v92, v93
	v_cvt_pk_bf16_f32 v86, v86, v87
	v_cvt_pk_bf16_f32 v87, v88, v89
	v_cvt_pk_bf16_f32 v82, v82, v83
	v_cvt_pk_bf16_f32 v83, v84, v85
	v_lshl_add_u64 v[90:91], v[98:99], 0, v[138:139]
	s_mov_b64 vcc, s[8:9]
	v_mov_b32_dpp v98, v86 row_ror:8 row_mask:0xf bank_mask:0xf bound_ctrl:1
	v_mov_b32_dpp v99, v87 row_ror:8 row_mask:0xf bank_mask:0xf bound_ctrl:1
	v_mov_b32_dpp v100, v82 row_ror:8 row_mask:0xf bank_mask:0xf bound_ctrl:1
	v_mov_b32_dpp v101, v83 row_ror:8 row_mask:0xf bank_mask:0xf bound_ctrl:1
	v_max_f32_e32 v78, 0, v78
	v_max_f32_e32 v74, 0, v74
	v_max_f32_e32 v79, 0, v79
	v_max_f32_e32 v75, 0, v75
	v_max_f32_e32 v80, 0, v80
	v_max_f32_e32 v76, 0, v76
	v_max_f32_e32 v81, 0, v81
	v_max_f32_e32 v77, 0, v77
	v_max_f32_e32 v70, 0, v70
	v_max_f32_e32 v66, 0, v66
	v_max_f32_e32 v71, 0, v71
	v_max_f32_e32 v67, 0, v67
	v_max_f32_e32 v72, 0, v72
	v_max_f32_e32 v68, 0, v68
	v_max_f32_e32 v73, 0, v73
	v_max_f32_e32 v69, 0, v69
	v_lshl_add_u64 v[92:93], v[90:91], 0, v[140:141]
	v_cndmask_b32_dpp v85, v97, v83, vcc row_ror:8 row_mask:0xf bank_mask:0xf bound_ctrl:1
	v_cndmask_b32_dpp v84, v96, v82, vcc row_ror:8 row_mask:0xf bank_mask:0xf bound_ctrl:1
	v_cndmask_b32_dpp v83, v95, v87, vcc row_ror:8 row_mask:0xf bank_mask:0xf bound_ctrl:1
	v_cndmask_b32_dpp v82, v94, v86, vcc row_ror:8 row_mask:0xf bank_mask:0xf bound_ctrl:1
	v_cndmask_b32_e64 v89, v97, v101, s[8:9]
	v_cndmask_b32_e64 v88, v96, v100, s[8:9]
	v_cndmask_b32_e64 v87, v95, v99, s[8:9]
	v_cndmask_b32_e64 v86, v94, v98, s[8:9]
	v_pk_mul_f32 v[78:79], v[78:79], v[78:79]
	v_pk_mul_f32 v[74:75], v[74:75], v[74:75]
	v_pk_mul_f32 v[80:81], v[80:81], v[80:81]
	v_pk_mul_f32 v[76:77], v[76:77], v[76:77]
	v_pk_mul_f32 v[70:71], v[70:71], v[70:71]
	v_pk_mul_f32 v[66:67], v[66:67], v[66:67]
	v_pk_mul_f32 v[72:73], v[72:73], v[72:73]
	v_pk_mul_f32 v[68:69], v[68:69], v[68:69]
	v_lshl_add_u64 v[90:91], v[90:91], 0, v[142:143]
	global_store_dwordx4 v[92:93], v[86:89], off
	global_store_dwordx4 v[90:91], v[82:85], off
	v_cvt_pk_bf16_f32 v78, v78, v79
	v_cvt_pk_bf16_f32 v79, v80, v81
	v_lshl_add_u64 v[82:83], s[22:23], 0, v[150:151]
	v_cvt_pk_bf16_f32 v80, v74, v75
	v_cvt_pk_bf16_f32 v81, v76, v77
	v_cvt_pk_bf16_f32 v70, v70, v71
	v_cvt_pk_bf16_f32 v71, v72, v73
	v_cvt_pk_bf16_f32 v66, v66, v67
	v_cvt_pk_bf16_f32 v67, v68, v69
	v_lshl_add_u64 v[74:75], v[82:83], 0, v[138:139]
	s_mov_b64 vcc, s[8:9]
	v_mov_b32_dpp v82, v70 row_ror:8 row_mask:0xf bank_mask:0xf bound_ctrl:1
	v_mov_b32_dpp v83, v71 row_ror:8 row_mask:0xf bank_mask:0xf bound_ctrl:1
	v_mov_b32_dpp v84, v66 row_ror:8 row_mask:0xf bank_mask:0xf bound_ctrl:1
	v_mov_b32_dpp v85, v67 row_ror:8 row_mask:0xf bank_mask:0xf bound_ctrl:1
	v_max_f32_e32 v62, 0, v62
	v_max_f32_e32 v58, 0, v58
	v_max_f32_e32 v63, 0, v63
	v_max_f32_e32 v59, 0, v59
	v_max_f32_e32 v64, 0, v64
	v_max_f32_e32 v60, 0, v60
	v_max_f32_e32 v65, 0, v65
	v_max_f32_e32 v61, 0, v61
	v_max_f32_e32 v54, 0, v54
	v_max_f32_e32 v50, 0, v50
	v_max_f32_e32 v55, 0, v55
	v_max_f32_e32 v51, 0, v51
	v_max_f32_e32 v56, 0, v56
	v_max_f32_e32 v52, 0, v52
	v_max_f32_e32 v57, 0, v57
	v_max_f32_e32 v53, 0, v53
	v_lshl_add_u64 v[76:77], v[74:75], 0, v[140:141]
	v_cndmask_b32_dpp v69, v81, v67, vcc row_ror:8 row_mask:0xf bank_mask:0xf bound_ctrl:1
	v_cndmask_b32_dpp v68, v80, v66, vcc row_ror:8 row_mask:0xf bank_mask:0xf bound_ctrl:1
	v_cndmask_b32_dpp v67, v79, v71, vcc row_ror:8 row_mask:0xf bank_mask:0xf bound_ctrl:1
	v_cndmask_b32_dpp v66, v78, v70, vcc row_ror:8 row_mask:0xf bank_mask:0xf bound_ctrl:1
	v_cndmask_b32_e64 v73, v81, v85, s[8:9]
	v_cndmask_b32_e64 v72, v80, v84, s[8:9]
	v_cndmask_b32_e64 v71, v79, v83, s[8:9]
	v_cndmask_b32_e64 v70, v78, v82, s[8:9]
	v_pk_mul_f32 v[62:63], v[62:63], v[62:63]
	v_pk_mul_f32 v[58:59], v[58:59], v[58:59]
	v_pk_mul_f32 v[64:65], v[64:65], v[64:65]
	v_pk_mul_f32 v[60:61], v[60:61], v[60:61]
	v_pk_mul_f32 v[54:55], v[54:55], v[54:55]
	v_pk_mul_f32 v[50:51], v[50:51], v[50:51]
	v_pk_mul_f32 v[56:57], v[56:57], v[56:57]
	v_pk_mul_f32 v[52:53], v[52:53], v[52:53]
	v_lshl_add_u64 v[74:75], v[74:75], 0, v[142:143]
	global_store_dwordx4 v[76:77], v[70:73], off
	global_store_dwordx4 v[74:75], v[66:69], off
	v_cvt_pk_bf16_f32 v62, v62, v63
	v_cvt_pk_bf16_f32 v63, v64, v65
	v_lshl_add_u64 v[66:67], s[22:23], 0, v[152:153]
	v_cvt_pk_bf16_f32 v64, v58, v59
	v_cvt_pk_bf16_f32 v65, v60, v61
	v_cvt_pk_bf16_f32 v54, v54, v55
	v_cvt_pk_bf16_f32 v55, v56, v57
	v_cvt_pk_bf16_f32 v50, v50, v51
	v_cvt_pk_bf16_f32 v51, v52, v53
	v_lshl_add_u64 v[58:59], v[66:67], 0, v[138:139]
	s_mov_b64 vcc, s[8:9]
	v_mov_b32_dpp v66, v54 row_ror:8 row_mask:0xf bank_mask:0xf bound_ctrl:1
	v_mov_b32_dpp v67, v55 row_ror:8 row_mask:0xf bank_mask:0xf bound_ctrl:1
	v_mov_b32_dpp v68, v50 row_ror:8 row_mask:0xf bank_mask:0xf bound_ctrl:1
	v_mov_b32_dpp v69, v51 row_ror:8 row_mask:0xf bank_mask:0xf bound_ctrl:1
	v_max_f32_e32 v46, 0, v46
	v_max_f32_e32 v42, 0, v42
	v_max_f32_e32 v47, 0, v47
	v_max_f32_e32 v43, 0, v43
	v_max_f32_e32 v48, 0, v48
	v_max_f32_e32 v44, 0, v44
	v_max_f32_e32 v49, 0, v49
	v_max_f32_e32 v45, 0, v45
	v_max_f32_e32 v38, 0, v38
	v_max_f32_e32 v34, 0, v34
	v_max_f32_e32 v39, 0, v39
	v_max_f32_e32 v35, 0, v35
	v_max_f32_e32 v40, 0, v40
	v_max_f32_e32 v36, 0, v36
	v_max_f32_e32 v41, 0, v41
	v_max_f32_e32 v37, 0, v37
; __device__ __forceinline__ unsigned pk2(float lo, float hi) { const f32x2 v = {lo, hi}; return __builtin_bit_cast(unsigned, __builtin_convertvector(v, bf16x2_t)); }
; #define PG8_BAR __builtin_amdgcn_s_barrier()
; template <class Epi, class Sched, bool ABLK = false, bool ALIGN_EPI = true, bool SP2 = true, bool BBLK = true>
; __device__ __forceinline__ void gemm_phase(LAS unsigned char* lds, const Gemm g, const Sched& S, const Epi& E) {
;     ...
;         if (!has_next) break;
; #pragma unroll
;         for (int a = 0; a < 2; ++a)
; #pragma unroll
;             for (int b = 0; b < 2; ++b)
; #pragma unroll
;                 for (int m = 0; m < 4; ++m)
; #pragma unroll
;                     for (int n = 0; n < 2; ++n) acc[a][b][m][n] = (f32x4){0.f, 0.f, 0.f, 0.f};
;         cur = nxt; uA = nuA; tbA = ntbA; cB = nB; ++ui;
;         if constexpr (ALIGN_EPI) { if (wr == 1) PG8_BAR; }
;     __device__ __forceinline__ void operator()(const f32x4 (&acc)[2][2][4][2], const Unit& u, int wr, int wc, int fr, int fq) const {
; #pragma unroll
;         for (int ai = 0; ai < 2; ++ai)
; #pragma unroll
;             for (int m = 0; m < 4; ++m) { unsigned char* rowp = (unsigned char*)(H + ((size_t)(u.pm * (FF / 64) + u.pn * 4 + wc) * 256 + (wr * 64 + fr + ai * 128 + m * 16)) * 64 + 8 * fq); u32x4 w[2];
; #pragma unroll
;                 for (int bj = 0; bj < 2; ++bj) { f32x4 v0 = acc[ai][bj][m][0], v1 = acc[ai][bj][m][1];
; #pragma unroll
;                     for (int j = 0; j < 4; ++j) { const float a = fmaxf(v0[j], 0.f), b = fmaxf(v1[j], 0.f); v0[j] = a * a; v1[j] = b * b; }
;                     w[bj].x = pk2(v0[0], v0[1]); w[bj].y = pk2(v0[2], v0[3]); w[bj].z = pk2(v1[0], v1[1]); w[bj].w = pk2(v1[2], v1[3]); }
;                 store_pair(rowp, (size_t)8 * 64 * 2, 64, w[0], w[1], fr >= 8); }
;     }
	v_lshl_add_u64 v[60:61], v[58:59], 0, v[140:141]
	v_cndmask_b32_dpp v53, v65, v51, vcc row_ror:8 row_mask:0xf bank_mask:0xf bound_ctrl:1
	v_cndmask_b32_dpp v52, v64, v50, vcc row_ror:8 row_mask:0xf bank_mask:0xf bound_ctrl:1
	v_cndmask_b32_dpp v51, v63, v55, vcc row_ror:8 row_mask:0xf bank_mask:0xf bound_ctrl:1
	v_cndmask_b32_dpp v50, v62, v54, vcc row_ror:8 row_mask:0xf bank_mask:0xf bound_ctrl:1
	v_cndmask_b32_e64 v57, v65, v69, s[8:9]
	v_cndmask_b32_e64 v56, v64, v68, s[8:9]
	v_cndmask_b32_e64 v55, v63, v67, s[8:9]
	v_cndmask_b32_e64 v54, v62, v66, s[8:9]
	v_pk_mul_f32 v[46:47], v[46:47], v[46:47]
	v_pk_mul_f32 v[42:43], v[42:43], v[42:43]
	v_pk_mul_f32 v[48:49], v[48:49], v[48:49]
	v_pk_mul_f32 v[44:45], v[44:45], v[44:45]
	v_pk_mul_f32 v[38:39], v[38:39], v[38:39]
	v_pk_mul_f32 v[34:35], v[34:35], v[34:35]
	v_pk_mul_f32 v[40:41], v[40:41], v[40:41]
	v_pk_mul_f32 v[36:37], v[36:37], v[36:37]
	v_lshl_add_u64 v[58:59], v[58:59], 0, v[142:143]
	global_store_dwordx4 v[60:61], v[54:57], off
	global_store_dwordx4 v[58:59], v[50:53], off
	v_cvt_pk_bf16_f32 v46, v46, v47
	v_cvt_pk_bf16_f32 v47, v48, v49
	v_lshl_add_u64 v[50:51], s[22:23], 0, v[154:155]
	v_cvt_pk_bf16_f32 v48, v42, v43
	v_cvt_pk_bf16_f32 v49, v44, v45
	v_cvt_pk_bf16_f32 v38, v38, v39
	v_cvt_pk_bf16_f32 v39, v40, v41
	v_cvt_pk_bf16_f32 v34, v34, v35
	v_cvt_pk_bf16_f32 v35, v36, v37
	v_lshl_add_u64 v[42:43], v[50:51], 0, v[138:139]
	s_mov_b64 vcc, s[8:9]
	v_mov_b32_dpp v50, v38 row_ror:8 row_mask:0xf bank_mask:0xf bound_ctrl:1
	v_mov_b32_dpp v51, v39 row_ror:8 row_mask:0xf bank_mask:0xf bound_ctrl:1
	v_mov_b32_dpp v52, v34 row_ror:8 row_mask:0xf bank_mask:0xf bound_ctrl:1
	v_mov_b32_dpp v53, v35 row_ror:8 row_mask:0xf bank_mask:0xf bound_ctrl:1
	v_max_f32_e32 v30, 0, v30
	v_max_f32_e32 v26, 0, v26
	v_max_f32_e32 v31, 0, v31
	v_max_f32_e32 v27, 0, v27
	v_max_f32_e32 v32, 0, v32
	v_max_f32_e32 v28, 0, v28
	v_max_f32_e32 v33, 0, v33
	v_max_f32_e32 v29, 0, v29
	v_max_f32_e32 v22, 0, v22
	v_max_f32_e32 v18, 0, v18
	v_max_f32_e32 v23, 0, v23
	v_max_f32_e32 v19, 0, v19
	v_max_f32_e32 v24, 0, v24
	v_max_f32_e32 v20, 0, v20
	v_max_f32_e32 v25, 0, v25
	v_max_f32_e32 v21, 0, v21
	v_lshl_add_u64 v[44:45], v[42:43], 0, v[140:141]
	v_cndmask_b32_dpp v37, v49, v35, vcc row_ror:8 row_mask:0xf bank_mask:0xf bound_ctrl:1
	v_cndmask_b32_dpp v36, v48, v34, vcc row_ror:8 row_mask:0xf bank_mask:0xf bound_ctrl:1
	v_cndmask_b32_dpp v35, v47, v39, vcc row_ror:8 row_mask:0xf bank_mask:0xf bound_ctrl:1
	v_cndmask_b32_dpp v34, v46, v38, vcc row_ror:8 row_mask:0xf bank_mask:0xf bound_ctrl:1
	v_cndmask_b32_e64 v41, v49, v53, s[8:9]
	v_cndmask_b32_e64 v40, v48, v52, s[8:9]
	v_cndmask_b32_e64 v39, v47, v51, s[8:9]
	v_cndmask_b32_e64 v38, v46, v50, s[8:9]
	v_pk_mul_f32 v[30:31], v[30:31], v[30:31]
	v_pk_mul_f32 v[26:27], v[26:27], v[26:27]
	v_pk_mul_f32 v[32:33], v[32:33], v[32:33]
	v_pk_mul_f32 v[28:29], v[28:29], v[28:29]
	v_pk_mul_f32 v[22:23], v[22:23], v[22:23]
	v_pk_mul_f32 v[18:19], v[18:19], v[18:19]
	v_pk_mul_f32 v[24:25], v[24:25], v[24:25]
	v_pk_mul_f32 v[20:21], v[20:21], v[20:21]
	v_lshl_add_u64 v[42:43], v[42:43], 0, v[142:143]
	global_store_dwordx4 v[44:45], v[38:41], off
	global_store_dwordx4 v[42:43], v[34:37], off
	v_cvt_pk_bf16_f32 v30, v30, v31
	v_cvt_pk_bf16_f32 v31, v32, v33
	v_lshl_add_u64 v[34:35], s[22:23], 0, v[156:157]
	v_cvt_pk_bf16_f32 v32, v26, v27
	v_cvt_pk_bf16_f32 v33, v28, v29
	v_cvt_pk_bf16_f32 v22, v22, v23
	v_cvt_pk_bf16_f32 v23, v24, v25
	v_cvt_pk_bf16_f32 v18, v18, v19
	v_cvt_pk_bf16_f32 v19, v20, v21
	v_lshl_add_u64 v[26:27], v[34:35], 0, v[138:139]
	s_mov_b64 vcc, s[8:9]
	v_mov_b32_dpp v34, v22 row_ror:8 row_mask:0xf bank_mask:0xf bound_ctrl:1
	v_mov_b32_dpp v35, v23 row_ror:8 row_mask:0xf bank_mask:0xf bound_ctrl:1
	v_mov_b32_dpp v36, v18 row_ror:8 row_mask:0xf bank_mask:0xf bound_ctrl:1
	v_mov_b32_dpp v37, v19 row_ror:8 row_mask:0xf bank_mask:0xf bound_ctrl:1
	v_max_f32_e32 v14, 0, v14
	v_max_f32_e32 v10, 0, v10
	v_max_f32_e32 v15, 0, v15
	v_max_f32_e32 v11, 0, v11
	v_max_f32_e32 v16, 0, v16
	v_max_f32_e32 v12, 0, v12
	v_max_f32_e32 v17, 0, v17
	v_max_f32_e32 v13, 0, v13
	v_max_f32_e32 v6, 0, v6
	v_max_f32_e32 v2, 0, v2
	v_max_f32_e32 v7, 0, v7
	v_max_f32_e32 v3, 0, v3
	v_max_f32_e32 v8, 0, v8
	v_max_f32_e32 v4, 0, v4
	v_max_f32_e32 v9, 0, v9
	v_max_f32_e32 v5, 0, v5
	v_lshl_add_u64 v[28:29], v[26:27], 0, v[140:141]
	v_cndmask_b32_dpp v21, v33, v19, vcc row_ror:8 row_mask:0xf bank_mask:0xf bound_ctrl:1
	v_cndmask_b32_dpp v20, v32, v18, vcc row_ror:8 row_mask:0xf bank_mask:0xf bound_ctrl:1
	v_cndmask_b32_dpp v19, v31, v23, vcc row_ror:8 row_mask:0xf bank_mask:0xf bound_ctrl:1
	v_cndmask_b32_dpp v18, v30, v22, vcc row_ror:8 row_mask:0xf bank_mask:0xf bound_ctrl:1
	v_cndmask_b32_e64 v25, v33, v37, s[8:9]
	v_cndmask_b32_e64 v24, v32, v36, s[8:9]
	v_cndmask_b32_e64 v23, v31, v35, s[8:9]
	v_cndmask_b32_e64 v22, v30, v34, s[8:9]
	v_pk_mul_f32 v[14:15], v[14:15], v[14:15]
	v_pk_mul_f32 v[10:11], v[10:11], v[10:11]
	v_pk_mul_f32 v[16:17], v[16:17], v[16:17]
	v_pk_mul_f32 v[12:13], v[12:13], v[12:13]
	v_pk_mul_f32 v[6:7], v[6:7], v[6:7]
	v_pk_mul_f32 v[2:3], v[2:3], v[2:3]
	v_pk_mul_f32 v[8:9], v[8:9], v[8:9]
	v_pk_mul_f32 v[4:5], v[4:5], v[4:5]
	v_lshl_add_u64 v[26:27], v[26:27], 0, v[142:143]
	global_store_dwordx4 v[28:29], v[22:25], off
	global_store_dwordx4 v[26:27], v[18:21], off
	v_cvt_pk_bf16_f32 v14, v14, v15
	v_cvt_pk_bf16_f32 v15, v16, v17
	v_lshl_add_u64 v[18:19], s[22:23], 0, v[158:159]
	v_cvt_pk_bf16_f32 v16, v10, v11
	v_cvt_pk_bf16_f32 v17, v12, v13
	v_cvt_pk_bf16_f32 v6, v6, v7
	v_cvt_pk_bf16_f32 v7, v8, v9
	v_cvt_pk_bf16_f32 v2, v2, v3
	v_cvt_pk_bf16_f32 v3, v4, v5
	v_lshl_add_u64 v[10:11], v[18:19], 0, v[138:139]
	s_mov_b64 vcc, s[8:9]
	v_mov_b32_dpp v18, v6 row_ror:8 row_mask:0xf bank_mask:0xf bound_ctrl:1
	v_mov_b32_dpp v19, v7 row_ror:8 row_mask:0xf bank_mask:0xf bound_ctrl:1
	v_mov_b32_dpp v20, v2 row_ror:8 row_mask:0xf bank_mask:0xf bound_ctrl:1
	v_mov_b32_dpp v21, v3 row_ror:8 row_mask:0xf bank_mask:0xf bound_ctrl:1
	v_lshl_add_u64 v[12:13], v[10:11], 0, v[140:141]
	v_cndmask_b32_dpp v5, v17, v3, vcc row_ror:8 row_mask:0xf bank_mask:0xf bound_ctrl:1
	v_cndmask_b32_dpp v4, v16, v2, vcc row_ror:8 row_mask:0xf bank_mask:0xf bound_ctrl:1
	v_cndmask_b32_dpp v3, v15, v7, vcc row_ror:8 row_mask:0xf bank_mask:0xf bound_ctrl:1
	v_cndmask_b32_dpp v2, v14, v6, vcc row_ror:8 row_mask:0xf bank_mask:0xf bound_ctrl:1
	v_cndmask_b32_e64 v9, v17, v21, s[8:9]
	v_cndmask_b32_e64 v8, v16, v20, s[8:9]
	v_cndmask_b32_e64 v7, v15, v19, s[8:9]
	v_cndmask_b32_e64 v6, v14, v18, s[8:9]
	s_andn2_b64 vcc, exec, s[18:19]
	s_mov_b64 s[4:5], -1
	v_lshl_add_u64 v[10:11], v[10:11], 0, v[142:143]
	global_store_dwordx4 v[12:13], v[6:9], off
	global_store_dwordx4 v[10:11], v[2:5], off
	s_cbranch_vccnz .LBB0_1160
	s_andn2_b64 vcc, exec, s[2:3]
	s_cbranch_vccnz .LBB0_1159
	s_barrier
	s_branch .LBB0_1159

; #define PG8_STAGE(bufoff, gbase, voff) do { _Pragma("unroll") for (int _i = 0; _i < 2; ++_i) \
;         __builtin_amdgcn_global_load_lds((const unsigned*)((const char*)(gbase) + (voff)[_i]), (LAS unsigned*)(lds + (bufoff) + ldsw + _i * 8192), 16, 0, 0); } while (0)
; #define PG8_LDA(dst, b, h) do { _Pragma("unroll") for (int m = 0; m < 4; ++m) _Pragma("unroll") for (int k = 0; k < 2; ++k) dst[m][k] = *(const LAS bf16x8*)(lds + PG8_SA(b, h) + aoff + m * 2048 + k * 1024); } while (0)
; #define PG8_LDB(dst, b, h) do { _Pragma("unroll") for (int n = 0; n < 2; ++n) _Pragma("unroll") for (int k = 0; k < 2; ++k) dst[n][k] = *(const LAS bf16x8*)(lds + PG8_SB(b, h) + boff + n * 2048 + k * 1024); } while (0)
; #define PG8_MMA(ai, bj, At, Bt) do { __builtin_amdgcn_s_setprio(1); _Pragma("unroll") for (int m = 0; m < 4; ++m) _Pragma("unroll") for (int n = 0; n < 2; ++n) _Pragma("unroll") for (int k = 0; k < 2; ++k) \
;         acc[ai][bj][m][n] = __builtin_amdgcn_mfma_f32_16x16x32_bf16(Bt[n][k], At[m][k], acc[ai][bj][m][n], 0, 0, 0); __builtin_amdgcn_s_setprio(0); } while (0)
; #define PG8_WAIT_V(n) asm volatile("s_waitcnt vmcnt(" #n ")" ::: "memory")
; #define PG8_WAIT_L(n) asm volatile("s_waitcnt lgkmcnt(" #n ")" ::: "memory")
; template <class Epi, class Sched, bool ABLK = false, bool ALIGN_EPI = true, bool SP2 = true, bool BBLK = true>
; __device__ __forceinline__ void gemm_phase(LAS unsigned char* lds, const Gemm g, const Sched& S, const Epi& E) {
;     ...
;             const char* a1 = a_tile(uA, tbA + t + 1);
;             const char* a2 = last ? a_tile(nuA, ntbA) : a_tile(uA, tbA + t + 2); const char* b2 = last ? nB : cB + (size_t)(t + 2) * kstepB;
;             const char* a3 = last ? a_tile(nuA, ntbA + 1) : a_tile(uA, tbA + t + 3); const char* b3 = b2 + kstepB;
;             if (last && has_next) S.a_ready(nxt);
;             if constexpr (SP2) {
;             PG8_LDB(B0, 0, 0); PG8_LDB(B1, 0, 1); PG8_SCHED; PG8_LDA(At, 0, 0); PG8_STAGE(PG8_SA(1, 1), a1 + hstepA, voffA);
;             PG8_WAIT_V(8); PG8_WAIT_L(0); PG8_BAR; PG8_MMA(0, 0, At, B0); PG8_MMA(0, 1, At, B1); PG8_BAR; PG8_SCHED;
;             PG8_LDA(At, 0, 1); PG8_STAGE(PG8_SB(0, 0), b2, voffB); PG8_STAGE(PG8_SB(0, 1), b2 + hstepB, voffB); PG8_STAGE(PG8_SA(0, 0), a2, voffA);
;             PG8_WAIT_V(8); PG8_WAIT_L(0); PG8_BAR; PG8_MMA(1, 0, At, B0); PG8_MMA(1, 1, At, B1); PG8_BAR; PG8_SCHED;
.Lksel_13_back:
	v_lshl_add_u64 v[216:217], v[142:143], 0, s[22:23]
	s_add_i32 m0, s35, 0xc000
	ds_read_b128 v[184:187], v151
	ds_read_b128 v[188:191], v151 offset:1024
	ds_read_b128 v[192:195], v151 offset:2048
	ds_read_b128 v[196:199], v151 offset:3072
	ds_read_b128 v[200:203], v151 offset:4096
	ds_read_b128 v[204:207], v151 offset:5120
	ds_read_b128 v[208:211], v151 offset:6144
	ds_read_b128 v[212:215], v151 offset:7168
	global_load_lds_dwordx4 v[216:217], off
	v_lshl_add_u64 v[216:217], v[144:145], 0, s[22:23]
	s_add_i32 m0, s35, 0xe000
	s_nop 0
	global_load_lds_dwordx4 v[216:217], off
	s_waitcnt vmcnt(8) lgkmcnt(0)
	s_barrier
	v_mfma_f32_16x16x32_bf16 v[126:129], v[152:155], v[184:187], v[126:129]
	v_mfma_f32_16x16x32_bf16 v[122:125], v[160:163], v[184:187], v[122:125]
	v_mfma_f32_16x16x32_bf16 v[110:113], v[152:155], v[192:195], v[110:113]
	v_mfma_f32_16x16x32_bf16 v[106:109], v[160:163], v[192:195], v[106:109]
	v_mfma_f32_16x16x32_bf16 v[94:97], v[152:155], v[200:203], v[94:97]
	v_mfma_f32_16x16x32_bf16 v[90:93], v[160:163], v[200:203], v[90:93]
	v_mfma_f32_16x16x32_bf16 v[78:81], v[152:155], v[208:211], v[78:81]
	v_mfma_f32_16x16x32_bf16 v[74:77], v[160:163], v[208:211], v[74:77]
	v_mfma_f32_16x16x32_bf16 v[126:129], v[156:159], v[188:191], v[126:129]
	v_mfma_f32_16x16x32_bf16 v[122:125], v[164:167], v[188:191], v[122:125]
	v_mfma_f32_16x16x32_bf16 v[110:113], v[156:159], v[196:199], v[110:113]
	v_mfma_f32_16x16x32_bf16 v[106:109], v[164:167], v[196:199], v[106:109]
	v_mfma_f32_16x16x32_bf16 v[94:97], v[156:159], v[204:207], v[94:97]
	v_mfma_f32_16x16x32_bf16 v[90:93], v[164:167], v[204:207], v[90:93]
	v_mfma_f32_16x16x32_bf16 v[78:81], v[156:159], v[212:215], v[78:81]
	v_mfma_f32_16x16x32_bf16 v[74:77], v[164:167], v[212:215], v[74:77]
	v_mfma_f32_16x16x32_bf16 v[118:121], v[168:171], v[184:187], v[118:121]
	v_mfma_f32_16x16x32_bf16 v[114:117], v[176:179], v[184:187], v[114:117]
	v_mfma_f32_16x16x32_bf16 v[102:105], v[168:171], v[192:195], v[102:105]
	v_mfma_f32_16x16x32_bf16 v[98:101], v[176:179], v[192:195], v[98:101]
	v_mfma_f32_16x16x32_bf16 v[86:89], v[168:171], v[200:203], v[86:89]
	v_mfma_f32_16x16x32_bf16 v[82:85], v[176:179], v[200:203], v[82:85]
	v_mfma_f32_16x16x32_bf16 v[70:73], v[168:171], v[208:211], v[70:73]
	v_mfma_f32_16x16x32_bf16 v[66:69], v[176:179], v[208:211], v[66:69]
	v_mfma_f32_16x16x32_bf16 v[118:121], v[172:175], v[188:191], v[118:121]
	v_mfma_f32_16x16x32_bf16 v[114:117], v[180:183], v[188:191], v[114:117]
	v_mfma_f32_16x16x32_bf16 v[102:105], v[172:175], v[196:199], v[102:105]
	v_mfma_f32_16x16x32_bf16 v[98:101], v[180:183], v[196:199], v[98:101]
	v_mfma_f32_16x16x32_bf16 v[86:89], v[172:175], v[204:207], v[86:89]
	v_mfma_f32_16x16x32_bf16 v[82:85], v[180:183], v[204:207], v[82:85]
	v_mfma_f32_16x16x32_bf16 v[70:73], v[172:175], v[212:215], v[70:73]
	v_mfma_f32_16x16x32_bf16 v[66:69], v[180:183], v[212:215], v[66:69]
	s_barrier
	s_add_i32 s59, s72, s34
	s_mov_b32 m0, s59
	ds_read_b128 v[184:187], v151 offset:16384
	ds_read_b128 v[188:191], v151 offset:17408
	ds_read_b128 v[192:195], v151 offset:18432
	ds_read_b128 v[196:199], v151 offset:19456
	ds_read_b128 v[200:203], v151 offset:20480
	ds_read_b128 v[204:207], v151 offset:21504
	ds_read_b128 v[208:211], v151 offset:22528
	ds_read_b128 v[212:215], v151 offset:23552
	global_load_lds_dwordx4 v130, s[26:27]
	s_add_i32 m0, s59, 0x2000
	s_add_u32 s64, s26, 0x4000
	s_addc_u32 s65, s27, 0
	s_add_i32 s59, s73, s34
	global_load_lds_dwordx4 v132, s[26:27]
	s_mov_b32 m0, s59
	s_nop 0
	global_load_lds_dwordx4 v130, s[64:65]
	s_add_i32 m0, s59, 0x2000
	s_nop 0
	global_load_lds_dwordx4 v132, s[64:65]
	s_mov_b32 m0, s35
	s_nop 0
	global_load_lds_dwordx4 v130, s[28:29]
	s_mov_b32 m0, s36
	s_nop 0
	global_load_lds_dwordx4 v132, s[28:29]
	s_waitcnt vmcnt(8) lgkmcnt(0)
	s_barrier
	v_mfma_f32_16x16x32_bf16 v[62:65], v[152:155], v[184:187], v[62:65]
	v_mfma_f32_16x16x32_bf16 v[58:61], v[160:163], v[184:187], v[58:61]
	v_mfma_f32_16x16x32_bf16 v[46:49], v[152:155], v[192:195], v[46:49]
	v_mfma_f32_16x16x32_bf16 v[42:45], v[160:163], v[192:195], v[42:45]
	v_mfma_f32_16x16x32_bf16 v[30:33], v[152:155], v[200:203], v[30:33]
	v_mfma_f32_16x16x32_bf16 v[26:29], v[160:163], v[200:203], v[26:29]
	v_mfma_f32_16x16x32_bf16 v[14:17], v[152:155], v[208:211], v[14:17]
	v_mfma_f32_16x16x32_bf16 v[10:13], v[160:163], v[208:211], v[10:13]
	v_mfma_f32_16x16x32_bf16 v[62:65], v[156:159], v[188:191], v[62:65]
	v_mfma_f32_16x16x32_bf16 v[58:61], v[164:167], v[188:191], v[58:61]
	v_mfma_f32_16x16x32_bf16 v[46:49], v[156:159], v[196:199], v[46:49]
	v_mfma_f32_16x16x32_bf16 v[42:45], v[164:167], v[196:199], v[42:45]
	v_mfma_f32_16x16x32_bf16 v[30:33], v[156:159], v[204:207], v[30:33]
	v_mfma_f32_16x16x32_bf16 v[26:29], v[164:167], v[204:207], v[26:29]
	v_mfma_f32_16x16x32_bf16 v[14:17], v[156:159], v[212:215], v[14:17]
	v_mfma_f32_16x16x32_bf16 v[10:13], v[164:167], v[212:215], v[10:13]
	v_mfma_f32_16x16x32_bf16 v[54:57], v[168:171], v[184:187], v[54:57]
	v_mfma_f32_16x16x32_bf16 v[50:53], v[176:179], v[184:187], v[50:53]
	v_mfma_f32_16x16x32_bf16 v[38:41], v[168:171], v[192:195], v[38:41]
	v_mfma_f32_16x16x32_bf16 v[34:37], v[176:179], v[192:195], v[34:37]
	v_mfma_f32_16x16x32_bf16 v[22:25], v[168:171], v[200:203], v[22:25]
	v_mfma_f32_16x16x32_bf16 v[18:21], v[176:179], v[200:203], v[18:21]
	v_mfma_f32_16x16x32_bf16 v[6:9], v[168:171], v[208:211], v[6:9]
	v_mfma_f32_16x16x32_bf16 v[2:5], v[176:179], v[208:211], v[2:5]
	v_mfma_f32_16x16x32_bf16 v[54:57], v[172:175], v[188:191], v[54:57]
	v_mfma_f32_16x16x32_bf16 v[50:53], v[180:183], v[188:191], v[50:53]
	v_mfma_f32_16x16x32_bf16 v[38:41], v[172:175], v[196:199], v[38:41]
	v_mfma_f32_16x16x32_bf16 v[34:37], v[180:183], v[196:199], v[34:37]
	v_mfma_f32_16x16x32_bf16 v[22:25], v[172:175], v[204:207], v[22:25]
	v_mfma_f32_16x16x32_bf16 v[18:21], v[180:183], v[204:207], v[18:21]
	v_mfma_f32_16x16x32_bf16 v[6:9], v[172:175], v[212:215], v[6:9]
	v_mfma_f32_16x16x32_bf16 v[2:5], v[180:183], v[212:215], v[2:5]
	s_barrier
; #define PG8_STAGE(bufoff, gbase, voff) do { _Pragma("unroll") for (int _i = 0; _i < 2; ++_i) \
;         __builtin_amdgcn_global_load_lds((const unsigned*)((const char*)(gbase) + (voff)[_i]), (LAS unsigned*)(lds + (bufoff) + ldsw + _i * 8192), 16, 0, 0); } while (0)
; #define PG8_LDA(dst, b, h) do { _Pragma("unroll") for (int m = 0; m < 4; ++m) _Pragma("unroll") for (int k = 0; k < 2; ++k) dst[m][k] = *(const LAS bf16x8*)(lds + PG8_SA(b, h) + aoff + m * 2048 + k * 1024); } while (0)
; #define PG8_LDB(dst, b, h) do { _Pragma("unroll") for (int n = 0; n < 2; ++n) _Pragma("unroll") for (int k = 0; k < 2; ++k) dst[n][k] = *(const LAS bf16x8*)(lds + PG8_SB(b, h) + boff + n * 2048 + k * 1024); } while (0)
; #define PG8_MMA(ai, bj, At, Bt) do { __builtin_amdgcn_s_setprio(1); _Pragma("unroll") for (int m = 0; m < 4; ++m) _Pragma("unroll") for (int n = 0; n < 2; ++n) _Pragma("unroll") for (int k = 0; k < 2; ++k) \
;         acc[ai][bj][m][n] = __builtin_amdgcn_mfma_f32_16x16x32_bf16(Bt[n][k], At[m][k], acc[ai][bj][m][n], 0, 0, 0); __builtin_amdgcn_s_setprio(0); } while (0)
; #define PG8_WAIT_V(n) asm volatile("s_waitcnt vmcnt(" #n ")" ::: "memory")
; #define PG8_WAIT_L(n) asm volatile("s_waitcnt lgkmcnt(" #n ")" ::: "memory")
; #define PG8_BAR __builtin_amdgcn_s_barrier()
; #define PG8_SCHED __builtin_amdgcn_sched_barrier(0)
; template <class Epi, class Sched, bool ABLK = false, bool ALIGN_EPI = true, bool SP2 = true, bool BBLK = true>
; __device__ __forceinline__ void gemm_phase(LAS unsigned char* lds, const Gemm g, const Sched& S, const Epi& E) {
;     ...
;             PG8_LDB(B0, 1, 0); PG8_LDB(B1, 1, 1); PG8_SCHED; PG8_LDA(At, 1, 0); PG8_STAGE(PG8_SA(0, 1), a2 + hstepA, voffA);
;             PG8_WAIT_V(8); PG8_WAIT_L(0); PG8_BAR; PG8_MMA(0, 0, At, B0); PG8_MMA(0, 1, At, B1); PG8_BAR; PG8_SCHED;
;             PG8_LDA(At, 1, 1); PG8_STAGE(PG8_SB(1, 0), b3, voffB); PG8_STAGE(PG8_SB(1, 1), b3 + hstepB, voffB); PG8_STAGE(PG8_SA(1, 0), a3, voffA);
;             PG8_WAIT_V(8); PG8_WAIT_L(0); PG8_BAR; PG8_MMA(1, 0, At, B0); PG8_MMA(1, 1, At, B1); PG8_BAR; PG8_SCHED;
	v_add_u32_e32 v164, s60, v147
	v_add_u32_e32 v180, s61, v147
	ds_read_b128 v[152:155], v164
	ds_read_b128 v[156:159], v164 offset:1024
	ds_read_b128 v[160:163], v164 offset:2048
	ds_read_b128 v[164:167], v164 offset:3072
	ds_read_b128 v[168:171], v180
	ds_read_b128 v[172:175], v180 offset:1024
	ds_read_b128 v[176:179], v180 offset:2048
	ds_read_b128 v[180:183], v180 offset:3072
	s_add_u32 s28, s28, 0x4000
	s_addc_u32 s29, s29, 0
	s_mov_b32 m0, s37
	ds_read_b128 v[184:187], v151 offset:32768
	ds_read_b128 v[188:191], v151 offset:33792
	ds_read_b128 v[192:195], v151 offset:34816
	ds_read_b128 v[196:199], v151 offset:35840
	ds_read_b128 v[200:203], v151 offset:36864
	ds_read_b128 v[204:207], v151 offset:37888
	ds_read_b128 v[208:211], v151 offset:38912
	ds_read_b128 v[212:215], v151 offset:39936
	global_load_lds_dwordx4 v130, s[28:29]
	s_mov_b32 m0, s40
	s_nop 0
	global_load_lds_dwordx4 v132, s[28:29]
	s_waitcnt vmcnt(8) lgkmcnt(0)
	s_barrier
	v_mfma_f32_16x16x32_bf16 v[126:129], v[152:155], v[184:187], v[126:129]
	v_mfma_f32_16x16x32_bf16 v[122:125], v[160:163], v[184:187], v[122:125]
	v_mfma_f32_16x16x32_bf16 v[110:113], v[152:155], v[192:195], v[110:113]
	v_mfma_f32_16x16x32_bf16 v[106:109], v[160:163], v[192:195], v[106:109]
	v_mfma_f32_16x16x32_bf16 v[94:97], v[152:155], v[200:203], v[94:97]
	v_mfma_f32_16x16x32_bf16 v[90:93], v[160:163], v[200:203], v[90:93]
	v_mfma_f32_16x16x32_bf16 v[78:81], v[152:155], v[208:211], v[78:81]
	v_mfma_f32_16x16x32_bf16 v[74:77], v[160:163], v[208:211], v[74:77]
	v_mfma_f32_16x16x32_bf16 v[126:129], v[156:159], v[188:191], v[126:129]
	v_mfma_f32_16x16x32_bf16 v[122:125], v[164:167], v[188:191], v[122:125]
	v_mfma_f32_16x16x32_bf16 v[110:113], v[156:159], v[196:199], v[110:113]
	v_mfma_f32_16x16x32_bf16 v[106:109], v[164:167], v[196:199], v[106:109]
	v_mfma_f32_16x16x32_bf16 v[94:97], v[156:159], v[204:207], v[94:97]
	v_mfma_f32_16x16x32_bf16 v[90:93], v[164:167], v[204:207], v[90:93]
	v_mfma_f32_16x16x32_bf16 v[78:81], v[156:159], v[212:215], v[78:81]
	v_mfma_f32_16x16x32_bf16 v[74:77], v[164:167], v[212:215], v[74:77]
	v_mfma_f32_16x16x32_bf16 v[118:121], v[168:171], v[184:187], v[118:121]
	v_mfma_f32_16x16x32_bf16 v[114:117], v[176:179], v[184:187], v[114:117]
	v_mfma_f32_16x16x32_bf16 v[102:105], v[168:171], v[192:195], v[102:105]
	v_mfma_f32_16x16x32_bf16 v[98:101], v[176:179], v[192:195], v[98:101]
	v_mfma_f32_16x16x32_bf16 v[86:89], v[168:171], v[200:203], v[86:89]
	v_mfma_f32_16x16x32_bf16 v[82:85], v[176:179], v[200:203], v[82:85]
	v_mfma_f32_16x16x32_bf16 v[70:73], v[168:171], v[208:211], v[70:73]
	v_mfma_f32_16x16x32_bf16 v[66:69], v[176:179], v[208:211], v[66:69]
	v_mfma_f32_16x16x32_bf16 v[118:121], v[172:175], v[188:191], v[118:121]
	v_mfma_f32_16x16x32_bf16 v[114:117], v[180:183], v[188:191], v[114:117]
	v_mfma_f32_16x16x32_bf16 v[102:105], v[172:175], v[196:199], v[102:105]
	v_mfma_f32_16x16x32_bf16 v[98:101], v[180:183], v[196:199], v[98:101]
	v_mfma_f32_16x16x32_bf16 v[86:89], v[172:175], v[204:207], v[86:89]
	v_mfma_f32_16x16x32_bf16 v[82:85], v[180:183], v[204:207], v[82:85]
	v_mfma_f32_16x16x32_bf16 v[70:73], v[172:175], v[212:215], v[70:73]
	v_mfma_f32_16x16x32_bf16 v[66:69], v[180:183], v[212:215], v[66:69]
	s_barrier
	s_add_u32 s28, s26, 0x8000
	s_addc_u32 s29, s27, 0
	s_add_i32 s59, s60, s34
	s_mov_b32 m0, s59
	ds_read_b128 v[184:187], v151 offset:49152
	ds_read_b128 v[188:191], v151 offset:50176
	ds_read_b128 v[192:195], v151 offset:51200
	ds_read_b128 v[196:199], v151 offset:52224
	ds_read_b128 v[200:203], v151 offset:53248
	ds_read_b128 v[204:207], v151 offset:54272
	ds_read_b128 v[208:211], v151 offset:55296
	ds_read_b128 v[212:215], v151 offset:56320
	global_load_lds_dwordx4 v130, s[28:29]
	s_add_i32 m0, s59, 0x2000
	s_add_u32 s26, s26, 0xc000
	v_lshl_add_u64 v[216:217], s[28:29], 0, v[132:133]
	s_addc_u32 s27, s27, 0
	s_add_i32 s28, s61, s34
	global_load_lds_dwordx4 v[216:217], off
	s_mov_b32 m0, s28
	s_nop 0
	global_load_lds_dwordx4 v130, s[26:27]
	s_add_i32 m0, s28, 0x2000
	s_nop 0
	global_load_lds_dwordx4 v132, s[26:27]
	s_mov_b32 m0, s41
	s_nop 0
	global_load_lds_dwordx4 v130, s[24:25]
	s_mov_b32 m0, s42
	s_nop 0
	global_load_lds_dwordx4 v132, s[24:25]
	s_waitcnt vmcnt(8) lgkmcnt(0)
	s_barrier
	v_mfma_f32_16x16x32_bf16 v[62:65], v[152:155], v[184:187], v[62:65]
	v_mfma_f32_16x16x32_bf16 v[58:61], v[160:163], v[184:187], v[58:61]
	v_mfma_f32_16x16x32_bf16 v[46:49], v[152:155], v[192:195], v[46:49]
	v_mfma_f32_16x16x32_bf16 v[42:45], v[160:163], v[192:195], v[42:45]
	v_mfma_f32_16x16x32_bf16 v[30:33], v[152:155], v[200:203], v[30:33]
	v_mfma_f32_16x16x32_bf16 v[26:29], v[160:163], v[200:203], v[26:29]
	v_mfma_f32_16x16x32_bf16 v[14:17], v[152:155], v[208:211], v[14:17]
	v_mfma_f32_16x16x32_bf16 v[10:13], v[160:163], v[208:211], v[10:13]
	v_mfma_f32_16x16x32_bf16 v[62:65], v[156:159], v[188:191], v[62:65]
	v_mfma_f32_16x16x32_bf16 v[58:61], v[164:167], v[188:191], v[58:61]
	v_mfma_f32_16x16x32_bf16 v[46:49], v[156:159], v[196:199], v[46:49]
	v_mfma_f32_16x16x32_bf16 v[42:45], v[164:167], v[196:199], v[42:45]
	v_mfma_f32_16x16x32_bf16 v[30:33], v[156:159], v[204:207], v[30:33]
	v_mfma_f32_16x16x32_bf16 v[26:29], v[164:167], v[204:207], v[26:29]
	v_mfma_f32_16x16x32_bf16 v[14:17], v[156:159], v[212:215], v[14:17]
	v_mfma_f32_16x16x32_bf16 v[10:13], v[164:167], v[212:215], v[10:13]
	v_mfma_f32_16x16x32_bf16 v[54:57], v[168:171], v[184:187], v[54:57]
	v_mfma_f32_16x16x32_bf16 v[50:53], v[176:179], v[184:187], v[50:53]
	v_mfma_f32_16x16x32_bf16 v[38:41], v[168:171], v[192:195], v[38:41]
	v_mfma_f32_16x16x32_bf16 v[34:37], v[176:179], v[192:195], v[34:37]
	v_mfma_f32_16x16x32_bf16 v[22:25], v[168:171], v[200:203], v[22:25]
	v_mfma_f32_16x16x32_bf16 v[18:21], v[176:179], v[200:203], v[18:21]
	v_mfma_f32_16x16x32_bf16 v[6:9], v[168:171], v[208:211], v[6:9]
	v_mfma_f32_16x16x32_bf16 v[2:5], v[176:179], v[208:211], v[2:5]
	v_mfma_f32_16x16x32_bf16 v[54:57], v[172:175], v[188:191], v[54:57]
	v_mfma_f32_16x16x32_bf16 v[50:53], v[180:183], v[188:191], v[50:53]
	v_mfma_f32_16x16x32_bf16 v[38:41], v[172:175], v[196:199], v[38:41]
	v_mfma_f32_16x16x32_bf16 v[34:37], v[180:183], v[196:199], v[34:37]
	v_mfma_f32_16x16x32_bf16 v[22:25], v[172:175], v[204:207], v[22:25]
	v_mfma_f32_16x16x32_bf16 v[18:21], v[180:183], v[204:207], v[18:21]
	v_mfma_f32_16x16x32_bf16 v[6:9], v[172:175], v[212:215], v[6:9]
	v_mfma_f32_16x16x32_bf16 v[2:5], v[180:183], v[212:215], v[2:5]
	s_barrier
; __device__ __forceinline__ unsigned pk2(float lo, float hi) { const f32x2 v = {lo, hi}; return __builtin_bit_cast(unsigned, __builtin_convertvector(v, bf16x2_t)); }
; __device__ __forceinline__ u32x4 ror8(u32x4 v) { u32x4 r;
; #pragma unroll
;     for (int i = 0; i < 4; ++i) r[i] = (unsigned)__builtin_amdgcn_mov_dpp((int)v[i], 0x128, 0xf, 0xf, true);
;     return r; }
; __device__ __forceinline__ void store_pair(unsigned char* own, size_t stride8, int hi_off, u32x4 lo, u32x4 hi, bool upper) {
;     const u32x4 tlo = ror8(lo), thi = ror8(hi);
;     const u32x4 A = upper ? thi : lo, B = upper ? hi : tlo;
;     unsigned char* pa = upper ? own - stride8 + hi_off : own;
;     unsigned char* pb = upper ? own + hi_off : own + stride8;
;     *(u32x4*)pa = A; *(u32x4*)pb = B;
;     __device__ __forceinline__ void operator()(const f32x4 (&acc)[2][2][4][2], const Unit& u, int wr, int wc, int fr, int fq) const {
;         const int row0 = u.pm * 256 + wr * 64 + fr, col0 = u.pn * 256 + wc * 64 + 8 * fq;
;         bf16_t* base = u.part == 0 ? Z + (size_t)row0 * D + col0 : P + ((size_t)(u.part - 1) * MS + (row0 - MP)) * D + col0;
; #pragma unroll
;         for (int ai = 0; ai < 2; ++ai)
; #pragma unroll
;             for (int m = 0; m < 4; ++m) { u32x4 w[2];
; #pragma unroll
;                 for (int bj = 0; bj < 2; ++bj) { const f32x4 v0 = acc[ai][bj][m][0], v1 = acc[ai][bj][m][1]; w[bj].x = pk2(v0[0], v0[1]); w[bj].y = pk2(v0[2], v0[3]); w[bj].z = pk2(v1[0], v1[1]); w[bj].w = pk2(v1[2], v1[3]); }
;                 store_pair((unsigned char*)(base + (size_t)(ai * 128 + m * 16) * D), (size_t)8 * D * 2, 64, w[0], w[1], fr >= 8); }
;     }
	s_add_u32 s22, s22, 0x10000
	s_addc_u32 s23, s23, 0
	s_cmp_ge_u32 s57, s44
	s_cbranch_scc0 .LBB0_1229
	v_lshl_add_u32 v143, s45, 8, v146
	v_add_u32_e32 v144, 0xffffe000, v143
	v_sub_co_u32_e64 v142, vcc, s43, 1
	v_mov_b32_e32 v145, s54
	s_nop 0
	v_cndmask_b32_e32 v144, v144, v143, vcc
	v_ashrrev_i32_e32 v143, 31, v142
	v_lshlrev_b64 v[142:143], 23, v[142:143]
	v_lshl_add_u64 v[142:143], s[12:13], 0, v[142:143]
	v_cndmask_b32_e32 v143, v143, v145, vcc
	v_mov_b32_e32 v145, s52
	v_cndmask_b32_e32 v142, v142, v145, vcc
	v_ashrrev_i32_e32 v145, 31, v144
	v_lshl_or_b32 v152, s78, 8, v148
	v_lshlrev_b64 v[144:145], 12, v[144:145]
	v_lshl_add_u64 v[142:143], v[142:143], 0, v[144:145]
	v_ashrrev_i32_e32 v153, 31, v152
	v_cvt_pk_bf16_f32 v126, v126, v127
	v_cvt_pk_bf16_f32 v127, v128, v129
	v_cvt_pk_bf16_f32 v128, v122, v123
	v_cvt_pk_bf16_f32 v124, v124, v125
	v_cvt_pk_bf16_f32 v118, v118, v119
	v_cvt_pk_bf16_f32 v119, v120, v121
	v_cvt_pk_bf16_f32 v114, v114, v115
	v_cvt_pk_bf16_f32 v115, v116, v117
	v_lshl_add_u64 v[142:143], v[152:153], 1, v[142:143]
	s_mov_b64 vcc, s[8:9]
	v_mov_b32_dpp v125, v118 row_ror:8 row_mask:0xf bank_mask:0xf bound_ctrl:1
	v_mov_b32_dpp v129, v119 row_ror:8 row_mask:0xf bank_mask:0xf bound_ctrl:1
	v_mov_b32_dpp v144, v114 row_ror:8 row_mask:0xf bank_mask:0xf bound_ctrl:1
	v_mov_b32_dpp v145, v115 row_ror:8 row_mask:0xf bank_mask:0xf bound_ctrl:1
	v_lshl_add_u64 v[122:123], v[142:143], 0, v[134:135]
	v_cndmask_b32_dpp v117, v124, v115, vcc row_ror:8 row_mask:0xf bank_mask:0xf bound_ctrl:1
	v_cndmask_b32_dpp v116, v128, v114, vcc row_ror:8 row_mask:0xf bank_mask:0xf bound_ctrl:1
	v_cndmask_b32_dpp v115, v127, v119, vcc row_ror:8 row_mask:0xf bank_mask:0xf bound_ctrl:1
	v_cndmask_b32_dpp v114, v126, v118, vcc row_ror:8 row_mask:0xf bank_mask:0xf bound_ctrl:1
	v_cndmask_b32_e64 v121, v124, v145, s[8:9]
	v_cndmask_b32_e64 v120, v128, v144, s[8:9]
	v_cndmask_b32_e64 v119, v127, v129, s[8:9]
	v_cndmask_b32_e64 v118, v126, v125, s[8:9]
	v_cvt_pk_bf16_f32 v110, v110, v111
	v_cvt_pk_bf16_f32 v111, v112, v113
	v_cvt_pk_bf16_f32 v112, v106, v107
	v_cvt_pk_bf16_f32 v113, v108, v109
	v_cvt_pk_bf16_f32 v102, v102, v103
	v_cvt_pk_bf16_f32 v103, v104, v105
	v_cvt_pk_bf16_f32 v98, v98, v99
	v_cvt_pk_bf16_f32 v99, v100, v101
	s_mov_b64 s[4:5], 0x10000
	v_lshl_add_u64 v[124:125], v[142:143], 0, v[136:137]
	s_and_b64 vcc, exec, s[6:7]
	s_cbranch_vccz .LBB0_1232
	s_barrier
.LBB0_1232:
	global_store_dwordx4 v[122:123], v[118:121], off
	global_store_dwordx4 v[124:125], v[114:117], off
	v_lshl_add_u64 v[106:107], v[142:143], 0, s[4:5]
	s_mov_b64 vcc, s[8:9]
	v_mov_b32_dpp v114, v102 row_ror:8 row_mask:0xf bank_mask:0xf bound_ctrl:1
	v_mov_b32_dpp v115, v103 row_ror:8 row_mask:0xf bank_mask:0xf bound_ctrl:1
	v_mov_b32_dpp v116, v98 row_ror:8 row_mask:0xf bank_mask:0xf bound_ctrl:1
	v_mov_b32_dpp v117, v99 row_ror:8 row_mask:0xf bank_mask:0xf bound_ctrl:1
	v_lshl_add_u64 v[108:109], v[106:107], 0, v[134:135]
	v_cndmask_b32_dpp v101, v113, v99, vcc row_ror:8 row_mask:0xf bank_mask:0xf bound_ctrl:1
	v_cndmask_b32_dpp v100, v112, v98, vcc row_ror:8 row_mask:0xf bank_mask:0xf bound_ctrl:1
	v_cndmask_b32_dpp v99, v111, v103, vcc row_ror:8 row_mask:0xf bank_mask:0xf bound_ctrl:1
	v_cndmask_b32_dpp v98, v110, v102, vcc row_ror:8 row_mask:0xf bank_mask:0xf bound_ctrl:1
	v_cndmask_b32_e64 v105, v113, v117, s[8:9]
	v_cndmask_b32_e64 v104, v112, v116, s[8:9]
	v_cndmask_b32_e64 v103, v111, v115, s[8:9]
	v_cndmask_b32_e64 v102, v110, v114, s[8:9]
	v_cvt_pk_bf16_f32 v94, v94, v95
	v_cvt_pk_bf16_f32 v95, v96, v97
	v_cvt_pk_bf16_f32 v96, v90, v91
	v_cvt_pk_bf16_f32 v97, v92, v93
	v_cvt_pk_bf16_f32 v86, v86, v87
	v_cvt_pk_bf16_f32 v87, v88, v89
	v_cvt_pk_bf16_f32 v82, v82, v83
	v_cvt_pk_bf16_f32 v83, v84, v85
	s_mov_b64 s[4:5], 0x20000
	v_lshl_add_u64 v[106:107], v[106:107], 0, v[136:137]
	global_store_dwordx4 v[108:109], v[102:105], off
	global_store_dwordx4 v[106:107], v[98:101], off
	v_lshl_add_u64 v[90:91], v[142:143], 0, s[4:5]
	s_mov_b64 vcc, s[8:9]
	v_mov_b32_dpp v98, v86 row_ror:8 row_mask:0xf bank_mask:0xf bound_ctrl:1
	v_mov_b32_dpp v99, v87 row_ror:8 row_mask:0xf bank_mask:0xf bound_ctrl:1
	v_mov_b32_dpp v100, v82 row_ror:8 row_mask:0xf bank_mask:0xf bound_ctrl:1
	v_mov_b32_dpp v101, v83 row_ror:8 row_mask:0xf bank_mask:0xf bound_ctrl:1
	v_lshl_add_u64 v[92:93], v[90:91], 0, v[134:135]
	v_cndmask_b32_dpp v85, v97, v83, vcc row_ror:8 row_mask:0xf bank_mask:0xf bound_ctrl:1
	v_cndmask_b32_dpp v84, v96, v82, vcc row_ror:8 row_mask:0xf bank_mask:0xf bound_ctrl:1
	v_cndmask_b32_dpp v83, v95, v87, vcc row_ror:8 row_mask:0xf bank_mask:0xf bound_ctrl:1
	v_cndmask_b32_dpp v82, v94, v86, vcc row_ror:8 row_mask:0xf bank_mask:0xf bound_ctrl:1
	v_cndmask_b32_e64 v89, v97, v101, s[8:9]
	v_cndmask_b32_e64 v88, v96, v100, s[8:9]
	v_cndmask_b32_e64 v87, v95, v99, s[8:9]
	v_cndmask_b32_e64 v86, v94, v98, s[8:9]
	v_cvt_pk_bf16_f32 v78, v78, v79
	v_cvt_pk_bf16_f32 v79, v80, v81
	v_cvt_pk_bf16_f32 v80, v74, v75
	v_cvt_pk_bf16_f32 v81, v76, v77
	v_cvt_pk_bf16_f32 v70, v70, v71
	v_cvt_pk_bf16_f32 v71, v72, v73
	v_cvt_pk_bf16_f32 v66, v66, v67
	v_cvt_pk_bf16_f32 v67, v68, v69
	s_mov_b64 s[4:5], 0x30000
	v_lshl_add_u64 v[90:91], v[90:91], 0, v[136:137]
	global_store_dwordx4 v[92:93], v[86:89], off
	global_store_dwordx4 v[90:91], v[82:85], off
	v_lshl_add_u64 v[74:75], v[142:143], 0, s[4:5]
	s_mov_b64 vcc, s[8:9]
	v_mov_b32_dpp v82, v70 row_ror:8 row_mask:0xf bank_mask:0xf bound_ctrl:1
	v_mov_b32_dpp v83, v71 row_ror:8 row_mask:0xf bank_mask:0xf bound_ctrl:1
	v_mov_b32_dpp v84, v66 row_ror:8 row_mask:0xf bank_mask:0xf bound_ctrl:1
	v_mov_b32_dpp v85, v67 row_ror:8 row_mask:0xf bank_mask:0xf bound_ctrl:1
; __device__ __forceinline__ unsigned pk2(float lo, float hi) { const f32x2 v = {lo, hi}; return __builtin_bit_cast(unsigned, __builtin_convertvector(v, bf16x2_t)); }
; #define PG8_BAR __builtin_amdgcn_s_barrier()
; template <class Epi, class Sched, bool ABLK = false, bool ALIGN_EPI = true, bool SP2 = true, bool BBLK = true>
; __device__ __forceinline__ void gemm_phase(LAS unsigned char* lds, const Gemm g, const Sched& S, const Epi& E) {
;     ...
;         if (!has_next) break;
; #pragma unroll
;         for (int a = 0; a < 2; ++a)
; #pragma unroll
;             for (int b = 0; b < 2; ++b)
; #pragma unroll
;                 for (int m = 0; m < 4; ++m)
; #pragma unroll
;                     for (int n = 0; n < 2; ++n) acc[a][b][m][n] = (f32x4){0.f, 0.f, 0.f, 0.f};
;         cur = nxt; uA = nuA; tbA = ntbA; cB = nB; ++ui;
;         if constexpr (ALIGN_EPI) { if (wr == 1) PG8_BAR; }
;     __device__ __forceinline__ void operator()(const f32x4 (&acc)[2][2][4][2], const Unit& u, int wr, int wc, int fr, int fq) const {
;         const int row0 = u.pm * 256 + wr * 64 + fr, col0 = u.pn * 256 + wc * 64 + 8 * fq;
;         bf16_t* base = u.part == 0 ? Z + (size_t)row0 * D + col0 : P + ((size_t)(u.part - 1) * MS + (row0 - MP)) * D + col0;
; #pragma unroll
;         for (int ai = 0; ai < 2; ++ai)
; #pragma unroll
;             for (int m = 0; m < 4; ++m) { u32x4 w[2];
; #pragma unroll
;                 for (int bj = 0; bj < 2; ++bj) { const f32x4 v0 = acc[ai][bj][m][0], v1 = acc[ai][bj][m][1]; w[bj].x = pk2(v0[0], v0[1]); w[bj].y = pk2(v0[2], v0[3]); w[bj].z = pk2(v1[0], v1[1]); w[bj].w = pk2(v1[2], v1[3]); }
;                 store_pair((unsigned char*)(base + (size_t)(ai * 128 + m * 16) * D), (size_t)8 * D * 2, 64, w[0], w[1], fr >= 8); }
;     }
	v_lshl_add_u64 v[76:77], v[74:75], 0, v[134:135]
	v_cndmask_b32_dpp v69, v81, v67, vcc row_ror:8 row_mask:0xf bank_mask:0xf bound_ctrl:1
	v_cndmask_b32_dpp v68, v80, v66, vcc row_ror:8 row_mask:0xf bank_mask:0xf bound_ctrl:1
	v_cndmask_b32_dpp v67, v79, v71, vcc row_ror:8 row_mask:0xf bank_mask:0xf bound_ctrl:1
	v_cndmask_b32_dpp v66, v78, v70, vcc row_ror:8 row_mask:0xf bank_mask:0xf bound_ctrl:1
	v_cndmask_b32_e64 v73, v81, v85, s[8:9]
	v_cndmask_b32_e64 v72, v80, v84, s[8:9]
	v_cndmask_b32_e64 v71, v79, v83, s[8:9]
	v_cndmask_b32_e64 v70, v78, v82, s[8:9]
	v_cvt_pk_bf16_f32 v62, v62, v63
	v_cvt_pk_bf16_f32 v63, v64, v65
	v_cvt_pk_bf16_f32 v64, v58, v59
	v_cvt_pk_bf16_f32 v65, v60, v61
	v_cvt_pk_bf16_f32 v54, v54, v55
	v_cvt_pk_bf16_f32 v55, v56, v57
	v_cvt_pk_bf16_f32 v50, v50, v51
	v_cvt_pk_bf16_f32 v51, v52, v53
	s_mov_b64 s[4:5], 0x80000
	v_lshl_add_u64 v[74:75], v[74:75], 0, v[136:137]
	global_store_dwordx4 v[76:77], v[70:73], off
	global_store_dwordx4 v[74:75], v[66:69], off
	v_lshl_add_u64 v[58:59], v[142:143], 0, s[4:5]
	s_mov_b64 vcc, s[8:9]
	v_mov_b32_dpp v66, v54 row_ror:8 row_mask:0xf bank_mask:0xf bound_ctrl:1
	v_mov_b32_dpp v67, v55 row_ror:8 row_mask:0xf bank_mask:0xf bound_ctrl:1
	v_mov_b32_dpp v68, v50 row_ror:8 row_mask:0xf bank_mask:0xf bound_ctrl:1
	v_mov_b32_dpp v69, v51 row_ror:8 row_mask:0xf bank_mask:0xf bound_ctrl:1
	v_lshl_add_u64 v[60:61], v[58:59], 0, v[134:135]
	v_cndmask_b32_dpp v53, v65, v51, vcc row_ror:8 row_mask:0xf bank_mask:0xf bound_ctrl:1
	v_cndmask_b32_dpp v52, v64, v50, vcc row_ror:8 row_mask:0xf bank_mask:0xf bound_ctrl:1
	v_cndmask_b32_dpp v51, v63, v55, vcc row_ror:8 row_mask:0xf bank_mask:0xf bound_ctrl:1
	v_cndmask_b32_dpp v50, v62, v54, vcc row_ror:8 row_mask:0xf bank_mask:0xf bound_ctrl:1
	v_cndmask_b32_e64 v57, v65, v69, s[8:9]
	v_cndmask_b32_e64 v56, v64, v68, s[8:9]
	v_cndmask_b32_e64 v55, v63, v67, s[8:9]
	v_cndmask_b32_e64 v54, v62, v66, s[8:9]
	v_cvt_pk_bf16_f32 v46, v46, v47
	v_cvt_pk_bf16_f32 v47, v48, v49
	v_cvt_pk_bf16_f32 v48, v42, v43
	v_cvt_pk_bf16_f32 v49, v44, v45
	v_cvt_pk_bf16_f32 v38, v38, v39
	v_cvt_pk_bf16_f32 v39, v40, v41
	v_cvt_pk_bf16_f32 v34, v34, v35
	v_cvt_pk_bf16_f32 v35, v36, v37
	s_mov_b64 s[4:5], 0x90000
	v_lshl_add_u64 v[58:59], v[58:59], 0, v[136:137]
	global_store_dwordx4 v[60:61], v[54:57], off
	global_store_dwordx4 v[58:59], v[50:53], off
	v_lshl_add_u64 v[42:43], v[142:143], 0, s[4:5]
	s_mov_b64 vcc, s[8:9]
	v_mov_b32_dpp v50, v38 row_ror:8 row_mask:0xf bank_mask:0xf bound_ctrl:1
	v_mov_b32_dpp v51, v39 row_ror:8 row_mask:0xf bank_mask:0xf bound_ctrl:1
	v_mov_b32_dpp v52, v34 row_ror:8 row_mask:0xf bank_mask:0xf bound_ctrl:1
	v_mov_b32_dpp v53, v35 row_ror:8 row_mask:0xf bank_mask:0xf bound_ctrl:1
	v_lshl_add_u64 v[44:45], v[42:43], 0, v[134:135]
	v_cndmask_b32_dpp v37, v49, v35, vcc row_ror:8 row_mask:0xf bank_mask:0xf bound_ctrl:1
	v_cndmask_b32_dpp v36, v48, v34, vcc row_ror:8 row_mask:0xf bank_mask:0xf bound_ctrl:1
	v_cndmask_b32_dpp v35, v47, v39, vcc row_ror:8 row_mask:0xf bank_mask:0xf bound_ctrl:1
	v_cndmask_b32_dpp v34, v46, v38, vcc row_ror:8 row_mask:0xf bank_mask:0xf bound_ctrl:1
	v_cndmask_b32_e64 v41, v49, v53, s[8:9]
	v_cndmask_b32_e64 v40, v48, v52, s[8:9]
	v_cndmask_b32_e64 v39, v47, v51, s[8:9]
	v_cndmask_b32_e64 v38, v46, v50, s[8:9]
	v_cvt_pk_bf16_f32 v30, v30, v31
	v_cvt_pk_bf16_f32 v31, v32, v33
	v_cvt_pk_bf16_f32 v32, v26, v27
	v_cvt_pk_bf16_f32 v33, v28, v29
	v_cvt_pk_bf16_f32 v22, v22, v23
	v_cvt_pk_bf16_f32 v23, v24, v25
	v_cvt_pk_bf16_f32 v18, v18, v19
	v_cvt_pk_bf16_f32 v19, v20, v21
	s_mov_b64 s[4:5], 0xa0000
	v_lshl_add_u64 v[42:43], v[42:43], 0, v[136:137]
	global_store_dwordx4 v[44:45], v[38:41], off
	global_store_dwordx4 v[42:43], v[34:37], off
	v_lshl_add_u64 v[26:27], v[142:143], 0, s[4:5]
	s_mov_b64 vcc, s[8:9]
	v_mov_b32_dpp v34, v22 row_ror:8 row_mask:0xf bank_mask:0xf bound_ctrl:1
	v_mov_b32_dpp v35, v23 row_ror:8 row_mask:0xf bank_mask:0xf bound_ctrl:1
	v_mov_b32_dpp v36, v18 row_ror:8 row_mask:0xf bank_mask:0xf bound_ctrl:1
	v_mov_b32_dpp v37, v19 row_ror:8 row_mask:0xf bank_mask:0xf bound_ctrl:1
	v_lshl_add_u64 v[28:29], v[26:27], 0, v[134:135]
	v_cndmask_b32_dpp v21, v33, v19, vcc row_ror:8 row_mask:0xf bank_mask:0xf bound_ctrl:1
	v_cndmask_b32_dpp v20, v32, v18, vcc row_ror:8 row_mask:0xf bank_mask:0xf bound_ctrl:1
	v_cndmask_b32_dpp v19, v31, v23, vcc row_ror:8 row_mask:0xf bank_mask:0xf bound_ctrl:1
	v_cndmask_b32_dpp v18, v30, v22, vcc row_ror:8 row_mask:0xf bank_mask:0xf bound_ctrl:1
	v_cndmask_b32_e64 v25, v33, v37, s[8:9]
	v_cndmask_b32_e64 v24, v32, v36, s[8:9]
	v_cndmask_b32_e64 v23, v31, v35, s[8:9]
	v_cndmask_b32_e64 v22, v30, v34, s[8:9]
	v_cvt_pk_bf16_f32 v14, v14, v15
	v_cvt_pk_bf16_f32 v15, v16, v17
	v_cvt_pk_bf16_f32 v16, v10, v11
	v_cvt_pk_bf16_f32 v17, v12, v13
	v_cvt_pk_bf16_f32 v6, v6, v7
	v_cvt_pk_bf16_f32 v7, v8, v9
	v_cvt_pk_bf16_f32 v2, v2, v3
	v_cvt_pk_bf16_f32 v3, v4, v5
	v_lshl_add_u64 v[26:27], v[26:27], 0, v[136:137]
	global_store_dwordx4 v[28:29], v[22:25], off
	global_store_dwordx4 v[26:27], v[18:21], off
	v_lshl_add_u64 v[10:11], v[142:143], 0, s[14:15]
	s_mov_b64 vcc, s[8:9]
	v_mov_b32_dpp v18, v6 row_ror:8 row_mask:0xf bank_mask:0xf bound_ctrl:1
	v_mov_b32_dpp v19, v7 row_ror:8 row_mask:0xf bank_mask:0xf bound_ctrl:1
	v_mov_b32_dpp v20, v2 row_ror:8 row_mask:0xf bank_mask:0xf bound_ctrl:1
	v_mov_b32_dpp v21, v3 row_ror:8 row_mask:0xf bank_mask:0xf bound_ctrl:1
	v_lshl_add_u64 v[12:13], v[10:11], 0, v[134:135]
	v_cndmask_b32_dpp v5, v17, v3, vcc row_ror:8 row_mask:0xf bank_mask:0xf bound_ctrl:1
	v_cndmask_b32_dpp v4, v16, v2, vcc row_ror:8 row_mask:0xf bank_mask:0xf bound_ctrl:1
	v_cndmask_b32_dpp v3, v15, v7, vcc row_ror:8 row_mask:0xf bank_mask:0xf bound_ctrl:1
	v_cndmask_b32_dpp v2, v14, v6, vcc row_ror:8 row_mask:0xf bank_mask:0xf bound_ctrl:1
	v_cndmask_b32_e64 v9, v17, v21, s[8:9]
	v_cndmask_b32_e64 v8, v16, v20, s[8:9]
	v_cndmask_b32_e64 v7, v15, v19, s[8:9]
	v_cndmask_b32_e64 v6, v14, v18, s[8:9]
	s_and_b64 vcc, exec, s[10:11]
	s_mov_b64 s[10:11], -1
	v_lshl_add_u64 v[10:11], v[10:11], 0, v[136:137]
	global_store_dwordx4 v[12:13], v[6:9], off
	global_store_dwordx4 v[10:11], v[2:5], off
	s_cbranch_vccnz .LBB0_1227
	s_andn2_b64 vcc, exec, s[2:3]
	s_cbranch_vccnz .LBB0_1226
	s_barrier
	s_branch .LBB0_1226

; #define PG8_STAGE(bufoff, gbase, voff) do { _Pragma("unroll") for (int _i = 0; _i < 2; ++_i) \
;         __builtin_amdgcn_global_load_lds((const unsigned*)((const char*)(gbase) + (voff)[_i]), (LAS unsigned*)(lds + (bufoff) + ldsw + _i * 8192), 16, 0, 0); } while (0)
; #define PG8_LDA(dst, b, h) do { _Pragma("unroll") for (int m = 0; m < 4; ++m) _Pragma("unroll") for (int k = 0; k < 2; ++k) dst[m][k] = *(const LAS bf16x8*)(lds + PG8_SA(b, h) + aoff + m * 2048 + k * 1024); } while (0)
; #define PG8_LDB(dst, b, h) do { _Pragma("unroll") for (int n = 0; n < 2; ++n) _Pragma("unroll") for (int k = 0; k < 2; ++k) dst[n][k] = *(const LAS bf16x8*)(lds + PG8_SB(b, h) + boff + n * 2048 + k * 1024); } while (0)
; #define PG8_MMA(ai, bj, At, Bt) do { __builtin_amdgcn_s_setprio(1); _Pragma("unroll") for (int m = 0; m < 4; ++m) _Pragma("unroll") for (int n = 0; n < 2; ++n) _Pragma("unroll") for (int k = 0; k < 2; ++k) \
;         acc[ai][bj][m][n] = __builtin_amdgcn_mfma_f32_16x16x32_bf16(Bt[n][k], At[m][k], acc[ai][bj][m][n], 0, 0, 0); __builtin_amdgcn_s_setprio(0); } while (0)
; #define PG8_WAIT_V(n) asm volatile("s_waitcnt vmcnt(" #n ")" ::: "memory")
; #define PG8_WAIT_L(n) asm volatile("s_waitcnt lgkmcnt(" #n ")" ::: "memory")
; template <class Epi, class Sched, bool ABLK = false, bool ALIGN_EPI = true, bool SP2 = true, bool BBLK = true>
; __device__ __forceinline__ void gemm_phase(LAS unsigned char* lds, const Gemm g, const Sched& S, const Epi& E) {
;     ...
;             const char* a1 = a_tile(uA, tbA + t + 1);
;             const char* a2 = last ? a_tile(nuA, ntbA) : a_tile(uA, tbA + t + 2); const char* b2 = last ? nB : cB + (size_t)(t + 2) * kstepB;
;             const char* a3 = last ? a_tile(nuA, ntbA + 1) : a_tile(uA, tbA + t + 3); const char* b3 = b2 + kstepB;
;             if (last && has_next) S.a_ready(nxt);
;             if constexpr (SP2) {
;             PG8_LDB(B0, 0, 0); PG8_LDB(B1, 0, 1); PG8_SCHED; PG8_LDA(At, 0, 0); PG8_STAGE(PG8_SA(1, 1), a1 + hstepA, voffA);
;             PG8_WAIT_V(8); PG8_WAIT_L(0); PG8_BAR; PG8_MMA(0, 0, At, B0); PG8_MMA(0, 1, At, B1); PG8_BAR; PG8_SCHED;
;             PG8_LDA(At, 0, 1); PG8_STAGE(PG8_SB(0, 0), b2, voffB); PG8_STAGE(PG8_SB(0, 1), b2 + hstepB, voffB); PG8_STAGE(PG8_SA(0, 0), a2, voffA);
;             PG8_WAIT_V(8); PG8_WAIT_L(0); PG8_BAR; PG8_MMA(1, 0, At, B0); PG8_MMA(1, 1, At, B1); PG8_BAR; PG8_SCHED;
.Lksel_17_back:
	v_lshl_add_u64 v[220:221], v[146:147], 0, s[26:27]
	s_add_i32 m0, s40, 0xc000
	ds_read_b128 v[188:191], v154
	ds_read_b128 v[192:195], v154 offset:1024
	ds_read_b128 v[196:199], v154 offset:2048
	ds_read_b128 v[200:203], v154 offset:3072
	ds_read_b128 v[204:207], v154 offset:4096
	ds_read_b128 v[208:211], v154 offset:5120
	ds_read_b128 v[212:215], v154 offset:6144
	ds_read_b128 v[216:219], v154 offset:7168
	global_load_lds_dwordx4 v[220:221], off
	v_lshl_add_u64 v[220:221], v[148:149], 0, s[26:27]
	s_add_i32 m0, s40, 0xe000
	s_nop 0
	global_load_lds_dwordx4 v[220:221], off
	s_waitcnt vmcnt(8) lgkmcnt(0)
	s_barrier
	v_mfma_f32_16x16x32_bf16 v[126:129], v[156:159], v[188:191], v[126:129]
	v_mfma_f32_16x16x32_bf16 v[122:125], v[164:167], v[188:191], v[122:125]
	v_mfma_f32_16x16x32_bf16 v[110:113], v[156:159], v[196:199], v[110:113]
	v_mfma_f32_16x16x32_bf16 v[106:109], v[164:167], v[196:199], v[106:109]
	v_mfma_f32_16x16x32_bf16 v[94:97], v[156:159], v[204:207], v[94:97]
	v_mfma_f32_16x16x32_bf16 v[90:93], v[164:167], v[204:207], v[90:93]
	v_mfma_f32_16x16x32_bf16 v[78:81], v[156:159], v[212:215], v[78:81]
	v_mfma_f32_16x16x32_bf16 v[74:77], v[164:167], v[212:215], v[74:77]
	v_mfma_f32_16x16x32_bf16 v[126:129], v[160:163], v[192:195], v[126:129]
	v_mfma_f32_16x16x32_bf16 v[122:125], v[168:171], v[192:195], v[122:125]
	v_mfma_f32_16x16x32_bf16 v[110:113], v[160:163], v[200:203], v[110:113]
	v_mfma_f32_16x16x32_bf16 v[106:109], v[168:171], v[200:203], v[106:109]
	v_mfma_f32_16x16x32_bf16 v[94:97], v[160:163], v[208:211], v[94:97]
	v_mfma_f32_16x16x32_bf16 v[90:93], v[168:171], v[208:211], v[90:93]
	v_mfma_f32_16x16x32_bf16 v[78:81], v[160:163], v[216:219], v[78:81]
	v_mfma_f32_16x16x32_bf16 v[74:77], v[168:171], v[216:219], v[74:77]
	v_mfma_f32_16x16x32_bf16 v[118:121], v[172:175], v[188:191], v[118:121]
	v_mfma_f32_16x16x32_bf16 v[114:117], v[180:183], v[188:191], v[114:117]
	v_mfma_f32_16x16x32_bf16 v[102:105], v[172:175], v[196:199], v[102:105]
	v_mfma_f32_16x16x32_bf16 v[98:101], v[180:183], v[196:199], v[98:101]
	v_mfma_f32_16x16x32_bf16 v[86:89], v[172:175], v[204:207], v[86:89]
	v_mfma_f32_16x16x32_bf16 v[82:85], v[180:183], v[204:207], v[82:85]
	v_mfma_f32_16x16x32_bf16 v[70:73], v[172:175], v[212:215], v[70:73]
	v_mfma_f32_16x16x32_bf16 v[66:69], v[180:183], v[212:215], v[66:69]
	v_mfma_f32_16x16x32_bf16 v[118:121], v[176:179], v[192:195], v[118:121]
	v_mfma_f32_16x16x32_bf16 v[114:117], v[184:187], v[192:195], v[114:117]
	v_mfma_f32_16x16x32_bf16 v[102:105], v[176:179], v[200:203], v[102:105]
	v_mfma_f32_16x16x32_bf16 v[98:101], v[184:187], v[200:203], v[98:101]
	v_mfma_f32_16x16x32_bf16 v[86:89], v[176:179], v[208:211], v[86:89]
	v_mfma_f32_16x16x32_bf16 v[82:85], v[184:187], v[208:211], v[82:85]
	v_mfma_f32_16x16x32_bf16 v[70:73], v[176:179], v[216:219], v[70:73]
	v_mfma_f32_16x16x32_bf16 v[66:69], v[184:187], v[216:219], v[66:69]
	s_barrier
	s_add_i32 s58, s72, s39
	s_mov_b32 m0, s58
	ds_read_b128 v[188:191], v154 offset:16384
	ds_read_b128 v[192:195], v154 offset:17408
	ds_read_b128 v[196:199], v154 offset:18432
	ds_read_b128 v[200:203], v154 offset:19456
	ds_read_b128 v[204:207], v154 offset:20480
	ds_read_b128 v[208:211], v154 offset:21504
	ds_read_b128 v[212:215], v154 offset:22528
	ds_read_b128 v[216:219], v154 offset:23552
	global_load_lds_dwordx4 v132, s[30:31]
	s_add_i32 m0, s58, 0x2000
	s_add_u32 s58, s30, 0x4000
	s_addc_u32 s59, s31, 0
	s_add_i32 s64, s73, s39
	global_load_lds_dwordx4 v136, s[30:31]
	s_mov_b32 m0, s64
	s_nop 0
	global_load_lds_dwordx4 v132, s[58:59]
	s_add_i32 m0, s64, 0x2000
	s_nop 0
	global_load_lds_dwordx4 v136, s[58:59]
	s_mov_b32 m0, s40
	s_nop 0
	global_load_lds_dwordx4 v130, s[34:35]
	s_mov_b32 m0, s41
	s_nop 0
	global_load_lds_dwordx4 v134, s[34:35]
	s_waitcnt vmcnt(8) lgkmcnt(0)
	s_barrier
	v_mfma_f32_16x16x32_bf16 v[62:65], v[156:159], v[188:191], v[62:65]
	v_mfma_f32_16x16x32_bf16 v[58:61], v[164:167], v[188:191], v[58:61]
	v_mfma_f32_16x16x32_bf16 v[46:49], v[156:159], v[196:199], v[46:49]
	v_mfma_f32_16x16x32_bf16 v[42:45], v[164:167], v[196:199], v[42:45]
	v_mfma_f32_16x16x32_bf16 v[30:33], v[156:159], v[204:207], v[30:33]
	v_mfma_f32_16x16x32_bf16 v[26:29], v[164:167], v[204:207], v[26:29]
	v_mfma_f32_16x16x32_bf16 v[14:17], v[156:159], v[212:215], v[14:17]
	v_mfma_f32_16x16x32_bf16 v[10:13], v[164:167], v[212:215], v[10:13]
	v_mfma_f32_16x16x32_bf16 v[62:65], v[160:163], v[192:195], v[62:65]
	v_mfma_f32_16x16x32_bf16 v[58:61], v[168:171], v[192:195], v[58:61]
	v_mfma_f32_16x16x32_bf16 v[46:49], v[160:163], v[200:203], v[46:49]
	v_mfma_f32_16x16x32_bf16 v[42:45], v[168:171], v[200:203], v[42:45]
	v_mfma_f32_16x16x32_bf16 v[30:33], v[160:163], v[208:211], v[30:33]
	v_mfma_f32_16x16x32_bf16 v[26:29], v[168:171], v[208:211], v[26:29]
	v_mfma_f32_16x16x32_bf16 v[14:17], v[160:163], v[216:219], v[14:17]
	v_mfma_f32_16x16x32_bf16 v[10:13], v[168:171], v[216:219], v[10:13]
	v_mfma_f32_16x16x32_bf16 v[54:57], v[172:175], v[188:191], v[54:57]
	v_mfma_f32_16x16x32_bf16 v[50:53], v[180:183], v[188:191], v[50:53]
	v_mfma_f32_16x16x32_bf16 v[38:41], v[172:175], v[196:199], v[38:41]
	v_mfma_f32_16x16x32_bf16 v[34:37], v[180:183], v[196:199], v[34:37]
	v_mfma_f32_16x16x32_bf16 v[22:25], v[172:175], v[204:207], v[22:25]
	v_mfma_f32_16x16x32_bf16 v[18:21], v[180:183], v[204:207], v[18:21]
	v_mfma_f32_16x16x32_bf16 v[6:9], v[172:175], v[212:215], v[6:9]
	v_mfma_f32_16x16x32_bf16 v[2:5], v[180:183], v[212:215], v[2:5]
	v_mfma_f32_16x16x32_bf16 v[54:57], v[176:179], v[192:195], v[54:57]
	v_mfma_f32_16x16x32_bf16 v[50:53], v[184:187], v[192:195], v[50:53]
	v_mfma_f32_16x16x32_bf16 v[38:41], v[176:179], v[200:203], v[38:41]
	v_mfma_f32_16x16x32_bf16 v[34:37], v[184:187], v[200:203], v[34:37]
	v_mfma_f32_16x16x32_bf16 v[22:25], v[176:179], v[208:211], v[22:25]
	v_mfma_f32_16x16x32_bf16 v[18:21], v[184:187], v[208:211], v[18:21]
	v_mfma_f32_16x16x32_bf16 v[6:9], v[176:179], v[216:219], v[6:9]
	v_mfma_f32_16x16x32_bf16 v[2:5], v[184:187], v[216:219], v[2:5]
	s_barrier
; #define PG8_STAGE(bufoff, gbase, voff) do { _Pragma("unroll") for (int _i = 0; _i < 2; ++_i) \
;         __builtin_amdgcn_global_load_lds((const unsigned*)((const char*)(gbase) + (voff)[_i]), (LAS unsigned*)(lds + (bufoff) + ldsw + _i * 8192), 16, 0, 0); } while (0)
; #define PG8_LDA(dst, b, h) do { _Pragma("unroll") for (int m = 0; m < 4; ++m) _Pragma("unroll") for (int k = 0; k < 2; ++k) dst[m][k] = *(const LAS bf16x8*)(lds + PG8_SA(b, h) + aoff + m * 2048 + k * 1024); } while (0)
; #define PG8_LDB(dst, b, h) do { _Pragma("unroll") for (int n = 0; n < 2; ++n) _Pragma("unroll") for (int k = 0; k < 2; ++k) dst[n][k] = *(const LAS bf16x8*)(lds + PG8_SB(b, h) + boff + n * 2048 + k * 1024); } while (0)
; #define PG8_MMA(ai, bj, At, Bt) do { __builtin_amdgcn_s_setprio(1); _Pragma("unroll") for (int m = 0; m < 4; ++m) _Pragma("unroll") for (int n = 0; n < 2; ++n) _Pragma("unroll") for (int k = 0; k < 2; ++k) \
;         acc[ai][bj][m][n] = __builtin_amdgcn_mfma_f32_16x16x32_bf16(Bt[n][k], At[m][k], acc[ai][bj][m][n], 0, 0, 0); __builtin_amdgcn_s_setprio(0); } while (0)
; #define PG8_WAIT_V(n) asm volatile("s_waitcnt vmcnt(" #n ")" ::: "memory")
; #define PG8_WAIT_L(n) asm volatile("s_waitcnt lgkmcnt(" #n ")" ::: "memory")
; #define PG8_BAR __builtin_amdgcn_s_barrier()
; #define PG8_SCHED __builtin_amdgcn_sched_barrier(0)
; template <class Epi, class Sched, bool ABLK = false, bool ALIGN_EPI = true, bool SP2 = true, bool BBLK = true>
; __device__ __forceinline__ void gemm_phase(LAS unsigned char* lds, const Gemm g, const Sched& S, const Epi& E) {
;     ...
;             PG8_LDB(B0, 1, 0); PG8_LDB(B1, 1, 1); PG8_SCHED; PG8_LDA(At, 1, 0); PG8_STAGE(PG8_SA(0, 1), a2 + hstepA, voffA);
;             PG8_WAIT_V(8); PG8_WAIT_L(0); PG8_BAR; PG8_MMA(0, 0, At, B0); PG8_MMA(0, 1, At, B1); PG8_BAR; PG8_SCHED;
;             PG8_LDA(At, 1, 1); PG8_STAGE(PG8_SB(1, 0), b3, voffB); PG8_STAGE(PG8_SB(1, 1), b3 + hstepB, voffB); PG8_STAGE(PG8_SA(1, 0), a3, voffA);
;             PG8_WAIT_V(8); PG8_WAIT_L(0); PG8_BAR; PG8_MMA(1, 0, At, B0); PG8_MMA(1, 1, At, B1); PG8_BAR; PG8_SCHED;
	v_add_u32_e32 v155, s60, v150
	ds_read_b128 v[156:159], v155
	ds_read_b128 v[160:163], v155 offset:1024
	ds_read_b128 v[164:167], v155 offset:2048
	ds_read_b128 v[168:171], v155 offset:3072
	v_add_u32_e32 v155, s61, v150
	ds_read_b128 v[172:175], v155
	ds_read_b128 v[176:179], v155 offset:1024
	ds_read_b128 v[180:183], v155 offset:2048
	ds_read_b128 v[184:187], v155 offset:3072
	s_add_u32 s34, s34, 0x80000
	s_addc_u32 s35, s35, 0
	s_mov_b32 m0, s42
	ds_read_b128 v[188:191], v154 offset:32768
	ds_read_b128 v[192:195], v154 offset:33792
	ds_read_b128 v[196:199], v154 offset:34816
	ds_read_b128 v[200:203], v154 offset:35840
	ds_read_b128 v[204:207], v154 offset:36864
	ds_read_b128 v[208:211], v154 offset:37888
	ds_read_b128 v[212:215], v154 offset:38912
	ds_read_b128 v[216:219], v154 offset:39936
	global_load_lds_dwordx4 v130, s[34:35]
	s_mov_b32 m0, s43
	s_nop 0
	global_load_lds_dwordx4 v134, s[34:35]
	s_waitcnt vmcnt(8) lgkmcnt(0)
	s_barrier
	v_mfma_f32_16x16x32_bf16 v[126:129], v[156:159], v[188:191], v[126:129]
	v_mfma_f32_16x16x32_bf16 v[122:125], v[164:167], v[188:191], v[122:125]
	v_mfma_f32_16x16x32_bf16 v[110:113], v[156:159], v[196:199], v[110:113]
	v_mfma_f32_16x16x32_bf16 v[106:109], v[164:167], v[196:199], v[106:109]
	v_mfma_f32_16x16x32_bf16 v[94:97], v[156:159], v[204:207], v[94:97]
	v_mfma_f32_16x16x32_bf16 v[90:93], v[164:167], v[204:207], v[90:93]
	v_mfma_f32_16x16x32_bf16 v[78:81], v[156:159], v[212:215], v[78:81]
	v_mfma_f32_16x16x32_bf16 v[74:77], v[164:167], v[212:215], v[74:77]
	v_mfma_f32_16x16x32_bf16 v[126:129], v[160:163], v[192:195], v[126:129]
	v_mfma_f32_16x16x32_bf16 v[122:125], v[168:171], v[192:195], v[122:125]
	v_mfma_f32_16x16x32_bf16 v[110:113], v[160:163], v[200:203], v[110:113]
	v_mfma_f32_16x16x32_bf16 v[106:109], v[168:171], v[200:203], v[106:109]
	v_mfma_f32_16x16x32_bf16 v[94:97], v[160:163], v[208:211], v[94:97]
	v_mfma_f32_16x16x32_bf16 v[90:93], v[168:171], v[208:211], v[90:93]
	v_mfma_f32_16x16x32_bf16 v[78:81], v[160:163], v[216:219], v[78:81]
	v_mfma_f32_16x16x32_bf16 v[74:77], v[168:171], v[216:219], v[74:77]
	v_mfma_f32_16x16x32_bf16 v[118:121], v[172:175], v[188:191], v[118:121]
	v_mfma_f32_16x16x32_bf16 v[114:117], v[180:183], v[188:191], v[114:117]
	v_mfma_f32_16x16x32_bf16 v[102:105], v[172:175], v[196:199], v[102:105]
	v_mfma_f32_16x16x32_bf16 v[98:101], v[180:183], v[196:199], v[98:101]
	v_mfma_f32_16x16x32_bf16 v[86:89], v[172:175], v[204:207], v[86:89]
	v_mfma_f32_16x16x32_bf16 v[82:85], v[180:183], v[204:207], v[82:85]
	v_mfma_f32_16x16x32_bf16 v[70:73], v[172:175], v[212:215], v[70:73]
	v_mfma_f32_16x16x32_bf16 v[66:69], v[180:183], v[212:215], v[66:69]
	v_mfma_f32_16x16x32_bf16 v[118:121], v[176:179], v[192:195], v[118:121]
	v_mfma_f32_16x16x32_bf16 v[114:117], v[184:187], v[192:195], v[114:117]
	v_mfma_f32_16x16x32_bf16 v[102:105], v[176:179], v[200:203], v[102:105]
	v_mfma_f32_16x16x32_bf16 v[98:101], v[184:187], v[200:203], v[98:101]
	v_mfma_f32_16x16x32_bf16 v[86:89], v[176:179], v[208:211], v[86:89]
	v_mfma_f32_16x16x32_bf16 v[82:85], v[184:187], v[208:211], v[82:85]
	v_mfma_f32_16x16x32_bf16 v[70:73], v[176:179], v[216:219], v[70:73]
	v_mfma_f32_16x16x32_bf16 v[66:69], v[184:187], v[216:219], v[66:69]
	s_barrier
	s_add_u32 s34, s30, 0x8000
	s_addc_u32 s35, s31, 0
	s_add_i32 s58, s60, s39
	s_mov_b32 m0, s58
	ds_read_b128 v[188:191], v154 offset:49152
	ds_read_b128 v[192:195], v154 offset:50176
	ds_read_b128 v[196:199], v154 offset:51200
	ds_read_b128 v[200:203], v154 offset:52224
	ds_read_b128 v[204:207], v154 offset:53248
	ds_read_b128 v[208:211], v154 offset:54272
	ds_read_b128 v[212:215], v154 offset:55296
	ds_read_b128 v[216:219], v154 offset:56320
	global_load_lds_dwordx4 v132, s[34:35]
	s_add_i32 m0, s58, 0x2000
	s_add_u32 s30, s30, 0xc000
	v_lshl_add_u64 v[220:221], s[34:35], 0, v[136:137]
	s_addc_u32 s31, s31, 0
	s_add_i32 s34, s61, s39
	global_load_lds_dwordx4 v[220:221], off
	s_mov_b32 m0, s34
	s_nop 0
	global_load_lds_dwordx4 v132, s[30:31]
	s_add_i32 m0, s34, 0x2000
	s_nop 0
	global_load_lds_dwordx4 v136, s[30:31]
	s_mov_b32 m0, s44
	s_nop 0
	global_load_lds_dwordx4 v130, s[28:29]
	s_mov_b32 m0, s45
	s_nop 0
	global_load_lds_dwordx4 v134, s[28:29]
	s_waitcnt vmcnt(8) lgkmcnt(0)
	s_barrier
	v_mfma_f32_16x16x32_bf16 v[62:65], v[156:159], v[188:191], v[62:65]
	v_mfma_f32_16x16x32_bf16 v[58:61], v[164:167], v[188:191], v[58:61]
	v_mfma_f32_16x16x32_bf16 v[46:49], v[156:159], v[196:199], v[46:49]
	v_mfma_f32_16x16x32_bf16 v[42:45], v[164:167], v[196:199], v[42:45]
	v_mfma_f32_16x16x32_bf16 v[30:33], v[156:159], v[204:207], v[30:33]
	v_mfma_f32_16x16x32_bf16 v[26:29], v[164:167], v[204:207], v[26:29]
	v_mfma_f32_16x16x32_bf16 v[14:17], v[156:159], v[212:215], v[14:17]
	v_mfma_f32_16x16x32_bf16 v[10:13], v[164:167], v[212:215], v[10:13]
	v_mfma_f32_16x16x32_bf16 v[62:65], v[160:163], v[192:195], v[62:65]
	v_mfma_f32_16x16x32_bf16 v[58:61], v[168:171], v[192:195], v[58:61]
	v_mfma_f32_16x16x32_bf16 v[46:49], v[160:163], v[200:203], v[46:49]
	v_mfma_f32_16x16x32_bf16 v[42:45], v[168:171], v[200:203], v[42:45]
	v_mfma_f32_16x16x32_bf16 v[30:33], v[160:163], v[208:211], v[30:33]
	v_mfma_f32_16x16x32_bf16 v[26:29], v[168:171], v[208:211], v[26:29]
	v_mfma_f32_16x16x32_bf16 v[14:17], v[160:163], v[216:219], v[14:17]
	v_mfma_f32_16x16x32_bf16 v[10:13], v[168:171], v[216:219], v[10:13]
	v_mfma_f32_16x16x32_bf16 v[54:57], v[172:175], v[188:191], v[54:57]
	v_mfma_f32_16x16x32_bf16 v[50:53], v[180:183], v[188:191], v[50:53]
	v_mfma_f32_16x16x32_bf16 v[38:41], v[172:175], v[196:199], v[38:41]
	v_mfma_f32_16x16x32_bf16 v[34:37], v[180:183], v[196:199], v[34:37]
	v_mfma_f32_16x16x32_bf16 v[22:25], v[172:175], v[204:207], v[22:25]
	v_mfma_f32_16x16x32_bf16 v[18:21], v[180:183], v[204:207], v[18:21]
	v_mfma_f32_16x16x32_bf16 v[6:9], v[172:175], v[212:215], v[6:9]
	v_mfma_f32_16x16x32_bf16 v[2:5], v[180:183], v[212:215], v[2:5]
	v_mfma_f32_16x16x32_bf16 v[54:57], v[176:179], v[192:195], v[54:57]
	v_mfma_f32_16x16x32_bf16 v[50:53], v[184:187], v[192:195], v[50:53]
	v_mfma_f32_16x16x32_bf16 v[38:41], v[176:179], v[200:203], v[38:41]
	v_mfma_f32_16x16x32_bf16 v[34:37], v[184:187], v[200:203], v[34:37]
	v_mfma_f32_16x16x32_bf16 v[22:25], v[176:179], v[208:211], v[22:25]
	v_mfma_f32_16x16x32_bf16 v[18:21], v[184:187], v[208:211], v[18:21]
	v_mfma_f32_16x16x32_bf16 v[6:9], v[176:179], v[216:219], v[6:9]
	v_mfma_f32_16x16x32_bf16 v[2:5], v[184:187], v[216:219], v[2:5]
	s_barrier
; __device__ __forceinline__ unsigned pk2(float lo, float hi) { const f32x2 v = {lo, hi}; return __builtin_bit_cast(unsigned, __builtin_convertvector(v, bf16x2_t)); }
; __device__ __forceinline__ u32x4 ror8(u32x4 v) { u32x4 r;
; #pragma unroll
;     for (int i = 0; i < 4; ++i) r[i] = (unsigned)__builtin_amdgcn_mov_dpp((int)v[i], 0x128, 0xf, 0xf, true);
;     return r; }
; __device__ __forceinline__ void store_pair(unsigned char* own, size_t stride8, int hi_off, u32x4 lo, u32x4 hi, bool upper) {
;     const u32x4 tlo = ror8(lo), thi = ror8(hi);
;     const u32x4 A = upper ? thi : lo, B = upper ? hi : tlo;
;     unsigned char* pa = upper ? own - stride8 + hi_off : own;
;     unsigned char* pb = upper ? own + hi_off : own + stride8;
;     *(u32x4*)pa = A; *(u32x4*)pb = B;
;     __device__ __forceinline__ void operator()(const f32x4 (&acc)[2][2][4][2], const Unit& u, int wr, int wc, int fr, int fq) const {
;         const int row0 = u.pm * 256 + wr * 64 + fr, col0 = u.pn * 256 + wc * 64 + 8 * fq;
;         bf16_t* base = u.part == 0 ? Z + (size_t)row0 * D + col0 : P + ((size_t)(u.part - 1) * MS + (row0 - MP)) * D + col0;
; #pragma unroll
;         for (int ai = 0; ai < 2; ++ai)
; #pragma unroll
;             for (int m = 0; m < 4; ++m) { u32x4 w[2];
; #pragma unroll
;                 for (int bj = 0; bj < 2; ++bj) { const f32x4 v0 = acc[ai][bj][m][0], v1 = acc[ai][bj][m][1]; w[bj].x = pk2(v0[0], v0[1]); w[bj].y = pk2(v0[2], v0[3]); w[bj].z = pk2(v1[0], v1[1]); w[bj].w = pk2(v1[2], v1[3]); }
;                 store_pair((unsigned char*)(base + (size_t)(ai * 128 + m * 16) * D), (size_t)8 * D * 2, 64, w[0], w[1], fr >= 8); }
;     }
	s_add_u32 s52, s52, 0x10000
	s_addc_u32 s53, s53, 0
	s_add_u32 s26, s26, 0x100
	s_addc_u32 s27, s27, 0
	s_cmp_ge_u32 s57, s47
	s_cbranch_scc0 .LBB0_1716
	v_lshl_add_u32 v147, s48, 8, v1
	v_add_u32_e32 v148, 0xffffe000, v147
	v_sub_co_u32_e64 v146, vcc, s46, 1
	v_mov_b32_e32 v149, s91
	s_nop 0
	v_cndmask_b32_e32 v148, v148, v147, vcc
	v_ashrrev_i32_e32 v147, 31, v146
	v_lshlrev_b64 v[146:147], 23, v[146:147]
	v_lshl_add_u64 v[146:147], s[12:13], 0, v[146:147]
	v_cndmask_b32_e32 v147, v147, v149, vcc
	v_mov_b32_e32 v149, s90
	v_cndmask_b32_e32 v146, v146, v149, vcc
	v_ashrrev_i32_e32 v149, 31, v148
	v_lshl_or_b32 v156, s78, 8, v151
	v_lshlrev_b64 v[148:149], 12, v[148:149]
	v_lshl_add_u64 v[146:147], v[146:147], 0, v[148:149]
	v_ashrrev_i32_e32 v157, 31, v156
	v_cvt_pk_bf16_f32 v126, v126, v127
	v_cvt_pk_bf16_f32 v127, v128, v129
	v_cvt_pk_bf16_f32 v128, v122, v123
	v_cvt_pk_bf16_f32 v124, v124, v125
	v_cvt_pk_bf16_f32 v118, v118, v119
	v_cvt_pk_bf16_f32 v119, v120, v121
	v_cvt_pk_bf16_f32 v114, v114, v115
	v_cvt_pk_bf16_f32 v115, v116, v117
	v_lshl_add_u64 v[146:147], v[156:157], 1, v[146:147]
	s_mov_b64 vcc, s[8:9]
	v_mov_b32_dpp v125, v118 row_ror:8 row_mask:0xf bank_mask:0xf bound_ctrl:1
	v_mov_b32_dpp v129, v119 row_ror:8 row_mask:0xf bank_mask:0xf bound_ctrl:1
	v_mov_b32_dpp v148, v114 row_ror:8 row_mask:0xf bank_mask:0xf bound_ctrl:1
	v_mov_b32_dpp v149, v115 row_ror:8 row_mask:0xf bank_mask:0xf bound_ctrl:1
	v_lshl_add_u64 v[122:123], v[146:147], 0, v[138:139]
	v_cndmask_b32_dpp v117, v124, v115, vcc row_ror:8 row_mask:0xf bank_mask:0xf bound_ctrl:1
	v_cndmask_b32_dpp v116, v128, v114, vcc row_ror:8 row_mask:0xf bank_mask:0xf bound_ctrl:1
	v_cndmask_b32_dpp v115, v127, v119, vcc row_ror:8 row_mask:0xf bank_mask:0xf bound_ctrl:1
	v_cndmask_b32_dpp v114, v126, v118, vcc row_ror:8 row_mask:0xf bank_mask:0xf bound_ctrl:1
	v_cndmask_b32_e64 v121, v124, v149, s[8:9]
	v_cndmask_b32_e64 v120, v128, v148, s[8:9]
	v_cndmask_b32_e64 v119, v127, v129, s[8:9]
	v_cndmask_b32_e64 v118, v126, v125, s[8:9]
	v_cvt_pk_bf16_f32 v110, v110, v111
	v_cvt_pk_bf16_f32 v111, v112, v113
	v_cvt_pk_bf16_f32 v112, v106, v107
	v_cvt_pk_bf16_f32 v113, v108, v109
	v_cvt_pk_bf16_f32 v102, v102, v103
	v_cvt_pk_bf16_f32 v103, v104, v105
	v_cvt_pk_bf16_f32 v98, v98, v99
	v_cvt_pk_bf16_f32 v99, v100, v101
	s_mov_b64 s[4:5], 0x10000
	v_lshl_add_u64 v[124:125], v[146:147], 0, v[140:141]
	s_and_b64 vcc, exec, s[6:7]
	s_cbranch_vccz .LBB0_1719
	s_barrier
.LBB0_1719:
	global_store_dwordx4 v[122:123], v[118:121], off
	global_store_dwordx4 v[124:125], v[114:117], off
	v_lshl_add_u64 v[106:107], v[146:147], 0, s[4:5]
	s_mov_b64 vcc, s[8:9]
	v_mov_b32_dpp v114, v102 row_ror:8 row_mask:0xf bank_mask:0xf bound_ctrl:1
	v_mov_b32_dpp v115, v103 row_ror:8 row_mask:0xf bank_mask:0xf bound_ctrl:1
	v_mov_b32_dpp v116, v98 row_ror:8 row_mask:0xf bank_mask:0xf bound_ctrl:1
	v_mov_b32_dpp v117, v99 row_ror:8 row_mask:0xf bank_mask:0xf bound_ctrl:1
	v_lshl_add_u64 v[108:109], v[106:107], 0, v[138:139]
	v_cndmask_b32_dpp v101, v113, v99, vcc row_ror:8 row_mask:0xf bank_mask:0xf bound_ctrl:1
	v_cndmask_b32_dpp v100, v112, v98, vcc row_ror:8 row_mask:0xf bank_mask:0xf bound_ctrl:1
	v_cndmask_b32_dpp v99, v111, v103, vcc row_ror:8 row_mask:0xf bank_mask:0xf bound_ctrl:1
	v_cndmask_b32_dpp v98, v110, v102, vcc row_ror:8 row_mask:0xf bank_mask:0xf bound_ctrl:1
	v_cndmask_b32_e64 v105, v113, v117, s[8:9]
	v_cndmask_b32_e64 v104, v112, v116, s[8:9]
	v_cndmask_b32_e64 v103, v111, v115, s[8:9]
	v_cndmask_b32_e64 v102, v110, v114, s[8:9]
	v_cvt_pk_bf16_f32 v94, v94, v95
	v_cvt_pk_bf16_f32 v95, v96, v97
	v_cvt_pk_bf16_f32 v96, v90, v91
	v_cvt_pk_bf16_f32 v97, v92, v93
	v_cvt_pk_bf16_f32 v86, v86, v87
	v_cvt_pk_bf16_f32 v87, v88, v89
	v_cvt_pk_bf16_f32 v82, v82, v83
	v_cvt_pk_bf16_f32 v83, v84, v85
	s_mov_b64 s[4:5], 0x20000
	v_lshl_add_u64 v[106:107], v[106:107], 0, v[140:141]
	global_store_dwordx4 v[108:109], v[102:105], off
	global_store_dwordx4 v[106:107], v[98:101], off
	v_lshl_add_u64 v[90:91], v[146:147], 0, s[4:5]
	s_mov_b64 vcc, s[8:9]
	v_mov_b32_dpp v98, v86 row_ror:8 row_mask:0xf bank_mask:0xf bound_ctrl:1
	v_mov_b32_dpp v99, v87 row_ror:8 row_mask:0xf bank_mask:0xf bound_ctrl:1
	v_mov_b32_dpp v100, v82 row_ror:8 row_mask:0xf bank_mask:0xf bound_ctrl:1
	v_mov_b32_dpp v101, v83 row_ror:8 row_mask:0xf bank_mask:0xf bound_ctrl:1
	v_lshl_add_u64 v[92:93], v[90:91], 0, v[138:139]
	v_cndmask_b32_dpp v85, v97, v83, vcc row_ror:8 row_mask:0xf bank_mask:0xf bound_ctrl:1
	v_cndmask_b32_dpp v84, v96, v82, vcc row_ror:8 row_mask:0xf bank_mask:0xf bound_ctrl:1
	v_cndmask_b32_dpp v83, v95, v87, vcc row_ror:8 row_mask:0xf bank_mask:0xf bound_ctrl:1
	v_cndmask_b32_dpp v82, v94, v86, vcc row_ror:8 row_mask:0xf bank_mask:0xf bound_ctrl:1
	v_cndmask_b32_e64 v89, v97, v101, s[8:9]
	v_cndmask_b32_e64 v88, v96, v100, s[8:9]
	v_cndmask_b32_e64 v87, v95, v99, s[8:9]
	v_cndmask_b32_e64 v86, v94, v98, s[8:9]
	v_cvt_pk_bf16_f32 v78, v78, v79
	v_cvt_pk_bf16_f32 v79, v80, v81
	v_cvt_pk_bf16_f32 v80, v74, v75
	v_cvt_pk_bf16_f32 v81, v76, v77
	v_cvt_pk_bf16_f32 v70, v70, v71
	v_cvt_pk_bf16_f32 v71, v72, v73
	v_cvt_pk_bf16_f32 v66, v66, v67
	v_cvt_pk_bf16_f32 v67, v68, v69
	s_mov_b64 s[4:5], 0x30000
	v_lshl_add_u64 v[90:91], v[90:91], 0, v[140:141]
	global_store_dwordx4 v[92:93], v[86:89], off
	global_store_dwordx4 v[90:91], v[82:85], off
	v_lshl_add_u64 v[74:75], v[146:147], 0, s[4:5]
	s_mov_b64 vcc, s[8:9]
	v_mov_b32_dpp v82, v70 row_ror:8 row_mask:0xf bank_mask:0xf bound_ctrl:1
	v_mov_b32_dpp v83, v71 row_ror:8 row_mask:0xf bank_mask:0xf bound_ctrl:1
	v_mov_b32_dpp v84, v66 row_ror:8 row_mask:0xf bank_mask:0xf bound_ctrl:1
; __device__ __forceinline__ unsigned pk2(float lo, float hi) { const f32x2 v = {lo, hi}; return __builtin_bit_cast(unsigned, __builtin_convertvector(v, bf16x2_t)); }
; #define PG8_BAR __builtin_amdgcn_s_barrier()
; template <class Epi, class Sched, bool ABLK = false, bool ALIGN_EPI = true, bool SP2 = true, bool BBLK = true>
; __device__ __forceinline__ void gemm_phase(LAS unsigned char* lds, const Gemm g, const Sched& S, const Epi& E) {
;     ...
;         if (!has_next) break;
; #pragma unroll
;         for (int a = 0; a < 2; ++a)
; #pragma unroll
;             for (int b = 0; b < 2; ++b)
; #pragma unroll
;                 for (int m = 0; m < 4; ++m)
; #pragma unroll
;                     for (int n = 0; n < 2; ++n) acc[a][b][m][n] = (f32x4){0.f, 0.f, 0.f, 0.f};
;         cur = nxt; uA = nuA; tbA = ntbA; cB = nB; ++ui;
;         if constexpr (ALIGN_EPI) { if (wr == 1) PG8_BAR; }
;     __device__ __forceinline__ void operator()(const f32x4 (&acc)[2][2][4][2], const Unit& u, int wr, int wc, int fr, int fq) const {
;         const int row0 = u.pm * 256 + wr * 64 + fr, col0 = u.pn * 256 + wc * 64 + 8 * fq;
;         bf16_t* base = u.part == 0 ? Z + (size_t)row0 * D + col0 : P + ((size_t)(u.part - 1) * MS + (row0 - MP)) * D + col0;
; #pragma unroll
;         for (int ai = 0; ai < 2; ++ai)
; #pragma unroll
;             for (int m = 0; m < 4; ++m) { u32x4 w[2];
; #pragma unroll
;                 for (int bj = 0; bj < 2; ++bj) { const f32x4 v0 = acc[ai][bj][m][0], v1 = acc[ai][bj][m][1]; w[bj].x = pk2(v0[0], v0[1]); w[bj].y = pk2(v0[2], v0[3]); w[bj].z = pk2(v1[0], v1[1]); w[bj].w = pk2(v1[2], v1[3]); }
;                 store_pair((unsigned char*)(base + (size_t)(ai * 128 + m * 16) * D), (size_t)8 * D * 2, 64, w[0], w[1], fr >= 8); }
;     }
	v_mov_b32_dpp v85, v67 row_ror:8 row_mask:0xf bank_mask:0xf bound_ctrl:1
	v_lshl_add_u64 v[76:77], v[74:75], 0, v[138:139]
	v_cndmask_b32_dpp v69, v81, v67, vcc row_ror:8 row_mask:0xf bank_mask:0xf bound_ctrl:1
	v_cndmask_b32_dpp v68, v80, v66, vcc row_ror:8 row_mask:0xf bank_mask:0xf bound_ctrl:1
	v_cndmask_b32_dpp v67, v79, v71, vcc row_ror:8 row_mask:0xf bank_mask:0xf bound_ctrl:1
	v_cndmask_b32_dpp v66, v78, v70, vcc row_ror:8 row_mask:0xf bank_mask:0xf bound_ctrl:1
	v_cndmask_b32_e64 v73, v81, v85, s[8:9]
	v_cndmask_b32_e64 v72, v80, v84, s[8:9]
	v_cndmask_b32_e64 v71, v79, v83, s[8:9]
	v_cndmask_b32_e64 v70, v78, v82, s[8:9]
	v_cvt_pk_bf16_f32 v62, v62, v63
	v_cvt_pk_bf16_f32 v63, v64, v65
	v_cvt_pk_bf16_f32 v64, v58, v59
	v_cvt_pk_bf16_f32 v65, v60, v61
	v_cvt_pk_bf16_f32 v54, v54, v55
	v_cvt_pk_bf16_f32 v55, v56, v57
	v_cvt_pk_bf16_f32 v50, v50, v51
	v_cvt_pk_bf16_f32 v51, v52, v53
	s_mov_b64 s[4:5], 0x80000
	v_lshl_add_u64 v[74:75], v[74:75], 0, v[140:141]
	global_store_dwordx4 v[76:77], v[70:73], off
	global_store_dwordx4 v[74:75], v[66:69], off
	v_lshl_add_u64 v[58:59], v[146:147], 0, s[4:5]
	s_mov_b64 vcc, s[8:9]
	v_mov_b32_dpp v66, v54 row_ror:8 row_mask:0xf bank_mask:0xf bound_ctrl:1
	v_mov_b32_dpp v67, v55 row_ror:8 row_mask:0xf bank_mask:0xf bound_ctrl:1
	v_mov_b32_dpp v68, v50 row_ror:8 row_mask:0xf bank_mask:0xf bound_ctrl:1
	v_mov_b32_dpp v69, v51 row_ror:8 row_mask:0xf bank_mask:0xf bound_ctrl:1
	v_lshl_add_u64 v[60:61], v[58:59], 0, v[138:139]
	v_cndmask_b32_dpp v53, v65, v51, vcc row_ror:8 row_mask:0xf bank_mask:0xf bound_ctrl:1
	v_cndmask_b32_dpp v52, v64, v50, vcc row_ror:8 row_mask:0xf bank_mask:0xf bound_ctrl:1
	v_cndmask_b32_dpp v51, v63, v55, vcc row_ror:8 row_mask:0xf bank_mask:0xf bound_ctrl:1
	v_cndmask_b32_dpp v50, v62, v54, vcc row_ror:8 row_mask:0xf bank_mask:0xf bound_ctrl:1
	v_cndmask_b32_e64 v57, v65, v69, s[8:9]
	v_cndmask_b32_e64 v56, v64, v68, s[8:9]
	v_cndmask_b32_e64 v55, v63, v67, s[8:9]
	v_cndmask_b32_e64 v54, v62, v66, s[8:9]
	v_cvt_pk_bf16_f32 v46, v46, v47
	v_cvt_pk_bf16_f32 v47, v48, v49
	v_cvt_pk_bf16_f32 v48, v42, v43
	v_cvt_pk_bf16_f32 v49, v44, v45
	v_cvt_pk_bf16_f32 v38, v38, v39
	v_cvt_pk_bf16_f32 v39, v40, v41
	v_cvt_pk_bf16_f32 v34, v34, v35
	v_cvt_pk_bf16_f32 v35, v36, v37
	v_lshl_add_u64 v[58:59], v[58:59], 0, v[140:141]
	global_store_dwordx4 v[60:61], v[54:57], off
	global_store_dwordx4 v[58:59], v[50:53], off
	v_lshl_add_u64 v[42:43], v[146:147], 0, s[14:15]
	s_mov_b64 vcc, s[8:9]
	v_mov_b32_dpp v50, v38 row_ror:8 row_mask:0xf bank_mask:0xf bound_ctrl:1
	v_mov_b32_dpp v51, v39 row_ror:8 row_mask:0xf bank_mask:0xf bound_ctrl:1
	v_mov_b32_dpp v52, v34 row_ror:8 row_mask:0xf bank_mask:0xf bound_ctrl:1
	v_mov_b32_dpp v53, v35 row_ror:8 row_mask:0xf bank_mask:0xf bound_ctrl:1
	v_lshl_add_u64 v[44:45], v[42:43], 0, v[138:139]
	v_cndmask_b32_dpp v37, v49, v35, vcc row_ror:8 row_mask:0xf bank_mask:0xf bound_ctrl:1
	v_cndmask_b32_dpp v36, v48, v34, vcc row_ror:8 row_mask:0xf bank_mask:0xf bound_ctrl:1
	v_cndmask_b32_dpp v35, v47, v39, vcc row_ror:8 row_mask:0xf bank_mask:0xf bound_ctrl:1
	v_cndmask_b32_dpp v34, v46, v38, vcc row_ror:8 row_mask:0xf bank_mask:0xf bound_ctrl:1
	v_cndmask_b32_e64 v41, v49, v53, s[8:9]
	v_cndmask_b32_e64 v40, v48, v52, s[8:9]
	v_cndmask_b32_e64 v39, v47, v51, s[8:9]
	v_cndmask_b32_e64 v38, v46, v50, s[8:9]
	v_cvt_pk_bf16_f32 v30, v30, v31
	v_cvt_pk_bf16_f32 v31, v32, v33
	v_cvt_pk_bf16_f32 v32, v26, v27
	v_cvt_pk_bf16_f32 v33, v28, v29
	v_cvt_pk_bf16_f32 v22, v22, v23
	v_cvt_pk_bf16_f32 v23, v24, v25
	v_cvt_pk_bf16_f32 v18, v18, v19
	v_cvt_pk_bf16_f32 v19, v20, v21
	v_lshl_add_u64 v[42:43], v[42:43], 0, v[140:141]
	global_store_dwordx4 v[44:45], v[38:41], off
	global_store_dwordx4 v[42:43], v[34:37], off
	v_lshl_add_u64 v[26:27], v[146:147], 0, s[16:17]
	s_mov_b64 vcc, s[8:9]
	v_mov_b32_dpp v34, v22 row_ror:8 row_mask:0xf bank_mask:0xf bound_ctrl:1
	v_mov_b32_dpp v35, v23 row_ror:8 row_mask:0xf bank_mask:0xf bound_ctrl:1
	v_mov_b32_dpp v36, v18 row_ror:8 row_mask:0xf bank_mask:0xf bound_ctrl:1
	v_mov_b32_dpp v37, v19 row_ror:8 row_mask:0xf bank_mask:0xf bound_ctrl:1
	v_lshl_add_u64 v[28:29], v[26:27], 0, v[138:139]
	v_cndmask_b32_dpp v21, v33, v19, vcc row_ror:8 row_mask:0xf bank_mask:0xf bound_ctrl:1
	v_cndmask_b32_dpp v20, v32, v18, vcc row_ror:8 row_mask:0xf bank_mask:0xf bound_ctrl:1
	v_cndmask_b32_dpp v19, v31, v23, vcc row_ror:8 row_mask:0xf bank_mask:0xf bound_ctrl:1
	v_cndmask_b32_dpp v18, v30, v22, vcc row_ror:8 row_mask:0xf bank_mask:0xf bound_ctrl:1
	v_cndmask_b32_e64 v25, v33, v37, s[8:9]
	v_cndmask_b32_e64 v24, v32, v36, s[8:9]
	v_cndmask_b32_e64 v23, v31, v35, s[8:9]
	v_cndmask_b32_e64 v22, v30, v34, s[8:9]
	v_cvt_pk_bf16_f32 v14, v14, v15
	v_cvt_pk_bf16_f32 v15, v16, v17
	v_cvt_pk_bf16_f32 v16, v10, v11
	v_cvt_pk_bf16_f32 v17, v12, v13
	v_cvt_pk_bf16_f32 v6, v6, v7
	v_cvt_pk_bf16_f32 v7, v8, v9
	v_cvt_pk_bf16_f32 v2, v2, v3
	v_cvt_pk_bf16_f32 v3, v4, v5
	v_lshl_add_u64 v[26:27], v[26:27], 0, v[140:141]
	global_store_dwordx4 v[28:29], v[22:25], off
	global_store_dwordx4 v[26:27], v[18:21], off
	v_lshl_add_u64 v[10:11], v[146:147], 0, s[18:19]
	s_mov_b64 vcc, s[8:9]
	v_mov_b32_dpp v18, v6 row_ror:8 row_mask:0xf bank_mask:0xf bound_ctrl:1
	v_mov_b32_dpp v19, v7 row_ror:8 row_mask:0xf bank_mask:0xf bound_ctrl:1
	v_mov_b32_dpp v20, v2 row_ror:8 row_mask:0xf bank_mask:0xf bound_ctrl:1
	v_mov_b32_dpp v21, v3 row_ror:8 row_mask:0xf bank_mask:0xf bound_ctrl:1
	v_lshl_add_u64 v[12:13], v[10:11], 0, v[138:139]
	v_cndmask_b32_dpp v5, v17, v3, vcc row_ror:8 row_mask:0xf bank_mask:0xf bound_ctrl:1
	v_cndmask_b32_dpp v4, v16, v2, vcc row_ror:8 row_mask:0xf bank_mask:0xf bound_ctrl:1
	v_cndmask_b32_dpp v3, v15, v7, vcc row_ror:8 row_mask:0xf bank_mask:0xf bound_ctrl:1
	v_cndmask_b32_dpp v2, v14, v6, vcc row_ror:8 row_mask:0xf bank_mask:0xf bound_ctrl:1
	v_cndmask_b32_e64 v9, v17, v21, s[8:9]
	v_cndmask_b32_e64 v8, v16, v20, s[8:9]
	v_cndmask_b32_e64 v7, v15, v19, s[8:9]
	v_cndmask_b32_e64 v6, v14, v18, s[8:9]
	s_and_b64 vcc, exec, s[10:11]
	s_mov_b64 s[10:11], -1
	v_lshl_add_u64 v[10:11], v[10:11], 0, v[140:141]
	global_store_dwordx4 v[12:13], v[6:9], off
	global_store_dwordx4 v[10:11], v[2:5], off
	s_cbranch_vccnz .LBB0_1714
	s_andn2_b64 vcc, exec, s[2:3]
	s_cbranch_vccnz .LBB0_1713
	s_barrier
	s_branch .LBB0_1713

; #define PG8_STAGE(bufoff, gbase, voff) do { _Pragma("unroll") for (int _i = 0; _i < 2; ++_i) \
;         __builtin_amdgcn_global_load_lds((const unsigned*)((const char*)(gbase) + (voff)[_i]), (LAS unsigned*)(lds + (bufoff) + ldsw + _i * 8192), 16, 0, 0); } while (0)
; #define PG8_LDA(dst, b, h) do { _Pragma("unroll") for (int m = 0; m < 4; ++m) _Pragma("unroll") for (int k = 0; k < 2; ++k) dst[m][k] = *(const LAS bf16x8*)(lds + PG8_SA(b, h) + aoff + m * 2048 + k * 1024); } while (0)
; #define PG8_LDB(dst, b, h) do { _Pragma("unroll") for (int n = 0; n < 2; ++n) _Pragma("unroll") for (int k = 0; k < 2; ++k) dst[n][k] = *(const LAS bf16x8*)(lds + PG8_SB(b, h) + boff + n * 2048 + k * 1024); } while (0)
; #define PG8_MMA(ai, bj, At, Bt) do { __builtin_amdgcn_s_setprio(1); _Pragma("unroll") for (int m = 0; m < 4; ++m) _Pragma("unroll") for (int n = 0; n < 2; ++n) _Pragma("unroll") for (int k = 0; k < 2; ++k) \
;         acc[ai][bj][m][n] = __builtin_amdgcn_mfma_f32_16x16x32_bf16(Bt[n][k], At[m][k], acc[ai][bj][m][n], 0, 0, 0); __builtin_amdgcn_s_setprio(0); } while (0)
; #define PG8_WAIT_V(n) asm volatile("s_waitcnt vmcnt(" #n ")" ::: "memory")
; #define PG8_WAIT_L(n) asm volatile("s_waitcnt lgkmcnt(" #n ")" ::: "memory")
; template <class Epi, class Sched, bool ABLK = false, bool ALIGN_EPI = true, bool SP2 = true, bool BBLK = true>
; __device__ __forceinline__ void gemm_phase(LAS unsigned char* lds, const Gemm g, const Sched& S, const Epi& E) {
;     ...
;             const char* a1 = a_tile(uA, tbA + t + 1);
;             const char* a2 = last ? a_tile(nuA, ntbA) : a_tile(uA, tbA + t + 2); const char* b2 = last ? nB : cB + (size_t)(t + 2) * kstepB;
;             const char* a3 = last ? a_tile(nuA, ntbA + 1) : a_tile(uA, tbA + t + 3); const char* b3 = b2 + kstepB;
;             if (last && has_next) S.a_ready(nxt);
;             if constexpr (SP2) {
;             PG8_LDB(B0, 0, 0); PG8_LDB(B1, 0, 1); PG8_SCHED; PG8_LDA(At, 0, 0); PG8_STAGE(PG8_SA(1, 1), a1 + hstepA, voffA);
;             PG8_WAIT_V(8); PG8_WAIT_L(0); PG8_BAR; PG8_MMA(0, 0, At, B0); PG8_MMA(0, 1, At, B1); PG8_BAR; PG8_SCHED;
;             PG8_LDA(At, 0, 1); PG8_STAGE(PG8_SB(0, 0), b2, voffB); PG8_STAGE(PG8_SB(0, 1), b2 + hstepB, voffB); PG8_STAGE(PG8_SA(0, 0), a2, voffA);
;             PG8_WAIT_V(8); PG8_WAIT_L(0); PG8_BAR; PG8_MMA(1, 0, At, B0); PG8_MMA(1, 1, At, B1); PG8_BAR; PG8_SCHED;
.Lksel_19_back:
	s_mov_b32 m0, s47
	v_lshl_add_u64 v[236:237], v[164:165], 0, s[28:29]
	ds_read_b128 v[204:207], v170
	ds_read_b128 v[208:211], v170 offset:1024
	ds_read_b128 v[212:215], v170 offset:2048
	ds_read_b128 v[216:219], v170 offset:3072
	ds_read_b128 v[220:223], v170 offset:4096
	ds_read_b128 v[224:227], v170 offset:5120
	ds_read_b128 v[228:231], v170 offset:6144
	ds_read_b128 v[232:235], v170 offset:7168
	global_load_lds_dwordx4 v[236:237], off
	v_lshl_add_u64 v[236:237], v[166:167], 0, s[28:29]
	s_mov_b32 m0, s48
	s_nop 0
	global_load_lds_dwordx4 v[236:237], off
	s_waitcnt vmcnt(8) lgkmcnt(0)
	s_barrier
	v_mfma_f32_16x16x32_bf16 v[126:129], v[172:175], v[204:207], v[126:129]
	v_mfma_f32_16x16x32_bf16 v[122:125], v[180:183], v[204:207], v[122:125]
	v_mfma_f32_16x16x32_bf16 v[110:113], v[172:175], v[212:215], v[110:113]
	v_mfma_f32_16x16x32_bf16 v[106:109], v[180:183], v[212:215], v[106:109]
	v_mfma_f32_16x16x32_bf16 v[94:97], v[172:175], v[220:223], v[94:97]
	v_mfma_f32_16x16x32_bf16 v[90:93], v[180:183], v[220:223], v[90:93]
	v_mfma_f32_16x16x32_bf16 v[78:81], v[172:175], v[228:231], v[78:81]
	v_mfma_f32_16x16x32_bf16 v[74:77], v[180:183], v[228:231], v[74:77]
	v_mfma_f32_16x16x32_bf16 v[126:129], v[176:179], v[208:211], v[126:129]
	v_mfma_f32_16x16x32_bf16 v[122:125], v[184:187], v[208:211], v[122:125]
	v_mfma_f32_16x16x32_bf16 v[110:113], v[176:179], v[216:219], v[110:113]
	v_mfma_f32_16x16x32_bf16 v[106:109], v[184:187], v[216:219], v[106:109]
	v_mfma_f32_16x16x32_bf16 v[94:97], v[176:179], v[224:227], v[94:97]
	v_mfma_f32_16x16x32_bf16 v[90:93], v[184:187], v[224:227], v[90:93]
	v_mfma_f32_16x16x32_bf16 v[78:81], v[176:179], v[232:235], v[78:81]
	v_mfma_f32_16x16x32_bf16 v[74:77], v[184:187], v[232:235], v[74:77]
	v_mfma_f32_16x16x32_bf16 v[118:121], v[188:191], v[204:207], v[118:121]
	v_mfma_f32_16x16x32_bf16 v[114:117], v[196:199], v[204:207], v[114:117]
	v_mfma_f32_16x16x32_bf16 v[102:105], v[188:191], v[212:215], v[102:105]
	v_mfma_f32_16x16x32_bf16 v[98:101], v[196:199], v[212:215], v[98:101]
	v_mfma_f32_16x16x32_bf16 v[86:89], v[188:191], v[220:223], v[86:89]
	v_mfma_f32_16x16x32_bf16 v[82:85], v[196:199], v[220:223], v[82:85]
	v_mfma_f32_16x16x32_bf16 v[70:73], v[188:191], v[228:231], v[70:73]
	v_mfma_f32_16x16x32_bf16 v[66:69], v[196:199], v[228:231], v[66:69]
	v_mfma_f32_16x16x32_bf16 v[118:121], v[192:195], v[208:211], v[118:121]
	v_mfma_f32_16x16x32_bf16 v[114:117], v[200:203], v[208:211], v[114:117]
	v_mfma_f32_16x16x32_bf16 v[102:105], v[192:195], v[216:219], v[102:105]
	v_mfma_f32_16x16x32_bf16 v[98:101], v[200:203], v[216:219], v[98:101]
	v_mfma_f32_16x16x32_bf16 v[86:89], v[192:195], v[224:227], v[86:89]
	v_mfma_f32_16x16x32_bf16 v[82:85], v[200:203], v[224:227], v[82:85]
	v_mfma_f32_16x16x32_bf16 v[70:73], v[192:195], v[232:235], v[70:73]
	v_mfma_f32_16x16x32_bf16 v[66:69], v[200:203], v[232:235], v[66:69]
	s_barrier
	s_mov_b32 m0, s49
	s_add_u32 s56, s34, 0x4000
	ds_read_b128 v[204:207], v170 offset:16384
	ds_read_b128 v[208:211], v170 offset:17408
	ds_read_b128 v[212:215], v170 offset:18432
	ds_read_b128 v[216:219], v170 offset:19456
	ds_read_b128 v[220:223], v170 offset:20480
	ds_read_b128 v[224:227], v170 offset:21504
	ds_read_b128 v[228:231], v170 offset:22528
	ds_read_b128 v[232:235], v170 offset:23552
	global_load_lds_dwordx4 v134, s[34:35]
	s_mov_b32 m0, s50
	s_addc_u32 s57, s35, 0
	s_add_i32 s55, s73, s39
	global_load_lds_dwordx4 v130, s[34:35]
	s_mov_b32 m0, s55
	s_nop 0
	global_load_lds_dwordx4 v134, s[56:57]
	s_add_i32 m0, s55, 0x2000
	s_nop 0
	global_load_lds_dwordx4 v130, s[56:57]
	s_mov_b32 m0, s25
	s_nop 0
	global_load_lds_dwordx4 v136, s[36:37]
	s_mov_b32 m0, s40
	s_nop 0
	global_load_lds_dwordx4 v132, s[36:37]
	s_waitcnt vmcnt(8) lgkmcnt(0)
	s_barrier
	v_mfma_f32_16x16x32_bf16 v[62:65], v[172:175], v[204:207], v[62:65]
	v_mfma_f32_16x16x32_bf16 v[58:61], v[180:183], v[204:207], v[58:61]
	v_mfma_f32_16x16x32_bf16 v[46:49], v[172:175], v[212:215], v[46:49]
	v_mfma_f32_16x16x32_bf16 v[42:45], v[180:183], v[212:215], v[42:45]
	v_mfma_f32_16x16x32_bf16 v[30:33], v[172:175], v[220:223], v[30:33]
	v_mfma_f32_16x16x32_bf16 v[26:29], v[180:183], v[220:223], v[26:29]
	v_mfma_f32_16x16x32_bf16 v[14:17], v[172:175], v[228:231], v[14:17]
	v_mfma_f32_16x16x32_bf16 v[10:13], v[180:183], v[228:231], v[10:13]
	v_mfma_f32_16x16x32_bf16 v[62:65], v[176:179], v[208:211], v[62:65]
	v_mfma_f32_16x16x32_bf16 v[58:61], v[184:187], v[208:211], v[58:61]
	v_mfma_f32_16x16x32_bf16 v[46:49], v[176:179], v[216:219], v[46:49]
	v_mfma_f32_16x16x32_bf16 v[42:45], v[184:187], v[216:219], v[42:45]
	v_mfma_f32_16x16x32_bf16 v[30:33], v[176:179], v[224:227], v[30:33]
	v_mfma_f32_16x16x32_bf16 v[26:29], v[184:187], v[224:227], v[26:29]
	v_mfma_f32_16x16x32_bf16 v[14:17], v[176:179], v[232:235], v[14:17]
	v_mfma_f32_16x16x32_bf16 v[10:13], v[184:187], v[232:235], v[10:13]
	v_mfma_f32_16x16x32_bf16 v[54:57], v[188:191], v[204:207], v[54:57]
	v_mfma_f32_16x16x32_bf16 v[50:53], v[196:199], v[204:207], v[50:53]
	v_mfma_f32_16x16x32_bf16 v[38:41], v[188:191], v[212:215], v[38:41]
	v_mfma_f32_16x16x32_bf16 v[34:37], v[196:199], v[212:215], v[34:37]
	v_mfma_f32_16x16x32_bf16 v[22:25], v[188:191], v[220:223], v[22:25]
	v_mfma_f32_16x16x32_bf16 v[18:21], v[196:199], v[220:223], v[18:21]
	v_mfma_f32_16x16x32_bf16 v[6:9], v[188:191], v[228:231], v[6:9]
	v_mfma_f32_16x16x32_bf16 v[2:5], v[196:199], v[228:231], v[2:5]
	v_mfma_f32_16x16x32_bf16 v[54:57], v[192:195], v[208:211], v[54:57]
	v_mfma_f32_16x16x32_bf16 v[50:53], v[200:203], v[208:211], v[50:53]
	v_mfma_f32_16x16x32_bf16 v[38:41], v[192:195], v[216:219], v[38:41]
	v_mfma_f32_16x16x32_bf16 v[34:37], v[200:203], v[216:219], v[34:37]
	v_mfma_f32_16x16x32_bf16 v[22:25], v[192:195], v[224:227], v[22:25]
	v_mfma_f32_16x16x32_bf16 v[18:21], v[200:203], v[224:227], v[18:21]
	v_mfma_f32_16x16x32_bf16 v[6:9], v[192:195], v[232:235], v[6:9]
	v_mfma_f32_16x16x32_bf16 v[2:5], v[200:203], v[232:235], v[2:5]
	s_barrier
; #define PG8_STAGE(bufoff, gbase, voff) do { _Pragma("unroll") for (int _i = 0; _i < 2; ++_i) \
;         __builtin_amdgcn_global_load_lds((const unsigned*)((const char*)(gbase) + (voff)[_i]), (LAS unsigned*)(lds + (bufoff) + ldsw + _i * 8192), 16, 0, 0); } while (0)
; #define PG8_LDA(dst, b, h) do { _Pragma("unroll") for (int m = 0; m < 4; ++m) _Pragma("unroll") for (int k = 0; k < 2; ++k) dst[m][k] = *(const LAS bf16x8*)(lds + PG8_SA(b, h) + aoff + m * 2048 + k * 1024); } while (0)
; #define PG8_LDB(dst, b, h) do { _Pragma("unroll") for (int n = 0; n < 2; ++n) _Pragma("unroll") for (int k = 0; k < 2; ++k) dst[n][k] = *(const LAS bf16x8*)(lds + PG8_SB(b, h) + boff + n * 2048 + k * 1024); } while (0)
; #define PG8_MMA(ai, bj, At, Bt) do { __builtin_amdgcn_s_setprio(1); _Pragma("unroll") for (int m = 0; m < 4; ++m) _Pragma("unroll") for (int n = 0; n < 2; ++n) _Pragma("unroll") for (int k = 0; k < 2; ++k) \
;         acc[ai][bj][m][n] = __builtin_amdgcn_mfma_f32_16x16x32_bf16(Bt[n][k], At[m][k], acc[ai][bj][m][n], 0, 0, 0); __builtin_amdgcn_s_setprio(0); } while (0)
; #define PG8_WAIT_V(n) asm volatile("s_waitcnt vmcnt(" #n ")" ::: "memory")
; #define PG8_WAIT_L(n) asm volatile("s_waitcnt lgkmcnt(" #n ")" ::: "memory")
; #define PG8_BAR __builtin_amdgcn_s_barrier()
; #define PG8_SCHED __builtin_amdgcn_sched_barrier(0)
; template <class Epi, class Sched, bool ABLK = false, bool ALIGN_EPI = true, bool SP2 = true, bool BBLK = true>
; __device__ __forceinline__ void gemm_phase(LAS unsigned char* lds, const Gemm g, const Sched& S, const Epi& E) {
;     ...
;             PG8_LDB(B0, 1, 0); PG8_LDB(B1, 1, 1); PG8_SCHED; PG8_LDA(At, 1, 0); PG8_STAGE(PG8_SA(0, 1), a2 + hstepA, voffA);
;             PG8_WAIT_V(8); PG8_WAIT_L(0); PG8_BAR; PG8_MMA(0, 0, At, B0); PG8_MMA(0, 1, At, B1); PG8_BAR; PG8_SCHED;
;             PG8_LDA(At, 1, 1); PG8_STAGE(PG8_SB(1, 0), b3, voffB); PG8_STAGE(PG8_SB(1, 1), b3 + hstepB, voffB); PG8_STAGE(PG8_SA(1, 0), a3, voffA);
	v_add_u32_e32 v171, s60, v1
	ds_read_b128 v[172:175], v171
	ds_read_b128 v[176:179], v171 offset:1024
	ds_read_b128 v[180:183], v171 offset:2048
	ds_read_b128 v[184:187], v171 offset:3072
	v_add_u32_e32 v171, s61, v1
	ds_read_b128 v[188:191], v171
	ds_read_b128 v[192:195], v171 offset:1024
	ds_read_b128 v[196:199], v171 offset:2048
	ds_read_b128 v[200:203], v171 offset:3072
	s_add_u32 s36, s36, 0x80000
	s_addc_u32 s37, s37, 0
	s_mov_b32 m0, s41
	ds_read_b128 v[204:207], v170 offset:32768
	ds_read_b128 v[208:211], v170 offset:33792
	ds_read_b128 v[212:215], v170 offset:34816
	ds_read_b128 v[216:219], v170 offset:35840
	ds_read_b128 v[220:223], v170 offset:36864
	ds_read_b128 v[224:227], v170 offset:37888
	ds_read_b128 v[228:231], v170 offset:38912
	ds_read_b128 v[232:235], v170 offset:39936
	global_load_lds_dwordx4 v136, s[36:37]
	s_mov_b32 m0, s42
	s_nop 0
	global_load_lds_dwordx4 v132, s[36:37]
	s_waitcnt vmcnt(8) lgkmcnt(0)
	s_barrier
	v_mfma_f32_16x16x32_bf16 v[126:129], v[172:175], v[204:207], v[126:129]
	v_mfma_f32_16x16x32_bf16 v[122:125], v[180:183], v[204:207], v[122:125]
	v_mfma_f32_16x16x32_bf16 v[110:113], v[172:175], v[212:215], v[110:113]
	v_mfma_f32_16x16x32_bf16 v[106:109], v[180:183], v[212:215], v[106:109]
	v_mfma_f32_16x16x32_bf16 v[94:97], v[172:175], v[220:223], v[94:97]
	v_mfma_f32_16x16x32_bf16 v[90:93], v[180:183], v[220:223], v[90:93]
	v_mfma_f32_16x16x32_bf16 v[78:81], v[172:175], v[228:231], v[78:81]
	v_mfma_f32_16x16x32_bf16 v[74:77], v[180:183], v[228:231], v[74:77]
	v_mfma_f32_16x16x32_bf16 v[126:129], v[176:179], v[208:211], v[126:129]
	v_mfma_f32_16x16x32_bf16 v[122:125], v[184:187], v[208:211], v[122:125]
	v_mfma_f32_16x16x32_bf16 v[110:113], v[176:179], v[216:219], v[110:113]
	v_mfma_f32_16x16x32_bf16 v[106:109], v[184:187], v[216:219], v[106:109]
	v_mfma_f32_16x16x32_bf16 v[94:97], v[176:179], v[224:227], v[94:97]
	v_mfma_f32_16x16x32_bf16 v[90:93], v[184:187], v[224:227], v[90:93]
	v_mfma_f32_16x16x32_bf16 v[78:81], v[176:179], v[232:235], v[78:81]
	v_mfma_f32_16x16x32_bf16 v[74:77], v[184:187], v[232:235], v[74:77]
	v_mfma_f32_16x16x32_bf16 v[118:121], v[188:191], v[204:207], v[118:121]
	v_mfma_f32_16x16x32_bf16 v[114:117], v[196:199], v[204:207], v[114:117]
	v_mfma_f32_16x16x32_bf16 v[102:105], v[188:191], v[212:215], v[102:105]
	v_mfma_f32_16x16x32_bf16 v[98:101], v[196:199], v[212:215], v[98:101]
	v_mfma_f32_16x16x32_bf16 v[86:89], v[188:191], v[220:223], v[86:89]
	v_mfma_f32_16x16x32_bf16 v[82:85], v[196:199], v[220:223], v[82:85]
	v_mfma_f32_16x16x32_bf16 v[70:73], v[188:191], v[228:231], v[70:73]
	v_mfma_f32_16x16x32_bf16 v[66:69], v[196:199], v[228:231], v[66:69]
	v_mfma_f32_16x16x32_bf16 v[118:121], v[192:195], v[208:211], v[118:121]
	v_mfma_f32_16x16x32_bf16 v[114:117], v[200:203], v[208:211], v[114:117]
	v_mfma_f32_16x16x32_bf16 v[102:105], v[192:195], v[216:219], v[102:105]
	v_mfma_f32_16x16x32_bf16 v[98:101], v[200:203], v[216:219], v[98:101]
	v_mfma_f32_16x16x32_bf16 v[86:89], v[192:195], v[224:227], v[86:89]
	v_mfma_f32_16x16x32_bf16 v[82:85], v[200:203], v[224:227], v[82:85]
	v_mfma_f32_16x16x32_bf16 v[70:73], v[192:195], v[232:235], v[70:73]
	v_mfma_f32_16x16x32_bf16 v[66:69], v[200:203], v[232:235], v[66:69]
	s_barrier
	s_add_u32 s36, s34, 0x8000
	s_addc_u32 s37, s35, 0
	s_add_i32 s55, s60, s39
	s_mov_b32 m0, s55
	ds_read_b128 v[204:207], v170 offset:49152
	ds_read_b128 v[208:211], v170 offset:50176
	ds_read_b128 v[212:215], v170 offset:51200
	ds_read_b128 v[216:219], v170 offset:52224
	ds_read_b128 v[220:223], v170 offset:53248
	ds_read_b128 v[224:227], v170 offset:54272
	ds_read_b128 v[228:231], v170 offset:55296
	ds_read_b128 v[232:235], v170 offset:56320
	global_load_lds_dwordx4 v134, s[36:37]
	s_add_i32 m0, s55, 0x2000
	s_add_u32 s34, s34, 0xc000
	v_lshl_add_u64 v[236:237], s[36:37], 0, v[130:131]
	s_addc_u32 s35, s35, 0
	s_add_i32 s36, s61, s39
	global_load_lds_dwordx4 v[236:237], off
	s_mov_b32 m0, s36
	s_nop 0
	global_load_lds_dwordx4 v134, s[34:35]
	s_add_i32 m0, s36, 0x2000
	s_nop 0
	global_load_lds_dwordx4 v130, s[34:35]
	s_mov_b32 m0, s45
	s_nop 0
	global_load_lds_dwordx4 v136, s[30:31]
	s_mov_b32 m0, s46
	s_nop 0
	global_load_lds_dwordx4 v132, s[30:31]
	s_waitcnt vmcnt(8) lgkmcnt(0)
	s_barrier
; __device__ __forceinline__ unsigned pk2(float lo, float hi) { const f32x2 v = {lo, hi}; return __builtin_bit_cast(unsigned, __builtin_convertvector(v, bf16x2_t)); }
; #define PG8_STAGE(bufoff, gbase, voff) do { _Pragma("unroll") for (int _i = 0; _i < 2; ++_i) \
;         __builtin_amdgcn_global_load_lds((const unsigned*)((const char*)(gbase) + (voff)[_i]), (LAS unsigned*)(lds + (bufoff) + ldsw + _i * 8192), 16, 0, 0); } while (0)
; #define PG8_LDA(dst, b, h) do { _Pragma("unroll") for (int m = 0; m < 4; ++m) _Pragma("unroll") for (int k = 0; k < 2; ++k) dst[m][k] = *(const LAS bf16x8*)(lds + PG8_SA(b, h) + aoff + m * 2048 + k * 1024); } while (0)
; #define PG8_WAIT_V(n) asm volatile("s_waitcnt vmcnt(" #n ")" ::: "memory")
; #define PG8_WAIT_L(n) asm volatile("s_waitcnt lgkmcnt(" #n ")" ::: "memory")
; #define PG8_BAR __builtin_amdgcn_s_barrier()
; #define PG8_SCHED __builtin_amdgcn_sched_barrier(0)
; template <class Epi, class Sched, bool ABLK = false, bool ALIGN_EPI = true, bool SP2 = true, bool BBLK = true>
; __device__ __forceinline__ void gemm_phase(LAS unsigned char* lds, const Gemm g, const Sched& S, const Epi& E) {
;     ...
;             PG8_LDA(At, 1, 1); PG8_STAGE(PG8_SB(1, 0), b3, voffB); PG8_STAGE(PG8_SB(1, 1), b3 + hstepB, voffB); PG8_STAGE(PG8_SA(1, 0), a3, voffA);
;             PG8_WAIT_V(8); PG8_WAIT_L(0); PG8_BAR; PG8_MMA(1, 0, At, B0); PG8_MMA(1, 1, At, B1); PG8_BAR; PG8_SCHED;
;     __device__ __forceinline__ void operator()(const f32x4 (&acc)[2][2][4][2], const Unit& u, int wr, int wc, int fr, int fq) const {
; #pragma unroll
;         for (int ai = 0; ai < 2; ++ai)
; #pragma unroll
;             for (int m = 0; m < 4; ++m) { unsigned char* rowp = (unsigned char*)(H + ((size_t)(u.pm * (FF / 64) + u.pn * 4 + wc) * 256 + (wr * 64 + fr + ai * 128 + m * 16)) * 64 + 8 * fq); u32x4 w[2];
; #pragma unroll
;                 for (int bj = 0; bj < 2; ++bj) { f32x4 v0 = acc[ai][bj][m][0], v1 = acc[ai][bj][m][1];
; #pragma unroll
;                     for (int j = 0; j < 4; ++j) { const float a = fmaxf(v0[j], 0.f), b = fmaxf(v1[j], 0.f); v0[j] = a * a; v1[j] = b * b; }
;                     w[bj].x = pk2(v0[0], v0[1]); w[bj].y = pk2(v0[2], v0[3]); w[bj].z = pk2(v1[0], v1[1]); w[bj].w = pk2(v1[2], v1[3]); }
;                 store_pair(rowp, (size_t)8 * 64 * 2, 64, w[0], w[1], fr >= 8); }
	v_mfma_f32_16x16x32_bf16 v[62:65], v[172:175], v[204:207], v[62:65]
	v_mfma_f32_16x16x32_bf16 v[58:61], v[180:183], v[204:207], v[58:61]
	v_mfma_f32_16x16x32_bf16 v[46:49], v[172:175], v[212:215], v[46:49]
	v_mfma_f32_16x16x32_bf16 v[42:45], v[180:183], v[212:215], v[42:45]
	v_mfma_f32_16x16x32_bf16 v[30:33], v[172:175], v[220:223], v[30:33]
	v_mfma_f32_16x16x32_bf16 v[26:29], v[180:183], v[220:223], v[26:29]
	v_mfma_f32_16x16x32_bf16 v[14:17], v[172:175], v[228:231], v[14:17]
	v_mfma_f32_16x16x32_bf16 v[10:13], v[180:183], v[228:231], v[10:13]
	v_mfma_f32_16x16x32_bf16 v[62:65], v[176:179], v[208:211], v[62:65]
	v_mfma_f32_16x16x32_bf16 v[58:61], v[184:187], v[208:211], v[58:61]
	v_mfma_f32_16x16x32_bf16 v[46:49], v[176:179], v[216:219], v[46:49]
	v_mfma_f32_16x16x32_bf16 v[42:45], v[184:187], v[216:219], v[42:45]
	v_mfma_f32_16x16x32_bf16 v[30:33], v[176:179], v[224:227], v[30:33]
	v_mfma_f32_16x16x32_bf16 v[26:29], v[184:187], v[224:227], v[26:29]
	v_mfma_f32_16x16x32_bf16 v[14:17], v[176:179], v[232:235], v[14:17]
	v_mfma_f32_16x16x32_bf16 v[10:13], v[184:187], v[232:235], v[10:13]
	v_mfma_f32_16x16x32_bf16 v[54:57], v[188:191], v[204:207], v[54:57]
	v_mfma_f32_16x16x32_bf16 v[50:53], v[196:199], v[204:207], v[50:53]
	v_mfma_f32_16x16x32_bf16 v[38:41], v[188:191], v[212:215], v[38:41]
	v_mfma_f32_16x16x32_bf16 v[34:37], v[196:199], v[212:215], v[34:37]
	v_mfma_f32_16x16x32_bf16 v[22:25], v[188:191], v[220:223], v[22:25]
	v_mfma_f32_16x16x32_bf16 v[18:21], v[196:199], v[220:223], v[18:21]
	v_mfma_f32_16x16x32_bf16 v[6:9], v[188:191], v[228:231], v[6:9]
	v_mfma_f32_16x16x32_bf16 v[2:5], v[196:199], v[228:231], v[2:5]
	v_mfma_f32_16x16x32_bf16 v[54:57], v[192:195], v[208:211], v[54:57]
	v_mfma_f32_16x16x32_bf16 v[50:53], v[200:203], v[208:211], v[50:53]
	v_mfma_f32_16x16x32_bf16 v[38:41], v[192:195], v[216:219], v[38:41]
	v_mfma_f32_16x16x32_bf16 v[34:37], v[200:203], v[216:219], v[34:37]
	v_mfma_f32_16x16x32_bf16 v[22:25], v[192:195], v[224:227], v[22:25]
	v_mfma_f32_16x16x32_bf16 v[18:21], v[200:203], v[224:227], v[18:21]
	v_mfma_f32_16x16x32_bf16 v[6:9], v[192:195], v[232:235], v[6:9]
	v_mfma_f32_16x16x32_bf16 v[2:5], v[200:203], v[232:235], v[2:5]
	s_barrier
	s_add_i32 s54, s54, 2
	s_add_u32 s28, s28, 0x100
	s_addc_u32 s29, s29, 0
	s_add_u32 s52, s52, 0x10000
	s_addc_u32 s53, s53, 0
	s_cmp_gt_u32 s54, 29
	s_cbranch_scc0 .LBB0_1842
	s_lshl_b32 s4, s22, 7
	s_lshl_b32 s5, s24, 2
	s_add_i32 s5, s5, s4
	s_or_b32 s4, s5, s44
	s_ashr_i32 s5, s4, 31
	s_lshl_b64 s[4:5], s[4:5], 15
	s_add_u32 s22, s62, s4
	v_max_f32_e32 v126, 0, v126
	v_max_f32_e32 v122, 0, v122
	v_max_f32_e32 v127, 0, v127
	v_max_f32_e32 v123, 0, v123
	v_max_f32_e32 v128, 0, v128
	v_max_f32_e32 v124, 0, v124
	v_max_f32_e32 v129, 0, v129
	v_max_f32_e32 v125, 0, v125
	v_max_f32_e32 v118, 0, v118
	v_max_f32_e32 v114, 0, v114
	v_max_f32_e32 v119, 0, v119
	v_max_f32_e32 v115, 0, v115
	v_max_f32_e32 v120, 0, v120
	v_max_f32_e32 v116, 0, v116
	v_max_f32_e32 v121, 0, v121
	v_max_f32_e32 v117, 0, v117
	s_addc_u32 s23, s83, s5
	v_pk_mul_f32 v[126:127], v[126:127], v[126:127]
	v_pk_mul_f32 v[122:123], v[122:123], v[122:123]
	v_pk_mul_f32 v[128:129], v[128:129], v[128:129]
	v_pk_mul_f32 v[124:125], v[124:125], v[124:125]
	v_pk_mul_f32 v[118:119], v[118:119], v[118:119]
	v_pk_mul_f32 v[114:115], v[114:115], v[114:115]
	v_pk_mul_f32 v[120:121], v[120:121], v[120:121]
	v_pk_mul_f32 v[116:117], v[116:117], v[116:117]
	v_lshl_add_u64 v[164:165], s[22:23], 0, v[144:145]
	v_cvt_pk_bf16_f32 v126, v126, v127
	v_cvt_pk_bf16_f32 v127, v128, v129
	v_cvt_pk_bf16_f32 v128, v122, v123
	v_cvt_pk_bf16_f32 v129, v124, v125
	v_cvt_pk_bf16_f32 v118, v118, v119
	v_cvt_pk_bf16_f32 v119, v120, v121
	v_cvt_pk_bf16_f32 v114, v114, v115
	v_cvt_pk_bf16_f32 v115, v116, v117
	v_lshl_add_u64 v[122:123], v[164:165], 0, v[138:139]
	s_mov_b64 vcc, s[8:9]
	v_mov_b32_dpp v164, v118 row_ror:8 row_mask:0xf bank_mask:0xf bound_ctrl:1
	v_mov_b32_dpp v165, v119 row_ror:8 row_mask:0xf bank_mask:0xf bound_ctrl:1
	v_mov_b32_dpp v166, v114 row_ror:8 row_mask:0xf bank_mask:0xf bound_ctrl:1
	v_mov_b32_dpp v167, v115 row_ror:8 row_mask:0xf bank_mask:0xf bound_ctrl:1
	v_max_f32_e32 v110, 0, v110
	v_max_f32_e32 v106, 0, v106
	v_max_f32_e32 v111, 0, v111
	v_max_f32_e32 v107, 0, v107
	v_max_f32_e32 v112, 0, v112
	v_max_f32_e32 v108, 0, v108
	v_max_f32_e32 v113, 0, v113
	v_max_f32_e32 v109, 0, v109
	v_max_f32_e32 v102, 0, v102
	v_max_f32_e32 v98, 0, v98
	v_max_f32_e32 v103, 0, v103
	v_max_f32_e32 v99, 0, v99
	v_max_f32_e32 v104, 0, v104
	v_max_f32_e32 v100, 0, v100
	v_max_f32_e32 v105, 0, v105
	v_max_f32_e32 v101, 0, v101
	v_lshl_add_u64 v[124:125], v[122:123], 0, v[140:141]
	v_cndmask_b32_dpp v117, v129, v115, vcc row_ror:8 row_mask:0xf bank_mask:0xf bound_ctrl:1
	v_cndmask_b32_dpp v116, v128, v114, vcc row_ror:8 row_mask:0xf bank_mask:0xf bound_ctrl:1
	v_cndmask_b32_dpp v115, v127, v119, vcc row_ror:8 row_mask:0xf bank_mask:0xf bound_ctrl:1
	v_cndmask_b32_dpp v114, v126, v118, vcc row_ror:8 row_mask:0xf bank_mask:0xf bound_ctrl:1
	v_cndmask_b32_e64 v121, v129, v167, s[8:9]
	v_cndmask_b32_e64 v120, v128, v166, s[8:9]
	v_cndmask_b32_e64 v119, v127, v165, s[8:9]
	v_cndmask_b32_e64 v118, v126, v164, s[8:9]
	v_pk_mul_f32 v[110:111], v[110:111], v[110:111]
	v_pk_mul_f32 v[106:107], v[106:107], v[106:107]
	v_pk_mul_f32 v[112:113], v[112:113], v[112:113]
	v_pk_mul_f32 v[108:109], v[108:109], v[108:109]
	v_pk_mul_f32 v[102:103], v[102:103], v[102:103]
	v_pk_mul_f32 v[98:99], v[98:99], v[98:99]
	v_pk_mul_f32 v[104:105], v[104:105], v[104:105]
	v_pk_mul_f32 v[100:101], v[100:101], v[100:101]
	v_lshl_add_u64 v[122:123], v[122:123], 0, v[142:143]
	s_and_b64 vcc, exec, s[6:7]
	s_cbranch_vccz .LBB0_1845
	s_barrier

; #define PG8_STAGE(bufoff, gbase, voff) do { _Pragma("unroll") for (int _i = 0; _i < 2; ++_i) \
;         __builtin_amdgcn_global_load_lds((const unsigned*)((const char*)(gbase) + (voff)[_i]), (LAS unsigned*)(lds + (bufoff) + ldsw + _i * 8192), 16, 0, 0); } while (0)
; #define PG8_LDA(dst, b, h) do { _Pragma("unroll") for (int m = 0; m < 4; ++m) _Pragma("unroll") for (int k = 0; k < 2; ++k) dst[m][k] = *(const LAS bf16x8*)(lds + PG8_SA(b, h) + aoff + m * 2048 + k * 1024); } while (0)
; #define PG8_LDB(dst, b, h) do { _Pragma("unroll") for (int n = 0; n < 2; ++n) _Pragma("unroll") for (int k = 0; k < 2; ++k) dst[n][k] = *(const LAS bf16x8*)(lds + PG8_SB(b, h) + boff + n * 2048 + k * 1024); } while (0)
; #define PG8_MMA(ai, bj, At, Bt) do { __builtin_amdgcn_s_setprio(1); _Pragma("unroll") for (int m = 0; m < 4; ++m) _Pragma("unroll") for (int n = 0; n < 2; ++n) _Pragma("unroll") for (int k = 0; k < 2; ++k) \
;         acc[ai][bj][m][n] = __builtin_amdgcn_mfma_f32_16x16x32_bf16(Bt[n][k], At[m][k], acc[ai][bj][m][n], 0, 0, 0); __builtin_amdgcn_s_setprio(0); } while (0)
; #define PG8_WAIT_V(n) asm volatile("s_waitcnt vmcnt(" #n ")" ::: "memory")
; #define PG8_WAIT_L(n) asm volatile("s_waitcnt lgkmcnt(" #n ")" ::: "memory")
; template <class Epi, class Sched, bool ABLK = false, bool ALIGN_EPI = true, bool SP2 = true, bool BBLK = true>
; __device__ __forceinline__ void gemm_phase(LAS unsigned char* lds, const Gemm g, const Sched& S, const Epi& E) {
;     ...
;             const char* a1 = a_tile(uA, tbA + t + 1);
;             const char* a2 = last ? a_tile(nuA, ntbA) : a_tile(uA, tbA + t + 2); const char* b2 = last ? nB : cB + (size_t)(t + 2) * kstepB;
;             const char* a3 = last ? a_tile(nuA, ntbA + 1) : a_tile(uA, tbA + t + 3); const char* b3 = b2 + kstepB;
;             if (last && has_next) S.a_ready(nxt);
;             if constexpr (SP2) {
;             PG8_LDB(B0, 0, 0); PG8_LDB(B1, 0, 1); PG8_SCHED; PG8_LDA(At, 0, 0); PG8_STAGE(PG8_SA(1, 1), a1 + hstepA, voffA);
;             PG8_WAIT_V(8); PG8_WAIT_L(0); PG8_BAR; PG8_MMA(0, 0, At, B0); PG8_MMA(0, 1, At, B1); PG8_BAR; PG8_SCHED;
;             PG8_LDA(At, 0, 1); PG8_STAGE(PG8_SB(0, 0), b2, voffB); PG8_STAGE(PG8_SB(0, 1), b2 + hstepB, voffB); PG8_STAGE(PG8_SA(0, 0), a2, voffA);
;             PG8_WAIT_V(8); PG8_WAIT_L(0); PG8_BAR; PG8_MMA(1, 0, At, B0); PG8_MMA(1, 1, At, B1); PG8_BAR; PG8_SCHED;
.Lksel_21_back:
	v_lshl_add_u64 v[216:217], v[142:143], 0, s[30:31]
	s_add_i32 m0, s41, 0xc000
	ds_read_b128 v[184:187], v150
	ds_read_b128 v[188:191], v150 offset:1024
	ds_read_b128 v[192:195], v150 offset:2048
	ds_read_b128 v[196:199], v150 offset:3072
	ds_read_b128 v[200:203], v150 offset:4096
	ds_read_b128 v[204:207], v150 offset:5120
	ds_read_b128 v[208:211], v150 offset:6144
	ds_read_b128 v[212:215], v150 offset:7168
	global_load_lds_dwordx4 v[216:217], off
	v_lshl_add_u64 v[216:217], v[144:145], 0, s[30:31]
	s_add_i32 m0, s41, 0xe000
	s_nop 0
	global_load_lds_dwordx4 v[216:217], off
	s_waitcnt vmcnt(8) lgkmcnt(0)
	s_barrier
	v_mfma_f32_16x16x32_bf16 v[126:129], v[152:155], v[184:187], v[126:129]
	v_mfma_f32_16x16x32_bf16 v[122:125], v[160:163], v[184:187], v[122:125]
	v_mfma_f32_16x16x32_bf16 v[110:113], v[152:155], v[192:195], v[110:113]
	v_mfma_f32_16x16x32_bf16 v[106:109], v[160:163], v[192:195], v[106:109]
	v_mfma_f32_16x16x32_bf16 v[94:97], v[152:155], v[200:203], v[94:97]
	v_mfma_f32_16x16x32_bf16 v[90:93], v[160:163], v[200:203], v[90:93]
	v_mfma_f32_16x16x32_bf16 v[78:81], v[152:155], v[208:211], v[78:81]
	v_mfma_f32_16x16x32_bf16 v[74:77], v[160:163], v[208:211], v[74:77]
	v_mfma_f32_16x16x32_bf16 v[126:129], v[156:159], v[188:191], v[126:129]
	v_mfma_f32_16x16x32_bf16 v[122:125], v[164:167], v[188:191], v[122:125]
	v_mfma_f32_16x16x32_bf16 v[110:113], v[156:159], v[196:199], v[110:113]
	v_mfma_f32_16x16x32_bf16 v[106:109], v[164:167], v[196:199], v[106:109]
	v_mfma_f32_16x16x32_bf16 v[94:97], v[156:159], v[204:207], v[94:97]
	v_mfma_f32_16x16x32_bf16 v[90:93], v[164:167], v[204:207], v[90:93]
	v_mfma_f32_16x16x32_bf16 v[78:81], v[156:159], v[212:215], v[78:81]
	v_mfma_f32_16x16x32_bf16 v[74:77], v[164:167], v[212:215], v[74:77]
	v_mfma_f32_16x16x32_bf16 v[118:121], v[168:171], v[184:187], v[118:121]
	v_mfma_f32_16x16x32_bf16 v[114:117], v[176:179], v[184:187], v[114:117]
	v_mfma_f32_16x16x32_bf16 v[102:105], v[168:171], v[192:195], v[102:105]
	v_mfma_f32_16x16x32_bf16 v[98:101], v[176:179], v[192:195], v[98:101]
	v_mfma_f32_16x16x32_bf16 v[86:89], v[168:171], v[200:203], v[86:89]
	v_mfma_f32_16x16x32_bf16 v[82:85], v[176:179], v[200:203], v[82:85]
	v_mfma_f32_16x16x32_bf16 v[70:73], v[168:171], v[208:211], v[70:73]
	v_mfma_f32_16x16x32_bf16 v[66:69], v[176:179], v[208:211], v[66:69]
	v_mfma_f32_16x16x32_bf16 v[118:121], v[172:175], v[188:191], v[118:121]
	v_mfma_f32_16x16x32_bf16 v[114:117], v[180:183], v[188:191], v[114:117]
	v_mfma_f32_16x16x32_bf16 v[102:105], v[172:175], v[196:199], v[102:105]
	v_mfma_f32_16x16x32_bf16 v[98:101], v[180:183], v[196:199], v[98:101]
	v_mfma_f32_16x16x32_bf16 v[86:89], v[172:175], v[204:207], v[86:89]
	v_mfma_f32_16x16x32_bf16 v[82:85], v[180:183], v[204:207], v[82:85]
	v_mfma_f32_16x16x32_bf16 v[70:73], v[172:175], v[212:215], v[70:73]
	v_mfma_f32_16x16x32_bf16 v[66:69], v[180:183], v[212:215], v[66:69]
	s_barrier
	s_add_i32 s59, s72, s40
	s_mov_b32 m0, s59
	ds_read_b128 v[184:187], v150 offset:16384
	ds_read_b128 v[188:191], v150 offset:17408
	ds_read_b128 v[192:195], v150 offset:18432
	ds_read_b128 v[196:199], v150 offset:19456
	ds_read_b128 v[200:203], v150 offset:20480
	ds_read_b128 v[204:207], v150 offset:21504
	ds_read_b128 v[208:211], v150 offset:22528
	ds_read_b128 v[212:215], v150 offset:23552
	global_load_lds_dwordx4 v130, s[36:37]
	s_add_i32 m0, s59, 0x2000
	s_add_u32 s64, s36, 0x4000
	s_addc_u32 s65, s37, 0
	s_add_i32 s59, s73, s40
	global_load_lds_dwordx4 v132, s[36:37]
	s_mov_b32 m0, s59
	s_nop 0
	global_load_lds_dwordx4 v130, s[64:65]
	s_add_i32 m0, s59, 0x2000
	s_nop 0
	global_load_lds_dwordx4 v132, s[64:65]
	s_mov_b32 m0, s41
	s_nop 0
	global_load_lds_dwordx4 v130, s[38:39]
	s_mov_b32 m0, s42
	s_nop 0
	global_load_lds_dwordx4 v132, s[38:39]
	s_waitcnt vmcnt(8) lgkmcnt(0)
	s_barrier
	v_mfma_f32_16x16x32_bf16 v[62:65], v[152:155], v[184:187], v[62:65]
	v_mfma_f32_16x16x32_bf16 v[58:61], v[160:163], v[184:187], v[58:61]
	v_mfma_f32_16x16x32_bf16 v[46:49], v[152:155], v[192:195], v[46:49]
	v_mfma_f32_16x16x32_bf16 v[42:45], v[160:163], v[192:195], v[42:45]
	v_mfma_f32_16x16x32_bf16 v[30:33], v[152:155], v[200:203], v[30:33]
	v_mfma_f32_16x16x32_bf16 v[26:29], v[160:163], v[200:203], v[26:29]
	v_mfma_f32_16x16x32_bf16 v[14:17], v[152:155], v[208:211], v[14:17]
	v_mfma_f32_16x16x32_bf16 v[10:13], v[160:163], v[208:211], v[10:13]
	v_mfma_f32_16x16x32_bf16 v[62:65], v[156:159], v[188:191], v[62:65]
	v_mfma_f32_16x16x32_bf16 v[58:61], v[164:167], v[188:191], v[58:61]
	v_mfma_f32_16x16x32_bf16 v[46:49], v[156:159], v[196:199], v[46:49]
	v_mfma_f32_16x16x32_bf16 v[42:45], v[164:167], v[196:199], v[42:45]
	v_mfma_f32_16x16x32_bf16 v[30:33], v[156:159], v[204:207], v[30:33]
	v_mfma_f32_16x16x32_bf16 v[26:29], v[164:167], v[204:207], v[26:29]
	v_mfma_f32_16x16x32_bf16 v[14:17], v[156:159], v[212:215], v[14:17]
	v_mfma_f32_16x16x32_bf16 v[10:13], v[164:167], v[212:215], v[10:13]
	v_mfma_f32_16x16x32_bf16 v[54:57], v[168:171], v[184:187], v[54:57]
	v_mfma_f32_16x16x32_bf16 v[50:53], v[176:179], v[184:187], v[50:53]
	v_mfma_f32_16x16x32_bf16 v[38:41], v[168:171], v[192:195], v[38:41]
	v_mfma_f32_16x16x32_bf16 v[34:37], v[176:179], v[192:195], v[34:37]
	v_mfma_f32_16x16x32_bf16 v[22:25], v[168:171], v[200:203], v[22:25]
	v_mfma_f32_16x16x32_bf16 v[18:21], v[176:179], v[200:203], v[18:21]
	v_mfma_f32_16x16x32_bf16 v[6:9], v[168:171], v[208:211], v[6:9]
	v_mfma_f32_16x16x32_bf16 v[2:5], v[176:179], v[208:211], v[2:5]
	v_mfma_f32_16x16x32_bf16 v[54:57], v[172:175], v[188:191], v[54:57]
	v_mfma_f32_16x16x32_bf16 v[50:53], v[180:183], v[188:191], v[50:53]
	v_mfma_f32_16x16x32_bf16 v[38:41], v[172:175], v[196:199], v[38:41]
	v_mfma_f32_16x16x32_bf16 v[34:37], v[180:183], v[196:199], v[34:37]
	v_mfma_f32_16x16x32_bf16 v[22:25], v[172:175], v[204:207], v[22:25]
	v_mfma_f32_16x16x32_bf16 v[18:21], v[180:183], v[204:207], v[18:21]
	v_mfma_f32_16x16x32_bf16 v[6:9], v[172:175], v[212:215], v[6:9]
	v_mfma_f32_16x16x32_bf16 v[2:5], v[180:183], v[212:215], v[2:5]
	s_barrier
; #define PG8_STAGE(bufoff, gbase, voff) do { _Pragma("unroll") for (int _i = 0; _i < 2; ++_i) \
;         __builtin_amdgcn_global_load_lds((const unsigned*)((const char*)(gbase) + (voff)[_i]), (LAS unsigned*)(lds + (bufoff) + ldsw + _i * 8192), 16, 0, 0); } while (0)
; #define PG8_LDA(dst, b, h) do { _Pragma("unroll") for (int m = 0; m < 4; ++m) _Pragma("unroll") for (int k = 0; k < 2; ++k) dst[m][k] = *(const LAS bf16x8*)(lds + PG8_SA(b, h) + aoff + m * 2048 + k * 1024); } while (0)
; #define PG8_LDB(dst, b, h) do { _Pragma("unroll") for (int n = 0; n < 2; ++n) _Pragma("unroll") for (int k = 0; k < 2; ++k) dst[n][k] = *(const LAS bf16x8*)(lds + PG8_SB(b, h) + boff + n * 2048 + k * 1024); } while (0)
; #define PG8_MMA(ai, bj, At, Bt) do { __builtin_amdgcn_s_setprio(1); _Pragma("unroll") for (int m = 0; m < 4; ++m) _Pragma("unroll") for (int n = 0; n < 2; ++n) _Pragma("unroll") for (int k = 0; k < 2; ++k) \
;         acc[ai][bj][m][n] = __builtin_amdgcn_mfma_f32_16x16x32_bf16(Bt[n][k], At[m][k], acc[ai][bj][m][n], 0, 0, 0); __builtin_amdgcn_s_setprio(0); } while (0)
; #define PG8_WAIT_V(n) asm volatile("s_waitcnt vmcnt(" #n ")" ::: "memory")
; #define PG8_WAIT_L(n) asm volatile("s_waitcnt lgkmcnt(" #n ")" ::: "memory")
; #define PG8_BAR __builtin_amdgcn_s_barrier()
; #define PG8_SCHED __builtin_amdgcn_sched_barrier(0)
; template <class Epi, class Sched, bool ABLK = false, bool ALIGN_EPI = true, bool SP2 = true, bool BBLK = true>
; __device__ __forceinline__ void gemm_phase(LAS unsigned char* lds, const Gemm g, const Sched& S, const Epi& E) {
;     ...
;             PG8_LDB(B0, 1, 0); PG8_LDB(B1, 1, 1); PG8_SCHED; PG8_LDA(At, 1, 0); PG8_STAGE(PG8_SA(0, 1), a2 + hstepA, voffA);
;             PG8_WAIT_V(8); PG8_WAIT_L(0); PG8_BAR; PG8_MMA(0, 0, At, B0); PG8_MMA(0, 1, At, B1); PG8_BAR; PG8_SCHED;
;             PG8_LDA(At, 1, 1); PG8_STAGE(PG8_SB(1, 0), b3, voffB); PG8_STAGE(PG8_SB(1, 1), b3 + hstepB, voffB); PG8_STAGE(PG8_SA(1, 0), a3, voffA);
;             PG8_WAIT_V(8); PG8_WAIT_L(0); PG8_BAR; PG8_MMA(1, 0, At, B0); PG8_MMA(1, 1, At, B1); PG8_BAR; PG8_SCHED;
	v_add_u32_e32 v151, s60, v146
	ds_read_b128 v[152:155], v151
	ds_read_b128 v[156:159], v151 offset:1024
	ds_read_b128 v[160:163], v151 offset:2048
	ds_read_b128 v[164:167], v151 offset:3072
	v_add_u32_e32 v151, s61, v146
	ds_read_b128 v[168:171], v151
	ds_read_b128 v[172:175], v151 offset:1024
	ds_read_b128 v[176:179], v151 offset:2048
	ds_read_b128 v[180:183], v151 offset:3072
	s_add_u32 s38, s38, 0x4000
	s_addc_u32 s39, s39, 0
	s_mov_b32 m0, s43
	ds_read_b128 v[184:187], v150 offset:32768
	ds_read_b128 v[188:191], v150 offset:33792
	ds_read_b128 v[192:195], v150 offset:34816
	ds_read_b128 v[196:199], v150 offset:35840
	ds_read_b128 v[200:203], v150 offset:36864
	ds_read_b128 v[204:207], v150 offset:37888
	ds_read_b128 v[208:211], v150 offset:38912
	ds_read_b128 v[212:215], v150 offset:39936
	global_load_lds_dwordx4 v130, s[38:39]
	s_mov_b32 m0, s44
	s_nop 0
	global_load_lds_dwordx4 v132, s[38:39]
	s_waitcnt vmcnt(8) lgkmcnt(0)
	s_barrier
	v_mfma_f32_16x16x32_bf16 v[126:129], v[152:155], v[184:187], v[126:129]
	v_mfma_f32_16x16x32_bf16 v[122:125], v[160:163], v[184:187], v[122:125]
	v_mfma_f32_16x16x32_bf16 v[110:113], v[152:155], v[192:195], v[110:113]
	v_mfma_f32_16x16x32_bf16 v[106:109], v[160:163], v[192:195], v[106:109]
	v_mfma_f32_16x16x32_bf16 v[94:97], v[152:155], v[200:203], v[94:97]
	v_mfma_f32_16x16x32_bf16 v[90:93], v[160:163], v[200:203], v[90:93]
	v_mfma_f32_16x16x32_bf16 v[78:81], v[152:155], v[208:211], v[78:81]
	v_mfma_f32_16x16x32_bf16 v[74:77], v[160:163], v[208:211], v[74:77]
	v_mfma_f32_16x16x32_bf16 v[126:129], v[156:159], v[188:191], v[126:129]
	v_mfma_f32_16x16x32_bf16 v[122:125], v[164:167], v[188:191], v[122:125]
	v_mfma_f32_16x16x32_bf16 v[110:113], v[156:159], v[196:199], v[110:113]
	v_mfma_f32_16x16x32_bf16 v[106:109], v[164:167], v[196:199], v[106:109]
	v_mfma_f32_16x16x32_bf16 v[94:97], v[156:159], v[204:207], v[94:97]
	v_mfma_f32_16x16x32_bf16 v[90:93], v[164:167], v[204:207], v[90:93]
	v_mfma_f32_16x16x32_bf16 v[78:81], v[156:159], v[212:215], v[78:81]
	v_mfma_f32_16x16x32_bf16 v[74:77], v[164:167], v[212:215], v[74:77]
	v_mfma_f32_16x16x32_bf16 v[118:121], v[168:171], v[184:187], v[118:121]
	v_mfma_f32_16x16x32_bf16 v[114:117], v[176:179], v[184:187], v[114:117]
	v_mfma_f32_16x16x32_bf16 v[102:105], v[168:171], v[192:195], v[102:105]
	v_mfma_f32_16x16x32_bf16 v[98:101], v[176:179], v[192:195], v[98:101]
	v_mfma_f32_16x16x32_bf16 v[86:89], v[168:171], v[200:203], v[86:89]
	v_mfma_f32_16x16x32_bf16 v[82:85], v[176:179], v[200:203], v[82:85]
	v_mfma_f32_16x16x32_bf16 v[70:73], v[168:171], v[208:211], v[70:73]
	v_mfma_f32_16x16x32_bf16 v[66:69], v[176:179], v[208:211], v[66:69]
	v_mfma_f32_16x16x32_bf16 v[118:121], v[172:175], v[188:191], v[118:121]
	v_mfma_f32_16x16x32_bf16 v[114:117], v[180:183], v[188:191], v[114:117]
	v_mfma_f32_16x16x32_bf16 v[102:105], v[172:175], v[196:199], v[102:105]
	v_mfma_f32_16x16x32_bf16 v[98:101], v[180:183], v[196:199], v[98:101]
	v_mfma_f32_16x16x32_bf16 v[86:89], v[172:175], v[204:207], v[86:89]
	v_mfma_f32_16x16x32_bf16 v[82:85], v[180:183], v[204:207], v[82:85]
	v_mfma_f32_16x16x32_bf16 v[70:73], v[172:175], v[212:215], v[70:73]
	v_mfma_f32_16x16x32_bf16 v[66:69], v[180:183], v[212:215], v[66:69]
	s_barrier
	s_add_u32 s38, s36, 0x8000
	s_addc_u32 s39, s37, 0
	s_add_i32 s59, s60, s40
	s_mov_b32 m0, s59
	ds_read_b128 v[184:187], v150 offset:49152
	ds_read_b128 v[188:191], v150 offset:50176
	ds_read_b128 v[192:195], v150 offset:51200
	ds_read_b128 v[196:199], v150 offset:52224
	ds_read_b128 v[200:203], v150 offset:53248
	ds_read_b128 v[204:207], v150 offset:54272
	ds_read_b128 v[208:211], v150 offset:55296
	ds_read_b128 v[212:215], v150 offset:56320
	global_load_lds_dwordx4 v130, s[38:39]
	s_add_i32 m0, s59, 0x2000
	s_add_u32 s36, s36, 0xc000
	v_lshl_add_u64 v[216:217], s[38:39], 0, v[132:133]
	s_addc_u32 s37, s37, 0
	s_add_i32 s38, s61, s40
	global_load_lds_dwordx4 v[216:217], off
	s_mov_b32 m0, s38
	s_nop 0
	global_load_lds_dwordx4 v130, s[36:37]
	s_add_i32 m0, s38, 0x2000
	s_nop 0
	global_load_lds_dwordx4 v132, s[36:37]
	s_mov_b32 m0, s45
	s_nop 0
	global_load_lds_dwordx4 v130, s[34:35]
	s_mov_b32 m0, s46
	s_nop 0
	global_load_lds_dwordx4 v132, s[34:35]
	s_waitcnt vmcnt(8) lgkmcnt(0)
	s_barrier
	v_mfma_f32_16x16x32_bf16 v[62:65], v[152:155], v[184:187], v[62:65]
	v_mfma_f32_16x16x32_bf16 v[58:61], v[160:163], v[184:187], v[58:61]
	v_mfma_f32_16x16x32_bf16 v[46:49], v[152:155], v[192:195], v[46:49]
	v_mfma_f32_16x16x32_bf16 v[42:45], v[160:163], v[192:195], v[42:45]
	v_mfma_f32_16x16x32_bf16 v[30:33], v[152:155], v[200:203], v[30:33]
	v_mfma_f32_16x16x32_bf16 v[26:29], v[160:163], v[200:203], v[26:29]
	v_mfma_f32_16x16x32_bf16 v[14:17], v[152:155], v[208:211], v[14:17]
	v_mfma_f32_16x16x32_bf16 v[10:13], v[160:163], v[208:211], v[10:13]
	v_mfma_f32_16x16x32_bf16 v[62:65], v[156:159], v[188:191], v[62:65]
	v_mfma_f32_16x16x32_bf16 v[58:61], v[164:167], v[188:191], v[58:61]
	v_mfma_f32_16x16x32_bf16 v[46:49], v[156:159], v[196:199], v[46:49]
	v_mfma_f32_16x16x32_bf16 v[42:45], v[164:167], v[196:199], v[42:45]
	v_mfma_f32_16x16x32_bf16 v[30:33], v[156:159], v[204:207], v[30:33]
	v_mfma_f32_16x16x32_bf16 v[26:29], v[164:167], v[204:207], v[26:29]
	v_mfma_f32_16x16x32_bf16 v[14:17], v[156:159], v[212:215], v[14:17]
	v_mfma_f32_16x16x32_bf16 v[10:13], v[164:167], v[212:215], v[10:13]
	v_mfma_f32_16x16x32_bf16 v[54:57], v[168:171], v[184:187], v[54:57]
	v_mfma_f32_16x16x32_bf16 v[50:53], v[176:179], v[184:187], v[50:53]
	v_mfma_f32_16x16x32_bf16 v[38:41], v[168:171], v[192:195], v[38:41]
	v_mfma_f32_16x16x32_bf16 v[34:37], v[176:179], v[192:195], v[34:37]
	v_mfma_f32_16x16x32_bf16 v[22:25], v[168:171], v[200:203], v[22:25]
	v_mfma_f32_16x16x32_bf16 v[18:21], v[176:179], v[200:203], v[18:21]
	v_mfma_f32_16x16x32_bf16 v[6:9], v[168:171], v[208:211], v[6:9]
	v_mfma_f32_16x16x32_bf16 v[2:5], v[176:179], v[208:211], v[2:5]
	v_mfma_f32_16x16x32_bf16 v[54:57], v[172:175], v[188:191], v[54:57]
	v_mfma_f32_16x16x32_bf16 v[50:53], v[180:183], v[188:191], v[50:53]
	v_mfma_f32_16x16x32_bf16 v[38:41], v[172:175], v[196:199], v[38:41]
	v_mfma_f32_16x16x32_bf16 v[34:37], v[180:183], v[196:199], v[34:37]
	v_mfma_f32_16x16x32_bf16 v[22:25], v[172:175], v[204:207], v[22:25]
	v_mfma_f32_16x16x32_bf16 v[18:21], v[180:183], v[204:207], v[18:21]
	v_mfma_f32_16x16x32_bf16 v[6:9], v[172:175], v[212:215], v[6:9]
	v_mfma_f32_16x16x32_bf16 v[2:5], v[180:183], v[212:215], v[2:5]
	s_barrier
; __device__ __forceinline__ unsigned pk2(float lo, float hi) { const f32x2 v = {lo, hi}; return __builtin_bit_cast(unsigned, __builtin_convertvector(v, bf16x2_t)); }
; __device__ __forceinline__ u32x4 ror8(u32x4 v) { u32x4 r;
; #pragma unroll
;     for (int i = 0; i < 4; ++i) r[i] = (unsigned)__builtin_amdgcn_mov_dpp((int)v[i], 0x128, 0xf, 0xf, true);
;     return r; }
; __device__ __forceinline__ void store_pair(unsigned char* own, size_t stride8, int hi_off, u32x4 lo, u32x4 hi, bool upper) {
;     const u32x4 tlo = ror8(lo), thi = ror8(hi);
;     const u32x4 A = upper ? thi : lo, B = upper ? hi : tlo;
;     unsigned char* pa = upper ? own - stride8 + hi_off : own;
;     unsigned char* pb = upper ? own + hi_off : own + stride8;
;     *(u32x4*)pa = A; *(u32x4*)pb = B;
;     __device__ __forceinline__ void operator()(const f32x4 (&acc)[2][2][4][2], const Unit& u, int wr, int wc, int fr, int fq) const {
;         const int row0 = u.pm * 256 + wr * 64 + fr, col0 = u.pn * 256 + wc * 64 + 8 * fq;
;         bf16_t* base = u.part == 0 ? Z + (size_t)row0 * D + col0 : P + ((size_t)(u.part - 1) * MS + (row0 - MP)) * D + col0;
; #pragma unroll
;         for (int ai = 0; ai < 2; ++ai)
; #pragma unroll
;             for (int m = 0; m < 4; ++m) { u32x4 w[2];
; #pragma unroll
;                 for (int bj = 0; bj < 2; ++bj) { const f32x4 v0 = acc[ai][bj][m][0], v1 = acc[ai][bj][m][1]; w[bj].x = pk2(v0[0], v0[1]); w[bj].y = pk2(v0[2], v0[3]); w[bj].z = pk2(v1[0], v1[1]); w[bj].w = pk2(v1[2], v1[3]); }
;                 store_pair((unsigned char*)(base + (size_t)(ai * 128 + m * 16) * D), (size_t)8 * D * 2, 64, w[0], w[1], fr >= 8); }
;     }
	s_add_u32 s30, s30, 0x10000
	s_addc_u32 s31, s31, 0
	s_cmp_ge_u32 s58, s48
	s_cbranch_scc0 .LBB0_1907
	v_lshl_add_u32 v143, s49, 8, v1
	v_add_u32_e32 v144, 0xffffe000, v143
	v_sub_co_u32_e64 v142, vcc, s47, 1
	v_mov_b32_e32 v145, s91
	s_nop 0
	v_cndmask_b32_e32 v144, v144, v143, vcc
	v_ashrrev_i32_e32 v143, 31, v142
	v_lshlrev_b64 v[142:143], 23, v[142:143]
	v_lshl_add_u64 v[142:143], s[12:13], 0, v[142:143]
	v_cndmask_b32_e32 v143, v143, v145, vcc
	v_mov_b32_e32 v145, s90
	v_cndmask_b32_e32 v142, v142, v145, vcc
	v_ashrrev_i32_e32 v145, 31, v144
	v_lshl_or_b32 v152, s78, 8, v147
	v_lshlrev_b64 v[144:145], 12, v[144:145]
	v_lshl_add_u64 v[142:143], v[142:143], 0, v[144:145]
	v_ashrrev_i32_e32 v153, 31, v152
	v_cvt_pk_bf16_f32 v126, v126, v127
	v_cvt_pk_bf16_f32 v127, v128, v129
	v_cvt_pk_bf16_f32 v128, v122, v123
	v_cvt_pk_bf16_f32 v124, v124, v125
	v_cvt_pk_bf16_f32 v118, v118, v119
	v_cvt_pk_bf16_f32 v119, v120, v121
	v_cvt_pk_bf16_f32 v114, v114, v115
	v_cvt_pk_bf16_f32 v115, v116, v117
	v_lshl_add_u64 v[142:143], v[152:153], 1, v[142:143]
	s_mov_b64 vcc, s[8:9]
	v_mov_b32_dpp v125, v118 row_ror:8 row_mask:0xf bank_mask:0xf bound_ctrl:1
	v_mov_b32_dpp v129, v119 row_ror:8 row_mask:0xf bank_mask:0xf bound_ctrl:1
	v_mov_b32_dpp v144, v114 row_ror:8 row_mask:0xf bank_mask:0xf bound_ctrl:1
	v_mov_b32_dpp v145, v115 row_ror:8 row_mask:0xf bank_mask:0xf bound_ctrl:1
	v_lshl_add_u64 v[122:123], v[142:143], 0, v[134:135]
	v_cndmask_b32_dpp v117, v124, v115, vcc row_ror:8 row_mask:0xf bank_mask:0xf bound_ctrl:1
	v_cndmask_b32_dpp v116, v128, v114, vcc row_ror:8 row_mask:0xf bank_mask:0xf bound_ctrl:1
	v_cndmask_b32_dpp v115, v127, v119, vcc row_ror:8 row_mask:0xf bank_mask:0xf bound_ctrl:1
	v_cndmask_b32_dpp v114, v126, v118, vcc row_ror:8 row_mask:0xf bank_mask:0xf bound_ctrl:1
	v_cndmask_b32_e64 v121, v124, v145, s[8:9]
	v_cndmask_b32_e64 v120, v128, v144, s[8:9]
	v_cndmask_b32_e64 v119, v127, v129, s[8:9]
	v_cndmask_b32_e64 v118, v126, v125, s[8:9]
	v_cvt_pk_bf16_f32 v110, v110, v111
	v_cvt_pk_bf16_f32 v111, v112, v113
	v_cvt_pk_bf16_f32 v112, v106, v107
	v_cvt_pk_bf16_f32 v113, v108, v109
	v_cvt_pk_bf16_f32 v102, v102, v103
	v_cvt_pk_bf16_f32 v103, v104, v105
	v_cvt_pk_bf16_f32 v98, v98, v99
	v_cvt_pk_bf16_f32 v99, v100, v101
	s_mov_b64 s[4:5], 0x10000
	v_lshl_add_u64 v[124:125], v[142:143], 0, v[136:137]
	s_and_b64 vcc, exec, s[6:7]
	s_cbranch_vccz .LBB0_1910
	s_barrier
.LBB0_1910:
	global_store_dwordx4 v[122:123], v[118:121], off
	global_store_dwordx4 v[124:125], v[114:117], off
	v_lshl_add_u64 v[106:107], v[142:143], 0, s[4:5]
	s_mov_b64 vcc, s[8:9]
	v_mov_b32_dpp v114, v102 row_ror:8 row_mask:0xf bank_mask:0xf bound_ctrl:1
	v_mov_b32_dpp v115, v103 row_ror:8 row_mask:0xf bank_mask:0xf bound_ctrl:1
	v_mov_b32_dpp v116, v98 row_ror:8 row_mask:0xf bank_mask:0xf bound_ctrl:1
	v_mov_b32_dpp v117, v99 row_ror:8 row_mask:0xf bank_mask:0xf bound_ctrl:1
	v_lshl_add_u64 v[108:109], v[106:107], 0, v[134:135]
	v_cndmask_b32_dpp v101, v113, v99, vcc row_ror:8 row_mask:0xf bank_mask:0xf bound_ctrl:1
	v_cndmask_b32_dpp v100, v112, v98, vcc row_ror:8 row_mask:0xf bank_mask:0xf bound_ctrl:1
	v_cndmask_b32_dpp v99, v111, v103, vcc row_ror:8 row_mask:0xf bank_mask:0xf bound_ctrl:1
	v_cndmask_b32_dpp v98, v110, v102, vcc row_ror:8 row_mask:0xf bank_mask:0xf bound_ctrl:1
	v_cndmask_b32_e64 v105, v113, v117, s[8:9]
	v_cndmask_b32_e64 v104, v112, v116, s[8:9]
	v_cndmask_b32_e64 v103, v111, v115, s[8:9]
	v_cndmask_b32_e64 v102, v110, v114, s[8:9]
	v_cvt_pk_bf16_f32 v94, v94, v95
	v_cvt_pk_bf16_f32 v95, v96, v97
	v_cvt_pk_bf16_f32 v96, v90, v91
	v_cvt_pk_bf16_f32 v97, v92, v93
	v_cvt_pk_bf16_f32 v86, v86, v87
	v_cvt_pk_bf16_f32 v87, v88, v89
	v_cvt_pk_bf16_f32 v82, v82, v83
	v_cvt_pk_bf16_f32 v83, v84, v85
	s_mov_b64 s[4:5], 0x20000
	v_lshl_add_u64 v[106:107], v[106:107], 0, v[136:137]
	global_store_dwordx4 v[108:109], v[102:105], off
	global_store_dwordx4 v[106:107], v[98:101], off
	v_lshl_add_u64 v[90:91], v[142:143], 0, s[4:5]
	s_mov_b64 vcc, s[8:9]
	v_mov_b32_dpp v98, v86 row_ror:8 row_mask:0xf bank_mask:0xf bound_ctrl:1
	v_mov_b32_dpp v99, v87 row_ror:8 row_mask:0xf bank_mask:0xf bound_ctrl:1
	v_mov_b32_dpp v100, v82 row_ror:8 row_mask:0xf bank_mask:0xf bound_ctrl:1
	v_mov_b32_dpp v101, v83 row_ror:8 row_mask:0xf bank_mask:0xf bound_ctrl:1
	v_lshl_add_u64 v[92:93], v[90:91], 0, v[134:135]
	v_cndmask_b32_dpp v85, v97, v83, vcc row_ror:8 row_mask:0xf bank_mask:0xf bound_ctrl:1
	v_cndmask_b32_dpp v84, v96, v82, vcc row_ror:8 row_mask:0xf bank_mask:0xf bound_ctrl:1
	v_cndmask_b32_dpp v83, v95, v87, vcc row_ror:8 row_mask:0xf bank_mask:0xf bound_ctrl:1
	v_cndmask_b32_dpp v82, v94, v86, vcc row_ror:8 row_mask:0xf bank_mask:0xf bound_ctrl:1
	v_cndmask_b32_e64 v89, v97, v101, s[8:9]
	v_cndmask_b32_e64 v88, v96, v100, s[8:9]
	v_cndmask_b32_e64 v87, v95, v99, s[8:9]
	v_cndmask_b32_e64 v86, v94, v98, s[8:9]
	v_cvt_pk_bf16_f32 v78, v78, v79
	v_cvt_pk_bf16_f32 v79, v80, v81
	v_cvt_pk_bf16_f32 v80, v74, v75
	v_cvt_pk_bf16_f32 v81, v76, v77
	v_cvt_pk_bf16_f32 v70, v70, v71
	v_cvt_pk_bf16_f32 v71, v72, v73
	v_cvt_pk_bf16_f32 v66, v66, v67
	v_cvt_pk_bf16_f32 v67, v68, v69
	v_lshl_add_u64 v[90:91], v[90:91], 0, v[136:137]
	global_store_dwordx4 v[92:93], v[86:89], off
	global_store_dwordx4 v[90:91], v[82:85], off
	v_lshl_add_u64 v[74:75], v[142:143], 0, s[14:15]
	s_mov_b64 vcc, s[8:9]
	v_mov_b32_dpp v82, v70 row_ror:8 row_mask:0xf bank_mask:0xf bound_ctrl:1
	v_mov_b32_dpp v83, v71 row_ror:8 row_mask:0xf bank_mask:0xf bound_ctrl:1
	v_mov_b32_dpp v84, v66 row_ror:8 row_mask:0xf bank_mask:0xf bound_ctrl:1
	v_mov_b32_dpp v85, v67 row_ror:8 row_mask:0xf bank_mask:0xf bound_ctrl:1
; __device__ __forceinline__ unsigned pk2(float lo, float hi) { const f32x2 v = {lo, hi}; return __builtin_bit_cast(unsigned, __builtin_convertvector(v, bf16x2_t)); }
; #define PG8_BAR __builtin_amdgcn_s_barrier()
; template <class Epi, class Sched, bool ABLK = false, bool ALIGN_EPI = true, bool SP2 = true, bool BBLK = true>
; __device__ __forceinline__ void gemm_phase(LAS unsigned char* lds, const Gemm g, const Sched& S, const Epi& E) {
;     ...
;         if (!has_next) break;
; #pragma unroll
;         for (int a = 0; a < 2; ++a)
; #pragma unroll
;             for (int b = 0; b < 2; ++b)
; #pragma unroll
;                 for (int m = 0; m < 4; ++m)
; #pragma unroll
;                     for (int n = 0; n < 2; ++n) acc[a][b][m][n] = (f32x4){0.f, 0.f, 0.f, 0.f};
;         cur = nxt; uA = nuA; tbA = ntbA; cB = nB; ++ui;
;         if constexpr (ALIGN_EPI) { if (wr == 1) PG8_BAR; }
;     __device__ __forceinline__ void operator()(const f32x4 (&acc)[2][2][4][2], const Unit& u, int wr, int wc, int fr, int fq) const {
;         const int row0 = u.pm * 256 + wr * 64 + fr, col0 = u.pn * 256 + wc * 64 + 8 * fq;
;         bf16_t* base = u.part == 0 ? Z + (size_t)row0 * D + col0 : P + ((size_t)(u.part - 1) * MS + (row0 - MP)) * D + col0;
; #pragma unroll
;         for (int ai = 0; ai < 2; ++ai)
; #pragma unroll
;             for (int m = 0; m < 4; ++m) { u32x4 w[2];
; #pragma unroll
;                 for (int bj = 0; bj < 2; ++bj) { const f32x4 v0 = acc[ai][bj][m][0], v1 = acc[ai][bj][m][1]; w[bj].x = pk2(v0[0], v0[1]); w[bj].y = pk2(v0[2], v0[3]); w[bj].z = pk2(v1[0], v1[1]); w[bj].w = pk2(v1[2], v1[3]); }
;                 store_pair((unsigned char*)(base + (size_t)(ai * 128 + m * 16) * D), (size_t)8 * D * 2, 64, w[0], w[1], fr >= 8); }
;     }
	v_lshl_add_u64 v[76:77], v[74:75], 0, v[134:135]
	v_cndmask_b32_dpp v69, v81, v67, vcc row_ror:8 row_mask:0xf bank_mask:0xf bound_ctrl:1
	v_cndmask_b32_dpp v68, v80, v66, vcc row_ror:8 row_mask:0xf bank_mask:0xf bound_ctrl:1
	v_cndmask_b32_dpp v67, v79, v71, vcc row_ror:8 row_mask:0xf bank_mask:0xf bound_ctrl:1
	v_cndmask_b32_dpp v66, v78, v70, vcc row_ror:8 row_mask:0xf bank_mask:0xf bound_ctrl:1
	v_cndmask_b32_e64 v73, v81, v85, s[8:9]
	v_cndmask_b32_e64 v72, v80, v84, s[8:9]
	v_cndmask_b32_e64 v71, v79, v83, s[8:9]
	v_cndmask_b32_e64 v70, v78, v82, s[8:9]
	v_cvt_pk_bf16_f32 v62, v62, v63
	v_cvt_pk_bf16_f32 v63, v64, v65
	v_cvt_pk_bf16_f32 v64, v58, v59
	v_cvt_pk_bf16_f32 v65, v60, v61
	v_cvt_pk_bf16_f32 v54, v54, v55
	v_cvt_pk_bf16_f32 v55, v56, v57
	v_cvt_pk_bf16_f32 v50, v50, v51
	v_cvt_pk_bf16_f32 v51, v52, v53
	v_lshl_add_u64 v[74:75], v[74:75], 0, v[136:137]
	global_store_dwordx4 v[76:77], v[70:73], off
	global_store_dwordx4 v[74:75], v[66:69], off
	v_lshl_add_u64 v[58:59], v[142:143], 0, s[16:17]
	s_mov_b64 vcc, s[8:9]
	v_mov_b32_dpp v66, v54 row_ror:8 row_mask:0xf bank_mask:0xf bound_ctrl:1
	v_mov_b32_dpp v67, v55 row_ror:8 row_mask:0xf bank_mask:0xf bound_ctrl:1
	v_mov_b32_dpp v68, v50 row_ror:8 row_mask:0xf bank_mask:0xf bound_ctrl:1
	v_mov_b32_dpp v69, v51 row_ror:8 row_mask:0xf bank_mask:0xf bound_ctrl:1
	v_lshl_add_u64 v[60:61], v[58:59], 0, v[134:135]
	v_cndmask_b32_dpp v53, v65, v51, vcc row_ror:8 row_mask:0xf bank_mask:0xf bound_ctrl:1
	v_cndmask_b32_dpp v52, v64, v50, vcc row_ror:8 row_mask:0xf bank_mask:0xf bound_ctrl:1
	v_cndmask_b32_dpp v51, v63, v55, vcc row_ror:8 row_mask:0xf bank_mask:0xf bound_ctrl:1
	v_cndmask_b32_dpp v50, v62, v54, vcc row_ror:8 row_mask:0xf bank_mask:0xf bound_ctrl:1
	v_cndmask_b32_e64 v57, v65, v69, s[8:9]
	v_cndmask_b32_e64 v56, v64, v68, s[8:9]
	v_cndmask_b32_e64 v55, v63, v67, s[8:9]
	v_cndmask_b32_e64 v54, v62, v66, s[8:9]
	v_cvt_pk_bf16_f32 v46, v46, v47
	v_cvt_pk_bf16_f32 v47, v48, v49
	v_cvt_pk_bf16_f32 v48, v42, v43
	v_cvt_pk_bf16_f32 v49, v44, v45
	v_cvt_pk_bf16_f32 v38, v38, v39
	v_cvt_pk_bf16_f32 v39, v40, v41
	v_cvt_pk_bf16_f32 v34, v34, v35
	v_cvt_pk_bf16_f32 v35, v36, v37
	v_lshl_add_u64 v[58:59], v[58:59], 0, v[136:137]
	global_store_dwordx4 v[60:61], v[54:57], off
	global_store_dwordx4 v[58:59], v[50:53], off
	v_lshl_add_u64 v[42:43], v[142:143], 0, s[18:19]
	s_mov_b64 vcc, s[8:9]
	v_mov_b32_dpp v50, v38 row_ror:8 row_mask:0xf bank_mask:0xf bound_ctrl:1
	v_mov_b32_dpp v51, v39 row_ror:8 row_mask:0xf bank_mask:0xf bound_ctrl:1
	v_mov_b32_dpp v52, v34 row_ror:8 row_mask:0xf bank_mask:0xf bound_ctrl:1
	v_mov_b32_dpp v53, v35 row_ror:8 row_mask:0xf bank_mask:0xf bound_ctrl:1
	v_lshl_add_u64 v[44:45], v[42:43], 0, v[134:135]
	v_cndmask_b32_dpp v37, v49, v35, vcc row_ror:8 row_mask:0xf bank_mask:0xf bound_ctrl:1
	v_cndmask_b32_dpp v36, v48, v34, vcc row_ror:8 row_mask:0xf bank_mask:0xf bound_ctrl:1
	v_cndmask_b32_dpp v35, v47, v39, vcc row_ror:8 row_mask:0xf bank_mask:0xf bound_ctrl:1
	v_cndmask_b32_dpp v34, v46, v38, vcc row_ror:8 row_mask:0xf bank_mask:0xf bound_ctrl:1
	v_cndmask_b32_e64 v41, v49, v53, s[8:9]
	v_cndmask_b32_e64 v40, v48, v52, s[8:9]
	v_cndmask_b32_e64 v39, v47, v51, s[8:9]
	v_cndmask_b32_e64 v38, v46, v50, s[8:9]
	v_cvt_pk_bf16_f32 v30, v30, v31
	v_cvt_pk_bf16_f32 v31, v32, v33
	v_cvt_pk_bf16_f32 v32, v26, v27
	v_cvt_pk_bf16_f32 v33, v28, v29
	v_cvt_pk_bf16_f32 v22, v22, v23
	v_cvt_pk_bf16_f32 v23, v24, v25
	v_cvt_pk_bf16_f32 v18, v18, v19
	v_cvt_pk_bf16_f32 v19, v20, v21
	v_lshl_add_u64 v[42:43], v[42:43], 0, v[136:137]
	global_store_dwordx4 v[44:45], v[38:41], off
	global_store_dwordx4 v[42:43], v[34:37], off
	v_lshl_add_u64 v[26:27], v[142:143], 0, s[20:21]
	s_mov_b64 vcc, s[8:9]
	v_mov_b32_dpp v34, v22 row_ror:8 row_mask:0xf bank_mask:0xf bound_ctrl:1
	v_mov_b32_dpp v35, v23 row_ror:8 row_mask:0xf bank_mask:0xf bound_ctrl:1
	v_mov_b32_dpp v36, v18 row_ror:8 row_mask:0xf bank_mask:0xf bound_ctrl:1
	v_mov_b32_dpp v37, v19 row_ror:8 row_mask:0xf bank_mask:0xf bound_ctrl:1
	v_lshl_add_u64 v[28:29], v[26:27], 0, v[134:135]
	v_cndmask_b32_dpp v21, v33, v19, vcc row_ror:8 row_mask:0xf bank_mask:0xf bound_ctrl:1
	v_cndmask_b32_dpp v20, v32, v18, vcc row_ror:8 row_mask:0xf bank_mask:0xf bound_ctrl:1
	v_cndmask_b32_dpp v19, v31, v23, vcc row_ror:8 row_mask:0xf bank_mask:0xf bound_ctrl:1
	v_cndmask_b32_dpp v18, v30, v22, vcc row_ror:8 row_mask:0xf bank_mask:0xf bound_ctrl:1
	v_cndmask_b32_e64 v25, v33, v37, s[8:9]
	v_cndmask_b32_e64 v24, v32, v36, s[8:9]
	v_cndmask_b32_e64 v23, v31, v35, s[8:9]
	v_cndmask_b32_e64 v22, v30, v34, s[8:9]
	v_cvt_pk_bf16_f32 v14, v14, v15
	v_cvt_pk_bf16_f32 v15, v16, v17
	v_cvt_pk_bf16_f32 v16, v10, v11
	v_cvt_pk_bf16_f32 v17, v12, v13
	v_cvt_pk_bf16_f32 v6, v6, v7
	v_cvt_pk_bf16_f32 v7, v8, v9
	v_cvt_pk_bf16_f32 v2, v2, v3
	v_cvt_pk_bf16_f32 v3, v4, v5
	v_lshl_add_u64 v[26:27], v[26:27], 0, v[136:137]
	global_store_dwordx4 v[28:29], v[22:25], off
	global_store_dwordx4 v[26:27], v[18:21], off
	v_lshl_add_u64 v[10:11], v[142:143], 0, s[22:23]
	s_mov_b64 vcc, s[8:9]
	v_mov_b32_dpp v18, v6 row_ror:8 row_mask:0xf bank_mask:0xf bound_ctrl:1
	v_mov_b32_dpp v19, v7 row_ror:8 row_mask:0xf bank_mask:0xf bound_ctrl:1
	v_mov_b32_dpp v20, v2 row_ror:8 row_mask:0xf bank_mask:0xf bound_ctrl:1
	v_mov_b32_dpp v21, v3 row_ror:8 row_mask:0xf bank_mask:0xf bound_ctrl:1
	v_lshl_add_u64 v[12:13], v[10:11], 0, v[134:135]
	v_cndmask_b32_dpp v5, v17, v3, vcc row_ror:8 row_mask:0xf bank_mask:0xf bound_ctrl:1
	v_cndmask_b32_dpp v4, v16, v2, vcc row_ror:8 row_mask:0xf bank_mask:0xf bound_ctrl:1
	v_cndmask_b32_dpp v3, v15, v7, vcc row_ror:8 row_mask:0xf bank_mask:0xf bound_ctrl:1
	v_cndmask_b32_dpp v2, v14, v6, vcc row_ror:8 row_mask:0xf bank_mask:0xf bound_ctrl:1
	v_cndmask_b32_e64 v9, v17, v21, s[8:9]
	v_cndmask_b32_e64 v8, v16, v20, s[8:9]
	v_cndmask_b32_e64 v7, v15, v19, s[8:9]
	v_cndmask_b32_e64 v6, v14, v18, s[8:9]
	s_and_b64 vcc, exec, s[10:11]
	s_mov_b64 s[10:11], -1
	v_lshl_add_u64 v[10:11], v[10:11], 0, v[136:137]
	global_store_dwordx4 v[12:13], v[6:9], off
	global_store_dwordx4 v[10:11], v[2:5], off
	s_cbranch_vccnz .LBB0_1905
	s_andn2_b64 vcc, exec, s[2:3]
	s_cbranch_vccnz .LBB0_1904
	s_barrier
	s_branch .LBB0_1904

; #define PG8_STAGE(bufoff, gbase, voff) do { _Pragma("unroll") for (int _i = 0; _i < 2; ++_i) \
;         __builtin_amdgcn_global_load_lds((const unsigned*)((const char*)(gbase) + (voff)[_i]), (LAS unsigned*)(lds + (bufoff) + ldsw + _i * 8192), 16, 0, 0); } while (0)
; #define PG8_LDA(dst, b, h) do { _Pragma("unroll") for (int m = 0; m < 4; ++m) _Pragma("unroll") for (int k = 0; k < 2; ++k) dst[m][k] = *(const LAS bf16x8*)(lds + PG8_SA(b, h) + aoff + m * 2048 + k * 1024); } while (0)
; #define PG8_LDB(dst, b, h) do { _Pragma("unroll") for (int n = 0; n < 2; ++n) _Pragma("unroll") for (int k = 0; k < 2; ++k) dst[n][k] = *(const LAS bf16x8*)(lds + PG8_SB(b, h) + boff + n * 2048 + k * 1024); } while (0)
; #define PG8_MMA(ai, bj, At, Bt) do { __builtin_amdgcn_s_setprio(1); _Pragma("unroll") for (int m = 0; m < 4; ++m) _Pragma("unroll") for (int n = 0; n < 2; ++n) _Pragma("unroll") for (int k = 0; k < 2; ++k) \
;         acc[ai][bj][m][n] = __builtin_amdgcn_mfma_f32_16x16x32_bf16(Bt[n][k], At[m][k], acc[ai][bj][m][n], 0, 0, 0); __builtin_amdgcn_s_setprio(0); } while (0)
; #define PG8_WAIT_V(n) asm volatile("s_waitcnt vmcnt(" #n ")" ::: "memory")
; #define PG8_WAIT_L(n) asm volatile("s_waitcnt lgkmcnt(" #n ")" ::: "memory")
; #define PG8_BAR __builtin_amdgcn_s_barrier()
; #define PG8_SCHED __builtin_amdgcn_sched_barrier(0)
; template <class Epi, class Sched, bool ABLK = false, bool ALIGN_EPI = true, bool SP2 = true, bool BBLK = true>
; __device__ __forceinline__ void gemm_phase(LAS unsigned char* lds, const Gemm g, const Sched& S, const Epi& E) {
;     ...
;             PG8_LDB(B0, 0, 0); PG8_LDB(B1, 0, 1); PG8_SCHED; PG8_LDA(At, 0, 0); PG8_STAGE(PG8_SA(1, 1), a1 + hstepA, voffA);
;             PG8_WAIT_V(8); PG8_WAIT_L(0); PG8_BAR; PG8_MMA(0, 0, At, B0); PG8_MMA(0, 1, At, B1); PG8_BAR; PG8_SCHED;
;             PG8_LDA(At, 0, 1); PG8_STAGE(PG8_SB(0, 0), b2, voffB); PG8_STAGE(PG8_SB(0, 1), b2 + hstepB, voffB); PG8_STAGE(PG8_SA(0, 0), a2, voffA);
;             PG8_WAIT_V(8); PG8_WAIT_L(0); PG8_BAR; PG8_MMA(1, 0, At, B0); PG8_MMA(1, 1, At, B1); PG8_BAR; PG8_SCHED;
.Lksel_25_back:
	s_mov_b32 m0, s50
	v_lshl_add_u64 v[236:237], v[164:165], 0, s[28:29]
	ds_read_b128 v[204:207], v170
	ds_read_b128 v[208:211], v170 offset:1024
	ds_read_b128 v[212:215], v170 offset:2048
	ds_read_b128 v[216:219], v170 offset:3072
	ds_read_b128 v[220:223], v170 offset:4096
	ds_read_b128 v[224:227], v170 offset:5120
	ds_read_b128 v[228:231], v170 offset:6144
	ds_read_b128 v[232:235], v170 offset:7168
	global_load_lds_dwordx4 v[236:237], off
	v_lshl_add_u64 v[236:237], v[166:167], 0, s[28:29]
	s_mov_b32 m0, s51
	s_nop 0
	global_load_lds_dwordx4 v[236:237], off
	s_waitcnt vmcnt(8) lgkmcnt(0)
	s_barrier
	v_mfma_f32_16x16x32_bf16 v[126:129], v[172:175], v[204:207], v[126:129]
	v_mfma_f32_16x16x32_bf16 v[122:125], v[180:183], v[204:207], v[122:125]
	v_mfma_f32_16x16x32_bf16 v[110:113], v[172:175], v[212:215], v[110:113]
	v_mfma_f32_16x16x32_bf16 v[106:109], v[180:183], v[212:215], v[106:109]
	v_mfma_f32_16x16x32_bf16 v[94:97], v[172:175], v[220:223], v[94:97]
	v_mfma_f32_16x16x32_bf16 v[90:93], v[180:183], v[220:223], v[90:93]
	v_mfma_f32_16x16x32_bf16 v[78:81], v[172:175], v[228:231], v[78:81]
	v_mfma_f32_16x16x32_bf16 v[74:77], v[180:183], v[228:231], v[74:77]
	v_mfma_f32_16x16x32_bf16 v[126:129], v[176:179], v[208:211], v[126:129]
	v_mfma_f32_16x16x32_bf16 v[122:125], v[184:187], v[208:211], v[122:125]
	v_mfma_f32_16x16x32_bf16 v[110:113], v[176:179], v[216:219], v[110:113]
	v_mfma_f32_16x16x32_bf16 v[106:109], v[184:187], v[216:219], v[106:109]
	v_mfma_f32_16x16x32_bf16 v[94:97], v[176:179], v[224:227], v[94:97]
	v_mfma_f32_16x16x32_bf16 v[90:93], v[184:187], v[224:227], v[90:93]
	v_mfma_f32_16x16x32_bf16 v[78:81], v[176:179], v[232:235], v[78:81]
	v_mfma_f32_16x16x32_bf16 v[74:77], v[184:187], v[232:235], v[74:77]
	v_mfma_f32_16x16x32_bf16 v[118:121], v[188:191], v[204:207], v[118:121]
	v_mfma_f32_16x16x32_bf16 v[114:117], v[196:199], v[204:207], v[114:117]
	v_mfma_f32_16x16x32_bf16 v[102:105], v[188:191], v[212:215], v[102:105]
	v_mfma_f32_16x16x32_bf16 v[98:101], v[196:199], v[212:215], v[98:101]
	v_mfma_f32_16x16x32_bf16 v[86:89], v[188:191], v[220:223], v[86:89]
	v_mfma_f32_16x16x32_bf16 v[82:85], v[196:199], v[220:223], v[82:85]
	v_mfma_f32_16x16x32_bf16 v[70:73], v[188:191], v[228:231], v[70:73]
	v_mfma_f32_16x16x32_bf16 v[66:69], v[196:199], v[228:231], v[66:69]
	v_mfma_f32_16x16x32_bf16 v[118:121], v[192:195], v[208:211], v[118:121]
	v_mfma_f32_16x16x32_bf16 v[114:117], v[200:203], v[208:211], v[114:117]
	v_mfma_f32_16x16x32_bf16 v[102:105], v[192:195], v[216:219], v[102:105]
	v_mfma_f32_16x16x32_bf16 v[98:101], v[200:203], v[216:219], v[98:101]
	v_mfma_f32_16x16x32_bf16 v[86:89], v[192:195], v[224:227], v[86:89]
	v_mfma_f32_16x16x32_bf16 v[82:85], v[200:203], v[224:227], v[82:85]
	v_mfma_f32_16x16x32_bf16 v[70:73], v[192:195], v[232:235], v[70:73]
	v_mfma_f32_16x16x32_bf16 v[66:69], v[200:203], v[232:235], v[66:69]
	s_barrier
	s_mov_b32 m0, s52
	s_add_u32 s58, s34, 0x4000
	ds_read_b128 v[204:207], v170 offset:16384
	ds_read_b128 v[208:211], v170 offset:17408
	ds_read_b128 v[212:215], v170 offset:18432
	ds_read_b128 v[216:219], v170 offset:19456
	ds_read_b128 v[220:223], v170 offset:20480
	ds_read_b128 v[224:227], v170 offset:21504
	ds_read_b128 v[228:231], v170 offset:22528
	ds_read_b128 v[232:235], v170 offset:23552
	global_load_lds_dwordx4 v134, s[34:35]
	s_mov_b32 m0, s53
	s_addc_u32 s59, s35, 0
	s_add_i32 s62, s73, s40
	global_load_lds_dwordx4 v130, s[34:35]
	s_mov_b32 m0, s62
	s_nop 0
	global_load_lds_dwordx4 v134, s[58:59]
	s_add_i32 m0, s62, 0x2000
	s_nop 0
	global_load_lds_dwordx4 v130, s[58:59]
	s_mov_b32 m0, s25
	s_nop 0
	global_load_lds_dwordx4 v136, s[36:37]
	s_mov_b32 m0, s43
	s_nop 0
	global_load_lds_dwordx4 v132, s[36:37]
	s_waitcnt vmcnt(8) lgkmcnt(0)
	s_barrier
	v_mfma_f32_16x16x32_bf16 v[62:65], v[172:175], v[204:207], v[62:65]
	v_mfma_f32_16x16x32_bf16 v[58:61], v[180:183], v[204:207], v[58:61]
	v_mfma_f32_16x16x32_bf16 v[46:49], v[172:175], v[212:215], v[46:49]
	v_mfma_f32_16x16x32_bf16 v[42:45], v[180:183], v[212:215], v[42:45]
	v_mfma_f32_16x16x32_bf16 v[30:33], v[172:175], v[220:223], v[30:33]
	v_mfma_f32_16x16x32_bf16 v[26:29], v[180:183], v[220:223], v[26:29]
	v_mfma_f32_16x16x32_bf16 v[14:17], v[172:175], v[228:231], v[14:17]
	v_mfma_f32_16x16x32_bf16 v[10:13], v[180:183], v[228:231], v[10:13]
	v_mfma_f32_16x16x32_bf16 v[62:65], v[176:179], v[208:211], v[62:65]
	v_mfma_f32_16x16x32_bf16 v[58:61], v[184:187], v[208:211], v[58:61]
	v_mfma_f32_16x16x32_bf16 v[46:49], v[176:179], v[216:219], v[46:49]
	v_mfma_f32_16x16x32_bf16 v[42:45], v[184:187], v[216:219], v[42:45]
	v_mfma_f32_16x16x32_bf16 v[30:33], v[176:179], v[224:227], v[30:33]
	v_mfma_f32_16x16x32_bf16 v[26:29], v[184:187], v[224:227], v[26:29]
	v_mfma_f32_16x16x32_bf16 v[14:17], v[176:179], v[232:235], v[14:17]
	v_mfma_f32_16x16x32_bf16 v[10:13], v[184:187], v[232:235], v[10:13]
	v_mfma_f32_16x16x32_bf16 v[54:57], v[188:191], v[204:207], v[54:57]
	v_mfma_f32_16x16x32_bf16 v[50:53], v[196:199], v[204:207], v[50:53]
	v_mfma_f32_16x16x32_bf16 v[38:41], v[188:191], v[212:215], v[38:41]
	v_mfma_f32_16x16x32_bf16 v[34:37], v[196:199], v[212:215], v[34:37]
	v_mfma_f32_16x16x32_bf16 v[22:25], v[188:191], v[220:223], v[22:25]
	v_mfma_f32_16x16x32_bf16 v[18:21], v[196:199], v[220:223], v[18:21]
	v_mfma_f32_16x16x32_bf16 v[6:9], v[188:191], v[228:231], v[6:9]
	v_mfma_f32_16x16x32_bf16 v[2:5], v[196:199], v[228:231], v[2:5]
	v_mfma_f32_16x16x32_bf16 v[54:57], v[192:195], v[208:211], v[54:57]
	v_mfma_f32_16x16x32_bf16 v[50:53], v[200:203], v[208:211], v[50:53]
	v_mfma_f32_16x16x32_bf16 v[38:41], v[192:195], v[216:219], v[38:41]
	v_mfma_f32_16x16x32_bf16 v[34:37], v[200:203], v[216:219], v[34:37]
	v_mfma_f32_16x16x32_bf16 v[22:25], v[192:195], v[224:227], v[22:25]
	v_mfma_f32_16x16x32_bf16 v[18:21], v[200:203], v[224:227], v[18:21]
	v_mfma_f32_16x16x32_bf16 v[6:9], v[192:195], v[232:235], v[6:9]
	v_mfma_f32_16x16x32_bf16 v[2:5], v[200:203], v[232:235], v[2:5]
	s_barrier
; #define PG8_STAGE(bufoff, gbase, voff) do { _Pragma("unroll") for (int _i = 0; _i < 2; ++_i) \
;         __builtin_amdgcn_global_load_lds((const unsigned*)((const char*)(gbase) + (voff)[_i]), (LAS unsigned*)(lds + (bufoff) + ldsw + _i * 8192), 16, 0, 0); } while (0)
; #define PG8_LDA(dst, b, h) do { _Pragma("unroll") for (int m = 0; m < 4; ++m) _Pragma("unroll") for (int k = 0; k < 2; ++k) dst[m][k] = *(const LAS bf16x8*)(lds + PG8_SA(b, h) + aoff + m * 2048 + k * 1024); } while (0)
; #define PG8_LDB(dst, b, h) do { _Pragma("unroll") for (int n = 0; n < 2; ++n) _Pragma("unroll") for (int k = 0; k < 2; ++k) dst[n][k] = *(const LAS bf16x8*)(lds + PG8_SB(b, h) + boff + n * 2048 + k * 1024); } while (0)
; #define PG8_MMA(ai, bj, At, Bt) do { __builtin_amdgcn_s_setprio(1); _Pragma("unroll") for (int m = 0; m < 4; ++m) _Pragma("unroll") for (int n = 0; n < 2; ++n) _Pragma("unroll") for (int k = 0; k < 2; ++k) \
;         acc[ai][bj][m][n] = __builtin_amdgcn_mfma_f32_16x16x32_bf16(Bt[n][k], At[m][k], acc[ai][bj][m][n], 0, 0, 0); __builtin_amdgcn_s_setprio(0); } while (0)
; #define PG8_WAIT_V(n) asm volatile("s_waitcnt vmcnt(" #n ")" ::: "memory")
; #define PG8_WAIT_L(n) asm volatile("s_waitcnt lgkmcnt(" #n ")" ::: "memory")
; #define PG8_BAR __builtin_amdgcn_s_barrier()
; #define PG8_SCHED __builtin_amdgcn_sched_barrier(0)
; template <class Epi, class Sched, bool ABLK = false, bool ALIGN_EPI = true, bool SP2 = true, bool BBLK = true>
; __device__ __forceinline__ void gemm_phase(LAS unsigned char* lds, const Gemm g, const Sched& S, const Epi& E) {
;     ...
;             PG8_LDB(B0, 1, 0); PG8_LDB(B1, 1, 1); PG8_SCHED; PG8_LDA(At, 1, 0); PG8_STAGE(PG8_SA(0, 1), a2 + hstepA, voffA);
;             PG8_WAIT_V(8); PG8_WAIT_L(0); PG8_BAR; PG8_MMA(0, 0, At, B0); PG8_MMA(0, 1, At, B1); PG8_BAR; PG8_SCHED;
;             PG8_LDA(At, 1, 1); PG8_STAGE(PG8_SB(1, 0), b3, voffB); PG8_STAGE(PG8_SB(1, 1), b3 + hstepB, voffB); PG8_STAGE(PG8_SA(1, 0), a3, voffA);
;             PG8_WAIT_V(8); PG8_WAIT_L(0); PG8_BAR; PG8_MMA(1, 0, At, B0); PG8_MMA(1, 1, At, B1); PG8_BAR; PG8_SCHED;
	v_add_u32_e32 v171, s60, v1
	ds_read_b128 v[172:175], v171
	ds_read_b128 v[176:179], v171 offset:1024
	ds_read_b128 v[180:183], v171 offset:2048
	ds_read_b128 v[184:187], v171 offset:3072
	v_add_u32_e32 v171, s61, v1
	ds_read_b128 v[188:191], v171
	ds_read_b128 v[192:195], v171 offset:1024
	ds_read_b128 v[196:199], v171 offset:2048
	ds_read_b128 v[200:203], v171 offset:3072
	s_add_u32 s36, s36, 0x80000
	s_addc_u32 s37, s37, 0
	s_mov_b32 m0, s44
	ds_read_b128 v[204:207], v170 offset:32768
	ds_read_b128 v[208:211], v170 offset:33792
	ds_read_b128 v[212:215], v170 offset:34816
	ds_read_b128 v[216:219], v170 offset:35840
	ds_read_b128 v[220:223], v170 offset:36864
	ds_read_b128 v[224:227], v170 offset:37888
	ds_read_b128 v[228:231], v170 offset:38912
	ds_read_b128 v[232:235], v170 offset:39936
	global_load_lds_dwordx4 v136, s[36:37]
	s_mov_b32 m0, s45
	s_nop 0
	global_load_lds_dwordx4 v132, s[36:37]
	s_waitcnt vmcnt(8) lgkmcnt(0)
	s_barrier
	v_mfma_f32_16x16x32_bf16 v[126:129], v[172:175], v[204:207], v[126:129]
	v_mfma_f32_16x16x32_bf16 v[122:125], v[180:183], v[204:207], v[122:125]
	v_mfma_f32_16x16x32_bf16 v[110:113], v[172:175], v[212:215], v[110:113]
	v_mfma_f32_16x16x32_bf16 v[106:109], v[180:183], v[212:215], v[106:109]
	v_mfma_f32_16x16x32_bf16 v[94:97], v[172:175], v[220:223], v[94:97]
	v_mfma_f32_16x16x32_bf16 v[90:93], v[180:183], v[220:223], v[90:93]
	v_mfma_f32_16x16x32_bf16 v[78:81], v[172:175], v[228:231], v[78:81]
	v_mfma_f32_16x16x32_bf16 v[74:77], v[180:183], v[228:231], v[74:77]
	v_mfma_f32_16x16x32_bf16 v[126:129], v[176:179], v[208:211], v[126:129]
	v_mfma_f32_16x16x32_bf16 v[122:125], v[184:187], v[208:211], v[122:125]
	v_mfma_f32_16x16x32_bf16 v[110:113], v[176:179], v[216:219], v[110:113]
	v_mfma_f32_16x16x32_bf16 v[106:109], v[184:187], v[216:219], v[106:109]
	v_mfma_f32_16x16x32_bf16 v[94:97], v[176:179], v[224:227], v[94:97]
	v_mfma_f32_16x16x32_bf16 v[90:93], v[184:187], v[224:227], v[90:93]
	v_mfma_f32_16x16x32_bf16 v[78:81], v[176:179], v[232:235], v[78:81]
	v_mfma_f32_16x16x32_bf16 v[74:77], v[184:187], v[232:235], v[74:77]
	v_mfma_f32_16x16x32_bf16 v[118:121], v[188:191], v[204:207], v[118:121]
	v_mfma_f32_16x16x32_bf16 v[114:117], v[196:199], v[204:207], v[114:117]
	v_mfma_f32_16x16x32_bf16 v[102:105], v[188:191], v[212:215], v[102:105]
	v_mfma_f32_16x16x32_bf16 v[98:101], v[196:199], v[212:215], v[98:101]
	v_mfma_f32_16x16x32_bf16 v[86:89], v[188:191], v[220:223], v[86:89]
	v_mfma_f32_16x16x32_bf16 v[82:85], v[196:199], v[220:223], v[82:85]
	v_mfma_f32_16x16x32_bf16 v[70:73], v[188:191], v[228:231], v[70:73]
	v_mfma_f32_16x16x32_bf16 v[66:69], v[196:199], v[228:231], v[66:69]
	v_mfma_f32_16x16x32_bf16 v[118:121], v[192:195], v[208:211], v[118:121]
	v_mfma_f32_16x16x32_bf16 v[114:117], v[200:203], v[208:211], v[114:117]
	v_mfma_f32_16x16x32_bf16 v[102:105], v[192:195], v[216:219], v[102:105]
	v_mfma_f32_16x16x32_bf16 v[98:101], v[200:203], v[216:219], v[98:101]
	v_mfma_f32_16x16x32_bf16 v[86:89], v[192:195], v[224:227], v[86:89]
	v_mfma_f32_16x16x32_bf16 v[82:85], v[200:203], v[224:227], v[82:85]
	v_mfma_f32_16x16x32_bf16 v[70:73], v[192:195], v[232:235], v[70:73]
	v_mfma_f32_16x16x32_bf16 v[66:69], v[200:203], v[232:235], v[66:69]
	s_barrier
	s_add_u32 s36, s34, 0x8000
	s_addc_u32 s37, s35, 0
	s_add_i32 s58, s60, s40
	s_mov_b32 m0, s58
	ds_read_b128 v[204:207], v170 offset:49152
	ds_read_b128 v[208:211], v170 offset:50176
	ds_read_b128 v[212:215], v170 offset:51200
	ds_read_b128 v[216:219], v170 offset:52224
	ds_read_b128 v[220:223], v170 offset:53248
	ds_read_b128 v[224:227], v170 offset:54272
	ds_read_b128 v[228:231], v170 offset:55296
	ds_read_b128 v[232:235], v170 offset:56320
	global_load_lds_dwordx4 v134, s[36:37]
	s_add_i32 m0, s58, 0x2000
	s_add_u32 s34, s34, 0xc000
	v_lshl_add_u64 v[236:237], s[36:37], 0, v[130:131]
	s_addc_u32 s35, s35, 0
	s_add_i32 s36, s61, s40
	global_load_lds_dwordx4 v[236:237], off
	s_mov_b32 m0, s36
	s_nop 0
	global_load_lds_dwordx4 v134, s[34:35]
	s_add_i32 m0, s36, 0x2000
	s_nop 0
	global_load_lds_dwordx4 v130, s[34:35]
	s_mov_b32 m0, s48
	s_nop 0
	global_load_lds_dwordx4 v136, s[30:31]
	s_mov_b32 m0, s49
	s_nop 0
	global_load_lds_dwordx4 v132, s[30:31]
	s_waitcnt vmcnt(8) lgkmcnt(0)
	s_barrier
	v_mfma_f32_16x16x32_bf16 v[62:65], v[172:175], v[204:207], v[62:65]
	v_mfma_f32_16x16x32_bf16 v[58:61], v[180:183], v[204:207], v[58:61]
	v_mfma_f32_16x16x32_bf16 v[46:49], v[172:175], v[212:215], v[46:49]
	v_mfma_f32_16x16x32_bf16 v[42:45], v[180:183], v[212:215], v[42:45]
	v_mfma_f32_16x16x32_bf16 v[30:33], v[172:175], v[220:223], v[30:33]
	v_mfma_f32_16x16x32_bf16 v[26:29], v[180:183], v[220:223], v[26:29]
	v_mfma_f32_16x16x32_bf16 v[14:17], v[172:175], v[228:231], v[14:17]
	v_mfma_f32_16x16x32_bf16 v[10:13], v[180:183], v[228:231], v[10:13]
	v_mfma_f32_16x16x32_bf16 v[62:65], v[176:179], v[208:211], v[62:65]
	v_mfma_f32_16x16x32_bf16 v[58:61], v[184:187], v[208:211], v[58:61]
	v_mfma_f32_16x16x32_bf16 v[46:49], v[176:179], v[216:219], v[46:49]
	v_mfma_f32_16x16x32_bf16 v[42:45], v[184:187], v[216:219], v[42:45]
	v_mfma_f32_16x16x32_bf16 v[30:33], v[176:179], v[224:227], v[30:33]
	v_mfma_f32_16x16x32_bf16 v[26:29], v[184:187], v[224:227], v[26:29]
	v_mfma_f32_16x16x32_bf16 v[14:17], v[176:179], v[232:235], v[14:17]
	v_mfma_f32_16x16x32_bf16 v[10:13], v[184:187], v[232:235], v[10:13]
	v_mfma_f32_16x16x32_bf16 v[54:57], v[188:191], v[204:207], v[54:57]
	v_mfma_f32_16x16x32_bf16 v[50:53], v[196:199], v[204:207], v[50:53]
	v_mfma_f32_16x16x32_bf16 v[38:41], v[188:191], v[212:215], v[38:41]
	v_mfma_f32_16x16x32_bf16 v[34:37], v[196:199], v[212:215], v[34:37]
	v_mfma_f32_16x16x32_bf16 v[22:25], v[188:191], v[220:223], v[22:25]
	v_mfma_f32_16x16x32_bf16 v[18:21], v[196:199], v[220:223], v[18:21]
	v_mfma_f32_16x16x32_bf16 v[6:9], v[188:191], v[228:231], v[6:9]
	v_mfma_f32_16x16x32_bf16 v[2:5], v[196:199], v[228:231], v[2:5]
	v_mfma_f32_16x16x32_bf16 v[54:57], v[192:195], v[208:211], v[54:57]
	v_mfma_f32_16x16x32_bf16 v[50:53], v[200:203], v[208:211], v[50:53]
	v_mfma_f32_16x16x32_bf16 v[38:41], v[192:195], v[216:219], v[38:41]
	v_mfma_f32_16x16x32_bf16 v[34:37], v[200:203], v[216:219], v[34:37]
	v_mfma_f32_16x16x32_bf16 v[22:25], v[192:195], v[224:227], v[22:25]
	v_mfma_f32_16x16x32_bf16 v[18:21], v[200:203], v[224:227], v[18:21]
	v_mfma_f32_16x16x32_bf16 v[6:9], v[192:195], v[232:235], v[6:9]
	v_mfma_f32_16x16x32_bf16 v[2:5], v[200:203], v[232:235], v[2:5]
	s_barrier
; __device__ __forceinline__ unsigned pk2(float lo, float hi) { const f32x2 v = {lo, hi}; return __builtin_bit_cast(unsigned, __builtin_convertvector(v, bf16x2_t)); }
; __device__ __forceinline__ u32x4 ror8(u32x4 v) { u32x4 r;
; #pragma unroll
;     for (int i = 0; i < 4; ++i) r[i] = (unsigned)__builtin_amdgcn_mov_dpp((int)v[i], 0x128, 0xf, 0xf, true);
;     return r; }
; __device__ __forceinline__ void store_pair(unsigned char* own, size_t stride8, int hi_off, u32x4 lo, u32x4 hi, bool upper) {
;     const u32x4 tlo = ror8(lo), thi = ror8(hi);
;     const u32x4 A = upper ? thi : lo, B = upper ? hi : tlo;
;     unsigned char* pa = upper ? own - stride8 + hi_off : own;
;     unsigned char* pb = upper ? own + hi_off : own + stride8;
;     *(u32x4*)pa = A; *(u32x4*)pb = B;
; }
;     __device__ __forceinline__ void operator()(const f32x4 (&acc)[2][2][4][2], const Unit& u, int wr, int wc, int fr, int fq) const {
; #pragma unroll
;         for (int ai = 0; ai < 2; ++ai)
; #pragma unroll
;             for (int m = 0; m < 4; ++m) { unsigned char* rowp = (unsigned char*)(H + ((size_t)(u.pm * (FF / 64) + u.pn * 4 + wc) * 256 + (wr * 64 + fr + ai * 128 + m * 16)) * 64 + 8 * fq); u32x4 w[2];
; #pragma unroll
;                 for (int bj = 0; bj < 2; ++bj) { f32x4 v0 = acc[ai][bj][m][0], v1 = acc[ai][bj][m][1];
; #pragma unroll
;                     for (int j = 0; j < 4; ++j) { const float a = fmaxf(v0[j], 0.f), b = fmaxf(v1[j], 0.f); v0[j] = a * a; v1[j] = b * b; }
;                     w[bj].x = pk2(v0[0], v0[1]); w[bj].y = pk2(v0[2], v0[3]); w[bj].z = pk2(v1[0], v1[1]); w[bj].w = pk2(v1[2], v1[3]); }
;                 store_pair(rowp, (size_t)8 * 64 * 2, 64, w[0], w[1], fr >= 8); }
	s_add_i32 s57, s57, 2
	s_add_u32 s28, s28, 0x100
	s_addc_u32 s29, s29, 0
	s_add_u32 s55, s55, 0x10000
	s_addc_u32 s56, s56, 0
	s_cmp_gt_u32 s57, 29
	s_cbranch_scc0 .LBB0_2263
	s_lshl_b32 s4, s22, 7
	s_lshl_b32 s5, s24, 2
	s_add_i32 s5, s5, s4
	s_or_b32 s4, s5, s47
	s_ashr_i32 s5, s4, 31
	s_lshl_b64 s[4:5], s[4:5], 15
	s_add_u32 s22, s1, s4
	v_max_f32_e32 v126, 0, v126
	v_max_f32_e32 v122, 0, v122
	v_max_f32_e32 v127, 0, v127
	v_max_f32_e32 v123, 0, v123
	v_max_f32_e32 v128, 0, v128
	v_max_f32_e32 v124, 0, v124
	v_max_f32_e32 v129, 0, v129
	v_max_f32_e32 v125, 0, v125
	v_max_f32_e32 v118, 0, v118
	v_max_f32_e32 v114, 0, v114
	v_max_f32_e32 v119, 0, v119
	v_max_f32_e32 v115, 0, v115
	v_max_f32_e32 v120, 0, v120
	v_max_f32_e32 v116, 0, v116
	v_max_f32_e32 v121, 0, v121
	v_max_f32_e32 v117, 0, v117
	s_addc_u32 s23, s33, s5
	v_pk_mul_f32 v[126:127], v[126:127], v[126:127]
	v_pk_mul_f32 v[122:123], v[122:123], v[122:123]
	v_pk_mul_f32 v[128:129], v[128:129], v[128:129]
	v_pk_mul_f32 v[124:125], v[124:125], v[124:125]
	v_pk_mul_f32 v[118:119], v[118:119], v[118:119]
	v_pk_mul_f32 v[114:115], v[114:115], v[114:115]
	v_pk_mul_f32 v[120:121], v[120:121], v[120:121]
	v_pk_mul_f32 v[116:117], v[116:117], v[116:117]
	v_lshl_add_u64 v[164:165], s[22:23], 0, v[144:145]
	v_cvt_pk_bf16_f32 v126, v126, v127
	v_cvt_pk_bf16_f32 v127, v128, v129
	v_cvt_pk_bf16_f32 v128, v122, v123
	v_cvt_pk_bf16_f32 v129, v124, v125
	v_cvt_pk_bf16_f32 v118, v118, v119
	v_cvt_pk_bf16_f32 v119, v120, v121
	v_cvt_pk_bf16_f32 v114, v114, v115
	v_cvt_pk_bf16_f32 v115, v116, v117
	v_lshl_add_u64 v[122:123], v[164:165], 0, v[138:139]
	s_mov_b64 vcc, s[2:3]
	v_mov_b32_dpp v164, v118 row_ror:8 row_mask:0xf bank_mask:0xf bound_ctrl:1
	v_mov_b32_dpp v165, v119 row_ror:8 row_mask:0xf bank_mask:0xf bound_ctrl:1
	v_mov_b32_dpp v166, v114 row_ror:8 row_mask:0xf bank_mask:0xf bound_ctrl:1
	v_mov_b32_dpp v167, v115 row_ror:8 row_mask:0xf bank_mask:0xf bound_ctrl:1
	v_max_f32_e32 v110, 0, v110
	v_max_f32_e32 v106, 0, v106
	v_max_f32_e32 v111, 0, v111
	v_max_f32_e32 v107, 0, v107
	v_max_f32_e32 v112, 0, v112
	v_max_f32_e32 v108, 0, v108
	v_max_f32_e32 v113, 0, v113
	v_max_f32_e32 v109, 0, v109
	v_max_f32_e32 v102, 0, v102
	v_max_f32_e32 v98, 0, v98
	v_max_f32_e32 v103, 0, v103
	v_max_f32_e32 v99, 0, v99
	v_max_f32_e32 v104, 0, v104
	v_max_f32_e32 v100, 0, v100
	v_max_f32_e32 v105, 0, v105
	v_max_f32_e32 v101, 0, v101
	v_lshl_add_u64 v[124:125], v[122:123], 0, v[140:141]
	v_cndmask_b32_dpp v117, v129, v115, vcc row_ror:8 row_mask:0xf bank_mask:0xf bound_ctrl:1
	v_cndmask_b32_dpp v116, v128, v114, vcc row_ror:8 row_mask:0xf bank_mask:0xf bound_ctrl:1
	v_cndmask_b32_dpp v115, v127, v119, vcc row_ror:8 row_mask:0xf bank_mask:0xf bound_ctrl:1
	v_cndmask_b32_dpp v114, v126, v118, vcc row_ror:8 row_mask:0xf bank_mask:0xf bound_ctrl:1
	v_cndmask_b32_e64 v121, v129, v167, s[2:3]
	v_cndmask_b32_e64 v120, v128, v166, s[2:3]
	v_cndmask_b32_e64 v119, v127, v165, s[2:3]
	v_cndmask_b32_e64 v118, v126, v164, s[2:3]
	v_pk_mul_f32 v[110:111], v[110:111], v[110:111]
	v_pk_mul_f32 v[106:107], v[106:107], v[106:107]
	v_pk_mul_f32 v[112:113], v[112:113], v[112:113]
	v_pk_mul_f32 v[108:109], v[108:109], v[108:109]
	v_pk_mul_f32 v[102:103], v[102:103], v[102:103]
	v_pk_mul_f32 v[98:99], v[98:99], v[98:99]
	v_pk_mul_f32 v[104:105], v[104:105], v[104:105]
	v_pk_mul_f32 v[100:101], v[100:101], v[100:101]
	v_lshl_add_u64 v[122:123], v[122:123], 0, v[142:143]
	s_and_b64 vcc, exec, s[10:11]
	s_cbranch_vccz .LBB0_2266
	s_barrier
.LBB0_2266:
	global_store_dwordx4 v[124:125], v[118:121], off
	global_store_dwordx4 v[122:123], v[114:117], off
	v_cvt_pk_bf16_f32 v110, v110, v111
	v_cvt_pk_bf16_f32 v111, v112, v113
	v_lshl_add_u64 v[114:115], s[22:23], 0, v[146:147]
	v_cvt_pk_bf16_f32 v112, v106, v107
	v_cvt_pk_bf16_f32 v113, v108, v109
	v_cvt_pk_bf16_f32 v102, v102, v103
	v_cvt_pk_bf16_f32 v103, v104, v105
	v_cvt_pk_bf16_f32 v98, v98, v99
	v_cvt_pk_bf16_f32 v99, v100, v101
	v_lshl_add_u64 v[106:107], v[114:115], 0, v[138:139]
	s_mov_b64 vcc, s[2:3]
	v_mov_b32_dpp v114, v102 row_ror:8 row_mask:0xf bank_mask:0xf bound_ctrl:1
	v_mov_b32_dpp v115, v103 row_ror:8 row_mask:0xf bank_mask:0xf bound_ctrl:1
	v_mov_b32_dpp v116, v98 row_ror:8 row_mask:0xf bank_mask:0xf bound_ctrl:1
	v_mov_b32_dpp v117, v99 row_ror:8 row_mask:0xf bank_mask:0xf bound_ctrl:1
	v_max_f32_e32 v94, 0, v94
	v_max_f32_e32 v90, 0, v90
	v_max_f32_e32 v95, 0, v95
	v_max_f32_e32 v91, 0, v91
	v_max_f32_e32 v96, 0, v96
	v_max_f32_e32 v92, 0, v92
	v_max_f32_e32 v97, 0, v97
	v_max_f32_e32 v93, 0, v93
	v_max_f32_e32 v86, 0, v86
	v_max_f32_e32 v82, 0, v82
	v_max_f32_e32 v87, 0, v87
	v_max_f32_e32 v83, 0, v83
	v_max_f32_e32 v88, 0, v88
	v_max_f32_e32 v84, 0, v84
	v_max_f32_e32 v89, 0, v89
	v_max_f32_e32 v85, 0, v85
	v_lshl_add_u64 v[108:109], v[106:107], 0, v[140:141]
	v_cndmask_b32_dpp v101, v113, v99, vcc row_ror:8 row_mask:0xf bank_mask:0xf bound_ctrl:1
	v_cndmask_b32_dpp v100, v112, v98, vcc row_ror:8 row_mask:0xf bank_mask:0xf bound_ctrl:1
	v_cndmask_b32_dpp v99, v111, v103, vcc row_ror:8 row_mask:0xf bank_mask:0xf bound_ctrl:1
	v_cndmask_b32_dpp v98, v110, v102, vcc row_ror:8 row_mask:0xf bank_mask:0xf bound_ctrl:1
	v_cndmask_b32_e64 v105, v113, v117, s[2:3]
	v_cndmask_b32_e64 v104, v112, v116, s[2:3]
	v_cndmask_b32_e64 v103, v111, v115, s[2:3]
	v_cndmask_b32_e64 v102, v110, v114, s[2:3]
	v_pk_mul_f32 v[94:95], v[94:95], v[94:95]
	v_pk_mul_f32 v[90:91], v[90:91], v[90:91]
	v_pk_mul_f32 v[96:97], v[96:97], v[96:97]
	v_pk_mul_f32 v[92:93], v[92:93], v[92:93]
	v_pk_mul_f32 v[86:87], v[86:87], v[86:87]
	v_pk_mul_f32 v[82:83], v[82:83], v[82:83]
	v_pk_mul_f32 v[88:89], v[88:89], v[88:89]
; __device__ __forceinline__ unsigned pk2(float lo, float hi) { const f32x2 v = {lo, hi}; return __builtin_bit_cast(unsigned, __builtin_convertvector(v, bf16x2_t)); }
; __device__ __forceinline__ u32x4 ror8(u32x4 v) { u32x4 r;
; #pragma unroll
;     for (int i = 0; i < 4; ++i) r[i] = (unsigned)__builtin_amdgcn_mov_dpp((int)v[i], 0x128, 0xf, 0xf, true);
;     return r; }
; __device__ __forceinline__ void store_pair(unsigned char* own, size_t stride8, int hi_off, u32x4 lo, u32x4 hi, bool upper) {
;     const u32x4 tlo = ror8(lo), thi = ror8(hi);
;     const u32x4 A = upper ? thi : lo, B = upper ? hi : tlo;
;     unsigned char* pa = upper ? own - stride8 + hi_off : own;
;     unsigned char* pb = upper ? own + hi_off : own + stride8;
;     *(u32x4*)pa = A; *(u32x4*)pb = B;
; }
;     __device__ __forceinline__ void operator()(const f32x4 (&acc)[2][2][4][2], const Unit& u, int wr, int wc, int fr, int fq) const {
; #pragma unroll
;         for (int ai = 0; ai < 2; ++ai)
; #pragma unroll
;             for (int m = 0; m < 4; ++m) { unsigned char* rowp = (unsigned char*)(H + ((size_t)(u.pm * (FF / 64) + u.pn * 4 + wc) * 256 + (wr * 64 + fr + ai * 128 + m * 16)) * 64 + 8 * fq); u32x4 w[2];
; #pragma unroll
;                 for (int bj = 0; bj < 2; ++bj) { f32x4 v0 = acc[ai][bj][m][0], v1 = acc[ai][bj][m][1];
; #pragma unroll
;                     for (int j = 0; j < 4; ++j) { const float a = fmaxf(v0[j], 0.f), b = fmaxf(v1[j], 0.f); v0[j] = a * a; v1[j] = b * b; }
;                     w[bj].x = pk2(v0[0], v0[1]); w[bj].y = pk2(v0[2], v0[3]); w[bj].z = pk2(v1[0], v1[1]); w[bj].w = pk2(v1[2], v1[3]); }
;                 store_pair(rowp, (size_t)8 * 64 * 2, 64, w[0], w[1], fr >= 8); }
	v_pk_mul_f32 v[84:85], v[84:85], v[84:85]
	v_lshl_add_u64 v[106:107], v[106:107], 0, v[142:143]
	global_store_dwordx4 v[108:109], v[102:105], off
	global_store_dwordx4 v[106:107], v[98:101], off
	v_cvt_pk_bf16_f32 v94, v94, v95
	v_cvt_pk_bf16_f32 v95, v96, v97
	v_lshl_add_u64 v[98:99], s[22:23], 0, v[148:149]
	v_cvt_pk_bf16_f32 v96, v90, v91
	v_cvt_pk_bf16_f32 v97, v92, v93
	v_cvt_pk_bf16_f32 v86, v86, v87
	v_cvt_pk_bf16_f32 v87, v88, v89
	v_cvt_pk_bf16_f32 v82, v82, v83
	v_cvt_pk_bf16_f32 v83, v84, v85
	v_lshl_add_u64 v[90:91], v[98:99], 0, v[138:139]
	s_mov_b64 vcc, s[2:3]
	v_mov_b32_dpp v98, v86 row_ror:8 row_mask:0xf bank_mask:0xf bound_ctrl:1
	v_mov_b32_dpp v99, v87 row_ror:8 row_mask:0xf bank_mask:0xf bound_ctrl:1
	v_mov_b32_dpp v100, v82 row_ror:8 row_mask:0xf bank_mask:0xf bound_ctrl:1
	v_mov_b32_dpp v101, v83 row_ror:8 row_mask:0xf bank_mask:0xf bound_ctrl:1
	v_max_f32_e32 v78, 0, v78
	v_max_f32_e32 v74, 0, v74
	v_max_f32_e32 v79, 0, v79
	v_max_f32_e32 v75, 0, v75
	v_max_f32_e32 v80, 0, v80
	v_max_f32_e32 v76, 0, v76
	v_max_f32_e32 v81, 0, v81
	v_max_f32_e32 v77, 0, v77
	v_max_f32_e32 v70, 0, v70
	v_max_f32_e32 v66, 0, v66
	v_max_f32_e32 v71, 0, v71
	v_max_f32_e32 v67, 0, v67
	v_max_f32_e32 v72, 0, v72
	v_max_f32_e32 v68, 0, v68
	v_max_f32_e32 v73, 0, v73
	v_max_f32_e32 v69, 0, v69
	v_lshl_add_u64 v[92:93], v[90:91], 0, v[140:141]
	v_cndmask_b32_dpp v85, v97, v83, vcc row_ror:8 row_mask:0xf bank_mask:0xf bound_ctrl:1
	v_cndmask_b32_dpp v84, v96, v82, vcc row_ror:8 row_mask:0xf bank_mask:0xf bound_ctrl:1
	v_cndmask_b32_dpp v83, v95, v87, vcc row_ror:8 row_mask:0xf bank_mask:0xf bound_ctrl:1
	v_cndmask_b32_dpp v82, v94, v86, vcc row_ror:8 row_mask:0xf bank_mask:0xf bound_ctrl:1
	v_cndmask_b32_e64 v89, v97, v101, s[2:3]
	v_cndmask_b32_e64 v88, v96, v100, s[2:3]
	v_cndmask_b32_e64 v87, v95, v99, s[2:3]
	v_cndmask_b32_e64 v86, v94, v98, s[2:3]
	v_pk_mul_f32 v[78:79], v[78:79], v[78:79]
	v_pk_mul_f32 v[74:75], v[74:75], v[74:75]
	v_pk_mul_f32 v[80:81], v[80:81], v[80:81]
	v_pk_mul_f32 v[76:77], v[76:77], v[76:77]
	v_pk_mul_f32 v[70:71], v[70:71], v[70:71]
	v_pk_mul_f32 v[66:67], v[66:67], v[66:67]
	v_pk_mul_f32 v[72:73], v[72:73], v[72:73]
	v_pk_mul_f32 v[68:69], v[68:69], v[68:69]
	v_lshl_add_u64 v[90:91], v[90:91], 0, v[142:143]
	global_store_dwordx4 v[92:93], v[86:89], off
	global_store_dwordx4 v[90:91], v[82:85], off
	v_cvt_pk_bf16_f32 v78, v78, v79
	v_cvt_pk_bf16_f32 v79, v80, v81
	v_lshl_add_u64 v[82:83], s[22:23], 0, v[150:151]
	v_cvt_pk_bf16_f32 v80, v74, v75
	v_cvt_pk_bf16_f32 v81, v76, v77
	v_cvt_pk_bf16_f32 v70, v70, v71
	v_cvt_pk_bf16_f32 v71, v72, v73
	v_cvt_pk_bf16_f32 v66, v66, v67
	v_cvt_pk_bf16_f32 v67, v68, v69
	v_lshl_add_u64 v[74:75], v[82:83], 0, v[138:139]
	s_mov_b64 vcc, s[2:3]
	v_mov_b32_dpp v82, v70 row_ror:8 row_mask:0xf bank_mask:0xf bound_ctrl:1
	v_mov_b32_dpp v83, v71 row_ror:8 row_mask:0xf bank_mask:0xf bound_ctrl:1
	v_mov_b32_dpp v84, v66 row_ror:8 row_mask:0xf bank_mask:0xf bound_ctrl:1
	v_mov_b32_dpp v85, v67 row_ror:8 row_mask:0xf bank_mask:0xf bound_ctrl:1
	v_max_f32_e32 v62, 0, v62
	v_max_f32_e32 v58, 0, v58
	v_max_f32_e32 v63, 0, v63
	v_max_f32_e32 v59, 0, v59
	v_max_f32_e32 v64, 0, v64
	v_max_f32_e32 v60, 0, v60
	v_max_f32_e32 v65, 0, v65
	v_max_f32_e32 v61, 0, v61
	v_max_f32_e32 v54, 0, v54
	v_max_f32_e32 v50, 0, v50
	v_max_f32_e32 v55, 0, v55
	v_max_f32_e32 v51, 0, v51
	v_max_f32_e32 v56, 0, v56
	v_max_f32_e32 v52, 0, v52
	v_max_f32_e32 v57, 0, v57
	v_max_f32_e32 v53, 0, v53
	v_lshl_add_u64 v[76:77], v[74:75], 0, v[140:141]
	v_cndmask_b32_dpp v69, v81, v67, vcc row_ror:8 row_mask:0xf bank_mask:0xf bound_ctrl:1
	v_cndmask_b32_dpp v68, v80, v66, vcc row_ror:8 row_mask:0xf bank_mask:0xf bound_ctrl:1
	v_cndmask_b32_dpp v67, v79, v71, vcc row_ror:8 row_mask:0xf bank_mask:0xf bound_ctrl:1
	v_cndmask_b32_dpp v66, v78, v70, vcc row_ror:8 row_mask:0xf bank_mask:0xf bound_ctrl:1
	v_cndmask_b32_e64 v73, v81, v85, s[2:3]
	v_cndmask_b32_e64 v72, v80, v84, s[2:3]
	v_cndmask_b32_e64 v71, v79, v83, s[2:3]
	v_cndmask_b32_e64 v70, v78, v82, s[2:3]
	v_pk_mul_f32 v[62:63], v[62:63], v[62:63]
	v_pk_mul_f32 v[58:59], v[58:59], v[58:59]
	v_pk_mul_f32 v[64:65], v[64:65], v[64:65]
	v_pk_mul_f32 v[60:61], v[60:61], v[60:61]
	v_pk_mul_f32 v[54:55], v[54:55], v[54:55]
	v_pk_mul_f32 v[50:51], v[50:51], v[50:51]
	v_pk_mul_f32 v[56:57], v[56:57], v[56:57]
	v_pk_mul_f32 v[52:53], v[52:53], v[52:53]
	v_lshl_add_u64 v[74:75], v[74:75], 0, v[142:143]
	global_store_dwordx4 v[76:77], v[70:73], off
	global_store_dwordx4 v[74:75], v[66:69], off
	v_cvt_pk_bf16_f32 v62, v62, v63
	v_cvt_pk_bf16_f32 v63, v64, v65
	v_lshl_add_u64 v[66:67], s[22:23], 0, v[152:153]
	v_cvt_pk_bf16_f32 v64, v58, v59
	v_cvt_pk_bf16_f32 v65, v60, v61
	v_cvt_pk_bf16_f32 v54, v54, v55
	v_cvt_pk_bf16_f32 v55, v56, v57
	v_cvt_pk_bf16_f32 v50, v50, v51
	v_cvt_pk_bf16_f32 v51, v52, v53
	v_lshl_add_u64 v[58:59], v[66:67], 0, v[138:139]
	s_mov_b64 vcc, s[2:3]
	v_mov_b32_dpp v66, v54 row_ror:8 row_mask:0xf bank_mask:0xf bound_ctrl:1
	v_mov_b32_dpp v67, v55 row_ror:8 row_mask:0xf bank_mask:0xf bound_ctrl:1
	v_mov_b32_dpp v68, v50 row_ror:8 row_mask:0xf bank_mask:0xf bound_ctrl:1
	v_mov_b32_dpp v69, v51 row_ror:8 row_mask:0xf bank_mask:0xf bound_ctrl:1
	v_max_f32_e32 v46, 0, v46
	v_max_f32_e32 v42, 0, v42
	v_max_f32_e32 v47, 0, v47
	v_max_f32_e32 v43, 0, v43
	v_max_f32_e32 v48, 0, v48
	v_max_f32_e32 v44, 0, v44
	v_max_f32_e32 v49, 0, v49
	v_max_f32_e32 v45, 0, v45
	v_max_f32_e32 v38, 0, v38
	v_max_f32_e32 v34, 0, v34
	v_max_f32_e32 v39, 0, v39
	v_max_f32_e32 v35, 0, v35
	v_max_f32_e32 v40, 0, v40
	v_max_f32_e32 v36, 0, v36
	v_max_f32_e32 v41, 0, v41
	v_max_f32_e32 v37, 0, v37
; __device__ __forceinline__ unsigned pk2(float lo, float hi) { const f32x2 v = {lo, hi}; return __builtin_bit_cast(unsigned, __builtin_convertvector(v, bf16x2_t)); }
; __device__ __forceinline__ u32x4 ror8(u32x4 v) { u32x4 r;
; #pragma unroll
;     for (int i = 0; i < 4; ++i) r[i] = (unsigned)__builtin_amdgcn_mov_dpp((int)v[i], 0x128, 0xf, 0xf, true);
;     return r; }
; __device__ __forceinline__ void store_pair(unsigned char* own, size_t stride8, int hi_off, u32x4 lo, u32x4 hi, bool upper) {
;     const u32x4 tlo = ror8(lo), thi = ror8(hi);
;     const u32x4 A = upper ? thi : lo, B = upper ? hi : tlo;
;     unsigned char* pa = upper ? own - stride8 + hi_off : own;
;     unsigned char* pb = upper ? own + hi_off : own + stride8;
;     *(u32x4*)pa = A; *(u32x4*)pb = B;
; }
;     __device__ __forceinline__ void operator()(const f32x4 (&acc)[2][2][4][2], const Unit& u, int wr, int wc, int fr, int fq) const {
; #pragma unroll
;         for (int ai = 0; ai < 2; ++ai)
; #pragma unroll
;             for (int m = 0; m < 4; ++m) { unsigned char* rowp = (unsigned char*)(H + ((size_t)(u.pm * (FF / 64) + u.pn * 4 + wc) * 256 + (wr * 64 + fr + ai * 128 + m * 16)) * 64 + 8 * fq); u32x4 w[2];
; #pragma unroll
;                 for (int bj = 0; bj < 2; ++bj) { f32x4 v0 = acc[ai][bj][m][0], v1 = acc[ai][bj][m][1];
; #pragma unroll
;                     for (int j = 0; j < 4; ++j) { const float a = fmaxf(v0[j], 0.f), b = fmaxf(v1[j], 0.f); v0[j] = a * a; v1[j] = b * b; }
;                     w[bj].x = pk2(v0[0], v0[1]); w[bj].y = pk2(v0[2], v0[3]); w[bj].z = pk2(v1[0], v1[1]); w[bj].w = pk2(v1[2], v1[3]); }
;                 store_pair(rowp, (size_t)8 * 64 * 2, 64, w[0], w[1], fr >= 8); }
	v_lshl_add_u64 v[60:61], v[58:59], 0, v[140:141]
	v_cndmask_b32_dpp v53, v65, v51, vcc row_ror:8 row_mask:0xf bank_mask:0xf bound_ctrl:1
	v_cndmask_b32_dpp v52, v64, v50, vcc row_ror:8 row_mask:0xf bank_mask:0xf bound_ctrl:1
	v_cndmask_b32_dpp v51, v63, v55, vcc row_ror:8 row_mask:0xf bank_mask:0xf bound_ctrl:1
	v_cndmask_b32_dpp v50, v62, v54, vcc row_ror:8 row_mask:0xf bank_mask:0xf bound_ctrl:1
	v_cndmask_b32_e64 v57, v65, v69, s[2:3]
	v_cndmask_b32_e64 v56, v64, v68, s[2:3]
	v_cndmask_b32_e64 v55, v63, v67, s[2:3]
	v_cndmask_b32_e64 v54, v62, v66, s[2:3]
	v_pk_mul_f32 v[46:47], v[46:47], v[46:47]
	v_pk_mul_f32 v[42:43], v[42:43], v[42:43]
	v_pk_mul_f32 v[48:49], v[48:49], v[48:49]
	v_pk_mul_f32 v[44:45], v[44:45], v[44:45]
	v_pk_mul_f32 v[38:39], v[38:39], v[38:39]
	v_pk_mul_f32 v[34:35], v[34:35], v[34:35]
	v_pk_mul_f32 v[40:41], v[40:41], v[40:41]
	v_pk_mul_f32 v[36:37], v[36:37], v[36:37]
	v_lshl_add_u64 v[58:59], v[58:59], 0, v[142:143]
	global_store_dwordx4 v[60:61], v[54:57], off
	global_store_dwordx4 v[58:59], v[50:53], off
	v_cvt_pk_bf16_f32 v46, v46, v47
	v_cvt_pk_bf16_f32 v47, v48, v49
	v_lshl_add_u64 v[50:51], s[22:23], 0, v[154:155]
	v_cvt_pk_bf16_f32 v48, v42, v43
	v_cvt_pk_bf16_f32 v49, v44, v45
	v_cvt_pk_bf16_f32 v38, v38, v39
	v_cvt_pk_bf16_f32 v39, v40, v41
	v_cvt_pk_bf16_f32 v34, v34, v35
	v_cvt_pk_bf16_f32 v35, v36, v37
	v_lshl_add_u64 v[42:43], v[50:51], 0, v[138:139]
	s_mov_b64 vcc, s[2:3]
	v_mov_b32_dpp v50, v38 row_ror:8 row_mask:0xf bank_mask:0xf bound_ctrl:1
	v_mov_b32_dpp v51, v39 row_ror:8 row_mask:0xf bank_mask:0xf bound_ctrl:1
	v_mov_b32_dpp v52, v34 row_ror:8 row_mask:0xf bank_mask:0xf bound_ctrl:1
	v_mov_b32_dpp v53, v35 row_ror:8 row_mask:0xf bank_mask:0xf bound_ctrl:1
	v_max_f32_e32 v30, 0, v30
	v_max_f32_e32 v26, 0, v26
	v_max_f32_e32 v31, 0, v31
	v_max_f32_e32 v27, 0, v27
	v_max_f32_e32 v32, 0, v32
	v_max_f32_e32 v28, 0, v28
	v_max_f32_e32 v33, 0, v33
	v_max_f32_e32 v29, 0, v29
	v_max_f32_e32 v22, 0, v22
	v_max_f32_e32 v18, 0, v18
	v_max_f32_e32 v23, 0, v23
	v_max_f32_e32 v19, 0, v19
	v_max_f32_e32 v24, 0, v24
	v_max_f32_e32 v20, 0, v20
	v_max_f32_e32 v25, 0, v25
	v_max_f32_e32 v21, 0, v21
	v_lshl_add_u64 v[44:45], v[42:43], 0, v[140:141]
	v_cndmask_b32_dpp v37, v49, v35, vcc row_ror:8 row_mask:0xf bank_mask:0xf bound_ctrl:1
	v_cndmask_b32_dpp v36, v48, v34, vcc row_ror:8 row_mask:0xf bank_mask:0xf bound_ctrl:1
	v_cndmask_b32_dpp v35, v47, v39, vcc row_ror:8 row_mask:0xf bank_mask:0xf bound_ctrl:1
	v_cndmask_b32_dpp v34, v46, v38, vcc row_ror:8 row_mask:0xf bank_mask:0xf bound_ctrl:1
	v_cndmask_b32_e64 v41, v49, v53, s[2:3]
	v_cndmask_b32_e64 v40, v48, v52, s[2:3]
	v_cndmask_b32_e64 v39, v47, v51, s[2:3]
	v_cndmask_b32_e64 v38, v46, v50, s[2:3]
	v_pk_mul_f32 v[30:31], v[30:31], v[30:31]
	v_pk_mul_f32 v[26:27], v[26:27], v[26:27]
	v_pk_mul_f32 v[32:33], v[32:33], v[32:33]
	v_pk_mul_f32 v[28:29], v[28:29], v[28:29]
	v_pk_mul_f32 v[22:23], v[22:23], v[22:23]
	v_pk_mul_f32 v[18:19], v[18:19], v[18:19]
	v_pk_mul_f32 v[24:25], v[24:25], v[24:25]
	v_pk_mul_f32 v[20:21], v[20:21], v[20:21]
	v_lshl_add_u64 v[42:43], v[42:43], 0, v[142:143]
	global_store_dwordx4 v[44:45], v[38:41], off
	global_store_dwordx4 v[42:43], v[34:37], off
	v_cvt_pk_bf16_f32 v30, v30, v31
	v_cvt_pk_bf16_f32 v31, v32, v33
	v_lshl_add_u64 v[34:35], s[22:23], 0, v[156:157]
	v_cvt_pk_bf16_f32 v32, v26, v27
	v_cvt_pk_bf16_f32 v33, v28, v29
	v_cvt_pk_bf16_f32 v22, v22, v23
	v_cvt_pk_bf16_f32 v23, v24, v25
	v_cvt_pk_bf16_f32 v18, v18, v19
	v_cvt_pk_bf16_f32 v19, v20, v21
	v_lshl_add_u64 v[26:27], v[34:35], 0, v[138:139]
	s_mov_b64 vcc, s[2:3]
	v_mov_b32_dpp v34, v22 row_ror:8 row_mask:0xf bank_mask:0xf bound_ctrl:1
	v_mov_b32_dpp v35, v23 row_ror:8 row_mask:0xf bank_mask:0xf bound_ctrl:1
	v_mov_b32_dpp v36, v18 row_ror:8 row_mask:0xf bank_mask:0xf bound_ctrl:1
	v_mov_b32_dpp v37, v19 row_ror:8 row_mask:0xf bank_mask:0xf bound_ctrl:1
	v_max_f32_e32 v14, 0, v14
	v_max_f32_e32 v10, 0, v10
	v_max_f32_e32 v15, 0, v15
	v_max_f32_e32 v11, 0, v11
	v_max_f32_e32 v16, 0, v16
	v_max_f32_e32 v12, 0, v12
	v_max_f32_e32 v17, 0, v17
	v_max_f32_e32 v13, 0, v13
	v_max_f32_e32 v6, 0, v6
	v_max_f32_e32 v2, 0, v2
	v_max_f32_e32 v7, 0, v7
	v_max_f32_e32 v3, 0, v3
	v_max_f32_e32 v8, 0, v8
	v_max_f32_e32 v4, 0, v4
	v_max_f32_e32 v9, 0, v9
	v_max_f32_e32 v5, 0, v5
	v_lshl_add_u64 v[28:29], v[26:27], 0, v[140:141]
	v_cndmask_b32_dpp v21, v33, v19, vcc row_ror:8 row_mask:0xf bank_mask:0xf bound_ctrl:1
	v_cndmask_b32_dpp v20, v32, v18, vcc row_ror:8 row_mask:0xf bank_mask:0xf bound_ctrl:1
	v_cndmask_b32_dpp v19, v31, v23, vcc row_ror:8 row_mask:0xf bank_mask:0xf bound_ctrl:1
	v_cndmask_b32_dpp v18, v30, v22, vcc row_ror:8 row_mask:0xf bank_mask:0xf bound_ctrl:1
	v_cndmask_b32_e64 v25, v33, v37, s[2:3]
	v_cndmask_b32_e64 v24, v32, v36, s[2:3]
	v_cndmask_b32_e64 v23, v31, v35, s[2:3]
	v_cndmask_b32_e64 v22, v30, v34, s[2:3]
	v_pk_mul_f32 v[14:15], v[14:15], v[14:15]
	v_pk_mul_f32 v[10:11], v[10:11], v[10:11]
	v_pk_mul_f32 v[16:17], v[16:17], v[16:17]
	v_pk_mul_f32 v[12:13], v[12:13], v[12:13]
	v_pk_mul_f32 v[6:7], v[6:7], v[6:7]
	v_pk_mul_f32 v[2:3], v[2:3], v[2:3]
	v_pk_mul_f32 v[8:9], v[8:9], v[8:9]
	v_pk_mul_f32 v[4:5], v[4:5], v[4:5]
	v_lshl_add_u64 v[26:27], v[26:27], 0, v[142:143]
	global_store_dwordx4 v[28:29], v[22:25], off
	global_store_dwordx4 v[26:27], v[18:21], off
	v_cvt_pk_bf16_f32 v14, v14, v15
	v_cvt_pk_bf16_f32 v15, v16, v17
	v_lshl_add_u64 v[18:19], s[22:23], 0, v[158:159]
	v_cvt_pk_bf16_f32 v16, v10, v11
	v_cvt_pk_bf16_f32 v17, v12, v13
	v_cvt_pk_bf16_f32 v6, v6, v7
	v_cvt_pk_bf16_f32 v7, v8, v9
	v_cvt_pk_bf16_f32 v2, v2, v3
	v_cvt_pk_bf16_f32 v3, v4, v5
	v_lshl_add_u64 v[10:11], v[18:19], 0, v[138:139]
	s_mov_b64 vcc, s[2:3]
	v_mov_b32_dpp v18, v6 row_ror:8 row_mask:0xf bank_mask:0xf bound_ctrl:1
	v_mov_b32_dpp v19, v7 row_ror:8 row_mask:0xf bank_mask:0xf bound_ctrl:1
	v_mov_b32_dpp v20, v2 row_ror:8 row_mask:0xf bank_mask:0xf bound_ctrl:1
	v_mov_b32_dpp v21, v3 row_ror:8 row_mask:0xf bank_mask:0xf bound_ctrl:1
	v_lshl_add_u64 v[12:13], v[10:11], 0, v[140:141]
	v_cndmask_b32_dpp v5, v17, v3, vcc row_ror:8 row_mask:0xf bank_mask:0xf bound_ctrl:1
	v_cndmask_b32_dpp v4, v16, v2, vcc row_ror:8 row_mask:0xf bank_mask:0xf bound_ctrl:1
	v_cndmask_b32_dpp v3, v15, v7, vcc row_ror:8 row_mask:0xf bank_mask:0xf bound_ctrl:1
	v_cndmask_b32_dpp v2, v14, v6, vcc row_ror:8 row_mask:0xf bank_mask:0xf bound_ctrl:1
	v_cndmask_b32_e64 v9, v17, v21, s[2:3]
	v_cndmask_b32_e64 v8, v16, v20, s[2:3]
	v_cndmask_b32_e64 v7, v15, v19, s[2:3]
	v_cndmask_b32_e64 v6, v14, v18, s[2:3]
	s_andn2_b64 vcc, exec, s[18:19]
	s_mov_b64 s[4:5], -1
	v_lshl_add_u64 v[10:11], v[10:11], 0, v[142:143]
	global_store_dwordx4 v[12:13], v[6:9], off
	global_store_dwordx4 v[10:11], v[2:5], off
	s_cbranch_vccnz .LBB0_2259
	s_andn2_b64 vcc, exec, s[6:7]
	s_cbranch_vccnz .LBB0_2258
	s_barrier
	s_branch .LBB0_2258

; #define PG8_STAGE(bufoff, gbase, voff) do { _Pragma("unroll") for (int _i = 0; _i < 2; ++_i) \
;         __builtin_amdgcn_global_load_lds((const unsigned*)((const char*)(gbase) + (voff)[_i]), (LAS unsigned*)(lds + (bufoff) + ldsw + _i * 8192), 16, 0, 0); } while (0)
; #define PG8_LDA(dst, b, h) do { _Pragma("unroll") for (int m = 0; m < 4; ++m) _Pragma("unroll") for (int k = 0; k < 2; ++k) dst[m][k] = *(const LAS bf16x8*)(lds + PG8_SA(b, h) + aoff + m * 2048 + k * 1024); } while (0)
; #define PG8_LDB(dst, b, h) do { _Pragma("unroll") for (int n = 0; n < 2; ++n) _Pragma("unroll") for (int k = 0; k < 2; ++k) dst[n][k] = *(const LAS bf16x8*)(lds + PG8_SB(b, h) + boff + n * 2048 + k * 1024); } while (0)
; #define PG8_MMA(ai, bj, At, Bt) do { __builtin_amdgcn_s_setprio(1); _Pragma("unroll") for (int m = 0; m < 4; ++m) _Pragma("unroll") for (int n = 0; n < 2; ++n) _Pragma("unroll") for (int k = 0; k < 2; ++k) \
;         acc[ai][bj][m][n] = __builtin_amdgcn_mfma_f32_16x16x32_bf16(Bt[n][k], At[m][k], acc[ai][bj][m][n], 0, 0, 0); __builtin_amdgcn_s_setprio(0); } while (0)
; #define PG8_WAIT_V(n) asm volatile("s_waitcnt vmcnt(" #n ")" ::: "memory")
; #define PG8_WAIT_L(n) asm volatile("s_waitcnt lgkmcnt(" #n ")" ::: "memory")
; #define PG8_BAR __builtin_amdgcn_s_barrier()
; #define PG8_SCHED __builtin_amdgcn_sched_barrier(0)
; template <class Epi, class Sched, bool ABLK = false, bool ALIGN_EPI = true, bool SP2 = true, bool BBLK = true>
; __device__ __forceinline__ void gemm_phase(LAS unsigned char* lds, const Gemm g, const Sched& S, const Epi& E) {
;     ...
;             PG8_LDB(B0, 0, 0); PG8_LDB(B1, 0, 1); PG8_SCHED; PG8_LDA(At, 0, 0); PG8_STAGE(PG8_SA(1, 1), a1 + hstepA, voffA);
;             PG8_WAIT_V(8); PG8_WAIT_L(0); PG8_BAR; PG8_MMA(0, 0, At, B0); PG8_MMA(0, 1, At, B1); PG8_BAR; PG8_SCHED;
;             PG8_LDA(At, 0, 1); PG8_STAGE(PG8_SB(0, 0), b2, voffB); PG8_STAGE(PG8_SB(0, 1), b2 + hstepB, voffB); PG8_STAGE(PG8_SA(0, 0), a2, voffA);
;             PG8_WAIT_V(8); PG8_WAIT_L(0); PG8_BAR; PG8_MMA(1, 0, At, B0); PG8_MMA(1, 1, At, B1); PG8_BAR; PG8_SCHED;
.Lksel_27_back:
	v_lshl_add_u64 v[216:217], v[142:143], 0, s[38:39]
	s_add_i32 m0, s49, 0xc000
	ds_read_b128 v[184:187], v150
	ds_read_b128 v[188:191], v150 offset:1024
	ds_read_b128 v[192:195], v150 offset:2048
	ds_read_b128 v[196:199], v150 offset:3072
	ds_read_b128 v[200:203], v150 offset:4096
	ds_read_b128 v[204:207], v150 offset:5120
	ds_read_b128 v[208:211], v150 offset:6144
	ds_read_b128 v[212:215], v150 offset:7168
	global_load_lds_dwordx4 v[216:217], off
	v_lshl_add_u64 v[216:217], v[144:145], 0, s[38:39]
	s_add_i32 m0, s49, 0xe000
	s_nop 0
	global_load_lds_dwordx4 v[216:217], off
	s_waitcnt vmcnt(8) lgkmcnt(0)
	s_barrier
	v_mfma_f32_16x16x32_bf16 v[126:129], v[152:155], v[184:187], v[126:129]
	v_mfma_f32_16x16x32_bf16 v[122:125], v[160:163], v[184:187], v[122:125]
	v_mfma_f32_16x16x32_bf16 v[110:113], v[152:155], v[192:195], v[110:113]
	v_mfma_f32_16x16x32_bf16 v[106:109], v[160:163], v[192:195], v[106:109]
	v_mfma_f32_16x16x32_bf16 v[94:97], v[152:155], v[200:203], v[94:97]
	v_mfma_f32_16x16x32_bf16 v[90:93], v[160:163], v[200:203], v[90:93]
	v_mfma_f32_16x16x32_bf16 v[78:81], v[152:155], v[208:211], v[78:81]
	v_mfma_f32_16x16x32_bf16 v[74:77], v[160:163], v[208:211], v[74:77]
	v_mfma_f32_16x16x32_bf16 v[126:129], v[156:159], v[188:191], v[126:129]
	v_mfma_f32_16x16x32_bf16 v[122:125], v[164:167], v[188:191], v[122:125]
	v_mfma_f32_16x16x32_bf16 v[110:113], v[156:159], v[196:199], v[110:113]
	v_mfma_f32_16x16x32_bf16 v[106:109], v[164:167], v[196:199], v[106:109]
	v_mfma_f32_16x16x32_bf16 v[94:97], v[156:159], v[204:207], v[94:97]
	v_mfma_f32_16x16x32_bf16 v[90:93], v[164:167], v[204:207], v[90:93]
	v_mfma_f32_16x16x32_bf16 v[78:81], v[156:159], v[212:215], v[78:81]
	v_mfma_f32_16x16x32_bf16 v[74:77], v[164:167], v[212:215], v[74:77]
	v_mfma_f32_16x16x32_bf16 v[118:121], v[168:171], v[184:187], v[118:121]
	v_mfma_f32_16x16x32_bf16 v[114:117], v[176:179], v[184:187], v[114:117]
	v_mfma_f32_16x16x32_bf16 v[102:105], v[168:171], v[192:195], v[102:105]
	v_mfma_f32_16x16x32_bf16 v[98:101], v[176:179], v[192:195], v[98:101]
	v_mfma_f32_16x16x32_bf16 v[86:89], v[168:171], v[200:203], v[86:89]
	v_mfma_f32_16x16x32_bf16 v[82:85], v[176:179], v[200:203], v[82:85]
	v_mfma_f32_16x16x32_bf16 v[70:73], v[168:171], v[208:211], v[70:73]
	v_mfma_f32_16x16x32_bf16 v[66:69], v[176:179], v[208:211], v[66:69]
	v_mfma_f32_16x16x32_bf16 v[118:121], v[172:175], v[188:191], v[118:121]
	v_mfma_f32_16x16x32_bf16 v[114:117], v[180:183], v[188:191], v[114:117]
	v_mfma_f32_16x16x32_bf16 v[102:105], v[172:175], v[196:199], v[102:105]
	v_mfma_f32_16x16x32_bf16 v[98:101], v[180:183], v[196:199], v[98:101]
	v_mfma_f32_16x16x32_bf16 v[86:89], v[172:175], v[204:207], v[86:89]
	v_mfma_f32_16x16x32_bf16 v[82:85], v[180:183], v[204:207], v[82:85]
	v_mfma_f32_16x16x32_bf16 v[70:73], v[172:175], v[212:215], v[70:73]
	v_mfma_f32_16x16x32_bf16 v[66:69], v[180:183], v[212:215], v[66:69]
	s_barrier
	s_add_i32 s70, s72, s48
	s_mov_b32 m0, s70
	ds_read_b128 v[184:187], v150 offset:16384
	ds_read_b128 v[188:191], v150 offset:17408
	ds_read_b128 v[192:195], v150 offset:18432
	ds_read_b128 v[196:199], v150 offset:19456
	ds_read_b128 v[200:203], v150 offset:20480
	ds_read_b128 v[204:207], v150 offset:21504
	ds_read_b128 v[208:211], v150 offset:22528
	ds_read_b128 v[212:215], v150 offset:23552
	global_load_lds_dwordx4 v130, s[42:43]
	s_add_i32 m0, s70, 0x2000
	s_add_u32 s76, s42, 0x4000
	s_addc_u32 s77, s43, 0
	s_add_i32 s70, s73, s48
	global_load_lds_dwordx4 v132, s[42:43]
	s_mov_b32 m0, s70
	s_nop 0
	global_load_lds_dwordx4 v130, s[76:77]
	s_add_i32 m0, s70, 0x2000
	s_nop 0
	global_load_lds_dwordx4 v132, s[76:77]
	s_mov_b32 m0, s49
	s_nop 0
	global_load_lds_dwordx4 v130, s[44:45]
	s_mov_b32 m0, s50
	s_nop 0
	global_load_lds_dwordx4 v132, s[44:45]
	s_waitcnt vmcnt(8) lgkmcnt(0)
	s_barrier
	v_mfma_f32_16x16x32_bf16 v[62:65], v[152:155], v[184:187], v[62:65]
	v_mfma_f32_16x16x32_bf16 v[58:61], v[160:163], v[184:187], v[58:61]
	v_mfma_f32_16x16x32_bf16 v[46:49], v[152:155], v[192:195], v[46:49]
	v_mfma_f32_16x16x32_bf16 v[42:45], v[160:163], v[192:195], v[42:45]
	v_mfma_f32_16x16x32_bf16 v[30:33], v[152:155], v[200:203], v[30:33]
	v_mfma_f32_16x16x32_bf16 v[26:29], v[160:163], v[200:203], v[26:29]
	v_mfma_f32_16x16x32_bf16 v[14:17], v[152:155], v[208:211], v[14:17]
	v_mfma_f32_16x16x32_bf16 v[10:13], v[160:163], v[208:211], v[10:13]
	v_mfma_f32_16x16x32_bf16 v[62:65], v[156:159], v[188:191], v[62:65]
	v_mfma_f32_16x16x32_bf16 v[58:61], v[164:167], v[188:191], v[58:61]
	v_mfma_f32_16x16x32_bf16 v[46:49], v[156:159], v[196:199], v[46:49]
	v_mfma_f32_16x16x32_bf16 v[42:45], v[164:167], v[196:199], v[42:45]
	v_mfma_f32_16x16x32_bf16 v[30:33], v[156:159], v[204:207], v[30:33]
	v_mfma_f32_16x16x32_bf16 v[26:29], v[164:167], v[204:207], v[26:29]
	v_mfma_f32_16x16x32_bf16 v[14:17], v[156:159], v[212:215], v[14:17]
	v_mfma_f32_16x16x32_bf16 v[10:13], v[164:167], v[212:215], v[10:13]
	v_mfma_f32_16x16x32_bf16 v[54:57], v[168:171], v[184:187], v[54:57]
	v_mfma_f32_16x16x32_bf16 v[50:53], v[176:179], v[184:187], v[50:53]
	v_mfma_f32_16x16x32_bf16 v[38:41], v[168:171], v[192:195], v[38:41]
	v_mfma_f32_16x16x32_bf16 v[34:37], v[176:179], v[192:195], v[34:37]
	v_mfma_f32_16x16x32_bf16 v[22:25], v[168:171], v[200:203], v[22:25]
	v_mfma_f32_16x16x32_bf16 v[18:21], v[176:179], v[200:203], v[18:21]
	v_mfma_f32_16x16x32_bf16 v[6:9], v[168:171], v[208:211], v[6:9]
	v_mfma_f32_16x16x32_bf16 v[2:5], v[176:179], v[208:211], v[2:5]
	v_mfma_f32_16x16x32_bf16 v[54:57], v[172:175], v[188:191], v[54:57]
	v_mfma_f32_16x16x32_bf16 v[50:53], v[180:183], v[188:191], v[50:53]
	v_mfma_f32_16x16x32_bf16 v[38:41], v[172:175], v[196:199], v[38:41]
	v_mfma_f32_16x16x32_bf16 v[34:37], v[180:183], v[196:199], v[34:37]
	v_mfma_f32_16x16x32_bf16 v[22:25], v[172:175], v[204:207], v[22:25]
	v_mfma_f32_16x16x32_bf16 v[18:21], v[180:183], v[204:207], v[18:21]
	v_mfma_f32_16x16x32_bf16 v[6:9], v[172:175], v[212:215], v[6:9]
	v_mfma_f32_16x16x32_bf16 v[2:5], v[180:183], v[212:215], v[2:5]
	s_barrier
; #define PG8_STAGE(bufoff, gbase, voff) do { _Pragma("unroll") for (int _i = 0; _i < 2; ++_i) \
;         __builtin_amdgcn_global_load_lds((const unsigned*)((const char*)(gbase) + (voff)[_i]), (LAS unsigned*)(lds + (bufoff) + ldsw + _i * 8192), 16, 0, 0); } while (0)
; #define PG8_LDA(dst, b, h) do { _Pragma("unroll") for (int m = 0; m < 4; ++m) _Pragma("unroll") for (int k = 0; k < 2; ++k) dst[m][k] = *(const LAS bf16x8*)(lds + PG8_SA(b, h) + aoff + m * 2048 + k * 1024); } while (0)
; #define PG8_LDB(dst, b, h) do { _Pragma("unroll") for (int n = 0; n < 2; ++n) _Pragma("unroll") for (int k = 0; k < 2; ++k) dst[n][k] = *(const LAS bf16x8*)(lds + PG8_SB(b, h) + boff + n * 2048 + k * 1024); } while (0)
; #define PG8_MMA(ai, bj, At, Bt) do { __builtin_amdgcn_s_setprio(1); _Pragma("unroll") for (int m = 0; m < 4; ++m) _Pragma("unroll") for (int n = 0; n < 2; ++n) _Pragma("unroll") for (int k = 0; k < 2; ++k) \
;         acc[ai][bj][m][n] = __builtin_amdgcn_mfma_f32_16x16x32_bf16(Bt[n][k], At[m][k], acc[ai][bj][m][n], 0, 0, 0); __builtin_amdgcn_s_setprio(0); } while (0)
; #define PG8_WAIT_V(n) asm volatile("s_waitcnt vmcnt(" #n ")" ::: "memory")
; #define PG8_WAIT_L(n) asm volatile("s_waitcnt lgkmcnt(" #n ")" ::: "memory")
; #define PG8_BAR __builtin_amdgcn_s_barrier()
; #define PG8_SCHED __builtin_amdgcn_sched_barrier(0)
; template <class Epi, class Sched, bool ABLK = false, bool ALIGN_EPI = true, bool SP2 = true, bool BBLK = true>
; __device__ __forceinline__ void gemm_phase(LAS unsigned char* lds, const Gemm g, const Sched& S, const Epi& E) {
;     ...
;             PG8_LDB(B0, 1, 0); PG8_LDB(B1, 1, 1); PG8_SCHED; PG8_LDA(At, 1, 0); PG8_STAGE(PG8_SA(0, 1), a2 + hstepA, voffA);
;             PG8_WAIT_V(8); PG8_WAIT_L(0); PG8_BAR; PG8_MMA(0, 0, At, B0); PG8_MMA(0, 1, At, B1); PG8_BAR; PG8_SCHED;
;             PG8_LDA(At, 1, 1); PG8_STAGE(PG8_SB(1, 0), b3, voffB); PG8_STAGE(PG8_SB(1, 1), b3 + hstepB, voffB); PG8_STAGE(PG8_SA(1, 0), a3, voffA);
;             PG8_WAIT_V(8); PG8_WAIT_L(0); PG8_BAR; PG8_MMA(1, 0, At, B0); PG8_MMA(1, 1, At, B1); PG8_BAR; PG8_SCHED;
	v_add_u32_e32 v151, s60, v146
	ds_read_b128 v[152:155], v151
	ds_read_b128 v[156:159], v151 offset:1024
	ds_read_b128 v[160:163], v151 offset:2048
	ds_read_b128 v[164:167], v151 offset:3072
	v_add_u32_e32 v151, s61, v146
	ds_read_b128 v[168:171], v151
	ds_read_b128 v[172:175], v151 offset:1024
	ds_read_b128 v[176:179], v151 offset:2048
	ds_read_b128 v[180:183], v151 offset:3072
	s_add_u32 s44, s44, 0x4000
	s_addc_u32 s45, s45, 0
	s_mov_b32 m0, s51
	ds_read_b128 v[184:187], v150 offset:32768
	ds_read_b128 v[188:191], v150 offset:33792
	ds_read_b128 v[192:195], v150 offset:34816
	ds_read_b128 v[196:199], v150 offset:35840
	ds_read_b128 v[200:203], v150 offset:36864
	ds_read_b128 v[204:207], v150 offset:37888
	ds_read_b128 v[208:211], v150 offset:38912
	ds_read_b128 v[212:215], v150 offset:39936
	global_load_lds_dwordx4 v130, s[44:45]
	s_mov_b32 m0, s52
	s_nop 0
	global_load_lds_dwordx4 v132, s[44:45]
	s_waitcnt vmcnt(8) lgkmcnt(0)
	s_barrier
	v_mfma_f32_16x16x32_bf16 v[126:129], v[152:155], v[184:187], v[126:129]
	v_mfma_f32_16x16x32_bf16 v[122:125], v[160:163], v[184:187], v[122:125]
	v_mfma_f32_16x16x32_bf16 v[110:113], v[152:155], v[192:195], v[110:113]
	v_mfma_f32_16x16x32_bf16 v[106:109], v[160:163], v[192:195], v[106:109]
	v_mfma_f32_16x16x32_bf16 v[94:97], v[152:155], v[200:203], v[94:97]
	v_mfma_f32_16x16x32_bf16 v[90:93], v[160:163], v[200:203], v[90:93]
	v_mfma_f32_16x16x32_bf16 v[78:81], v[152:155], v[208:211], v[78:81]
	v_mfma_f32_16x16x32_bf16 v[74:77], v[160:163], v[208:211], v[74:77]
	v_mfma_f32_16x16x32_bf16 v[126:129], v[156:159], v[188:191], v[126:129]
	v_mfma_f32_16x16x32_bf16 v[122:125], v[164:167], v[188:191], v[122:125]
	v_mfma_f32_16x16x32_bf16 v[110:113], v[156:159], v[196:199], v[110:113]
	v_mfma_f32_16x16x32_bf16 v[106:109], v[164:167], v[196:199], v[106:109]
	v_mfma_f32_16x16x32_bf16 v[94:97], v[156:159], v[204:207], v[94:97]
	v_mfma_f32_16x16x32_bf16 v[90:93], v[164:167], v[204:207], v[90:93]
	v_mfma_f32_16x16x32_bf16 v[78:81], v[156:159], v[212:215], v[78:81]
	v_mfma_f32_16x16x32_bf16 v[74:77], v[164:167], v[212:215], v[74:77]
	v_mfma_f32_16x16x32_bf16 v[118:121], v[168:171], v[184:187], v[118:121]
	v_mfma_f32_16x16x32_bf16 v[114:117], v[176:179], v[184:187], v[114:117]
	v_mfma_f32_16x16x32_bf16 v[102:105], v[168:171], v[192:195], v[102:105]
	v_mfma_f32_16x16x32_bf16 v[98:101], v[176:179], v[192:195], v[98:101]
	v_mfma_f32_16x16x32_bf16 v[86:89], v[168:171], v[200:203], v[86:89]
	v_mfma_f32_16x16x32_bf16 v[82:85], v[176:179], v[200:203], v[82:85]
	v_mfma_f32_16x16x32_bf16 v[70:73], v[168:171], v[208:211], v[70:73]
	v_mfma_f32_16x16x32_bf16 v[66:69], v[176:179], v[208:211], v[66:69]
	v_mfma_f32_16x16x32_bf16 v[118:121], v[172:175], v[188:191], v[118:121]
	v_mfma_f32_16x16x32_bf16 v[114:117], v[180:183], v[188:191], v[114:117]
	v_mfma_f32_16x16x32_bf16 v[102:105], v[172:175], v[196:199], v[102:105]
	v_mfma_f32_16x16x32_bf16 v[98:101], v[180:183], v[196:199], v[98:101]
	v_mfma_f32_16x16x32_bf16 v[86:89], v[172:175], v[204:207], v[86:89]
	v_mfma_f32_16x16x32_bf16 v[82:85], v[180:183], v[204:207], v[82:85]
	v_mfma_f32_16x16x32_bf16 v[70:73], v[172:175], v[212:215], v[70:73]
	v_mfma_f32_16x16x32_bf16 v[66:69], v[180:183], v[212:215], v[66:69]
	s_barrier
	s_add_u32 s44, s42, 0x8000
	s_addc_u32 s45, s43, 0
	s_add_i32 s70, s60, s48
	s_mov_b32 m0, s70
	ds_read_b128 v[184:187], v150 offset:49152
	ds_read_b128 v[188:191], v150 offset:50176
	ds_read_b128 v[192:195], v150 offset:51200
	ds_read_b128 v[196:199], v150 offset:52224
	ds_read_b128 v[200:203], v150 offset:53248
	ds_read_b128 v[204:207], v150 offset:54272
	ds_read_b128 v[208:211], v150 offset:55296
	ds_read_b128 v[212:215], v150 offset:56320
	global_load_lds_dwordx4 v130, s[44:45]
	s_add_i32 m0, s70, 0x2000
	s_add_u32 s42, s42, 0xc000
	v_lshl_add_u64 v[216:217], s[44:45], 0, v[132:133]
	s_addc_u32 s43, s43, 0
	s_add_i32 s44, s61, s48
	global_load_lds_dwordx4 v[216:217], off
	s_mov_b32 m0, s44
	s_nop 0
	global_load_lds_dwordx4 v130, s[42:43]
	s_add_i32 m0, s44, 0x2000
	s_nop 0
	global_load_lds_dwordx4 v132, s[42:43]
	s_mov_b32 m0, s53
	s_nop 0
	global_load_lds_dwordx4 v130, s[40:41]
	s_mov_b32 m0, s54
	s_nop 0
	global_load_lds_dwordx4 v132, s[40:41]
	s_waitcnt vmcnt(8) lgkmcnt(0)
	s_barrier
	v_mfma_f32_16x16x32_bf16 v[62:65], v[152:155], v[184:187], v[62:65]
	v_mfma_f32_16x16x32_bf16 v[58:61], v[160:163], v[184:187], v[58:61]
	v_mfma_f32_16x16x32_bf16 v[46:49], v[152:155], v[192:195], v[46:49]
	v_mfma_f32_16x16x32_bf16 v[42:45], v[160:163], v[192:195], v[42:45]
	v_mfma_f32_16x16x32_bf16 v[30:33], v[152:155], v[200:203], v[30:33]
	v_mfma_f32_16x16x32_bf16 v[26:29], v[160:163], v[200:203], v[26:29]
	v_mfma_f32_16x16x32_bf16 v[14:17], v[152:155], v[208:211], v[14:17]
	v_mfma_f32_16x16x32_bf16 v[10:13], v[160:163], v[208:211], v[10:13]
	v_mfma_f32_16x16x32_bf16 v[62:65], v[156:159], v[188:191], v[62:65]
	v_mfma_f32_16x16x32_bf16 v[58:61], v[164:167], v[188:191], v[58:61]
	v_mfma_f32_16x16x32_bf16 v[46:49], v[156:159], v[196:199], v[46:49]
	v_mfma_f32_16x16x32_bf16 v[42:45], v[164:167], v[196:199], v[42:45]
	v_mfma_f32_16x16x32_bf16 v[30:33], v[156:159], v[204:207], v[30:33]
	v_mfma_f32_16x16x32_bf16 v[26:29], v[164:167], v[204:207], v[26:29]
	v_mfma_f32_16x16x32_bf16 v[14:17], v[156:159], v[212:215], v[14:17]
	v_mfma_f32_16x16x32_bf16 v[10:13], v[164:167], v[212:215], v[10:13]
	v_mfma_f32_16x16x32_bf16 v[54:57], v[168:171], v[184:187], v[54:57]
	v_mfma_f32_16x16x32_bf16 v[50:53], v[176:179], v[184:187], v[50:53]
	v_mfma_f32_16x16x32_bf16 v[38:41], v[168:171], v[192:195], v[38:41]
	v_mfma_f32_16x16x32_bf16 v[34:37], v[176:179], v[192:195], v[34:37]
	v_mfma_f32_16x16x32_bf16 v[22:25], v[168:171], v[200:203], v[22:25]
	v_mfma_f32_16x16x32_bf16 v[18:21], v[176:179], v[200:203], v[18:21]
	v_mfma_f32_16x16x32_bf16 v[6:9], v[168:171], v[208:211], v[6:9]
	v_mfma_f32_16x16x32_bf16 v[2:5], v[176:179], v[208:211], v[2:5]
	v_mfma_f32_16x16x32_bf16 v[54:57], v[172:175], v[188:191], v[54:57]
	v_mfma_f32_16x16x32_bf16 v[50:53], v[180:183], v[188:191], v[50:53]
	v_mfma_f32_16x16x32_bf16 v[38:41], v[172:175], v[196:199], v[38:41]
	v_mfma_f32_16x16x32_bf16 v[34:37], v[180:183], v[196:199], v[34:37]
	v_mfma_f32_16x16x32_bf16 v[22:25], v[172:175], v[204:207], v[22:25]
	v_mfma_f32_16x16x32_bf16 v[18:21], v[180:183], v[204:207], v[18:21]
	v_mfma_f32_16x16x32_bf16 v[6:9], v[172:175], v[212:215], v[6:9]
	v_mfma_f32_16x16x32_bf16 v[2:5], v[180:183], v[212:215], v[2:5]
	s_barrier
; __device__ __forceinline__ unsigned pk2(float lo, float hi) { const f32x2 v = {lo, hi}; return __builtin_bit_cast(unsigned, __builtin_convertvector(v, bf16x2_t)); }
; __device__ __forceinline__ u32x4 ror8(u32x4 v) { u32x4 r;
; #pragma unroll
;     for (int i = 0; i < 4; ++i) r[i] = (unsigned)__builtin_amdgcn_mov_dpp((int)v[i], 0x128, 0xf, 0xf, true);
;     return r; }
; __device__ __forceinline__ void store_pair(unsigned char* own, size_t stride8, int hi_off, u32x4 lo, u32x4 hi, bool upper) {
;     const u32x4 tlo = ror8(lo), thi = ror8(hi);
;     const u32x4 A = upper ? thi : lo, B = upper ? hi : tlo;
;     unsigned char* pa = upper ? own - stride8 + hi_off : own;
;     unsigned char* pb = upper ? own + hi_off : own + stride8;
;     *(u32x4*)pa = A; *(u32x4*)pb = B;
; }
;     __device__ __forceinline__ void operator()(const f32x4 (&acc)[2][2][4][2], const Unit& u, int wr, int wc, int fr, int fq) const {
;         const int row0 = u.pm * 256 + wr * 64 + fr, col0 = u.pn * 256 + wc * 64 + 8 * fq;
;         bf16_t* base = u.part == 0 ? Z + (size_t)row0 * D + col0 : P + ((size_t)(u.part - 1) * MS + (row0 - MP)) * D + col0;
; #pragma unroll
;         for (int ai = 0; ai < 2; ++ai)
; #pragma unroll
;             for (int m = 0; m < 4; ++m) { u32x4 w[2];
; #pragma unroll
;                 for (int bj = 0; bj < 2; ++bj) { const f32x4 v0 = acc[ai][bj][m][0], v1 = acc[ai][bj][m][1]; w[bj].x = pk2(v0[0], v0[1]); w[bj].y = pk2(v0[2], v0[3]); w[bj].z = pk2(v1[0], v1[1]); w[bj].w = pk2(v1[2], v1[3]); }
;                 store_pair((unsigned char*)(base + (size_t)(ai * 128 + m * 16) * D), (size_t)8 * D * 2, 64, w[0], w[1], fr >= 8); }
	s_add_u32 s38, s38, 0x10000
	s_addc_u32 s39, s39, 0
	s_cmp_ge_u32 s67, s56
	s_cbranch_scc0 .LBB0_2328
	v_lshl_add_u32 v143, s82, 8, v1
	v_add_u32_e32 v144, 0xffffe000, v143
	v_sub_co_u32_e64 v142, vcc, s55, 1
	v_mov_b32_e32 v145, s9
	s_nop 0
	v_cndmask_b32_e32 v144, v144, v143, vcc
	v_ashrrev_i32_e32 v143, 31, v142
	v_lshlrev_b64 v[142:143], 23, v[142:143]
	v_lshl_add_u64 v[142:143], s[12:13], 0, v[142:143]
	v_cndmask_b32_e32 v143, v143, v145, vcc
	v_mov_b32_e32 v145, s8
	v_cndmask_b32_e32 v142, v142, v145, vcc
	v_ashrrev_i32_e32 v145, 31, v144
	v_lshl_or_b32 v152, s78, 8, v147
	v_lshlrev_b64 v[144:145], 12, v[144:145]
	v_lshl_add_u64 v[142:143], v[142:143], 0, v[144:145]
	v_ashrrev_i32_e32 v153, 31, v152
	v_cvt_pk_bf16_f32 v126, v126, v127
	v_cvt_pk_bf16_f32 v127, v128, v129
	v_cvt_pk_bf16_f32 v128, v122, v123
	v_cvt_pk_bf16_f32 v124, v124, v125
	v_cvt_pk_bf16_f32 v118, v118, v119
	v_cvt_pk_bf16_f32 v119, v120, v121
	v_cvt_pk_bf16_f32 v114, v114, v115
	v_cvt_pk_bf16_f32 v115, v116, v117
	v_lshl_add_u64 v[142:143], v[152:153], 1, v[142:143]
	s_mov_b64 vcc, s[2:3]
	v_mov_b32_dpp v125, v118 row_ror:8 row_mask:0xf bank_mask:0xf bound_ctrl:1
	v_mov_b32_dpp v129, v119 row_ror:8 row_mask:0xf bank_mask:0xf bound_ctrl:1
	v_mov_b32_dpp v144, v114 row_ror:8 row_mask:0xf bank_mask:0xf bound_ctrl:1
	v_mov_b32_dpp v145, v115 row_ror:8 row_mask:0xf bank_mask:0xf bound_ctrl:1
	v_lshl_add_u64 v[122:123], v[142:143], 0, v[134:135]
	v_cndmask_b32_dpp v117, v124, v115, vcc row_ror:8 row_mask:0xf bank_mask:0xf bound_ctrl:1
	v_cndmask_b32_dpp v116, v128, v114, vcc row_ror:8 row_mask:0xf bank_mask:0xf bound_ctrl:1
	v_cndmask_b32_dpp v115, v127, v119, vcc row_ror:8 row_mask:0xf bank_mask:0xf bound_ctrl:1
	v_cndmask_b32_dpp v114, v126, v118, vcc row_ror:8 row_mask:0xf bank_mask:0xf bound_ctrl:1
	v_cndmask_b32_e64 v121, v124, v145, s[2:3]
	v_cndmask_b32_e64 v120, v128, v144, s[2:3]
	v_cndmask_b32_e64 v119, v127, v129, s[2:3]
	v_cndmask_b32_e64 v118, v126, v125, s[2:3]
	v_cvt_pk_bf16_f32 v110, v110, v111
	v_cvt_pk_bf16_f32 v111, v112, v113
	v_cvt_pk_bf16_f32 v112, v106, v107
	v_cvt_pk_bf16_f32 v113, v108, v109
	v_cvt_pk_bf16_f32 v102, v102, v103
	v_cvt_pk_bf16_f32 v103, v104, v105
	v_cvt_pk_bf16_f32 v98, v98, v99
	v_cvt_pk_bf16_f32 v99, v100, v101
	v_lshl_add_u64 v[124:125], v[142:143], 0, v[136:137]
	s_and_b64 vcc, exec, s[14:15]
	s_cbranch_vccz .LBB0_2331
	s_barrier
.LBB0_2331:
	global_store_dwordx4 v[122:123], v[118:121], off
	global_store_dwordx4 v[124:125], v[114:117], off
	v_lshl_add_u64 v[106:107], v[142:143], 0, s[16:17]
	s_mov_b64 vcc, s[2:3]
	v_mov_b32_dpp v114, v102 row_ror:8 row_mask:0xf bank_mask:0xf bound_ctrl:1
	v_mov_b32_dpp v115, v103 row_ror:8 row_mask:0xf bank_mask:0xf bound_ctrl:1
	v_mov_b32_dpp v116, v98 row_ror:8 row_mask:0xf bank_mask:0xf bound_ctrl:1
	v_mov_b32_dpp v117, v99 row_ror:8 row_mask:0xf bank_mask:0xf bound_ctrl:1
	v_lshl_add_u64 v[108:109], v[106:107], 0, v[134:135]
	v_cndmask_b32_dpp v101, v113, v99, vcc row_ror:8 row_mask:0xf bank_mask:0xf bound_ctrl:1
	v_cndmask_b32_dpp v100, v112, v98, vcc row_ror:8 row_mask:0xf bank_mask:0xf bound_ctrl:1
	v_cndmask_b32_dpp v99, v111, v103, vcc row_ror:8 row_mask:0xf bank_mask:0xf bound_ctrl:1
	v_cndmask_b32_dpp v98, v110, v102, vcc row_ror:8 row_mask:0xf bank_mask:0xf bound_ctrl:1
	v_cndmask_b32_e64 v105, v113, v117, s[2:3]
	v_cndmask_b32_e64 v104, v112, v116, s[2:3]
	v_cndmask_b32_e64 v103, v111, v115, s[2:3]
	v_cndmask_b32_e64 v102, v110, v114, s[2:3]
	v_cvt_pk_bf16_f32 v94, v94, v95
	v_cvt_pk_bf16_f32 v95, v96, v97
	v_cvt_pk_bf16_f32 v96, v90, v91
	v_cvt_pk_bf16_f32 v97, v92, v93
	v_cvt_pk_bf16_f32 v86, v86, v87
	v_cvt_pk_bf16_f32 v87, v88, v89
	v_cvt_pk_bf16_f32 v82, v82, v83
	v_cvt_pk_bf16_f32 v83, v84, v85
	v_lshl_add_u64 v[106:107], v[106:107], 0, v[136:137]
	global_store_dwordx4 v[108:109], v[102:105], off
	global_store_dwordx4 v[106:107], v[98:101], off
	v_lshl_add_u64 v[90:91], v[142:143], 0, s[18:19]
	s_mov_b64 vcc, s[2:3]
	v_mov_b32_dpp v98, v86 row_ror:8 row_mask:0xf bank_mask:0xf bound_ctrl:1
	v_mov_b32_dpp v99, v87 row_ror:8 row_mask:0xf bank_mask:0xf bound_ctrl:1
	v_mov_b32_dpp v100, v82 row_ror:8 row_mask:0xf bank_mask:0xf bound_ctrl:1
	v_mov_b32_dpp v101, v83 row_ror:8 row_mask:0xf bank_mask:0xf bound_ctrl:1
	v_lshl_add_u64 v[92:93], v[90:91], 0, v[134:135]
	v_cndmask_b32_dpp v85, v97, v83, vcc row_ror:8 row_mask:0xf bank_mask:0xf bound_ctrl:1
	v_cndmask_b32_dpp v84, v96, v82, vcc row_ror:8 row_mask:0xf bank_mask:0xf bound_ctrl:1
	v_cndmask_b32_dpp v83, v95, v87, vcc row_ror:8 row_mask:0xf bank_mask:0xf bound_ctrl:1
	v_cndmask_b32_dpp v82, v94, v86, vcc row_ror:8 row_mask:0xf bank_mask:0xf bound_ctrl:1
	v_cndmask_b32_e64 v89, v97, v101, s[2:3]
	v_cndmask_b32_e64 v88, v96, v100, s[2:3]
	v_cndmask_b32_e64 v87, v95, v99, s[2:3]
	v_cndmask_b32_e64 v86, v94, v98, s[2:3]
	v_cvt_pk_bf16_f32 v78, v78, v79
	v_cvt_pk_bf16_f32 v79, v80, v81
	v_cvt_pk_bf16_f32 v80, v74, v75
	v_cvt_pk_bf16_f32 v81, v76, v77
	v_cvt_pk_bf16_f32 v70, v70, v71
	v_cvt_pk_bf16_f32 v71, v72, v73
	v_cvt_pk_bf16_f32 v66, v66, v67
	v_cvt_pk_bf16_f32 v67, v68, v69
	v_lshl_add_u64 v[90:91], v[90:91], 0, v[136:137]
	global_store_dwordx4 v[92:93], v[86:89], off
	global_store_dwordx4 v[90:91], v[82:85], off
	v_lshl_add_u64 v[74:75], v[142:143], 0, s[20:21]
	s_mov_b64 vcc, s[2:3]
	v_mov_b32_dpp v82, v70 row_ror:8 row_mask:0xf bank_mask:0xf bound_ctrl:1
	v_mov_b32_dpp v83, v71 row_ror:8 row_mask:0xf bank_mask:0xf bound_ctrl:1
	v_mov_b32_dpp v84, v66 row_ror:8 row_mask:0xf bank_mask:0xf bound_ctrl:1
	v_mov_b32_dpp v85, v67 row_ror:8 row_mask:0xf bank_mask:0xf bound_ctrl:1
	v_lshl_add_u64 v[76:77], v[74:75], 0, v[134:135]
; __device__ __forceinline__ unsigned pk2(float lo, float hi) { const f32x2 v = {lo, hi}; return __builtin_bit_cast(unsigned, __builtin_convertvector(v, bf16x2_t)); }
; __device__ __forceinline__ u32x4 ror8(u32x4 v) { u32x4 r;
; #pragma unroll
;     for (int i = 0; i < 4; ++i) r[i] = (unsigned)__builtin_amdgcn_mov_dpp((int)v[i], 0x128, 0xf, 0xf, true);
;     return r; }
; __device__ __forceinline__ void store_pair(unsigned char* own, size_t stride8, int hi_off, u32x4 lo, u32x4 hi, bool upper) {
;     const u32x4 tlo = ror8(lo), thi = ror8(hi);
;     const u32x4 A = upper ? thi : lo, B = upper ? hi : tlo;
;     unsigned char* pa = upper ? own - stride8 + hi_off : own;
;     unsigned char* pb = upper ? own + hi_off : own + stride8;
;     *(u32x4*)pa = A; *(u32x4*)pb = B;
; }
;     __device__ __forceinline__ void operator()(const f32x4 (&acc)[2][2][4][2], const Unit& u, int wr, int wc, int fr, int fq) const {
;         const int row0 = u.pm * 256 + wr * 64 + fr, col0 = u.pn * 256 + wc * 64 + 8 * fq;
;         bf16_t* base = u.part == 0 ? Z + (size_t)row0 * D + col0 : P + ((size_t)(u.part - 1) * MS + (row0 - MP)) * D + col0;
; #pragma unroll
;         for (int ai = 0; ai < 2; ++ai)
; #pragma unroll
;             for (int m = 0; m < 4; ++m) { u32x4 w[2];
; #pragma unroll
;                 for (int bj = 0; bj < 2; ++bj) { const f32x4 v0 = acc[ai][bj][m][0], v1 = acc[ai][bj][m][1]; w[bj].x = pk2(v0[0], v0[1]); w[bj].y = pk2(v0[2], v0[3]); w[bj].z = pk2(v1[0], v1[1]); w[bj].w = pk2(v1[2], v1[3]); }
;                 store_pair((unsigned char*)(base + (size_t)(ai * 128 + m * 16) * D), (size_t)8 * D * 2, 64, w[0], w[1], fr >= 8); }
	v_cndmask_b32_dpp v69, v81, v67, vcc row_ror:8 row_mask:0xf bank_mask:0xf bound_ctrl:1
	v_cndmask_b32_dpp v68, v80, v66, vcc row_ror:8 row_mask:0xf bank_mask:0xf bound_ctrl:1
	v_cndmask_b32_dpp v67, v79, v71, vcc row_ror:8 row_mask:0xf bank_mask:0xf bound_ctrl:1
	v_cndmask_b32_dpp v66, v78, v70, vcc row_ror:8 row_mask:0xf bank_mask:0xf bound_ctrl:1
	v_cndmask_b32_e64 v73, v81, v85, s[2:3]
	v_cndmask_b32_e64 v72, v80, v84, s[2:3]
	v_cndmask_b32_e64 v71, v79, v83, s[2:3]
	v_cndmask_b32_e64 v70, v78, v82, s[2:3]
	v_cvt_pk_bf16_f32 v62, v62, v63
	v_cvt_pk_bf16_f32 v63, v64, v65
	v_cvt_pk_bf16_f32 v64, v58, v59
	v_cvt_pk_bf16_f32 v65, v60, v61
	v_cvt_pk_bf16_f32 v54, v54, v55
	v_cvt_pk_bf16_f32 v55, v56, v57
	v_cvt_pk_bf16_f32 v50, v50, v51
	v_cvt_pk_bf16_f32 v51, v52, v53
	v_lshl_add_u64 v[74:75], v[74:75], 0, v[136:137]
	global_store_dwordx4 v[76:77], v[70:73], off
	global_store_dwordx4 v[74:75], v[66:69], off
	v_lshl_add_u64 v[58:59], v[142:143], 0, s[22:23]
	s_mov_b64 vcc, s[2:3]
	v_mov_b32_dpp v66, v54 row_ror:8 row_mask:0xf bank_mask:0xf bound_ctrl:1
	v_mov_b32_dpp v67, v55 row_ror:8 row_mask:0xf bank_mask:0xf bound_ctrl:1
	v_mov_b32_dpp v68, v50 row_ror:8 row_mask:0xf bank_mask:0xf bound_ctrl:1
	v_mov_b32_dpp v69, v51 row_ror:8 row_mask:0xf bank_mask:0xf bound_ctrl:1
	v_lshl_add_u64 v[60:61], v[58:59], 0, v[134:135]
	v_cndmask_b32_dpp v53, v65, v51, vcc row_ror:8 row_mask:0xf bank_mask:0xf bound_ctrl:1
	v_cndmask_b32_dpp v52, v64, v50, vcc row_ror:8 row_mask:0xf bank_mask:0xf bound_ctrl:1
	v_cndmask_b32_dpp v51, v63, v55, vcc row_ror:8 row_mask:0xf bank_mask:0xf bound_ctrl:1
	v_cndmask_b32_dpp v50, v62, v54, vcc row_ror:8 row_mask:0xf bank_mask:0xf bound_ctrl:1
	v_cndmask_b32_e64 v57, v65, v69, s[2:3]
	v_cndmask_b32_e64 v56, v64, v68, s[2:3]
	v_cndmask_b32_e64 v55, v63, v67, s[2:3]
	v_cndmask_b32_e64 v54, v62, v66, s[2:3]
	v_cvt_pk_bf16_f32 v46, v46, v47
	v_cvt_pk_bf16_f32 v47, v48, v49
	v_cvt_pk_bf16_f32 v48, v42, v43
	v_cvt_pk_bf16_f32 v49, v44, v45
	v_cvt_pk_bf16_f32 v38, v38, v39
	v_cvt_pk_bf16_f32 v39, v40, v41
	v_cvt_pk_bf16_f32 v34, v34, v35
	v_cvt_pk_bf16_f32 v35, v36, v37
	v_lshl_add_u64 v[58:59], v[58:59], 0, v[136:137]
	global_store_dwordx4 v[60:61], v[54:57], off
	global_store_dwordx4 v[58:59], v[50:53], off
	v_lshl_add_u64 v[42:43], v[142:143], 0, s[24:25]
	s_mov_b64 vcc, s[2:3]
	v_mov_b32_dpp v50, v38 row_ror:8 row_mask:0xf bank_mask:0xf bound_ctrl:1
	v_mov_b32_dpp v51, v39 row_ror:8 row_mask:0xf bank_mask:0xf bound_ctrl:1
	v_mov_b32_dpp v52, v34 row_ror:8 row_mask:0xf bank_mask:0xf bound_ctrl:1
	v_mov_b32_dpp v53, v35 row_ror:8 row_mask:0xf bank_mask:0xf bound_ctrl:1
	v_lshl_add_u64 v[44:45], v[42:43], 0, v[134:135]
	v_cndmask_b32_dpp v37, v49, v35, vcc row_ror:8 row_mask:0xf bank_mask:0xf bound_ctrl:1
	v_cndmask_b32_dpp v36, v48, v34, vcc row_ror:8 row_mask:0xf bank_mask:0xf bound_ctrl:1
	v_cndmask_b32_dpp v35, v47, v39, vcc row_ror:8 row_mask:0xf bank_mask:0xf bound_ctrl:1
	v_cndmask_b32_dpp v34, v46, v38, vcc row_ror:8 row_mask:0xf bank_mask:0xf bound_ctrl:1
	v_cndmask_b32_e64 v41, v49, v53, s[2:3]
	v_cndmask_b32_e64 v40, v48, v52, s[2:3]
	v_cndmask_b32_e64 v39, v47, v51, s[2:3]
	v_cndmask_b32_e64 v38, v46, v50, s[2:3]
	v_cvt_pk_bf16_f32 v30, v30, v31
	v_cvt_pk_bf16_f32 v31, v32, v33
	v_cvt_pk_bf16_f32 v32, v26, v27
	v_cvt_pk_bf16_f32 v33, v28, v29
	v_cvt_pk_bf16_f32 v22, v22, v23
	v_cvt_pk_bf16_f32 v23, v24, v25
	v_cvt_pk_bf16_f32 v18, v18, v19
	v_cvt_pk_bf16_f32 v19, v20, v21
	v_lshl_add_u64 v[42:43], v[42:43], 0, v[136:137]
	global_store_dwordx4 v[44:45], v[38:41], off
	global_store_dwordx4 v[42:43], v[34:37], off
	v_lshl_add_u64 v[26:27], v[142:143], 0, s[26:27]
	s_mov_b64 vcc, s[2:3]
	v_mov_b32_dpp v34, v22 row_ror:8 row_mask:0xf bank_mask:0xf bound_ctrl:1
	v_mov_b32_dpp v35, v23 row_ror:8 row_mask:0xf bank_mask:0xf bound_ctrl:1
	v_mov_b32_dpp v36, v18 row_ror:8 row_mask:0xf bank_mask:0xf bound_ctrl:1
	v_mov_b32_dpp v37, v19 row_ror:8 row_mask:0xf bank_mask:0xf bound_ctrl:1
	v_lshl_add_u64 v[28:29], v[26:27], 0, v[134:135]
	v_cndmask_b32_dpp v21, v33, v19, vcc row_ror:8 row_mask:0xf bank_mask:0xf bound_ctrl:1
	v_cndmask_b32_dpp v20, v32, v18, vcc row_ror:8 row_mask:0xf bank_mask:0xf bound_ctrl:1
	v_cndmask_b32_dpp v19, v31, v23, vcc row_ror:8 row_mask:0xf bank_mask:0xf bound_ctrl:1
	v_cndmask_b32_dpp v18, v30, v22, vcc row_ror:8 row_mask:0xf bank_mask:0xf bound_ctrl:1
	v_cndmask_b32_e64 v25, v33, v37, s[2:3]
	v_cndmask_b32_e64 v24, v32, v36, s[2:3]
	v_cndmask_b32_e64 v23, v31, v35, s[2:3]
	v_cndmask_b32_e64 v22, v30, v34, s[2:3]
	v_cvt_pk_bf16_f32 v14, v14, v15
	v_cvt_pk_bf16_f32 v15, v16, v17
	v_cvt_pk_bf16_f32 v16, v10, v11
	v_cvt_pk_bf16_f32 v17, v12, v13
	v_cvt_pk_bf16_f32 v6, v6, v7
	v_cvt_pk_bf16_f32 v7, v8, v9
	v_cvt_pk_bf16_f32 v2, v2, v3
	v_cvt_pk_bf16_f32 v3, v4, v5
	v_lshl_add_u64 v[26:27], v[26:27], 0, v[136:137]
	global_store_dwordx4 v[28:29], v[22:25], off
	global_store_dwordx4 v[26:27], v[18:21], off
	v_lshl_add_u64 v[10:11], v[142:143], 0, s[28:29]
	s_mov_b64 vcc, s[2:3]
	v_mov_b32_dpp v18, v6 row_ror:8 row_mask:0xf bank_mask:0xf bound_ctrl:1
	v_mov_b32_dpp v19, v7 row_ror:8 row_mask:0xf bank_mask:0xf bound_ctrl:1
	v_mov_b32_dpp v20, v2 row_ror:8 row_mask:0xf bank_mask:0xf bound_ctrl:1
	v_mov_b32_dpp v21, v3 row_ror:8 row_mask:0xf bank_mask:0xf bound_ctrl:1
	v_lshl_add_u64 v[12:13], v[10:11], 0, v[134:135]
	v_cndmask_b32_dpp v5, v17, v3, vcc row_ror:8 row_mask:0xf bank_mask:0xf bound_ctrl:1
	v_cndmask_b32_dpp v4, v16, v2, vcc row_ror:8 row_mask:0xf bank_mask:0xf bound_ctrl:1
	v_cndmask_b32_dpp v3, v15, v7, vcc row_ror:8 row_mask:0xf bank_mask:0xf bound_ctrl:1
	v_cndmask_b32_dpp v2, v14, v6, vcc row_ror:8 row_mask:0xf bank_mask:0xf bound_ctrl:1
	v_cndmask_b32_e64 v9, v17, v21, s[2:3]
	v_cndmask_b32_e64 v8, v16, v20, s[2:3]
	v_cndmask_b32_e64 v7, v15, v19, s[2:3]
	v_cndmask_b32_e64 v6, v14, v18, s[2:3]
	s_and_b64 vcc, exec, s[6:7]
	s_mov_b64 s[6:7], -1
	v_lshl_add_u64 v[10:11], v[10:11], 0, v[136:137]
	global_store_dwordx4 v[12:13], v[6:9], off
	global_store_dwordx4 v[10:11], v[2:5], off
	s_cbranch_vccnz .LBB0_2326
	s_andn2_b64 vcc, exec, s[10:11]
	s_cbranch_vccnz .LBB0_2325
	s_barrier
	s_branch .LBB0_2325
